# c14: same as c13 but without the snake (m,n) order: adjacent k-step pairs in the original accumulator order
# speedup vs baseline: 1.0177x; 1.0005x over previous
.LBB0_343:
	s_ashr_i32 s11, s10, 31
	s_lshl_b64 s[12:13], s[10:11], 20
	s_add_u32 s12, s26, s12
	s_addc_u32 s13, s27, s13
	s_and_b64 s[14:15], s[2:3], exec
	s_cselect_b32 s11, s13, s21
	s_cselect_b32 s75, s12, s20
	s_ashr_i32 s9, s8, 31
	s_lshl_b64 s[14:15], s[8:9], 20
	s_add_u32 s14, s28, s14
	s_addc_u32 s15, s29, s15
	s_and_b64 s[22:23], s[2:3], exec
	s_cselect_b32 s9, s15, s19
	s_cselect_b32 s76, s14, s18
	s_add_u32 s77, s18, 0x100
	s_addc_u32 s78, s19, 0
	s_add_u32 s18, s20, 0x80080
	s_addc_u32 s19, s21, 0
	s_add_u32 s79, s20, 0x100
	s_addc_u32 s80, s21, 0
	s_mov_b32 s81, -2
	ds_read_b128 v[148:151], v143
	ds_read_b128 v[152:155], v143 offset:1024
	ds_read_b128 v[156:159], v143 offset:2048
	ds_read_b128 v[160:163], v143 offset:3072
	ds_read_b128 v[164:167], v144
	ds_read_b128 v[168:171], v144 offset:1024
	ds_read_b128 v[172:175], v144 offset:2048
	ds_read_b128 v[176:179], v144 offset:3072
	s_cmp_eq_u32 s81, 28
	s_cselect_b32 s21, s9, s78
	s_cselect_b32 s20, s76, s77
	s_cselect_b32 s23, s11, s80
	s_cselect_b32 s22, s75, s79
	ds_read_b128 v[180:183], v145
	ds_read_b128 v[184:187], v145 offset:1024
	ds_read_b128 v[188:191], v145 offset:2048
	ds_read_b128 v[192:195], v145 offset:3072
	ds_read_b128 v[196:199], v145 offset:4096
	ds_read_b128 v[200:203], v145 offset:5120
	ds_read_b128 v[204:207], v145 offset:6144
	ds_read_b128 v[208:211], v145 offset:7168
	s_add_u32 s82, s18, 0xfff80000
	s_addc_u32 s83, s19, -1
	s_mov_b32 s86, m0
	s_mov_b32 m0, s64
	s_nop 0
	global_load_lds_dwordx4 v138, s[82:83]
	s_mov_b32 m0, s86
	s_nop 0
	s_mov_b32 s86, m0
	s_mov_b32 m0, s67
	s_nop 0
	global_load_lds_dwordx4 v140, s[82:83]
	s_mov_b32 m0, s86
	s_mov_b32 s82, m0
	s_mov_b32 m0, s65
	s_nop 0
	global_load_lds_dwordx4 v138, s[18:19]
	s_mov_b32 m0, s82
	s_nop 0
	s_mov_b32 s82, m0
	s_mov_b32 m0, s73
	s_nop 0
	global_load_lds_dwordx4 v140, s[18:19]
	s_mov_b32 m0, s82
	s_waitcnt vmcnt(8)
	s_waitcnt lgkmcnt(0)
	s_barrier
	s_setprio 1
	s_waitcnt lgkmcnt(7)
	v_mfma_f32_16x16x32_bf16 v[126:129], v[148:151], v[180:183], 0
	v_mfma_f32_16x16x32_bf16 v[126:129], v[152:155], v[184:187], v[126:129]
	s_waitcnt lgkmcnt(5)
	v_mfma_f32_16x16x32_bf16 v[122:125], v[156:159], v[180:183], 0
	v_mfma_f32_16x16x32_bf16 v[122:125], v[160:163], v[184:187], v[122:125]
	s_waitcnt lgkmcnt(3)
	v_mfma_f32_16x16x32_bf16 v[110:113], v[148:151], v[188:191], 0
	v_mfma_f32_16x16x32_bf16 v[110:113], v[152:155], v[192:195], v[110:113]
	s_waitcnt lgkmcnt(1)
	v_mfma_f32_16x16x32_bf16 v[106:109], v[156:159], v[188:191], 0
	v_mfma_f32_16x16x32_bf16 v[106:109], v[160:163], v[192:195], v[106:109]
	v_mfma_f32_16x16x32_bf16 v[94:97], v[148:151], v[196:199], 0
	v_mfma_f32_16x16x32_bf16 v[94:97], v[152:155], v[200:203], v[94:97]
	v_mfma_f32_16x16x32_bf16 v[90:93], v[156:159], v[196:199], 0
	v_mfma_f32_16x16x32_bf16 v[90:93], v[160:163], v[200:203], v[90:93]
	v_mfma_f32_16x16x32_bf16 v[78:81], v[148:151], v[204:207], 0
	v_mfma_f32_16x16x32_bf16 v[78:81], v[152:155], v[208:211], v[78:81]
	s_waitcnt lgkmcnt(0)
	v_mfma_f32_16x16x32_bf16 v[74:77], v[156:159], v[204:207], 0
	v_mfma_f32_16x16x32_bf16 v[74:77], v[160:163], v[208:211], v[74:77]
	s_setprio 0
	s_setprio 1
	v_mfma_f32_16x16x32_bf16 v[118:121], v[164:167], v[180:183], 0
	v_mfma_f32_16x16x32_bf16 v[118:121], v[168:171], v[184:187], v[118:121]
	v_mfma_f32_16x16x32_bf16 v[114:117], v[172:175], v[180:183], 0
	v_mfma_f32_16x16x32_bf16 v[114:117], v[176:179], v[184:187], v[114:117]
	v_mfma_f32_16x16x32_bf16 v[102:105], v[164:167], v[188:191], 0
	v_mfma_f32_16x16x32_bf16 v[102:105], v[168:171], v[192:195], v[102:105]
	v_mfma_f32_16x16x32_bf16 v[98:101], v[172:175], v[188:191], 0
	v_mfma_f32_16x16x32_bf16 v[98:101], v[176:179], v[192:195], v[98:101]
	v_mfma_f32_16x16x32_bf16 v[86:89], v[164:167], v[196:199], 0
	v_mfma_f32_16x16x32_bf16 v[86:89], v[168:171], v[200:203], v[86:89]
	v_mfma_f32_16x16x32_bf16 v[82:85], v[172:175], v[196:199], 0
	v_mfma_f32_16x16x32_bf16 v[82:85], v[176:179], v[200:203], v[82:85]
	v_mfma_f32_16x16x32_bf16 v[70:73], v[164:167], v[204:207], 0
	v_mfma_f32_16x16x32_bf16 v[70:73], v[168:171], v[208:211], v[70:73]
	s_setprio 2
	s_barrier
	v_mfma_f32_16x16x32_bf16 v[66:69], v[172:175], v[204:207], 0
	v_mfma_f32_16x16x32_bf16 v[66:69], v[176:179], v[208:211], v[66:69]
	s_setprio 0
	ds_read_b128 v[180:183], v145 offset:16384
	ds_read_b128 v[184:187], v145 offset:17408
	ds_read_b128 v[188:191], v145 offset:18432
	ds_read_b128 v[192:195], v145 offset:19456
	ds_read_b128 v[196:199], v145 offset:20480
	ds_read_b128 v[200:203], v145 offset:21504
	ds_read_b128 v[204:207], v145 offset:22528
	ds_read_b128 v[208:211], v145 offset:23552
	s_mov_b32 s82, m0
	s_mov_b32 m0, s35
	s_nop 0
	global_load_lds_dwordx4 v139, s[20:21]
	s_mov_b32 m0, s82
	s_nop 0
	s_mov_b32 s82, m0
	s_mov_b32 m0, s36
	s_nop 0
	global_load_lds_dwordx4 v141, s[20:21]
	s_mov_b32 m0, s82
	s_add_u32 s82, s20, 0x80000
	s_addc_u32 s83, s21, 0
	s_mov_b32 s86, m0
	s_mov_b32 m0, s37
	s_nop 0
	global_load_lds_dwordx4 v139, s[82:83]
	s_mov_b32 m0, s86
	s_nop 0
	s_mov_b32 s86, m0
	s_mov_b32 m0, s42
	s_nop 0
	global_load_lds_dwordx4 v141, s[82:83]
	s_mov_b32 m0, s86
	s_waitcnt vmcnt(4)
	s_waitcnt lgkmcnt(0)
	s_barrier
	s_setprio 1
	s_waitcnt lgkmcnt(7)
	v_mfma_f32_16x16x32_bf16 v[62:65], v[148:151], v[180:183], 0
	v_mfma_f32_16x16x32_bf16 v[62:65], v[152:155], v[184:187], v[62:65]
	s_waitcnt lgkmcnt(5)
	v_mfma_f32_16x16x32_bf16 v[58:61], v[156:159], v[180:183], 0
	v_mfma_f32_16x16x32_bf16 v[58:61], v[160:163], v[184:187], v[58:61]
	s_waitcnt lgkmcnt(3)
	v_mfma_f32_16x16x32_bf16 v[46:49], v[148:151], v[188:191], 0
	v_mfma_f32_16x16x32_bf16 v[46:49], v[152:155], v[192:195], v[46:49]
	s_waitcnt lgkmcnt(1)
	v_mfma_f32_16x16x32_bf16 v[42:45], v[156:159], v[188:191], 0
	v_mfma_f32_16x16x32_bf16 v[42:45], v[160:163], v[192:195], v[42:45]
	v_mfma_f32_16x16x32_bf16 v[30:33], v[148:151], v[196:199], 0
	v_mfma_f32_16x16x32_bf16 v[30:33], v[152:155], v[200:203], v[30:33]
	v_mfma_f32_16x16x32_bf16 v[26:29], v[156:159], v[196:199], 0
	v_mfma_f32_16x16x32_bf16 v[26:29], v[160:163], v[200:203], v[26:29]
	v_mfma_f32_16x16x32_bf16 v[14:17], v[148:151], v[204:207], 0
	v_mfma_f32_16x16x32_bf16 v[14:17], v[152:155], v[208:211], v[14:17]
	s_waitcnt lgkmcnt(0)
	v_mfma_f32_16x16x32_bf16 v[10:13], v[156:159], v[204:207], 0
	v_mfma_f32_16x16x32_bf16 v[10:13], v[160:163], v[208:211], v[10:13]
	s_setprio 0
	s_setprio 1
	v_mfma_f32_16x16x32_bf16 v[54:57], v[164:167], v[180:183], 0
	v_mfma_f32_16x16x32_bf16 v[54:57], v[168:171], v[184:187], v[54:57]
	v_mfma_f32_16x16x32_bf16 v[50:53], v[172:175], v[180:183], 0
	v_mfma_f32_16x16x32_bf16 v[50:53], v[176:179], v[184:187], v[50:53]
	v_mfma_f32_16x16x32_bf16 v[38:41], v[164:167], v[188:191], 0
	v_mfma_f32_16x16x32_bf16 v[38:41], v[168:171], v[192:195], v[38:41]
	v_mfma_f32_16x16x32_bf16 v[34:37], v[172:175], v[188:191], 0
	v_mfma_f32_16x16x32_bf16 v[34:37], v[176:179], v[192:195], v[34:37]
	v_mfma_f32_16x16x32_bf16 v[22:25], v[164:167], v[196:199], 0
	v_mfma_f32_16x16x32_bf16 v[22:25], v[168:171], v[200:203], v[22:25]
	v_mfma_f32_16x16x32_bf16 v[18:21], v[172:175], v[196:199], 0
	v_mfma_f32_16x16x32_bf16 v[18:21], v[176:179], v[200:203], v[18:21]
	v_mfma_f32_16x16x32_bf16 v[6:9], v[164:167], v[204:207], 0
	v_mfma_f32_16x16x32_bf16 v[6:9], v[168:171], v[208:211], v[6:9]
	s_setprio 2
	s_barrier
	v_mfma_f32_16x16x32_bf16 v[2:5], v[172:175], v[204:207], 0
	v_mfma_f32_16x16x32_bf16 v[2:5], v[176:179], v[208:211], v[2:5]
	s_setprio 0
	ds_read_b128 v[148:151], v146
	ds_read_b128 v[152:155], v146 offset:1024
	ds_read_b128 v[156:159], v146 offset:2048
	ds_read_b128 v[160:163], v146 offset:3072
	ds_read_b128 v[164:167], v147
	ds_read_b128 v[168:171], v147 offset:1024
	ds_read_b128 v[172:175], v147 offset:2048
	ds_read_b128 v[176:179], v147 offset:3072
	ds_read_b128 v[180:183], v145 offset:32768
	ds_read_b128 v[184:187], v145 offset:33792
	ds_read_b128 v[188:191], v145 offset:34816
	ds_read_b128 v[192:195], v145 offset:35840
	ds_read_b128 v[196:199], v145 offset:36864
	ds_read_b128 v[200:203], v145 offset:37888
	ds_read_b128 v[204:207], v145 offset:38912
	ds_read_b128 v[208:211], v145 offset:39936
	s_mov_b32 s82, m0
	s_mov_b32 m0, s31
	s_nop 0
	global_load_lds_dwordx4 v138, s[22:23]
	s_mov_b32 m0, s82
	s_nop 0
	s_mov_b32 s82, m0
	s_mov_b32 m0, s43
	s_nop 0
	global_load_lds_dwordx4 v140, s[22:23]
	s_mov_b32 m0, s82
	s_add_u32 s22, s22, 0x80000
	s_addc_u32 s23, s23, 0
	s_mov_b32 s82, m0
	s_mov_b32 m0, s46
	s_nop 0
	global_load_lds_dwordx4 v138, s[22:23]
	s_mov_b32 m0, s82
	s_nop 0
	s_mov_b32 s82, m0
	s_mov_b32 m0, s47
	s_nop 0
	global_load_lds_dwordx4 v140, s[22:23]
	s_mov_b32 m0, s82
	s_waitcnt vmcnt(8)
	s_waitcnt lgkmcnt(0)
	s_barrier
	s_setprio 1
	s_waitcnt lgkmcnt(7)
	v_mfma_f32_16x16x32_bf16 v[126:129], v[148:151], v[180:183], v[126:129]
	v_mfma_f32_16x16x32_bf16 v[126:129], v[152:155], v[184:187], v[126:129]
	s_waitcnt lgkmcnt(5)
	v_mfma_f32_16x16x32_bf16 v[122:125], v[156:159], v[180:183], v[122:125]
	v_mfma_f32_16x16x32_bf16 v[122:125], v[160:163], v[184:187], v[122:125]
	s_waitcnt lgkmcnt(3)
	v_mfma_f32_16x16x32_bf16 v[110:113], v[148:151], v[188:191], v[110:113]
	v_mfma_f32_16x16x32_bf16 v[110:113], v[152:155], v[192:195], v[110:113]
	s_waitcnt lgkmcnt(1)
	v_mfma_f32_16x16x32_bf16 v[106:109], v[156:159], v[188:191], v[106:109]
	v_mfma_f32_16x16x32_bf16 v[106:109], v[160:163], v[192:195], v[106:109]
	v_mfma_f32_16x16x32_bf16 v[94:97], v[148:151], v[196:199], v[94:97]
	v_mfma_f32_16x16x32_bf16 v[94:97], v[152:155], v[200:203], v[94:97]
	v_mfma_f32_16x16x32_bf16 v[90:93], v[156:159], v[196:199], v[90:93]
	v_mfma_f32_16x16x32_bf16 v[90:93], v[160:163], v[200:203], v[90:93]
	v_mfma_f32_16x16x32_bf16 v[78:81], v[148:151], v[204:207], v[78:81]
	v_mfma_f32_16x16x32_bf16 v[78:81], v[152:155], v[208:211], v[78:81]
	s_waitcnt lgkmcnt(0)
	v_mfma_f32_16x16x32_bf16 v[74:77], v[156:159], v[204:207], v[74:77]
	v_mfma_f32_16x16x32_bf16 v[74:77], v[160:163], v[208:211], v[74:77]
	s_setprio 0
	s_setprio 1
	v_mfma_f32_16x16x32_bf16 v[118:121], v[164:167], v[180:183], v[118:121]
	v_mfma_f32_16x16x32_bf16 v[118:121], v[168:171], v[184:187], v[118:121]
	v_mfma_f32_16x16x32_bf16 v[114:117], v[172:175], v[180:183], v[114:117]
	v_mfma_f32_16x16x32_bf16 v[114:117], v[176:179], v[184:187], v[114:117]
	v_mfma_f32_16x16x32_bf16 v[102:105], v[164:167], v[188:191], v[102:105]
	v_mfma_f32_16x16x32_bf16 v[102:105], v[168:171], v[192:195], v[102:105]
	v_mfma_f32_16x16x32_bf16 v[98:101], v[172:175], v[188:191], v[98:101]
	v_mfma_f32_16x16x32_bf16 v[98:101], v[176:179], v[192:195], v[98:101]
	v_mfma_f32_16x16x32_bf16 v[86:89], v[164:167], v[196:199], v[86:89]
	v_mfma_f32_16x16x32_bf16 v[86:89], v[168:171], v[200:203], v[86:89]
	v_mfma_f32_16x16x32_bf16 v[82:85], v[172:175], v[196:199], v[82:85]
	v_mfma_f32_16x16x32_bf16 v[82:85], v[176:179], v[200:203], v[82:85]
	v_mfma_f32_16x16x32_bf16 v[70:73], v[164:167], v[204:207], v[70:73]
	v_mfma_f32_16x16x32_bf16 v[70:73], v[168:171], v[208:211], v[70:73]
	s_setprio 2
	s_barrier
	v_mfma_f32_16x16x32_bf16 v[66:69], v[172:175], v[204:207], v[66:69]
	v_mfma_f32_16x16x32_bf16 v[66:69], v[176:179], v[208:211], v[66:69]
	s_setprio 0
	ds_read_b128 v[180:183], v145 offset:49152
	ds_read_b128 v[184:187], v145 offset:50176
	ds_read_b128 v[188:191], v145 offset:51200
	ds_read_b128 v[192:195], v145 offset:52224
	ds_read_b128 v[196:199], v145 offset:53248
	ds_read_b128 v[200:203], v145 offset:54272
	ds_read_b128 v[204:207], v145 offset:55296
	ds_read_b128 v[208:211], v145 offset:56320
	s_add_u32 s22, s20, 0x80
	s_addc_u32 s23, s21, 0
	s_mov_b32 s82, m0
	s_mov_b32 m0, s48
	s_nop 0
	global_load_lds_dwordx4 v139, s[22:23]
	s_mov_b32 m0, s82
	s_add_u32 s20, s20, 0x80080
	s_mov_b32 s82, m0
	s_mov_b32 m0, s49
	s_nop 0
	global_load_lds_dwordx4 v141, s[22:23]
	s_mov_b32 m0, s82
	s_addc_u32 s21, s21, 0
	s_mov_b32 s22, m0
	s_mov_b32 m0, s56
	s_nop 0
	global_load_lds_dwordx4 v139, s[20:21]
	s_mov_b32 m0, s22
	s_nop 0
	s_mov_b32 s22, m0
	s_mov_b32 m0, s57
	s_nop 0
	global_load_lds_dwordx4 v141, s[20:21]
	s_mov_b32 m0, s22
	s_waitcnt vmcnt(4)
	s_waitcnt lgkmcnt(0)
	s_barrier
	s_setprio 1
	s_waitcnt lgkmcnt(7)
	v_mfma_f32_16x16x32_bf16 v[62:65], v[148:151], v[180:183], v[62:65]
	v_mfma_f32_16x16x32_bf16 v[62:65], v[152:155], v[184:187], v[62:65]
	s_waitcnt lgkmcnt(5)
	v_mfma_f32_16x16x32_bf16 v[58:61], v[156:159], v[180:183], v[58:61]
	v_mfma_f32_16x16x32_bf16 v[58:61], v[160:163], v[184:187], v[58:61]
	s_waitcnt lgkmcnt(3)
	v_mfma_f32_16x16x32_bf16 v[46:49], v[148:151], v[188:191], v[46:49]
	v_mfma_f32_16x16x32_bf16 v[46:49], v[152:155], v[192:195], v[46:49]
	s_waitcnt lgkmcnt(1)
	v_mfma_f32_16x16x32_bf16 v[42:45], v[156:159], v[188:191], v[42:45]
	v_mfma_f32_16x16x32_bf16 v[42:45], v[160:163], v[192:195], v[42:45]
	v_mfma_f32_16x16x32_bf16 v[30:33], v[148:151], v[196:199], v[30:33]
	v_mfma_f32_16x16x32_bf16 v[30:33], v[152:155], v[200:203], v[30:33]
	v_mfma_f32_16x16x32_bf16 v[26:29], v[156:159], v[196:199], v[26:29]
	v_mfma_f32_16x16x32_bf16 v[26:29], v[160:163], v[200:203], v[26:29]
	v_mfma_f32_16x16x32_bf16 v[14:17], v[148:151], v[204:207], v[14:17]
	v_mfma_f32_16x16x32_bf16 v[14:17], v[152:155], v[208:211], v[14:17]
	s_waitcnt lgkmcnt(0)
	v_mfma_f32_16x16x32_bf16 v[10:13], v[156:159], v[204:207], v[10:13]
	v_mfma_f32_16x16x32_bf16 v[10:13], v[160:163], v[208:211], v[10:13]
	s_setprio 0
	s_setprio 1
	v_mfma_f32_16x16x32_bf16 v[54:57], v[164:167], v[180:183], v[54:57]
	v_mfma_f32_16x16x32_bf16 v[54:57], v[168:171], v[184:187], v[54:57]
	v_mfma_f32_16x16x32_bf16 v[50:53], v[172:175], v[180:183], v[50:53]
	v_mfma_f32_16x16x32_bf16 v[50:53], v[176:179], v[184:187], v[50:53]
	v_mfma_f32_16x16x32_bf16 v[38:41], v[164:167], v[188:191], v[38:41]
	v_mfma_f32_16x16x32_bf16 v[38:41], v[168:171], v[192:195], v[38:41]
	v_mfma_f32_16x16x32_bf16 v[34:37], v[172:175], v[188:191], v[34:37]
	v_mfma_f32_16x16x32_bf16 v[34:37], v[176:179], v[192:195], v[34:37]
	v_mfma_f32_16x16x32_bf16 v[22:25], v[164:167], v[196:199], v[22:25]
	v_mfma_f32_16x16x32_bf16 v[22:25], v[168:171], v[200:203], v[22:25]
	v_mfma_f32_16x16x32_bf16 v[18:21], v[172:175], v[196:199], v[18:21]
	v_mfma_f32_16x16x32_bf16 v[18:21], v[176:179], v[200:203], v[18:21]
	v_mfma_f32_16x16x32_bf16 v[6:9], v[164:167], v[204:207], v[6:9]
	v_mfma_f32_16x16x32_bf16 v[6:9], v[168:171], v[208:211], v[6:9]
	s_setprio 2
	s_barrier
	v_mfma_f32_16x16x32_bf16 v[2:5], v[172:175], v[204:207], v[2:5]
	v_mfma_f32_16x16x32_bf16 v[2:5], v[176:179], v[208:211], v[2:5]
	s_setprio 0
	s_add_i32 s81, s81, 2
	s_add_u32 s77, s77, 0x100
	s_addc_u32 s78, s78, 0
	s_add_u32 s18, s18, 0x100
	s_addc_u32 s19, s19, 0
	s_add_u32 s79, s79, 0x100
	s_addc_u32 s80, s80, 0
	s_cmp_gt_u32 s81, 29
	.p2align 6
.LBB0_344:
	ds_read_b128 v[148:151], v143
	ds_read_b128 v[152:155], v143 offset:1024
	ds_read_b128 v[156:159], v143 offset:2048
	ds_read_b128 v[160:163], v143 offset:3072
	ds_read_b128 v[164:167], v144
	ds_read_b128 v[168:171], v144 offset:1024
	ds_read_b128 v[172:175], v144 offset:2048
	ds_read_b128 v[176:179], v144 offset:3072
	s_cmp_eq_u32 s81, 28
	s_cselect_b32 s21, s9, s78
	s_cselect_b32 s20, s76, s77
	s_cselect_b32 s23, s11, s80
	s_cselect_b32 s22, s75, s79
	ds_read_b128 v[180:183], v145
	ds_read_b128 v[184:187], v145 offset:1024
	ds_read_b128 v[188:191], v145 offset:2048
	ds_read_b128 v[192:195], v145 offset:3072
	ds_read_b128 v[196:199], v145 offset:4096
	ds_read_b128 v[200:203], v145 offset:5120
	ds_read_b128 v[204:207], v145 offset:6144
	ds_read_b128 v[208:211], v145 offset:7168
	s_add_u32 s82, s18, 0xfff80000
	s_addc_u32 s83, s19, -1
	s_mov_b32 s86, m0
	s_mov_b32 m0, s64
	s_nop 0
	global_load_lds_dwordx4 v138, s[82:83]
	s_mov_b32 m0, s86
	s_nop 0
	s_mov_b32 s86, m0
	s_mov_b32 m0, s67
	s_nop 0
	global_load_lds_dwordx4 v140, s[82:83]
	s_mov_b32 m0, s86
	s_mov_b32 s82, m0
	s_mov_b32 m0, s65
	s_nop 0
	global_load_lds_dwordx4 v138, s[18:19]
	s_mov_b32 m0, s82
	s_nop 0
	s_mov_b32 s82, m0
	s_mov_b32 m0, s73
	s_nop 0
	global_load_lds_dwordx4 v140, s[18:19]
	s_mov_b32 m0, s82
	s_waitcnt vmcnt(8)
	s_waitcnt lgkmcnt(0)
	s_barrier
	s_setprio 1
	s_waitcnt lgkmcnt(7)
	v_mfma_f32_16x16x32_bf16 v[126:129], v[148:151], v[180:183], v[126:129]
	v_mfma_f32_16x16x32_bf16 v[126:129], v[152:155], v[184:187], v[126:129]
	s_waitcnt lgkmcnt(5)
	v_mfma_f32_16x16x32_bf16 v[122:125], v[156:159], v[180:183], v[122:125]
	v_mfma_f32_16x16x32_bf16 v[122:125], v[160:163], v[184:187], v[122:125]
	s_waitcnt lgkmcnt(3)
	v_mfma_f32_16x16x32_bf16 v[110:113], v[148:151], v[188:191], v[110:113]
	v_mfma_f32_16x16x32_bf16 v[110:113], v[152:155], v[192:195], v[110:113]
	s_waitcnt lgkmcnt(1)
	v_mfma_f32_16x16x32_bf16 v[106:109], v[156:159], v[188:191], v[106:109]
	v_mfma_f32_16x16x32_bf16 v[106:109], v[160:163], v[192:195], v[106:109]
	v_mfma_f32_16x16x32_bf16 v[94:97], v[148:151], v[196:199], v[94:97]
	v_mfma_f32_16x16x32_bf16 v[94:97], v[152:155], v[200:203], v[94:97]
	v_mfma_f32_16x16x32_bf16 v[90:93], v[156:159], v[196:199], v[90:93]
	v_mfma_f32_16x16x32_bf16 v[90:93], v[160:163], v[200:203], v[90:93]
	v_mfma_f32_16x16x32_bf16 v[78:81], v[148:151], v[204:207], v[78:81]
	v_mfma_f32_16x16x32_bf16 v[78:81], v[152:155], v[208:211], v[78:81]
	s_waitcnt lgkmcnt(0)
	v_mfma_f32_16x16x32_bf16 v[74:77], v[156:159], v[204:207], v[74:77]
	v_mfma_f32_16x16x32_bf16 v[74:77], v[160:163], v[208:211], v[74:77]
	s_setprio 0
	s_setprio 1
	v_mfma_f32_16x16x32_bf16 v[118:121], v[164:167], v[180:183], v[118:121]
	v_mfma_f32_16x16x32_bf16 v[118:121], v[168:171], v[184:187], v[118:121]
	v_mfma_f32_16x16x32_bf16 v[114:117], v[172:175], v[180:183], v[114:117]
	v_mfma_f32_16x16x32_bf16 v[114:117], v[176:179], v[184:187], v[114:117]
	v_mfma_f32_16x16x32_bf16 v[102:105], v[164:167], v[188:191], v[102:105]
	v_mfma_f32_16x16x32_bf16 v[102:105], v[168:171], v[192:195], v[102:105]
	v_mfma_f32_16x16x32_bf16 v[98:101], v[172:175], v[188:191], v[98:101]
	v_mfma_f32_16x16x32_bf16 v[98:101], v[176:179], v[192:195], v[98:101]
	v_mfma_f32_16x16x32_bf16 v[86:89], v[164:167], v[196:199], v[86:89]
	v_mfma_f32_16x16x32_bf16 v[86:89], v[168:171], v[200:203], v[86:89]
	v_mfma_f32_16x16x32_bf16 v[82:85], v[172:175], v[196:199], v[82:85]
	v_mfma_f32_16x16x32_bf16 v[82:85], v[176:179], v[200:203], v[82:85]
	v_mfma_f32_16x16x32_bf16 v[70:73], v[164:167], v[204:207], v[70:73]
	v_mfma_f32_16x16x32_bf16 v[70:73], v[168:171], v[208:211], v[70:73]
	s_setprio 2
	s_barrier
	v_mfma_f32_16x16x32_bf16 v[66:69], v[172:175], v[204:207], v[66:69]
	v_mfma_f32_16x16x32_bf16 v[66:69], v[176:179], v[208:211], v[66:69]
	s_setprio 0
	ds_read_b128 v[180:183], v145 offset:16384
	ds_read_b128 v[184:187], v145 offset:17408
	ds_read_b128 v[188:191], v145 offset:18432
	ds_read_b128 v[192:195], v145 offset:19456
	ds_read_b128 v[196:199], v145 offset:20480
	ds_read_b128 v[200:203], v145 offset:21504
	ds_read_b128 v[204:207], v145 offset:22528
	ds_read_b128 v[208:211], v145 offset:23552
	s_mov_b32 s82, m0
	s_mov_b32 m0, s35
	s_nop 0
	global_load_lds_dwordx4 v139, s[20:21]
	s_mov_b32 m0, s82
	s_nop 0
	s_mov_b32 s82, m0
	s_mov_b32 m0, s36
	s_nop 0
	global_load_lds_dwordx4 v141, s[20:21]
	s_mov_b32 m0, s82
	s_add_u32 s82, s20, 0x80000
	s_addc_u32 s83, s21, 0
	s_mov_b32 s86, m0
	s_mov_b32 m0, s37
	s_nop 0
	global_load_lds_dwordx4 v139, s[82:83]
	s_mov_b32 m0, s86
	s_nop 0
	s_mov_b32 s86, m0
	s_mov_b32 m0, s42
	s_nop 0
	global_load_lds_dwordx4 v141, s[82:83]
	s_mov_b32 m0, s86
	s_waitcnt vmcnt(4)
	s_waitcnt lgkmcnt(0)
	s_barrier
	s_setprio 1
	s_waitcnt lgkmcnt(7)
	v_mfma_f32_16x16x32_bf16 v[62:65], v[148:151], v[180:183], v[62:65]
	v_mfma_f32_16x16x32_bf16 v[62:65], v[152:155], v[184:187], v[62:65]
	s_waitcnt lgkmcnt(5)
	v_mfma_f32_16x16x32_bf16 v[58:61], v[156:159], v[180:183], v[58:61]
	v_mfma_f32_16x16x32_bf16 v[58:61], v[160:163], v[184:187], v[58:61]
	s_waitcnt lgkmcnt(3)
	v_mfma_f32_16x16x32_bf16 v[46:49], v[148:151], v[188:191], v[46:49]
	v_mfma_f32_16x16x32_bf16 v[46:49], v[152:155], v[192:195], v[46:49]
	s_waitcnt lgkmcnt(1)
	v_mfma_f32_16x16x32_bf16 v[42:45], v[156:159], v[188:191], v[42:45]
	v_mfma_f32_16x16x32_bf16 v[42:45], v[160:163], v[192:195], v[42:45]
	v_mfma_f32_16x16x32_bf16 v[30:33], v[148:151], v[196:199], v[30:33]
	v_mfma_f32_16x16x32_bf16 v[30:33], v[152:155], v[200:203], v[30:33]
	v_mfma_f32_16x16x32_bf16 v[26:29], v[156:159], v[196:199], v[26:29]
	v_mfma_f32_16x16x32_bf16 v[26:29], v[160:163], v[200:203], v[26:29]
	v_mfma_f32_16x16x32_bf16 v[14:17], v[148:151], v[204:207], v[14:17]
	v_mfma_f32_16x16x32_bf16 v[14:17], v[152:155], v[208:211], v[14:17]
	s_waitcnt lgkmcnt(0)
	v_mfma_f32_16x16x32_bf16 v[10:13], v[156:159], v[204:207], v[10:13]
	v_mfma_f32_16x16x32_bf16 v[10:13], v[160:163], v[208:211], v[10:13]
	s_setprio 0
	s_setprio 1
	v_mfma_f32_16x16x32_bf16 v[54:57], v[164:167], v[180:183], v[54:57]
	v_mfma_f32_16x16x32_bf16 v[54:57], v[168:171], v[184:187], v[54:57]
	v_mfma_f32_16x16x32_bf16 v[50:53], v[172:175], v[180:183], v[50:53]
	v_mfma_f32_16x16x32_bf16 v[50:53], v[176:179], v[184:187], v[50:53]
	v_mfma_f32_16x16x32_bf16 v[38:41], v[164:167], v[188:191], v[38:41]
	v_mfma_f32_16x16x32_bf16 v[38:41], v[168:171], v[192:195], v[38:41]
	v_mfma_f32_16x16x32_bf16 v[34:37], v[172:175], v[188:191], v[34:37]
	v_mfma_f32_16x16x32_bf16 v[34:37], v[176:179], v[192:195], v[34:37]
	v_mfma_f32_16x16x32_bf16 v[22:25], v[164:167], v[196:199], v[22:25]
	v_mfma_f32_16x16x32_bf16 v[22:25], v[168:171], v[200:203], v[22:25]
	v_mfma_f32_16x16x32_bf16 v[18:21], v[172:175], v[196:199], v[18:21]
	v_mfma_f32_16x16x32_bf16 v[18:21], v[176:179], v[200:203], v[18:21]
	v_mfma_f32_16x16x32_bf16 v[6:9], v[164:167], v[204:207], v[6:9]
	v_mfma_f32_16x16x32_bf16 v[6:9], v[168:171], v[208:211], v[6:9]
	s_setprio 2
	s_barrier
	v_mfma_f32_16x16x32_bf16 v[2:5], v[172:175], v[204:207], v[2:5]
	v_mfma_f32_16x16x32_bf16 v[2:5], v[176:179], v[208:211], v[2:5]
	s_setprio 0
	ds_read_b128 v[148:151], v146
	ds_read_b128 v[152:155], v146 offset:1024
	ds_read_b128 v[156:159], v146 offset:2048
	ds_read_b128 v[160:163], v146 offset:3072
	ds_read_b128 v[164:167], v147
	ds_read_b128 v[168:171], v147 offset:1024
	ds_read_b128 v[172:175], v147 offset:2048
	ds_read_b128 v[176:179], v147 offset:3072
	ds_read_b128 v[180:183], v145 offset:32768
	ds_read_b128 v[184:187], v145 offset:33792
	ds_read_b128 v[188:191], v145 offset:34816
	ds_read_b128 v[192:195], v145 offset:35840
	ds_read_b128 v[196:199], v145 offset:36864
	ds_read_b128 v[200:203], v145 offset:37888
	ds_read_b128 v[204:207], v145 offset:38912
	ds_read_b128 v[208:211], v145 offset:39936
	s_mov_b32 s82, m0
	s_mov_b32 m0, s31
	s_nop 0
	global_load_lds_dwordx4 v138, s[22:23]
	s_mov_b32 m0, s82
	s_nop 0
	s_mov_b32 s82, m0
	s_mov_b32 m0, s43
	s_nop 0
	global_load_lds_dwordx4 v140, s[22:23]
	s_mov_b32 m0, s82
	s_add_u32 s22, s22, 0x80000
	s_addc_u32 s23, s23, 0
	s_mov_b32 s82, m0
	s_mov_b32 m0, s46
	s_nop 0
	global_load_lds_dwordx4 v138, s[22:23]
	s_mov_b32 m0, s82
	s_nop 0
	s_mov_b32 s82, m0
	s_mov_b32 m0, s47
	s_nop 0
	global_load_lds_dwordx4 v140, s[22:23]
	s_mov_b32 m0, s82
	s_waitcnt vmcnt(8)
	s_waitcnt lgkmcnt(0)
	s_barrier
	s_setprio 1
	s_waitcnt lgkmcnt(7)
	v_mfma_f32_16x16x32_bf16 v[126:129], v[148:151], v[180:183], v[126:129]
	v_mfma_f32_16x16x32_bf16 v[126:129], v[152:155], v[184:187], v[126:129]
	s_waitcnt lgkmcnt(5)
	v_mfma_f32_16x16x32_bf16 v[122:125], v[156:159], v[180:183], v[122:125]
	v_mfma_f32_16x16x32_bf16 v[122:125], v[160:163], v[184:187], v[122:125]
	s_waitcnt lgkmcnt(3)
	v_mfma_f32_16x16x32_bf16 v[110:113], v[148:151], v[188:191], v[110:113]
	v_mfma_f32_16x16x32_bf16 v[110:113], v[152:155], v[192:195], v[110:113]
	s_waitcnt lgkmcnt(1)
	v_mfma_f32_16x16x32_bf16 v[106:109], v[156:159], v[188:191], v[106:109]
	v_mfma_f32_16x16x32_bf16 v[106:109], v[160:163], v[192:195], v[106:109]
	v_mfma_f32_16x16x32_bf16 v[94:97], v[148:151], v[196:199], v[94:97]
	v_mfma_f32_16x16x32_bf16 v[94:97], v[152:155], v[200:203], v[94:97]
	v_mfma_f32_16x16x32_bf16 v[90:93], v[156:159], v[196:199], v[90:93]
	v_mfma_f32_16x16x32_bf16 v[90:93], v[160:163], v[200:203], v[90:93]
	v_mfma_f32_16x16x32_bf16 v[78:81], v[148:151], v[204:207], v[78:81]
	v_mfma_f32_16x16x32_bf16 v[78:81], v[152:155], v[208:211], v[78:81]
	s_waitcnt lgkmcnt(0)
	v_mfma_f32_16x16x32_bf16 v[74:77], v[156:159], v[204:207], v[74:77]
	v_mfma_f32_16x16x32_bf16 v[74:77], v[160:163], v[208:211], v[74:77]
	s_setprio 0
	s_setprio 1
	v_mfma_f32_16x16x32_bf16 v[118:121], v[164:167], v[180:183], v[118:121]
	v_mfma_f32_16x16x32_bf16 v[118:121], v[168:171], v[184:187], v[118:121]
	v_mfma_f32_16x16x32_bf16 v[114:117], v[172:175], v[180:183], v[114:117]
	v_mfma_f32_16x16x32_bf16 v[114:117], v[176:179], v[184:187], v[114:117]
	v_mfma_f32_16x16x32_bf16 v[102:105], v[164:167], v[188:191], v[102:105]
	v_mfma_f32_16x16x32_bf16 v[102:105], v[168:171], v[192:195], v[102:105]
	v_mfma_f32_16x16x32_bf16 v[98:101], v[172:175], v[188:191], v[98:101]
	v_mfma_f32_16x16x32_bf16 v[98:101], v[176:179], v[192:195], v[98:101]
	v_mfma_f32_16x16x32_bf16 v[86:89], v[164:167], v[196:199], v[86:89]
	v_mfma_f32_16x16x32_bf16 v[86:89], v[168:171], v[200:203], v[86:89]
	v_mfma_f32_16x16x32_bf16 v[82:85], v[172:175], v[196:199], v[82:85]
	v_mfma_f32_16x16x32_bf16 v[82:85], v[176:179], v[200:203], v[82:85]
	v_mfma_f32_16x16x32_bf16 v[70:73], v[164:167], v[204:207], v[70:73]
	v_mfma_f32_16x16x32_bf16 v[70:73], v[168:171], v[208:211], v[70:73]
	s_setprio 2
	s_barrier
	v_mfma_f32_16x16x32_bf16 v[66:69], v[172:175], v[204:207], v[66:69]
	v_mfma_f32_16x16x32_bf16 v[66:69], v[176:179], v[208:211], v[66:69]
	s_setprio 0
	ds_read_b128 v[180:183], v145 offset:49152
	ds_read_b128 v[184:187], v145 offset:50176
	ds_read_b128 v[188:191], v145 offset:51200
	ds_read_b128 v[192:195], v145 offset:52224
	ds_read_b128 v[196:199], v145 offset:53248
	ds_read_b128 v[200:203], v145 offset:54272
	ds_read_b128 v[204:207], v145 offset:55296
	ds_read_b128 v[208:211], v145 offset:56320
	s_add_u32 s22, s20, 0x80
	s_addc_u32 s23, s21, 0
	s_mov_b32 s82, m0
	s_mov_b32 m0, s48
	s_nop 0
	global_load_lds_dwordx4 v139, s[22:23]
	s_mov_b32 m0, s82
	s_add_u32 s20, s20, 0x80080
	s_mov_b32 s82, m0
	s_mov_b32 m0, s49
	s_nop 0
	global_load_lds_dwordx4 v141, s[22:23]
	s_mov_b32 m0, s82
	s_addc_u32 s21, s21, 0
	s_mov_b32 s22, m0
	s_mov_b32 m0, s56
	s_nop 0
	global_load_lds_dwordx4 v139, s[20:21]
	s_mov_b32 m0, s22
	s_nop 0
	s_mov_b32 s22, m0
	s_mov_b32 m0, s57
	s_nop 0
	global_load_lds_dwordx4 v141, s[20:21]
	s_mov_b32 m0, s22
	s_waitcnt vmcnt(4)
	s_waitcnt lgkmcnt(0)
	s_barrier
	s_setprio 1
	s_waitcnt lgkmcnt(7)
	v_mfma_f32_16x16x32_bf16 v[62:65], v[148:151], v[180:183], v[62:65]
	v_mfma_f32_16x16x32_bf16 v[62:65], v[152:155], v[184:187], v[62:65]
	s_waitcnt lgkmcnt(5)
	v_mfma_f32_16x16x32_bf16 v[58:61], v[156:159], v[180:183], v[58:61]
	v_mfma_f32_16x16x32_bf16 v[58:61], v[160:163], v[184:187], v[58:61]
	s_waitcnt lgkmcnt(3)
	v_mfma_f32_16x16x32_bf16 v[46:49], v[148:151], v[188:191], v[46:49]
	v_mfma_f32_16x16x32_bf16 v[46:49], v[152:155], v[192:195], v[46:49]
	s_waitcnt lgkmcnt(1)
	v_mfma_f32_16x16x32_bf16 v[42:45], v[156:159], v[188:191], v[42:45]
	v_mfma_f32_16x16x32_bf16 v[42:45], v[160:163], v[192:195], v[42:45]
	v_mfma_f32_16x16x32_bf16 v[30:33], v[148:151], v[196:199], v[30:33]
	v_mfma_f32_16x16x32_bf16 v[30:33], v[152:155], v[200:203], v[30:33]
	v_mfma_f32_16x16x32_bf16 v[26:29], v[156:159], v[196:199], v[26:29]
	v_mfma_f32_16x16x32_bf16 v[26:29], v[160:163], v[200:203], v[26:29]
	v_mfma_f32_16x16x32_bf16 v[14:17], v[148:151], v[204:207], v[14:17]
	v_mfma_f32_16x16x32_bf16 v[14:17], v[152:155], v[208:211], v[14:17]
	s_waitcnt lgkmcnt(0)
	v_mfma_f32_16x16x32_bf16 v[10:13], v[156:159], v[204:207], v[10:13]
	v_mfma_f32_16x16x32_bf16 v[10:13], v[160:163], v[208:211], v[10:13]
	s_setprio 0
	s_setprio 1
	v_mfma_f32_16x16x32_bf16 v[54:57], v[164:167], v[180:183], v[54:57]
	v_mfma_f32_16x16x32_bf16 v[54:57], v[168:171], v[184:187], v[54:57]
	v_mfma_f32_16x16x32_bf16 v[50:53], v[172:175], v[180:183], v[50:53]
	v_mfma_f32_16x16x32_bf16 v[50:53], v[176:179], v[184:187], v[50:53]
	v_mfma_f32_16x16x32_bf16 v[38:41], v[164:167], v[188:191], v[38:41]
	v_mfma_f32_16x16x32_bf16 v[38:41], v[168:171], v[192:195], v[38:41]
	v_mfma_f32_16x16x32_bf16 v[34:37], v[172:175], v[188:191], v[34:37]
	v_mfma_f32_16x16x32_bf16 v[34:37], v[176:179], v[192:195], v[34:37]
	v_mfma_f32_16x16x32_bf16 v[22:25], v[164:167], v[196:199], v[22:25]
	v_mfma_f32_16x16x32_bf16 v[22:25], v[168:171], v[200:203], v[22:25]
	v_mfma_f32_16x16x32_bf16 v[18:21], v[172:175], v[196:199], v[18:21]
	v_mfma_f32_16x16x32_bf16 v[18:21], v[176:179], v[200:203], v[18:21]
	v_mfma_f32_16x16x32_bf16 v[6:9], v[164:167], v[204:207], v[6:9]
	v_mfma_f32_16x16x32_bf16 v[6:9], v[168:171], v[208:211], v[6:9]
	s_setprio 2
	s_barrier
	v_mfma_f32_16x16x32_bf16 v[2:5], v[172:175], v[204:207], v[2:5]
	v_mfma_f32_16x16x32_bf16 v[2:5], v[176:179], v[208:211], v[2:5]
	s_setprio 0
	s_add_i32 s81, s81, 2
	s_add_u32 s77, s77, 0x100
	s_addc_u32 s78, s78, 0
	s_add_u32 s18, s18, 0x100
	s_addc_u32 s19, s19, 0
	s_add_u32 s79, s79, 0x100
	s_addc_u32 s80, s80, 0
	s_cmp_gt_u32 s81, 29
	s_cbranch_scc0 .LBB0_344
	s_and_b64 vcc, exec, s[6:7]
	s_cbranch_vccz .LBB0_347
	s_barrier

.LBB0_472:
	s_ashr_i32 s13, s12, 31
	s_lshl_b64 s[14:15], s[12:13], 15
	s_add_u32 s14, s28, s14
	s_addc_u32 s15, s29, s15
	s_and_b64 s[16:17], s[2:3], exec
	s_cselect_b32 s13, s15, s23
	s_cselect_b32 s76, s14, s22
	s_ashr_i32 s11, s10, 31
	s_lshl_b64 s[16:17], s[10:11], 15
	s_add_u32 s16, s30, s16
	s_addc_u32 s17, s31, s17
	s_and_b64 s[24:25], s[2:3], exec
	s_cselect_b32 s11, s17, s21
	s_cselect_b32 s77, s16, s20
	s_add_u32 s78, s20, 0x80000
	s_addc_u32 s79, s21, 0
	s_add_u32 s20, s22, 0x204000
	s_addc_u32 s21, s23, 0
	s_add_u32 s80, s22, 0x400000
	s_addc_u32 s81, s23, 0
	s_mov_b32 s82, -2
	s_waitcnt vmcnt(25)
	s_waitcnt vmcnt(24)
	s_waitcnt vmcnt(23)
	s_waitcnt vmcnt(22)
	s_waitcnt vmcnt(21)
	s_waitcnt vmcnt(20)
	s_waitcnt vmcnt(15)
	s_waitcnt vmcnt(14)
	s_waitcnt vmcnt(13)
	s_waitcnt vmcnt(12)
	s_waitcnt vmcnt(7)
	s_waitcnt vmcnt(6)
	s_waitcnt vmcnt(5)
	s_waitcnt vmcnt(4)
	s_waitcnt vmcnt(3)
	s_waitcnt vmcnt(2)
	s_waitcnt vmcnt(1)
	s_waitcnt vmcnt(0)
	ds_read_b128 v[134:137], v161
	ds_read_b128 v[138:141], v161 offset:1024
	ds_read_b128 v[142:145], v161 offset:2048
	ds_read_b128 v[146:149], v161 offset:3072
	ds_read_b128 v[150:153], v162
	ds_read_b128 v[166:169], v162 offset:1024
	ds_read_b128 v[170:173], v162 offset:2048
	ds_read_b128 v[174:177], v162 offset:3072
	s_cmpk_eq_i32 s82, 0x52
	s_cselect_b32 s23, s11, s79
	s_cselect_b32 s22, s77, s78
	s_cselect_b32 s25, s13, s81
	s_cselect_b32 s24, s76, s80
	ds_read_b128 v[178:181], v163
	ds_read_b128 v[182:185], v163 offset:1024
	ds_read_b128 v[186:189], v163 offset:2048
	ds_read_b128 v[190:193], v163 offset:3072
	ds_read_b128 v[194:197], v163 offset:4096
	ds_read_b128 v[198:201], v163 offset:5120
	ds_read_b128 v[202:205], v163 offset:6144
	ds_read_b128 v[206:209], v163 offset:7168
	s_add_u32 s86, s20, 0xffffc000
	s_addc_u32 s87, s21, -1
	s_mov_b32 s83, m0
	s_mov_b32 m0, s65
	s_nop 0
	global_load_lds_dwordx4 v1, s[86:87]
	s_mov_b32 m0, s83
	s_nop 0
	s_mov_b32 s83, m0
	s_mov_b32 m0, s67
	s_nop 0
	global_load_lds_dwordx4 v157, s[86:87]
	s_mov_b32 m0, s83
	s_nop 0
	s_mov_b32 s83, m0
	s_mov_b32 m0, s66
	s_nop 0
	global_load_lds_dwordx4 v1, s[20:21]
	s_mov_b32 m0, s83
	s_nop 0
	s_mov_b32 s83, m0
	s_mov_b32 m0, s73
	s_nop 0
	global_load_lds_dwordx4 v157, s[20:21]
	s_mov_b32 m0, s83
	s_waitcnt vmcnt(8)
	s_waitcnt lgkmcnt(0)
	s_barrier
	s_setprio 1
	s_waitcnt lgkmcnt(7)
	v_mfma_f32_16x16x32_bf16 v[126:129], v[134:137], v[178:181], 0
	v_mfma_f32_16x16x32_bf16 v[126:129], v[138:141], v[182:185], v[126:129]
	s_waitcnt lgkmcnt(5)
	v_mfma_f32_16x16x32_bf16 v[122:125], v[142:145], v[178:181], 0
	v_mfma_f32_16x16x32_bf16 v[122:125], v[146:149], v[182:185], v[122:125]
	s_waitcnt lgkmcnt(3)
	v_mfma_f32_16x16x32_bf16 v[118:121], v[134:137], v[186:189], 0
	v_mfma_f32_16x16x32_bf16 v[118:121], v[138:141], v[190:193], v[118:121]
	s_waitcnt lgkmcnt(1)
	v_mfma_f32_16x16x32_bf16 v[114:117], v[142:145], v[186:189], 0
	v_mfma_f32_16x16x32_bf16 v[114:117], v[146:149], v[190:193], v[114:117]
	v_mfma_f32_16x16x32_bf16 v[102:105], v[134:137], v[194:197], 0
	v_mfma_f32_16x16x32_bf16 v[102:105], v[138:141], v[198:201], v[102:105]
	v_mfma_f32_16x16x32_bf16 v[94:97], v[142:145], v[194:197], 0
	v_mfma_f32_16x16x32_bf16 v[94:97], v[146:149], v[198:201], v[94:97]
	v_mfma_f32_16x16x32_bf16 v[86:89], v[134:137], v[202:205], 0
	v_mfma_f32_16x16x32_bf16 v[86:89], v[138:141], v[206:209], v[86:89]
	s_waitcnt lgkmcnt(0)
	v_mfma_f32_16x16x32_bf16 v[78:81], v[142:145], v[202:205], 0
	v_mfma_f32_16x16x32_bf16 v[78:81], v[146:149], v[206:209], v[78:81]
	s_setprio 0
	s_setprio 1
	v_mfma_f32_16x16x32_bf16 v[110:113], v[150:153], v[178:181], 0
	v_mfma_f32_16x16x32_bf16 v[110:113], v[166:169], v[182:185], v[110:113]
	v_mfma_f32_16x16x32_bf16 v[106:109], v[170:173], v[178:181], 0
	v_mfma_f32_16x16x32_bf16 v[106:109], v[174:177], v[182:185], v[106:109]
	v_mfma_f32_16x16x32_bf16 v[98:101], v[150:153], v[186:189], 0
	v_mfma_f32_16x16x32_bf16 v[98:101], v[166:169], v[190:193], v[98:101]
	v_mfma_f32_16x16x32_bf16 v[90:93], v[170:173], v[186:189], 0
	v_mfma_f32_16x16x32_bf16 v[90:93], v[174:177], v[190:193], v[90:93]
	v_mfma_f32_16x16x32_bf16 v[82:85], v[150:153], v[194:197], 0
	v_mfma_f32_16x16x32_bf16 v[82:85], v[166:169], v[198:201], v[82:85]
	v_mfma_f32_16x16x32_bf16 v[74:77], v[170:173], v[194:197], 0
	v_mfma_f32_16x16x32_bf16 v[74:77], v[174:177], v[198:201], v[74:77]
	v_mfma_f32_16x16x32_bf16 v[70:73], v[150:153], v[202:205], 0
	v_mfma_f32_16x16x32_bf16 v[70:73], v[166:169], v[206:209], v[70:73]
	s_setprio 2
	s_barrier
	v_mfma_f32_16x16x32_bf16 v[66:69], v[170:173], v[202:205], 0
	v_mfma_f32_16x16x32_bf16 v[66:69], v[174:177], v[206:209], v[66:69]
	s_setprio 0
	ds_read_b128 v[178:181], v163 offset:16384
	ds_read_b128 v[182:185], v163 offset:17408
	ds_read_b128 v[186:189], v163 offset:18432
	ds_read_b128 v[190:193], v163 offset:19456
	ds_read_b128 v[194:197], v163 offset:20480
	ds_read_b128 v[198:201], v163 offset:21504
	ds_read_b128 v[202:205], v163 offset:22528
	ds_read_b128 v[206:209], v163 offset:23552
	s_mov_b32 s83, m0
	s_mov_b32 m0, s19
	s_nop 0
	global_load_lds_dwordx4 v156, s[22:23]
	s_mov_b32 m0, s83
	s_add_u32 s86, s22, 0x4000
	s_mov_b32 s83, m0
	s_mov_b32 m0, s35
	s_nop 0
	global_load_lds_dwordx4 v158, s[22:23]
	s_mov_b32 m0, s83
	s_addc_u32 s87, s23, 0
	s_mov_b32 s83, m0
	s_mov_b32 m0, s36
	s_nop 0
	global_load_lds_dwordx4 v156, s[86:87]
	s_mov_b32 m0, s83
	s_nop 0
	s_mov_b32 s83, m0
	s_mov_b32 m0, s37
	s_nop 0
	global_load_lds_dwordx4 v158, s[86:87]
	s_mov_b32 m0, s83
	s_waitcnt vmcnt(4)
	s_waitcnt lgkmcnt(0)
	s_barrier
	s_setprio 1
	s_waitcnt lgkmcnt(7)
	v_mfma_f32_16x16x32_bf16 v[62:65], v[134:137], v[178:181], 0
	v_mfma_f32_16x16x32_bf16 v[62:65], v[138:141], v[182:185], v[62:65]
	s_waitcnt lgkmcnt(5)
	v_mfma_f32_16x16x32_bf16 v[58:61], v[142:145], v[178:181], 0
	v_mfma_f32_16x16x32_bf16 v[58:61], v[146:149], v[182:185], v[58:61]
	s_waitcnt lgkmcnt(3)
	v_mfma_f32_16x16x32_bf16 v[54:57], v[134:137], v[186:189], 0
	v_mfma_f32_16x16x32_bf16 v[54:57], v[138:141], v[190:193], v[54:57]
	s_waitcnt lgkmcnt(1)
	v_mfma_f32_16x16x32_bf16 v[46:49], v[142:145], v[186:189], 0
	v_mfma_f32_16x16x32_bf16 v[46:49], v[146:149], v[190:193], v[46:49]
	v_mfma_f32_16x16x32_bf16 v[38:41], v[134:137], v[194:197], 0
	v_mfma_f32_16x16x32_bf16 v[38:41], v[138:141], v[198:201], v[38:41]
	v_mfma_f32_16x16x32_bf16 v[30:33], v[142:145], v[194:197], 0
	v_mfma_f32_16x16x32_bf16 v[30:33], v[146:149], v[198:201], v[30:33]
	v_mfma_f32_16x16x32_bf16 v[22:25], v[134:137], v[202:205], 0
	v_mfma_f32_16x16x32_bf16 v[22:25], v[138:141], v[206:209], v[22:25]
	s_waitcnt lgkmcnt(0)
	v_mfma_f32_16x16x32_bf16 v[14:17], v[142:145], v[202:205], 0
	v_mfma_f32_16x16x32_bf16 v[14:17], v[146:149], v[206:209], v[14:17]
	s_setprio 0
	s_setprio 1
	v_mfma_f32_16x16x32_bf16 v[50:53], v[150:153], v[178:181], 0
	v_mfma_f32_16x16x32_bf16 v[50:53], v[166:169], v[182:185], v[50:53]
	v_mfma_f32_16x16x32_bf16 v[42:45], v[170:173], v[178:181], 0
	v_mfma_f32_16x16x32_bf16 v[42:45], v[174:177], v[182:185], v[42:45]
	v_mfma_f32_16x16x32_bf16 v[34:37], v[150:153], v[186:189], 0
	v_mfma_f32_16x16x32_bf16 v[34:37], v[166:169], v[190:193], v[34:37]
	v_mfma_f32_16x16x32_bf16 v[26:29], v[170:173], v[186:189], 0
	v_mfma_f32_16x16x32_bf16 v[26:29], v[174:177], v[190:193], v[26:29]
	v_mfma_f32_16x16x32_bf16 v[18:21], v[150:153], v[194:197], 0
	v_mfma_f32_16x16x32_bf16 v[18:21], v[166:169], v[198:201], v[18:21]
	v_mfma_f32_16x16x32_bf16 v[10:13], v[170:173], v[194:197], 0
	v_mfma_f32_16x16x32_bf16 v[10:13], v[174:177], v[198:201], v[10:13]
	v_mfma_f32_16x16x32_bf16 v[6:9], v[150:153], v[202:205], 0
	v_mfma_f32_16x16x32_bf16 v[6:9], v[166:169], v[206:209], v[6:9]
	s_setprio 2
	s_barrier
	v_mfma_f32_16x16x32_bf16 v[2:5], v[170:173], v[202:205], 0
	v_mfma_f32_16x16x32_bf16 v[2:5], v[174:177], v[206:209], v[2:5]
	s_setprio 0
	ds_read_b128 v[134:137], v164
	ds_read_b128 v[138:141], v164 offset:1024
	ds_read_b128 v[142:145], v164 offset:2048
	ds_read_b128 v[146:149], v164 offset:3072
	ds_read_b128 v[150:153], v165
	ds_read_b128 v[166:169], v165 offset:1024
	ds_read_b128 v[170:173], v165 offset:2048
	ds_read_b128 v[174:177], v165 offset:3072
	ds_read_b128 v[178:181], v163 offset:32768
	ds_read_b128 v[182:185], v163 offset:33792
	ds_read_b128 v[186:189], v163 offset:34816
	ds_read_b128 v[190:193], v163 offset:35840
	ds_read_b128 v[194:197], v163 offset:36864
	ds_read_b128 v[198:201], v163 offset:37888
	ds_read_b128 v[202:205], v163 offset:38912
	ds_read_b128 v[206:209], v163 offset:39936
	s_mov_b32 s83, m0
	s_mov_b32 m0, s34
	s_nop 0
	global_load_lds_dwordx4 v1, s[24:25]
	s_mov_b32 m0, s83
	s_nop 0
	s_mov_b32 s83, m0
	s_mov_b32 m0, s42
	s_nop 0
	global_load_lds_dwordx4 v157, s[24:25]
	s_mov_b32 m0, s83
	s_add_u32 s24, s24, 0x4000
	s_addc_u32 s25, s25, 0
	s_mov_b32 s83, m0
	s_mov_b32 m0, s43
	s_nop 0
	global_load_lds_dwordx4 v1, s[24:25]
	s_mov_b32 m0, s83
	s_nop 0
	s_mov_b32 s83, m0
	s_mov_b32 m0, s46
	s_nop 0
	global_load_lds_dwordx4 v157, s[24:25]
	s_mov_b32 m0, s83
	s_waitcnt vmcnt(8)
	s_waitcnt lgkmcnt(0)
	s_barrier
	s_setprio 1
	s_waitcnt lgkmcnt(7)
	v_mfma_f32_16x16x32_bf16 v[126:129], v[134:137], v[178:181], v[126:129]
	v_mfma_f32_16x16x32_bf16 v[126:129], v[138:141], v[182:185], v[126:129]
	s_waitcnt lgkmcnt(5)
	v_mfma_f32_16x16x32_bf16 v[122:125], v[142:145], v[178:181], v[122:125]
	v_mfma_f32_16x16x32_bf16 v[122:125], v[146:149], v[182:185], v[122:125]
	s_waitcnt lgkmcnt(3)
	v_mfma_f32_16x16x32_bf16 v[118:121], v[134:137], v[186:189], v[118:121]
	v_mfma_f32_16x16x32_bf16 v[118:121], v[138:141], v[190:193], v[118:121]
	s_waitcnt lgkmcnt(1)
	v_mfma_f32_16x16x32_bf16 v[114:117], v[142:145], v[186:189], v[114:117]
	v_mfma_f32_16x16x32_bf16 v[114:117], v[146:149], v[190:193], v[114:117]
	v_mfma_f32_16x16x32_bf16 v[102:105], v[134:137], v[194:197], v[102:105]
	v_mfma_f32_16x16x32_bf16 v[102:105], v[138:141], v[198:201], v[102:105]
	v_mfma_f32_16x16x32_bf16 v[94:97], v[142:145], v[194:197], v[94:97]
	v_mfma_f32_16x16x32_bf16 v[94:97], v[146:149], v[198:201], v[94:97]
	v_mfma_f32_16x16x32_bf16 v[86:89], v[134:137], v[202:205], v[86:89]
	v_mfma_f32_16x16x32_bf16 v[86:89], v[138:141], v[206:209], v[86:89]
	s_waitcnt lgkmcnt(0)
	v_mfma_f32_16x16x32_bf16 v[78:81], v[142:145], v[202:205], v[78:81]
	v_mfma_f32_16x16x32_bf16 v[78:81], v[146:149], v[206:209], v[78:81]
	s_setprio 0
	s_setprio 1
	v_mfma_f32_16x16x32_bf16 v[110:113], v[150:153], v[178:181], v[110:113]
	v_mfma_f32_16x16x32_bf16 v[110:113], v[166:169], v[182:185], v[110:113]
	v_mfma_f32_16x16x32_bf16 v[106:109], v[170:173], v[178:181], v[106:109]
	v_mfma_f32_16x16x32_bf16 v[106:109], v[174:177], v[182:185], v[106:109]
	v_mfma_f32_16x16x32_bf16 v[98:101], v[150:153], v[186:189], v[98:101]
	v_mfma_f32_16x16x32_bf16 v[98:101], v[166:169], v[190:193], v[98:101]
	v_mfma_f32_16x16x32_bf16 v[90:93], v[170:173], v[186:189], v[90:93]
	v_mfma_f32_16x16x32_bf16 v[90:93], v[174:177], v[190:193], v[90:93]
	v_mfma_f32_16x16x32_bf16 v[82:85], v[150:153], v[194:197], v[82:85]
	v_mfma_f32_16x16x32_bf16 v[82:85], v[166:169], v[198:201], v[82:85]
	v_mfma_f32_16x16x32_bf16 v[74:77], v[170:173], v[194:197], v[74:77]
	v_mfma_f32_16x16x32_bf16 v[74:77], v[174:177], v[198:201], v[74:77]
	v_mfma_f32_16x16x32_bf16 v[70:73], v[150:153], v[202:205], v[70:73]
	v_mfma_f32_16x16x32_bf16 v[70:73], v[166:169], v[206:209], v[70:73]
	s_setprio 2
	s_barrier
	v_mfma_f32_16x16x32_bf16 v[66:69], v[170:173], v[202:205], v[66:69]
	v_mfma_f32_16x16x32_bf16 v[66:69], v[174:177], v[206:209], v[66:69]
	s_setprio 0
	ds_read_b128 v[178:181], v163 offset:49152
	ds_read_b128 v[182:185], v163 offset:50176
	ds_read_b128 v[186:189], v163 offset:51200
	ds_read_b128 v[190:193], v163 offset:52224
	ds_read_b128 v[194:197], v163 offset:53248
	ds_read_b128 v[198:201], v163 offset:54272
	ds_read_b128 v[202:205], v163 offset:55296
	ds_read_b128 v[206:209], v163 offset:56320
	s_add_u32 s24, s22, 0x40000
	s_addc_u32 s25, s23, 0
	s_mov_b32 s83, m0
	s_mov_b32 m0, s47
	s_nop 0
	global_load_lds_dwordx4 v156, s[24:25]
	s_mov_b32 m0, s83
	s_add_u32 s22, s22, 0x44000
	s_mov_b32 s83, m0
	s_mov_b32 m0, s48
	s_nop 0
	global_load_lds_dwordx4 v158, s[24:25]
	s_mov_b32 m0, s83
	s_addc_u32 s23, s23, 0
	s_mov_b32 s24, m0
	s_mov_b32 m0, s49
	s_nop 0
	global_load_lds_dwordx4 v156, s[22:23]
	s_mov_b32 m0, s24
	s_nop 0
	s_mov_b32 s24, m0
	s_mov_b32 m0, s56
	s_nop 0
	global_load_lds_dwordx4 v158, s[22:23]
	s_mov_b32 m0, s24
	s_waitcnt vmcnt(4)
	s_waitcnt lgkmcnt(0)
	s_barrier
	s_setprio 1
	s_waitcnt lgkmcnt(7)
	v_mfma_f32_16x16x32_bf16 v[62:65], v[134:137], v[178:181], v[62:65]
	v_mfma_f32_16x16x32_bf16 v[62:65], v[138:141], v[182:185], v[62:65]
	s_waitcnt lgkmcnt(5)
	v_mfma_f32_16x16x32_bf16 v[58:61], v[142:145], v[178:181], v[58:61]
	v_mfma_f32_16x16x32_bf16 v[58:61], v[146:149], v[182:185], v[58:61]
	s_waitcnt lgkmcnt(3)
	v_mfma_f32_16x16x32_bf16 v[54:57], v[134:137], v[186:189], v[54:57]
	v_mfma_f32_16x16x32_bf16 v[54:57], v[138:141], v[190:193], v[54:57]
	s_waitcnt lgkmcnt(1)
	v_mfma_f32_16x16x32_bf16 v[46:49], v[142:145], v[186:189], v[46:49]
	v_mfma_f32_16x16x32_bf16 v[46:49], v[146:149], v[190:193], v[46:49]
	v_mfma_f32_16x16x32_bf16 v[38:41], v[134:137], v[194:197], v[38:41]
	v_mfma_f32_16x16x32_bf16 v[38:41], v[138:141], v[198:201], v[38:41]
	v_mfma_f32_16x16x32_bf16 v[30:33], v[142:145], v[194:197], v[30:33]
	v_mfma_f32_16x16x32_bf16 v[30:33], v[146:149], v[198:201], v[30:33]
	v_mfma_f32_16x16x32_bf16 v[22:25], v[134:137], v[202:205], v[22:25]
	v_mfma_f32_16x16x32_bf16 v[22:25], v[138:141], v[206:209], v[22:25]
	s_waitcnt lgkmcnt(0)
	v_mfma_f32_16x16x32_bf16 v[14:17], v[142:145], v[202:205], v[14:17]
	v_mfma_f32_16x16x32_bf16 v[14:17], v[146:149], v[206:209], v[14:17]
	s_setprio 0
	s_setprio 1
	v_mfma_f32_16x16x32_bf16 v[50:53], v[150:153], v[178:181], v[50:53]
	v_mfma_f32_16x16x32_bf16 v[50:53], v[166:169], v[182:185], v[50:53]
	v_mfma_f32_16x16x32_bf16 v[42:45], v[170:173], v[178:181], v[42:45]
	v_mfma_f32_16x16x32_bf16 v[42:45], v[174:177], v[182:185], v[42:45]
	v_mfma_f32_16x16x32_bf16 v[34:37], v[150:153], v[186:189], v[34:37]
	v_mfma_f32_16x16x32_bf16 v[34:37], v[166:169], v[190:193], v[34:37]
	v_mfma_f32_16x16x32_bf16 v[26:29], v[170:173], v[186:189], v[26:29]
	v_mfma_f32_16x16x32_bf16 v[26:29], v[174:177], v[190:193], v[26:29]
	v_mfma_f32_16x16x32_bf16 v[18:21], v[150:153], v[194:197], v[18:21]
	v_mfma_f32_16x16x32_bf16 v[18:21], v[166:169], v[198:201], v[18:21]
	v_mfma_f32_16x16x32_bf16 v[10:13], v[170:173], v[194:197], v[10:13]
	v_mfma_f32_16x16x32_bf16 v[10:13], v[174:177], v[198:201], v[10:13]
	v_mfma_f32_16x16x32_bf16 v[6:9], v[150:153], v[202:205], v[6:9]
	v_mfma_f32_16x16x32_bf16 v[6:9], v[166:169], v[206:209], v[6:9]
	s_setprio 2
	s_barrier
	v_mfma_f32_16x16x32_bf16 v[2:5], v[170:173], v[202:205], v[2:5]
	v_mfma_f32_16x16x32_bf16 v[2:5], v[174:177], v[206:209], v[2:5]
	s_setprio 0
	s_add_i32 s82, s82, 2
	s_add_u32 s78, s78, 0x80000
	s_addc_u32 s79, s79, 0
	s_add_u32 s20, s20, 0x400000
	s_addc_u32 s21, s21, 0
	s_add_u32 s80, s80, 0x400000
	s_addc_u32 s81, s81, 0
	s_cmpk_gt_u32 s82, 0x53
	.p2align 6
.LBB0_473:
	ds_read_b128 v[134:137], v161
	ds_read_b128 v[138:141], v161 offset:1024
	ds_read_b128 v[142:145], v161 offset:2048
	ds_read_b128 v[146:149], v161 offset:3072
	ds_read_b128 v[150:153], v162
	ds_read_b128 v[166:169], v162 offset:1024
	ds_read_b128 v[170:173], v162 offset:2048
	ds_read_b128 v[174:177], v162 offset:3072
	s_cmpk_eq_i32 s82, 0x52
	s_cselect_b32 s23, s11, s79
	s_cselect_b32 s22, s77, s78
	s_cselect_b32 s25, s13, s81
	s_cselect_b32 s24, s76, s80
	ds_read_b128 v[178:181], v163
	ds_read_b128 v[182:185], v163 offset:1024
	ds_read_b128 v[186:189], v163 offset:2048
	ds_read_b128 v[190:193], v163 offset:3072
	ds_read_b128 v[194:197], v163 offset:4096
	ds_read_b128 v[198:201], v163 offset:5120
	ds_read_b128 v[202:205], v163 offset:6144
	ds_read_b128 v[206:209], v163 offset:7168
	s_add_u32 s86, s20, 0xffffc000
	s_addc_u32 s87, s21, -1
	s_mov_b32 s83, m0
	s_mov_b32 m0, s65
	s_nop 0
	global_load_lds_dwordx4 v1, s[86:87]
	s_mov_b32 m0, s83
	s_nop 0
	s_mov_b32 s83, m0
	s_mov_b32 m0, s67
	s_nop 0
	global_load_lds_dwordx4 v157, s[86:87]
	s_mov_b32 m0, s83
	s_nop 0
	s_mov_b32 s83, m0
	s_mov_b32 m0, s66
	s_nop 0
	global_load_lds_dwordx4 v1, s[20:21]
	s_mov_b32 m0, s83
	s_nop 0
	s_mov_b32 s83, m0
	s_mov_b32 m0, s73
	s_nop 0
	global_load_lds_dwordx4 v157, s[20:21]
	s_mov_b32 m0, s83
	s_waitcnt vmcnt(8)
	s_waitcnt lgkmcnt(0)
	s_barrier
	s_setprio 1
	s_waitcnt lgkmcnt(7)
	v_mfma_f32_16x16x32_bf16 v[126:129], v[134:137], v[178:181], v[126:129]
	v_mfma_f32_16x16x32_bf16 v[126:129], v[138:141], v[182:185], v[126:129]
	s_waitcnt lgkmcnt(5)
	v_mfma_f32_16x16x32_bf16 v[122:125], v[142:145], v[178:181], v[122:125]
	v_mfma_f32_16x16x32_bf16 v[122:125], v[146:149], v[182:185], v[122:125]
	s_waitcnt lgkmcnt(3)
	v_mfma_f32_16x16x32_bf16 v[118:121], v[134:137], v[186:189], v[118:121]
	v_mfma_f32_16x16x32_bf16 v[118:121], v[138:141], v[190:193], v[118:121]
	s_waitcnt lgkmcnt(1)
	v_mfma_f32_16x16x32_bf16 v[114:117], v[142:145], v[186:189], v[114:117]
	v_mfma_f32_16x16x32_bf16 v[114:117], v[146:149], v[190:193], v[114:117]
	v_mfma_f32_16x16x32_bf16 v[102:105], v[134:137], v[194:197], v[102:105]
	v_mfma_f32_16x16x32_bf16 v[102:105], v[138:141], v[198:201], v[102:105]
	v_mfma_f32_16x16x32_bf16 v[94:97], v[142:145], v[194:197], v[94:97]
	v_mfma_f32_16x16x32_bf16 v[94:97], v[146:149], v[198:201], v[94:97]
	v_mfma_f32_16x16x32_bf16 v[86:89], v[134:137], v[202:205], v[86:89]
	v_mfma_f32_16x16x32_bf16 v[86:89], v[138:141], v[206:209], v[86:89]
	s_waitcnt lgkmcnt(0)
	v_mfma_f32_16x16x32_bf16 v[78:81], v[142:145], v[202:205], v[78:81]
	v_mfma_f32_16x16x32_bf16 v[78:81], v[146:149], v[206:209], v[78:81]
	s_setprio 0
	s_setprio 1
	v_mfma_f32_16x16x32_bf16 v[110:113], v[150:153], v[178:181], v[110:113]
	v_mfma_f32_16x16x32_bf16 v[110:113], v[166:169], v[182:185], v[110:113]
	v_mfma_f32_16x16x32_bf16 v[106:109], v[170:173], v[178:181], v[106:109]
	v_mfma_f32_16x16x32_bf16 v[106:109], v[174:177], v[182:185], v[106:109]
	v_mfma_f32_16x16x32_bf16 v[98:101], v[150:153], v[186:189], v[98:101]
	v_mfma_f32_16x16x32_bf16 v[98:101], v[166:169], v[190:193], v[98:101]
	v_mfma_f32_16x16x32_bf16 v[90:93], v[170:173], v[186:189], v[90:93]
	v_mfma_f32_16x16x32_bf16 v[90:93], v[174:177], v[190:193], v[90:93]
	v_mfma_f32_16x16x32_bf16 v[82:85], v[150:153], v[194:197], v[82:85]
	v_mfma_f32_16x16x32_bf16 v[82:85], v[166:169], v[198:201], v[82:85]
	v_mfma_f32_16x16x32_bf16 v[74:77], v[170:173], v[194:197], v[74:77]
	v_mfma_f32_16x16x32_bf16 v[74:77], v[174:177], v[198:201], v[74:77]
	v_mfma_f32_16x16x32_bf16 v[70:73], v[150:153], v[202:205], v[70:73]
	v_mfma_f32_16x16x32_bf16 v[70:73], v[166:169], v[206:209], v[70:73]
	s_setprio 2
	s_barrier
	v_mfma_f32_16x16x32_bf16 v[66:69], v[170:173], v[202:205], v[66:69]
	v_mfma_f32_16x16x32_bf16 v[66:69], v[174:177], v[206:209], v[66:69]
	s_setprio 0
	ds_read_b128 v[178:181], v163 offset:16384
	ds_read_b128 v[182:185], v163 offset:17408
	ds_read_b128 v[186:189], v163 offset:18432
	ds_read_b128 v[190:193], v163 offset:19456
	ds_read_b128 v[194:197], v163 offset:20480
	ds_read_b128 v[198:201], v163 offset:21504
	ds_read_b128 v[202:205], v163 offset:22528
	ds_read_b128 v[206:209], v163 offset:23552
	s_mov_b32 s83, m0
	s_mov_b32 m0, s19
	s_nop 0
	global_load_lds_dwordx4 v156, s[22:23]
	s_mov_b32 m0, s83
	s_add_u32 s86, s22, 0x4000
	s_mov_b32 s83, m0
	s_mov_b32 m0, s35
	s_nop 0
	global_load_lds_dwordx4 v158, s[22:23]
	s_mov_b32 m0, s83
	s_addc_u32 s87, s23, 0
	s_mov_b32 s83, m0
	s_mov_b32 m0, s36
	s_nop 0
	global_load_lds_dwordx4 v156, s[86:87]
	s_mov_b32 m0, s83
	s_nop 0
	s_mov_b32 s83, m0
	s_mov_b32 m0, s37
	s_nop 0
	global_load_lds_dwordx4 v158, s[86:87]
	s_mov_b32 m0, s83
	s_waitcnt vmcnt(4)
	s_waitcnt lgkmcnt(0)
	s_barrier
	s_setprio 1
	s_waitcnt lgkmcnt(7)
	v_mfma_f32_16x16x32_bf16 v[62:65], v[134:137], v[178:181], v[62:65]
	v_mfma_f32_16x16x32_bf16 v[62:65], v[138:141], v[182:185], v[62:65]
	s_waitcnt lgkmcnt(5)
	v_mfma_f32_16x16x32_bf16 v[58:61], v[142:145], v[178:181], v[58:61]
	v_mfma_f32_16x16x32_bf16 v[58:61], v[146:149], v[182:185], v[58:61]
	s_waitcnt lgkmcnt(3)
	v_mfma_f32_16x16x32_bf16 v[54:57], v[134:137], v[186:189], v[54:57]
	v_mfma_f32_16x16x32_bf16 v[54:57], v[138:141], v[190:193], v[54:57]
	s_waitcnt lgkmcnt(1)
	v_mfma_f32_16x16x32_bf16 v[46:49], v[142:145], v[186:189], v[46:49]
	v_mfma_f32_16x16x32_bf16 v[46:49], v[146:149], v[190:193], v[46:49]
	v_mfma_f32_16x16x32_bf16 v[38:41], v[134:137], v[194:197], v[38:41]
	v_mfma_f32_16x16x32_bf16 v[38:41], v[138:141], v[198:201], v[38:41]
	v_mfma_f32_16x16x32_bf16 v[30:33], v[142:145], v[194:197], v[30:33]
	v_mfma_f32_16x16x32_bf16 v[30:33], v[146:149], v[198:201], v[30:33]
	v_mfma_f32_16x16x32_bf16 v[22:25], v[134:137], v[202:205], v[22:25]
	v_mfma_f32_16x16x32_bf16 v[22:25], v[138:141], v[206:209], v[22:25]
	s_waitcnt lgkmcnt(0)
	v_mfma_f32_16x16x32_bf16 v[14:17], v[142:145], v[202:205], v[14:17]
	v_mfma_f32_16x16x32_bf16 v[14:17], v[146:149], v[206:209], v[14:17]
	s_setprio 0
	s_setprio 1
	v_mfma_f32_16x16x32_bf16 v[50:53], v[150:153], v[178:181], v[50:53]
	v_mfma_f32_16x16x32_bf16 v[50:53], v[166:169], v[182:185], v[50:53]
	v_mfma_f32_16x16x32_bf16 v[42:45], v[170:173], v[178:181], v[42:45]
	v_mfma_f32_16x16x32_bf16 v[42:45], v[174:177], v[182:185], v[42:45]
	v_mfma_f32_16x16x32_bf16 v[34:37], v[150:153], v[186:189], v[34:37]
	v_mfma_f32_16x16x32_bf16 v[34:37], v[166:169], v[190:193], v[34:37]
	v_mfma_f32_16x16x32_bf16 v[26:29], v[170:173], v[186:189], v[26:29]
	v_mfma_f32_16x16x32_bf16 v[26:29], v[174:177], v[190:193], v[26:29]
	v_mfma_f32_16x16x32_bf16 v[18:21], v[150:153], v[194:197], v[18:21]
	v_mfma_f32_16x16x32_bf16 v[18:21], v[166:169], v[198:201], v[18:21]
	v_mfma_f32_16x16x32_bf16 v[10:13], v[170:173], v[194:197], v[10:13]
	v_mfma_f32_16x16x32_bf16 v[10:13], v[174:177], v[198:201], v[10:13]
	v_mfma_f32_16x16x32_bf16 v[6:9], v[150:153], v[202:205], v[6:9]
	v_mfma_f32_16x16x32_bf16 v[6:9], v[166:169], v[206:209], v[6:9]
	s_setprio 2
	s_barrier
	v_mfma_f32_16x16x32_bf16 v[2:5], v[170:173], v[202:205], v[2:5]
	v_mfma_f32_16x16x32_bf16 v[2:5], v[174:177], v[206:209], v[2:5]
	s_setprio 0
	ds_read_b128 v[134:137], v164
	ds_read_b128 v[138:141], v164 offset:1024
	ds_read_b128 v[142:145], v164 offset:2048
	ds_read_b128 v[146:149], v164 offset:3072
	ds_read_b128 v[150:153], v165
	ds_read_b128 v[166:169], v165 offset:1024
	ds_read_b128 v[170:173], v165 offset:2048
	ds_read_b128 v[174:177], v165 offset:3072
	ds_read_b128 v[178:181], v163 offset:32768
	ds_read_b128 v[182:185], v163 offset:33792
	ds_read_b128 v[186:189], v163 offset:34816
	ds_read_b128 v[190:193], v163 offset:35840
	ds_read_b128 v[194:197], v163 offset:36864
	ds_read_b128 v[198:201], v163 offset:37888
	ds_read_b128 v[202:205], v163 offset:38912
	ds_read_b128 v[206:209], v163 offset:39936
	s_mov_b32 s83, m0
	s_mov_b32 m0, s34
	s_nop 0
	global_load_lds_dwordx4 v1, s[24:25]
	s_mov_b32 m0, s83
	s_nop 0
	s_mov_b32 s83, m0
	s_mov_b32 m0, s42
	s_nop 0
	global_load_lds_dwordx4 v157, s[24:25]
	s_mov_b32 m0, s83
	s_add_u32 s24, s24, 0x4000
	s_addc_u32 s25, s25, 0
	s_mov_b32 s83, m0
	s_mov_b32 m0, s43
	s_nop 0
	global_load_lds_dwordx4 v1, s[24:25]
	s_mov_b32 m0, s83
	s_nop 0
	s_mov_b32 s83, m0
	s_mov_b32 m0, s46
	s_nop 0
	global_load_lds_dwordx4 v157, s[24:25]
	s_mov_b32 m0, s83
	s_waitcnt vmcnt(8)
	s_waitcnt lgkmcnt(0)
	s_barrier
	s_setprio 1
	s_waitcnt lgkmcnt(7)
	v_mfma_f32_16x16x32_bf16 v[126:129], v[134:137], v[178:181], v[126:129]
	v_mfma_f32_16x16x32_bf16 v[126:129], v[138:141], v[182:185], v[126:129]
	s_waitcnt lgkmcnt(5)
	v_mfma_f32_16x16x32_bf16 v[122:125], v[142:145], v[178:181], v[122:125]
	v_mfma_f32_16x16x32_bf16 v[122:125], v[146:149], v[182:185], v[122:125]
	s_waitcnt lgkmcnt(3)
	v_mfma_f32_16x16x32_bf16 v[118:121], v[134:137], v[186:189], v[118:121]
	v_mfma_f32_16x16x32_bf16 v[118:121], v[138:141], v[190:193], v[118:121]
	s_waitcnt lgkmcnt(1)
	v_mfma_f32_16x16x32_bf16 v[114:117], v[142:145], v[186:189], v[114:117]
	v_mfma_f32_16x16x32_bf16 v[114:117], v[146:149], v[190:193], v[114:117]
	v_mfma_f32_16x16x32_bf16 v[102:105], v[134:137], v[194:197], v[102:105]
	v_mfma_f32_16x16x32_bf16 v[102:105], v[138:141], v[198:201], v[102:105]
	v_mfma_f32_16x16x32_bf16 v[94:97], v[142:145], v[194:197], v[94:97]
	v_mfma_f32_16x16x32_bf16 v[94:97], v[146:149], v[198:201], v[94:97]
	v_mfma_f32_16x16x32_bf16 v[86:89], v[134:137], v[202:205], v[86:89]
	v_mfma_f32_16x16x32_bf16 v[86:89], v[138:141], v[206:209], v[86:89]
	s_waitcnt lgkmcnt(0)
	v_mfma_f32_16x16x32_bf16 v[78:81], v[142:145], v[202:205], v[78:81]
	v_mfma_f32_16x16x32_bf16 v[78:81], v[146:149], v[206:209], v[78:81]
	s_setprio 0
	s_setprio 1
	v_mfma_f32_16x16x32_bf16 v[110:113], v[150:153], v[178:181], v[110:113]
	v_mfma_f32_16x16x32_bf16 v[110:113], v[166:169], v[182:185], v[110:113]
	v_mfma_f32_16x16x32_bf16 v[106:109], v[170:173], v[178:181], v[106:109]
	v_mfma_f32_16x16x32_bf16 v[106:109], v[174:177], v[182:185], v[106:109]
	v_mfma_f32_16x16x32_bf16 v[98:101], v[150:153], v[186:189], v[98:101]
	v_mfma_f32_16x16x32_bf16 v[98:101], v[166:169], v[190:193], v[98:101]
	v_mfma_f32_16x16x32_bf16 v[90:93], v[170:173], v[186:189], v[90:93]
	v_mfma_f32_16x16x32_bf16 v[90:93], v[174:177], v[190:193], v[90:93]
	v_mfma_f32_16x16x32_bf16 v[82:85], v[150:153], v[194:197], v[82:85]
	v_mfma_f32_16x16x32_bf16 v[82:85], v[166:169], v[198:201], v[82:85]
	v_mfma_f32_16x16x32_bf16 v[74:77], v[170:173], v[194:197], v[74:77]
	v_mfma_f32_16x16x32_bf16 v[74:77], v[174:177], v[198:201], v[74:77]
	v_mfma_f32_16x16x32_bf16 v[70:73], v[150:153], v[202:205], v[70:73]
	v_mfma_f32_16x16x32_bf16 v[70:73], v[166:169], v[206:209], v[70:73]
	s_setprio 2
	s_barrier
	v_mfma_f32_16x16x32_bf16 v[66:69], v[170:173], v[202:205], v[66:69]
	v_mfma_f32_16x16x32_bf16 v[66:69], v[174:177], v[206:209], v[66:69]
	s_setprio 0
	ds_read_b128 v[178:181], v163 offset:49152
	ds_read_b128 v[182:185], v163 offset:50176
	ds_read_b128 v[186:189], v163 offset:51200
	ds_read_b128 v[190:193], v163 offset:52224
	ds_read_b128 v[194:197], v163 offset:53248
	ds_read_b128 v[198:201], v163 offset:54272
	ds_read_b128 v[202:205], v163 offset:55296
	ds_read_b128 v[206:209], v163 offset:56320
	s_add_u32 s24, s22, 0x40000
	s_addc_u32 s25, s23, 0
	s_mov_b32 s83, m0
	s_mov_b32 m0, s47
	s_nop 0
	global_load_lds_dwordx4 v156, s[24:25]
	s_mov_b32 m0, s83
	s_add_u32 s22, s22, 0x44000
	s_mov_b32 s83, m0
	s_mov_b32 m0, s48
	s_nop 0
	global_load_lds_dwordx4 v158, s[24:25]
	s_mov_b32 m0, s83
	s_addc_u32 s23, s23, 0
	s_mov_b32 s24, m0
	s_mov_b32 m0, s49
	s_nop 0
	global_load_lds_dwordx4 v156, s[22:23]
	s_mov_b32 m0, s24
	s_nop 0
	s_mov_b32 s24, m0
	s_mov_b32 m0, s56
	s_nop 0
	global_load_lds_dwordx4 v158, s[22:23]
	s_mov_b32 m0, s24
	s_waitcnt vmcnt(4)
	s_waitcnt lgkmcnt(0)
	s_barrier
	s_setprio 1
	s_waitcnt lgkmcnt(7)
	v_mfma_f32_16x16x32_bf16 v[62:65], v[134:137], v[178:181], v[62:65]
	v_mfma_f32_16x16x32_bf16 v[62:65], v[138:141], v[182:185], v[62:65]
	s_waitcnt lgkmcnt(5)
	v_mfma_f32_16x16x32_bf16 v[58:61], v[142:145], v[178:181], v[58:61]
	v_mfma_f32_16x16x32_bf16 v[58:61], v[146:149], v[182:185], v[58:61]
	s_waitcnt lgkmcnt(3)
	v_mfma_f32_16x16x32_bf16 v[54:57], v[134:137], v[186:189], v[54:57]
	v_mfma_f32_16x16x32_bf16 v[54:57], v[138:141], v[190:193], v[54:57]
	s_waitcnt lgkmcnt(1)
	v_mfma_f32_16x16x32_bf16 v[46:49], v[142:145], v[186:189], v[46:49]
	v_mfma_f32_16x16x32_bf16 v[46:49], v[146:149], v[190:193], v[46:49]
	v_mfma_f32_16x16x32_bf16 v[38:41], v[134:137], v[194:197], v[38:41]
	v_mfma_f32_16x16x32_bf16 v[38:41], v[138:141], v[198:201], v[38:41]
	v_mfma_f32_16x16x32_bf16 v[30:33], v[142:145], v[194:197], v[30:33]
	v_mfma_f32_16x16x32_bf16 v[30:33], v[146:149], v[198:201], v[30:33]
	v_mfma_f32_16x16x32_bf16 v[22:25], v[134:137], v[202:205], v[22:25]
	v_mfma_f32_16x16x32_bf16 v[22:25], v[138:141], v[206:209], v[22:25]
	s_waitcnt lgkmcnt(0)
	v_mfma_f32_16x16x32_bf16 v[14:17], v[142:145], v[202:205], v[14:17]
	v_mfma_f32_16x16x32_bf16 v[14:17], v[146:149], v[206:209], v[14:17]
	s_setprio 0
	s_setprio 1
	v_mfma_f32_16x16x32_bf16 v[50:53], v[150:153], v[178:181], v[50:53]
	v_mfma_f32_16x16x32_bf16 v[50:53], v[166:169], v[182:185], v[50:53]
	v_mfma_f32_16x16x32_bf16 v[42:45], v[170:173], v[178:181], v[42:45]
	v_mfma_f32_16x16x32_bf16 v[42:45], v[174:177], v[182:185], v[42:45]
	v_mfma_f32_16x16x32_bf16 v[34:37], v[150:153], v[186:189], v[34:37]
	v_mfma_f32_16x16x32_bf16 v[34:37], v[166:169], v[190:193], v[34:37]
	v_mfma_f32_16x16x32_bf16 v[26:29], v[170:173], v[186:189], v[26:29]
	v_mfma_f32_16x16x32_bf16 v[26:29], v[174:177], v[190:193], v[26:29]
	v_mfma_f32_16x16x32_bf16 v[18:21], v[150:153], v[194:197], v[18:21]
	v_mfma_f32_16x16x32_bf16 v[18:21], v[166:169], v[198:201], v[18:21]
	v_mfma_f32_16x16x32_bf16 v[10:13], v[170:173], v[194:197], v[10:13]
	v_mfma_f32_16x16x32_bf16 v[10:13], v[174:177], v[198:201], v[10:13]
	v_mfma_f32_16x16x32_bf16 v[6:9], v[150:153], v[202:205], v[6:9]
	v_mfma_f32_16x16x32_bf16 v[6:9], v[166:169], v[206:209], v[6:9]
	s_setprio 2
	s_barrier
	v_mfma_f32_16x16x32_bf16 v[2:5], v[170:173], v[202:205], v[2:5]
	v_mfma_f32_16x16x32_bf16 v[2:5], v[174:177], v[206:209], v[2:5]
	s_setprio 0
	s_add_i32 s82, s82, 2
	s_add_u32 s78, s78, 0x80000
	s_addc_u32 s79, s79, 0
	s_add_u32 s20, s20, 0x400000
	s_addc_u32 s21, s21, 0
	s_add_u32 s80, s80, 0x400000
	s_addc_u32 s81, s81, 0
	s_cmpk_gt_u32 s82, 0x53
	s_cbranch_scc0 .LBB0_473
	s_and_b64 vcc, exec, s[8:9]
	s_cbranch_vccz .LBB0_476
	s_barrier

.LBB0_653:
	s_ashr_i32 s23, s22, 31
	s_lshl_b64 s[24:25], s[22:23], 20
	s_add_u32 s24, s35, s24
	s_addc_u32 s25, s36, s25
	s_and_b64 s[26:27], s[2:3], exec
	s_cselect_b32 s7, s25, s11
	s_cselect_b32 s9, s24, s10
	s_ashr_i32 s21, s20, 31
	s_lshl_b64 s[26:27], s[20:21], 20
	s_add_u32 s26, s37, s26
	s_addc_u32 s27, s40, s27
	s_and_b64 s[28:29], s[2:3], exec
	s_cselect_b32 s21, s27, s5
	s_cselect_b32 s23, s26, s4
	s_add_u32 s30, s4, 0x100
	s_addc_u32 s31, s5, 0
	s_add_u32 s4, s10, 0x80080
	s_addc_u32 s5, s11, 0
	s_add_u32 s33, s10, 0x100
	s_addc_u32 s73, s11, 0
	s_mov_b32 s74, -2
	s_waitcnt vmcnt(25)
	s_waitcnt vmcnt(24)
	s_waitcnt vmcnt(15)
	s_waitcnt vmcnt(14)
	s_waitcnt vmcnt(13)
	s_waitcnt vmcnt(12)
	s_waitcnt vmcnt(11)
	s_waitcnt vmcnt(10)
	s_waitcnt vmcnt(9)
	s_waitcnt vmcnt(8)
	s_waitcnt vmcnt(7)
	s_waitcnt vmcnt(6)
	s_waitcnt vmcnt(5)
	s_waitcnt vmcnt(4)
	s_waitcnt vmcnt(3)
	s_waitcnt vmcnt(2)
	s_waitcnt vmcnt(1)
	s_waitcnt vmcnt(0)
	ds_read_b128 v[130:133], v161
	ds_read_b128 v[138:141], v161 offset:1024
	ds_read_b128 v[142:145], v161 offset:2048
	ds_read_b128 v[146:149], v161 offset:3072
	ds_read_b128 v[150:153], v162
	ds_read_b128 v[168:171], v162 offset:1024
	ds_read_b128 v[172:175], v162 offset:2048
	ds_read_b128 v[176:179], v162 offset:3072
	s_cmp_eq_u32 s74, 28
	s_cselect_b32 s11, s21, s31
	s_cselect_b32 s10, s23, s30
	s_cselect_b32 s29, s7, s73
	s_cselect_b32 s28, s9, s33
	ds_read_b128 v[180:183], v163
	ds_read_b128 v[184:187], v163 offset:1024
	ds_read_b128 v[188:191], v163 offset:2048
	ds_read_b128 v[192:195], v163 offset:3072
	ds_read_b128 v[196:199], v163 offset:4096
	ds_read_b128 v[200:203], v163 offset:5120
	ds_read_b128 v[204:207], v163 offset:6144
	ds_read_b128 v[208:211], v163 offset:7168
	s_add_u32 s76, s4, 0xfff80000
	s_addc_u32 s77, s5, -1
	s_mov_b32 s75, m0
	s_mov_b32 m0, s80
	s_nop 0
	global_load_lds_dwordx4 v1, s[76:77]
	s_mov_b32 m0, s75
	s_nop 0
	s_mov_b32 s75, m0
	s_mov_b32 m0, s82
	s_nop 0
	global_load_lds_dwordx4 v157, s[76:77]
	s_mov_b32 m0, s75
	s_nop 0
	s_mov_b32 s75, m0
	s_mov_b32 m0, s81
	s_nop 0
	global_load_lds_dwordx4 v1, s[4:5]
	s_mov_b32 m0, s75
	s_nop 0
	s_mov_b32 s75, m0
	s_mov_b32 m0, s83
	s_nop 0
	global_load_lds_dwordx4 v157, s[4:5]
	s_mov_b32 m0, s75
	s_waitcnt vmcnt(8)
	s_waitcnt lgkmcnt(0)
	s_barrier
	s_setprio 1
	s_waitcnt lgkmcnt(7)
	v_mfma_f32_16x16x32_bf16 v[126:129], v[130:133], v[180:183], 0
	v_mfma_f32_16x16x32_bf16 v[126:129], v[138:141], v[184:187], v[126:129]
	s_waitcnt lgkmcnt(5)
	v_mfma_f32_16x16x32_bf16 v[122:125], v[142:145], v[180:183], 0
	v_mfma_f32_16x16x32_bf16 v[122:125], v[146:149], v[184:187], v[122:125]
	s_waitcnt lgkmcnt(3)
	v_mfma_f32_16x16x32_bf16 v[110:113], v[130:133], v[188:191], 0
	v_mfma_f32_16x16x32_bf16 v[110:113], v[138:141], v[192:195], v[110:113]
	s_waitcnt lgkmcnt(1)
	v_mfma_f32_16x16x32_bf16 v[106:109], v[142:145], v[188:191], 0
	v_mfma_f32_16x16x32_bf16 v[106:109], v[146:149], v[192:195], v[106:109]
	v_mfma_f32_16x16x32_bf16 v[94:97], v[130:133], v[196:199], 0
	v_mfma_f32_16x16x32_bf16 v[94:97], v[138:141], v[200:203], v[94:97]
	v_mfma_f32_16x16x32_bf16 v[90:93], v[142:145], v[196:199], 0
	v_mfma_f32_16x16x32_bf16 v[90:93], v[146:149], v[200:203], v[90:93]
	v_mfma_f32_16x16x32_bf16 v[78:81], v[130:133], v[204:207], 0
	v_mfma_f32_16x16x32_bf16 v[78:81], v[138:141], v[208:211], v[78:81]
	s_waitcnt lgkmcnt(0)
	v_mfma_f32_16x16x32_bf16 v[74:77], v[142:145], v[204:207], 0
	v_mfma_f32_16x16x32_bf16 v[74:77], v[146:149], v[208:211], v[74:77]
	s_setprio 0
	s_setprio 1
	v_mfma_f32_16x16x32_bf16 v[118:121], v[150:153], v[180:183], 0
	v_mfma_f32_16x16x32_bf16 v[118:121], v[168:171], v[184:187], v[118:121]
	v_mfma_f32_16x16x32_bf16 v[114:117], v[172:175], v[180:183], 0
	v_mfma_f32_16x16x32_bf16 v[114:117], v[176:179], v[184:187], v[114:117]
	v_mfma_f32_16x16x32_bf16 v[102:105], v[150:153], v[188:191], 0
	v_mfma_f32_16x16x32_bf16 v[102:105], v[168:171], v[192:195], v[102:105]
	v_mfma_f32_16x16x32_bf16 v[98:101], v[172:175], v[188:191], 0
	v_mfma_f32_16x16x32_bf16 v[98:101], v[176:179], v[192:195], v[98:101]
	v_mfma_f32_16x16x32_bf16 v[86:89], v[150:153], v[196:199], 0
	v_mfma_f32_16x16x32_bf16 v[86:89], v[168:171], v[200:203], v[86:89]
	v_mfma_f32_16x16x32_bf16 v[82:85], v[172:175], v[196:199], 0
	v_mfma_f32_16x16x32_bf16 v[82:85], v[176:179], v[200:203], v[82:85]
	v_mfma_f32_16x16x32_bf16 v[70:73], v[150:153], v[204:207], 0
	v_mfma_f32_16x16x32_bf16 v[70:73], v[168:171], v[208:211], v[70:73]
	s_setprio 2
	s_barrier
	v_mfma_f32_16x16x32_bf16 v[66:69], v[172:175], v[204:207], 0
	v_mfma_f32_16x16x32_bf16 v[66:69], v[176:179], v[208:211], v[66:69]
	s_setprio 0
	ds_read_b128 v[180:183], v163 offset:16384
	ds_read_b128 v[184:187], v163 offset:17408
	ds_read_b128 v[188:191], v163 offset:18432
	ds_read_b128 v[192:195], v163 offset:19456
	ds_read_b128 v[196:199], v163 offset:20480
	ds_read_b128 v[200:203], v163 offset:21504
	ds_read_b128 v[204:207], v163 offset:22528
	ds_read_b128 v[208:211], v163 offset:23552
	s_mov_b32 s75, m0
	s_mov_b32 m0, s43
	s_nop 0
	global_load_lds_dwordx4 v156, s[10:11]
	s_mov_b32 m0, s75
	s_add_u32 s76, s10, 0x80000
	s_mov_b32 s75, m0
	s_mov_b32 m0, s46
	s_nop 0
	global_load_lds_dwordx4 v158, s[10:11]
	s_mov_b32 m0, s75
	s_addc_u32 s77, s11, 0
	s_mov_b32 s75, m0
	s_mov_b32 m0, s47
	s_nop 0
	global_load_lds_dwordx4 v156, s[76:77]
	s_mov_b32 m0, s75
	s_nop 0
	s_mov_b32 s75, m0
	s_mov_b32 m0, s48
	s_nop 0
	global_load_lds_dwordx4 v158, s[76:77]
	s_mov_b32 m0, s75
	s_waitcnt vmcnt(4)
	s_waitcnt lgkmcnt(0)
	s_barrier
	s_setprio 1
	s_waitcnt lgkmcnt(7)
	v_mfma_f32_16x16x32_bf16 v[62:65], v[130:133], v[180:183], 0
	v_mfma_f32_16x16x32_bf16 v[62:65], v[138:141], v[184:187], v[62:65]
	s_waitcnt lgkmcnt(5)
	v_mfma_f32_16x16x32_bf16 v[58:61], v[142:145], v[180:183], 0
	v_mfma_f32_16x16x32_bf16 v[58:61], v[146:149], v[184:187], v[58:61]
	s_waitcnt lgkmcnt(3)
	v_mfma_f32_16x16x32_bf16 v[46:49], v[130:133], v[188:191], 0
	v_mfma_f32_16x16x32_bf16 v[46:49], v[138:141], v[192:195], v[46:49]
	s_waitcnt lgkmcnt(1)
	v_mfma_f32_16x16x32_bf16 v[42:45], v[142:145], v[188:191], 0
	v_mfma_f32_16x16x32_bf16 v[42:45], v[146:149], v[192:195], v[42:45]
	v_mfma_f32_16x16x32_bf16 v[30:33], v[130:133], v[196:199], 0
	v_mfma_f32_16x16x32_bf16 v[30:33], v[138:141], v[200:203], v[30:33]
	v_mfma_f32_16x16x32_bf16 v[26:29], v[142:145], v[196:199], 0
	v_mfma_f32_16x16x32_bf16 v[26:29], v[146:149], v[200:203], v[26:29]
	v_mfma_f32_16x16x32_bf16 v[14:17], v[130:133], v[204:207], 0
	v_mfma_f32_16x16x32_bf16 v[14:17], v[138:141], v[208:211], v[14:17]
	s_waitcnt lgkmcnt(0)
	v_mfma_f32_16x16x32_bf16 v[10:13], v[142:145], v[204:207], 0
	v_mfma_f32_16x16x32_bf16 v[10:13], v[146:149], v[208:211], v[10:13]
	s_setprio 0
	s_setprio 1
	v_mfma_f32_16x16x32_bf16 v[54:57], v[150:153], v[180:183], 0
	v_mfma_f32_16x16x32_bf16 v[54:57], v[168:171], v[184:187], v[54:57]
	v_mfma_f32_16x16x32_bf16 v[50:53], v[172:175], v[180:183], 0
	v_mfma_f32_16x16x32_bf16 v[50:53], v[176:179], v[184:187], v[50:53]
	v_mfma_f32_16x16x32_bf16 v[38:41], v[150:153], v[188:191], 0
	v_mfma_f32_16x16x32_bf16 v[38:41], v[168:171], v[192:195], v[38:41]
	v_mfma_f32_16x16x32_bf16 v[34:37], v[172:175], v[188:191], 0
	v_mfma_f32_16x16x32_bf16 v[34:37], v[176:179], v[192:195], v[34:37]
	v_mfma_f32_16x16x32_bf16 v[22:25], v[150:153], v[196:199], 0
	v_mfma_f32_16x16x32_bf16 v[22:25], v[168:171], v[200:203], v[22:25]
	v_mfma_f32_16x16x32_bf16 v[18:21], v[172:175], v[196:199], 0
	v_mfma_f32_16x16x32_bf16 v[18:21], v[176:179], v[200:203], v[18:21]
	v_mfma_f32_16x16x32_bf16 v[6:9], v[150:153], v[204:207], 0
	v_mfma_f32_16x16x32_bf16 v[6:9], v[168:171], v[208:211], v[6:9]
	s_setprio 2
	s_barrier
	v_mfma_f32_16x16x32_bf16 v[2:5], v[172:175], v[204:207], 0
	v_mfma_f32_16x16x32_bf16 v[2:5], v[176:179], v[208:211], v[2:5]
	s_setprio 0
	ds_read_b128 v[130:133], v164
	ds_read_b128 v[138:141], v164 offset:1024
	ds_read_b128 v[142:145], v164 offset:2048
	ds_read_b128 v[146:149], v164 offset:3072
	ds_read_b128 v[150:153], v165
	ds_read_b128 v[168:171], v165 offset:1024
	ds_read_b128 v[172:175], v165 offset:2048
	ds_read_b128 v[176:179], v165 offset:3072
	ds_read_b128 v[180:183], v163 offset:32768
	ds_read_b128 v[184:187], v163 offset:33792
	ds_read_b128 v[188:191], v163 offset:34816
	ds_read_b128 v[192:195], v163 offset:35840
	ds_read_b128 v[196:199], v163 offset:36864
	ds_read_b128 v[200:203], v163 offset:37888
	ds_read_b128 v[204:207], v163 offset:38912
	ds_read_b128 v[208:211], v163 offset:39936
	s_mov_b32 s75, m0
	s_mov_b32 m0, s42
	s_nop 0
	global_load_lds_dwordx4 v1, s[28:29]
	s_mov_b32 m0, s75
	s_nop 0
	s_mov_b32 s75, m0
	s_mov_b32 m0, s49
	s_nop 0
	global_load_lds_dwordx4 v157, s[28:29]
	s_mov_b32 m0, s75
	s_add_u32 s28, s28, 0x80000
	s_addc_u32 s29, s29, 0
	s_mov_b32 s75, m0
	s_mov_b32 m0, s56
	s_nop 0
	global_load_lds_dwordx4 v1, s[28:29]
	s_mov_b32 m0, s75
	s_nop 0
	s_mov_b32 s75, m0
	s_mov_b32 m0, s57
	s_nop 0
	global_load_lds_dwordx4 v157, s[28:29]
	s_mov_b32 m0, s75
	s_waitcnt vmcnt(8)
	s_waitcnt lgkmcnt(0)
	s_barrier
	s_setprio 1
	s_waitcnt lgkmcnt(7)
	v_mfma_f32_16x16x32_bf16 v[126:129], v[130:133], v[180:183], v[126:129]
	v_mfma_f32_16x16x32_bf16 v[126:129], v[138:141], v[184:187], v[126:129]
	s_waitcnt lgkmcnt(5)
	v_mfma_f32_16x16x32_bf16 v[122:125], v[142:145], v[180:183], v[122:125]
	v_mfma_f32_16x16x32_bf16 v[122:125], v[146:149], v[184:187], v[122:125]
	s_waitcnt lgkmcnt(3)
	v_mfma_f32_16x16x32_bf16 v[110:113], v[130:133], v[188:191], v[110:113]
	v_mfma_f32_16x16x32_bf16 v[110:113], v[138:141], v[192:195], v[110:113]
	s_waitcnt lgkmcnt(1)
	v_mfma_f32_16x16x32_bf16 v[106:109], v[142:145], v[188:191], v[106:109]
	v_mfma_f32_16x16x32_bf16 v[106:109], v[146:149], v[192:195], v[106:109]
	v_mfma_f32_16x16x32_bf16 v[94:97], v[130:133], v[196:199], v[94:97]
	v_mfma_f32_16x16x32_bf16 v[94:97], v[138:141], v[200:203], v[94:97]
	v_mfma_f32_16x16x32_bf16 v[90:93], v[142:145], v[196:199], v[90:93]
	v_mfma_f32_16x16x32_bf16 v[90:93], v[146:149], v[200:203], v[90:93]
	v_mfma_f32_16x16x32_bf16 v[78:81], v[130:133], v[204:207], v[78:81]
	v_mfma_f32_16x16x32_bf16 v[78:81], v[138:141], v[208:211], v[78:81]
	s_waitcnt lgkmcnt(0)
	v_mfma_f32_16x16x32_bf16 v[74:77], v[142:145], v[204:207], v[74:77]
	v_mfma_f32_16x16x32_bf16 v[74:77], v[146:149], v[208:211], v[74:77]
	s_setprio 0
	s_setprio 1
	v_mfma_f32_16x16x32_bf16 v[118:121], v[150:153], v[180:183], v[118:121]
	v_mfma_f32_16x16x32_bf16 v[118:121], v[168:171], v[184:187], v[118:121]
	v_mfma_f32_16x16x32_bf16 v[114:117], v[172:175], v[180:183], v[114:117]
	v_mfma_f32_16x16x32_bf16 v[114:117], v[176:179], v[184:187], v[114:117]
	v_mfma_f32_16x16x32_bf16 v[102:105], v[150:153], v[188:191], v[102:105]
	v_mfma_f32_16x16x32_bf16 v[102:105], v[168:171], v[192:195], v[102:105]
	v_mfma_f32_16x16x32_bf16 v[98:101], v[172:175], v[188:191], v[98:101]
	v_mfma_f32_16x16x32_bf16 v[98:101], v[176:179], v[192:195], v[98:101]
	v_mfma_f32_16x16x32_bf16 v[86:89], v[150:153], v[196:199], v[86:89]
	v_mfma_f32_16x16x32_bf16 v[86:89], v[168:171], v[200:203], v[86:89]
	v_mfma_f32_16x16x32_bf16 v[82:85], v[172:175], v[196:199], v[82:85]
	v_mfma_f32_16x16x32_bf16 v[82:85], v[176:179], v[200:203], v[82:85]
	v_mfma_f32_16x16x32_bf16 v[70:73], v[150:153], v[204:207], v[70:73]
	v_mfma_f32_16x16x32_bf16 v[70:73], v[168:171], v[208:211], v[70:73]
	s_setprio 2
	s_barrier
	v_mfma_f32_16x16x32_bf16 v[66:69], v[172:175], v[204:207], v[66:69]
	v_mfma_f32_16x16x32_bf16 v[66:69], v[176:179], v[208:211], v[66:69]
	s_setprio 0
	ds_read_b128 v[180:183], v163 offset:49152
	ds_read_b128 v[184:187], v163 offset:50176
	ds_read_b128 v[188:191], v163 offset:51200
	ds_read_b128 v[192:195], v163 offset:52224
	ds_read_b128 v[196:199], v163 offset:53248
	ds_read_b128 v[200:203], v163 offset:54272
	ds_read_b128 v[204:207], v163 offset:55296
	ds_read_b128 v[208:211], v163 offset:56320
	s_add_u32 s28, s10, 0x80
	s_addc_u32 s29, s11, 0
	s_mov_b32 s75, m0
	s_mov_b32 m0, s64
	s_nop 0
	global_load_lds_dwordx4 v156, s[28:29]
	s_mov_b32 m0, s75
	s_add_u32 s10, s10, 0x80080
	s_mov_b32 s75, m0
	s_mov_b32 m0, s65
	s_nop 0
	global_load_lds_dwordx4 v158, s[28:29]
	s_mov_b32 m0, s75
	s_addc_u32 s11, s11, 0
	s_mov_b32 s28, m0
	s_mov_b32 m0, s66
	s_nop 0
	global_load_lds_dwordx4 v156, s[10:11]
	s_mov_b32 m0, s28
	s_nop 0
	s_mov_b32 s28, m0
	s_mov_b32 m0, s67
	s_nop 0
	global_load_lds_dwordx4 v158, s[10:11]
	s_mov_b32 m0, s28
	s_waitcnt vmcnt(4)
	s_waitcnt lgkmcnt(0)
	s_barrier
	s_setprio 1
	s_waitcnt lgkmcnt(7)
	v_mfma_f32_16x16x32_bf16 v[62:65], v[130:133], v[180:183], v[62:65]
	v_mfma_f32_16x16x32_bf16 v[62:65], v[138:141], v[184:187], v[62:65]
	s_waitcnt lgkmcnt(5)
	v_mfma_f32_16x16x32_bf16 v[58:61], v[142:145], v[180:183], v[58:61]
	v_mfma_f32_16x16x32_bf16 v[58:61], v[146:149], v[184:187], v[58:61]
	s_waitcnt lgkmcnt(3)
	v_mfma_f32_16x16x32_bf16 v[46:49], v[130:133], v[188:191], v[46:49]
	v_mfma_f32_16x16x32_bf16 v[46:49], v[138:141], v[192:195], v[46:49]
	s_waitcnt lgkmcnt(1)
	v_mfma_f32_16x16x32_bf16 v[42:45], v[142:145], v[188:191], v[42:45]
	v_mfma_f32_16x16x32_bf16 v[42:45], v[146:149], v[192:195], v[42:45]
	v_mfma_f32_16x16x32_bf16 v[30:33], v[130:133], v[196:199], v[30:33]
	v_mfma_f32_16x16x32_bf16 v[30:33], v[138:141], v[200:203], v[30:33]
	v_mfma_f32_16x16x32_bf16 v[26:29], v[142:145], v[196:199], v[26:29]
	v_mfma_f32_16x16x32_bf16 v[26:29], v[146:149], v[200:203], v[26:29]
	v_mfma_f32_16x16x32_bf16 v[14:17], v[130:133], v[204:207], v[14:17]
	v_mfma_f32_16x16x32_bf16 v[14:17], v[138:141], v[208:211], v[14:17]
	s_waitcnt lgkmcnt(0)
	v_mfma_f32_16x16x32_bf16 v[10:13], v[142:145], v[204:207], v[10:13]
	v_mfma_f32_16x16x32_bf16 v[10:13], v[146:149], v[208:211], v[10:13]
	s_setprio 0
	s_setprio 1
	v_mfma_f32_16x16x32_bf16 v[54:57], v[150:153], v[180:183], v[54:57]
	v_mfma_f32_16x16x32_bf16 v[54:57], v[168:171], v[184:187], v[54:57]
	v_mfma_f32_16x16x32_bf16 v[50:53], v[172:175], v[180:183], v[50:53]
	v_mfma_f32_16x16x32_bf16 v[50:53], v[176:179], v[184:187], v[50:53]
	v_mfma_f32_16x16x32_bf16 v[38:41], v[150:153], v[188:191], v[38:41]
	v_mfma_f32_16x16x32_bf16 v[38:41], v[168:171], v[192:195], v[38:41]
	v_mfma_f32_16x16x32_bf16 v[34:37], v[172:175], v[188:191], v[34:37]
	v_mfma_f32_16x16x32_bf16 v[34:37], v[176:179], v[192:195], v[34:37]
	v_mfma_f32_16x16x32_bf16 v[22:25], v[150:153], v[196:199], v[22:25]
	v_mfma_f32_16x16x32_bf16 v[22:25], v[168:171], v[200:203], v[22:25]
	v_mfma_f32_16x16x32_bf16 v[18:21], v[172:175], v[196:199], v[18:21]
	v_mfma_f32_16x16x32_bf16 v[18:21], v[176:179], v[200:203], v[18:21]
	v_mfma_f32_16x16x32_bf16 v[6:9], v[150:153], v[204:207], v[6:9]
	v_mfma_f32_16x16x32_bf16 v[6:9], v[168:171], v[208:211], v[6:9]
	s_setprio 2
	s_barrier
	v_mfma_f32_16x16x32_bf16 v[2:5], v[172:175], v[204:207], v[2:5]
	v_mfma_f32_16x16x32_bf16 v[2:5], v[176:179], v[208:211], v[2:5]
	s_setprio 0
	s_add_i32 s74, s74, 2
	s_add_u32 s30, s30, 0x100
	s_addc_u32 s31, s31, 0
	s_add_u32 s4, s4, 0x100
	s_addc_u32 s5, s5, 0
	s_add_u32 s33, s33, 0x100
	s_addc_u32 s73, s73, 0
	s_cmp_gt_u32 s74, 29
	.p2align 6
.LBB0_654:
	ds_read_b128 v[130:133], v161
	ds_read_b128 v[138:141], v161 offset:1024
	ds_read_b128 v[142:145], v161 offset:2048
	ds_read_b128 v[146:149], v161 offset:3072
	ds_read_b128 v[150:153], v162
	ds_read_b128 v[168:171], v162 offset:1024
	ds_read_b128 v[172:175], v162 offset:2048
	ds_read_b128 v[176:179], v162 offset:3072
	s_cmp_eq_u32 s74, 28
	s_cselect_b32 s11, s21, s31
	s_cselect_b32 s10, s23, s30
	s_cselect_b32 s29, s7, s73
	s_cselect_b32 s28, s9, s33
	ds_read_b128 v[180:183], v163
	ds_read_b128 v[184:187], v163 offset:1024
	ds_read_b128 v[188:191], v163 offset:2048
	ds_read_b128 v[192:195], v163 offset:3072
	ds_read_b128 v[196:199], v163 offset:4096
	ds_read_b128 v[200:203], v163 offset:5120
	ds_read_b128 v[204:207], v163 offset:6144
	ds_read_b128 v[208:211], v163 offset:7168
	s_add_u32 s76, s4, 0xfff80000
	s_addc_u32 s77, s5, -1
	s_mov_b32 s75, m0
	s_mov_b32 m0, s80
	s_nop 0
	global_load_lds_dwordx4 v1, s[76:77]
	s_mov_b32 m0, s75
	s_nop 0
	s_mov_b32 s75, m0
	s_mov_b32 m0, s82
	s_nop 0
	global_load_lds_dwordx4 v157, s[76:77]
	s_mov_b32 m0, s75
	s_nop 0
	s_mov_b32 s75, m0
	s_mov_b32 m0, s81
	s_nop 0
	global_load_lds_dwordx4 v1, s[4:5]
	s_mov_b32 m0, s75
	s_nop 0
	s_mov_b32 s75, m0
	s_mov_b32 m0, s83
	s_nop 0
	global_load_lds_dwordx4 v157, s[4:5]
	s_mov_b32 m0, s75
	s_waitcnt vmcnt(8)
	s_waitcnt lgkmcnt(0)
	s_barrier
	s_setprio 1
	s_waitcnt lgkmcnt(7)
	v_mfma_f32_16x16x32_bf16 v[126:129], v[130:133], v[180:183], v[126:129]
	v_mfma_f32_16x16x32_bf16 v[126:129], v[138:141], v[184:187], v[126:129]
	s_waitcnt lgkmcnt(5)
	v_mfma_f32_16x16x32_bf16 v[122:125], v[142:145], v[180:183], v[122:125]
	v_mfma_f32_16x16x32_bf16 v[122:125], v[146:149], v[184:187], v[122:125]
	s_waitcnt lgkmcnt(3)
	v_mfma_f32_16x16x32_bf16 v[110:113], v[130:133], v[188:191], v[110:113]
	v_mfma_f32_16x16x32_bf16 v[110:113], v[138:141], v[192:195], v[110:113]
	s_waitcnt lgkmcnt(1)
	v_mfma_f32_16x16x32_bf16 v[106:109], v[142:145], v[188:191], v[106:109]
	v_mfma_f32_16x16x32_bf16 v[106:109], v[146:149], v[192:195], v[106:109]
	v_mfma_f32_16x16x32_bf16 v[94:97], v[130:133], v[196:199], v[94:97]
	v_mfma_f32_16x16x32_bf16 v[94:97], v[138:141], v[200:203], v[94:97]
	v_mfma_f32_16x16x32_bf16 v[90:93], v[142:145], v[196:199], v[90:93]
	v_mfma_f32_16x16x32_bf16 v[90:93], v[146:149], v[200:203], v[90:93]
	v_mfma_f32_16x16x32_bf16 v[78:81], v[130:133], v[204:207], v[78:81]
	v_mfma_f32_16x16x32_bf16 v[78:81], v[138:141], v[208:211], v[78:81]
	s_waitcnt lgkmcnt(0)
	v_mfma_f32_16x16x32_bf16 v[74:77], v[142:145], v[204:207], v[74:77]
	v_mfma_f32_16x16x32_bf16 v[74:77], v[146:149], v[208:211], v[74:77]
	s_setprio 0
	s_setprio 1
	v_mfma_f32_16x16x32_bf16 v[118:121], v[150:153], v[180:183], v[118:121]
	v_mfma_f32_16x16x32_bf16 v[118:121], v[168:171], v[184:187], v[118:121]
	v_mfma_f32_16x16x32_bf16 v[114:117], v[172:175], v[180:183], v[114:117]
	v_mfma_f32_16x16x32_bf16 v[114:117], v[176:179], v[184:187], v[114:117]
	v_mfma_f32_16x16x32_bf16 v[102:105], v[150:153], v[188:191], v[102:105]
	v_mfma_f32_16x16x32_bf16 v[102:105], v[168:171], v[192:195], v[102:105]
	v_mfma_f32_16x16x32_bf16 v[98:101], v[172:175], v[188:191], v[98:101]
	v_mfma_f32_16x16x32_bf16 v[98:101], v[176:179], v[192:195], v[98:101]
	v_mfma_f32_16x16x32_bf16 v[86:89], v[150:153], v[196:199], v[86:89]
	v_mfma_f32_16x16x32_bf16 v[86:89], v[168:171], v[200:203], v[86:89]
	v_mfma_f32_16x16x32_bf16 v[82:85], v[172:175], v[196:199], v[82:85]
	v_mfma_f32_16x16x32_bf16 v[82:85], v[176:179], v[200:203], v[82:85]
	v_mfma_f32_16x16x32_bf16 v[70:73], v[150:153], v[204:207], v[70:73]
	v_mfma_f32_16x16x32_bf16 v[70:73], v[168:171], v[208:211], v[70:73]
	s_setprio 2
	s_barrier
	v_mfma_f32_16x16x32_bf16 v[66:69], v[172:175], v[204:207], v[66:69]
	v_mfma_f32_16x16x32_bf16 v[66:69], v[176:179], v[208:211], v[66:69]
	s_setprio 0
	ds_read_b128 v[180:183], v163 offset:16384
	ds_read_b128 v[184:187], v163 offset:17408
	ds_read_b128 v[188:191], v163 offset:18432
	ds_read_b128 v[192:195], v163 offset:19456
	ds_read_b128 v[196:199], v163 offset:20480
	ds_read_b128 v[200:203], v163 offset:21504
	ds_read_b128 v[204:207], v163 offset:22528
	ds_read_b128 v[208:211], v163 offset:23552
	s_mov_b32 s75, m0
	s_mov_b32 m0, s43
	s_nop 0
	global_load_lds_dwordx4 v156, s[10:11]
	s_mov_b32 m0, s75
	s_add_u32 s76, s10, 0x80000
	s_mov_b32 s75, m0
	s_mov_b32 m0, s46
	s_nop 0
	global_load_lds_dwordx4 v158, s[10:11]
	s_mov_b32 m0, s75
	s_addc_u32 s77, s11, 0
	s_mov_b32 s75, m0
	s_mov_b32 m0, s47
	s_nop 0
	global_load_lds_dwordx4 v156, s[76:77]
	s_mov_b32 m0, s75
	s_nop 0
	s_mov_b32 s75, m0
	s_mov_b32 m0, s48
	s_nop 0
	global_load_lds_dwordx4 v158, s[76:77]
	s_mov_b32 m0, s75
	s_waitcnt vmcnt(4)
	s_waitcnt lgkmcnt(0)
	s_barrier
	s_setprio 1
	s_waitcnt lgkmcnt(7)
	v_mfma_f32_16x16x32_bf16 v[62:65], v[130:133], v[180:183], v[62:65]
	v_mfma_f32_16x16x32_bf16 v[62:65], v[138:141], v[184:187], v[62:65]
	s_waitcnt lgkmcnt(5)
	v_mfma_f32_16x16x32_bf16 v[58:61], v[142:145], v[180:183], v[58:61]
	v_mfma_f32_16x16x32_bf16 v[58:61], v[146:149], v[184:187], v[58:61]
	s_waitcnt lgkmcnt(3)
	v_mfma_f32_16x16x32_bf16 v[46:49], v[130:133], v[188:191], v[46:49]
	v_mfma_f32_16x16x32_bf16 v[46:49], v[138:141], v[192:195], v[46:49]
	s_waitcnt lgkmcnt(1)
	v_mfma_f32_16x16x32_bf16 v[42:45], v[142:145], v[188:191], v[42:45]
	v_mfma_f32_16x16x32_bf16 v[42:45], v[146:149], v[192:195], v[42:45]
	v_mfma_f32_16x16x32_bf16 v[30:33], v[130:133], v[196:199], v[30:33]
	v_mfma_f32_16x16x32_bf16 v[30:33], v[138:141], v[200:203], v[30:33]
	v_mfma_f32_16x16x32_bf16 v[26:29], v[142:145], v[196:199], v[26:29]
	v_mfma_f32_16x16x32_bf16 v[26:29], v[146:149], v[200:203], v[26:29]
	v_mfma_f32_16x16x32_bf16 v[14:17], v[130:133], v[204:207], v[14:17]
	v_mfma_f32_16x16x32_bf16 v[14:17], v[138:141], v[208:211], v[14:17]
	s_waitcnt lgkmcnt(0)
	v_mfma_f32_16x16x32_bf16 v[10:13], v[142:145], v[204:207], v[10:13]
	v_mfma_f32_16x16x32_bf16 v[10:13], v[146:149], v[208:211], v[10:13]
	s_setprio 0
	s_setprio 1
	v_mfma_f32_16x16x32_bf16 v[54:57], v[150:153], v[180:183], v[54:57]
	v_mfma_f32_16x16x32_bf16 v[54:57], v[168:171], v[184:187], v[54:57]
	v_mfma_f32_16x16x32_bf16 v[50:53], v[172:175], v[180:183], v[50:53]
	v_mfma_f32_16x16x32_bf16 v[50:53], v[176:179], v[184:187], v[50:53]
	v_mfma_f32_16x16x32_bf16 v[38:41], v[150:153], v[188:191], v[38:41]
	v_mfma_f32_16x16x32_bf16 v[38:41], v[168:171], v[192:195], v[38:41]
	v_mfma_f32_16x16x32_bf16 v[34:37], v[172:175], v[188:191], v[34:37]
	v_mfma_f32_16x16x32_bf16 v[34:37], v[176:179], v[192:195], v[34:37]
	v_mfma_f32_16x16x32_bf16 v[22:25], v[150:153], v[196:199], v[22:25]
	v_mfma_f32_16x16x32_bf16 v[22:25], v[168:171], v[200:203], v[22:25]
	v_mfma_f32_16x16x32_bf16 v[18:21], v[172:175], v[196:199], v[18:21]
	v_mfma_f32_16x16x32_bf16 v[18:21], v[176:179], v[200:203], v[18:21]
	v_mfma_f32_16x16x32_bf16 v[6:9], v[150:153], v[204:207], v[6:9]
	v_mfma_f32_16x16x32_bf16 v[6:9], v[168:171], v[208:211], v[6:9]
	s_setprio 2
	s_barrier
	v_mfma_f32_16x16x32_bf16 v[2:5], v[172:175], v[204:207], v[2:5]
	v_mfma_f32_16x16x32_bf16 v[2:5], v[176:179], v[208:211], v[2:5]
	s_setprio 0
	ds_read_b128 v[130:133], v164
	ds_read_b128 v[138:141], v164 offset:1024
	ds_read_b128 v[142:145], v164 offset:2048
	ds_read_b128 v[146:149], v164 offset:3072
	ds_read_b128 v[150:153], v165
	ds_read_b128 v[168:171], v165 offset:1024
	ds_read_b128 v[172:175], v165 offset:2048
	ds_read_b128 v[176:179], v165 offset:3072
	ds_read_b128 v[180:183], v163 offset:32768
	ds_read_b128 v[184:187], v163 offset:33792
	ds_read_b128 v[188:191], v163 offset:34816
	ds_read_b128 v[192:195], v163 offset:35840
	ds_read_b128 v[196:199], v163 offset:36864
	ds_read_b128 v[200:203], v163 offset:37888
	ds_read_b128 v[204:207], v163 offset:38912
	ds_read_b128 v[208:211], v163 offset:39936
	s_mov_b32 s75, m0
	s_mov_b32 m0, s42
	s_nop 0
	global_load_lds_dwordx4 v1, s[28:29]
	s_mov_b32 m0, s75
	s_nop 0
	s_mov_b32 s75, m0
	s_mov_b32 m0, s49
	s_nop 0
	global_load_lds_dwordx4 v157, s[28:29]
	s_mov_b32 m0, s75
	s_add_u32 s28, s28, 0x80000
	s_addc_u32 s29, s29, 0
	s_mov_b32 s75, m0
	s_mov_b32 m0, s56
	s_nop 0
	global_load_lds_dwordx4 v1, s[28:29]
	s_mov_b32 m0, s75
	s_nop 0
	s_mov_b32 s75, m0
	s_mov_b32 m0, s57
	s_nop 0
	global_load_lds_dwordx4 v157, s[28:29]
	s_mov_b32 m0, s75
	s_waitcnt vmcnt(8)
	s_waitcnt lgkmcnt(0)
	s_barrier
	s_setprio 1
	s_waitcnt lgkmcnt(7)
	v_mfma_f32_16x16x32_bf16 v[126:129], v[130:133], v[180:183], v[126:129]
	v_mfma_f32_16x16x32_bf16 v[126:129], v[138:141], v[184:187], v[126:129]
	s_waitcnt lgkmcnt(5)
	v_mfma_f32_16x16x32_bf16 v[122:125], v[142:145], v[180:183], v[122:125]
	v_mfma_f32_16x16x32_bf16 v[122:125], v[146:149], v[184:187], v[122:125]
	s_waitcnt lgkmcnt(3)
	v_mfma_f32_16x16x32_bf16 v[110:113], v[130:133], v[188:191], v[110:113]
	v_mfma_f32_16x16x32_bf16 v[110:113], v[138:141], v[192:195], v[110:113]
	s_waitcnt lgkmcnt(1)
	v_mfma_f32_16x16x32_bf16 v[106:109], v[142:145], v[188:191], v[106:109]
	v_mfma_f32_16x16x32_bf16 v[106:109], v[146:149], v[192:195], v[106:109]
	v_mfma_f32_16x16x32_bf16 v[94:97], v[130:133], v[196:199], v[94:97]
	v_mfma_f32_16x16x32_bf16 v[94:97], v[138:141], v[200:203], v[94:97]
	v_mfma_f32_16x16x32_bf16 v[90:93], v[142:145], v[196:199], v[90:93]
	v_mfma_f32_16x16x32_bf16 v[90:93], v[146:149], v[200:203], v[90:93]
	v_mfma_f32_16x16x32_bf16 v[78:81], v[130:133], v[204:207], v[78:81]
	v_mfma_f32_16x16x32_bf16 v[78:81], v[138:141], v[208:211], v[78:81]
	s_waitcnt lgkmcnt(0)
	v_mfma_f32_16x16x32_bf16 v[74:77], v[142:145], v[204:207], v[74:77]
	v_mfma_f32_16x16x32_bf16 v[74:77], v[146:149], v[208:211], v[74:77]
	s_setprio 0
	s_setprio 1
	v_mfma_f32_16x16x32_bf16 v[118:121], v[150:153], v[180:183], v[118:121]
	v_mfma_f32_16x16x32_bf16 v[118:121], v[168:171], v[184:187], v[118:121]
	v_mfma_f32_16x16x32_bf16 v[114:117], v[172:175], v[180:183], v[114:117]
	v_mfma_f32_16x16x32_bf16 v[114:117], v[176:179], v[184:187], v[114:117]
	v_mfma_f32_16x16x32_bf16 v[102:105], v[150:153], v[188:191], v[102:105]
	v_mfma_f32_16x16x32_bf16 v[102:105], v[168:171], v[192:195], v[102:105]
	v_mfma_f32_16x16x32_bf16 v[98:101], v[172:175], v[188:191], v[98:101]
	v_mfma_f32_16x16x32_bf16 v[98:101], v[176:179], v[192:195], v[98:101]
	v_mfma_f32_16x16x32_bf16 v[86:89], v[150:153], v[196:199], v[86:89]
	v_mfma_f32_16x16x32_bf16 v[86:89], v[168:171], v[200:203], v[86:89]
	v_mfma_f32_16x16x32_bf16 v[82:85], v[172:175], v[196:199], v[82:85]
	v_mfma_f32_16x16x32_bf16 v[82:85], v[176:179], v[200:203], v[82:85]
	v_mfma_f32_16x16x32_bf16 v[70:73], v[150:153], v[204:207], v[70:73]
	v_mfma_f32_16x16x32_bf16 v[70:73], v[168:171], v[208:211], v[70:73]
	s_setprio 2
	s_barrier
	v_mfma_f32_16x16x32_bf16 v[66:69], v[172:175], v[204:207], v[66:69]
	v_mfma_f32_16x16x32_bf16 v[66:69], v[176:179], v[208:211], v[66:69]
	s_setprio 0
	ds_read_b128 v[180:183], v163 offset:49152
	ds_read_b128 v[184:187], v163 offset:50176
	ds_read_b128 v[188:191], v163 offset:51200
	ds_read_b128 v[192:195], v163 offset:52224
	ds_read_b128 v[196:199], v163 offset:53248
	ds_read_b128 v[200:203], v163 offset:54272
	ds_read_b128 v[204:207], v163 offset:55296
	ds_read_b128 v[208:211], v163 offset:56320
	s_add_u32 s28, s10, 0x80
	s_addc_u32 s29, s11, 0
	s_mov_b32 s75, m0
	s_mov_b32 m0, s64
	s_nop 0
	global_load_lds_dwordx4 v156, s[28:29]
	s_mov_b32 m0, s75
	s_add_u32 s10, s10, 0x80080
	s_mov_b32 s75, m0
	s_mov_b32 m0, s65
	s_nop 0
	global_load_lds_dwordx4 v158, s[28:29]
	s_mov_b32 m0, s75
	s_addc_u32 s11, s11, 0
	s_mov_b32 s28, m0
	s_mov_b32 m0, s66
	s_nop 0
	global_load_lds_dwordx4 v156, s[10:11]
	s_mov_b32 m0, s28
	s_nop 0
	s_mov_b32 s28, m0
	s_mov_b32 m0, s67
	s_nop 0
	global_load_lds_dwordx4 v158, s[10:11]
	s_mov_b32 m0, s28
	s_waitcnt vmcnt(4)
	s_waitcnt lgkmcnt(0)
	s_barrier
	s_setprio 1
	s_waitcnt lgkmcnt(7)
	v_mfma_f32_16x16x32_bf16 v[62:65], v[130:133], v[180:183], v[62:65]
	v_mfma_f32_16x16x32_bf16 v[62:65], v[138:141], v[184:187], v[62:65]
	s_waitcnt lgkmcnt(5)
	v_mfma_f32_16x16x32_bf16 v[58:61], v[142:145], v[180:183], v[58:61]
	v_mfma_f32_16x16x32_bf16 v[58:61], v[146:149], v[184:187], v[58:61]
	s_waitcnt lgkmcnt(3)
	v_mfma_f32_16x16x32_bf16 v[46:49], v[130:133], v[188:191], v[46:49]
	v_mfma_f32_16x16x32_bf16 v[46:49], v[138:141], v[192:195], v[46:49]
	s_waitcnt lgkmcnt(1)
	v_mfma_f32_16x16x32_bf16 v[42:45], v[142:145], v[188:191], v[42:45]
	v_mfma_f32_16x16x32_bf16 v[42:45], v[146:149], v[192:195], v[42:45]
	v_mfma_f32_16x16x32_bf16 v[30:33], v[130:133], v[196:199], v[30:33]
	v_mfma_f32_16x16x32_bf16 v[30:33], v[138:141], v[200:203], v[30:33]
	v_mfma_f32_16x16x32_bf16 v[26:29], v[142:145], v[196:199], v[26:29]
	v_mfma_f32_16x16x32_bf16 v[26:29], v[146:149], v[200:203], v[26:29]
	v_mfma_f32_16x16x32_bf16 v[14:17], v[130:133], v[204:207], v[14:17]
	v_mfma_f32_16x16x32_bf16 v[14:17], v[138:141], v[208:211], v[14:17]
	s_waitcnt lgkmcnt(0)
	v_mfma_f32_16x16x32_bf16 v[10:13], v[142:145], v[204:207], v[10:13]
	v_mfma_f32_16x16x32_bf16 v[10:13], v[146:149], v[208:211], v[10:13]
	s_setprio 0
	s_setprio 1
	v_mfma_f32_16x16x32_bf16 v[54:57], v[150:153], v[180:183], v[54:57]
	v_mfma_f32_16x16x32_bf16 v[54:57], v[168:171], v[184:187], v[54:57]
	v_mfma_f32_16x16x32_bf16 v[50:53], v[172:175], v[180:183], v[50:53]
	v_mfma_f32_16x16x32_bf16 v[50:53], v[176:179], v[184:187], v[50:53]
	v_mfma_f32_16x16x32_bf16 v[38:41], v[150:153], v[188:191], v[38:41]
	v_mfma_f32_16x16x32_bf16 v[38:41], v[168:171], v[192:195], v[38:41]
	v_mfma_f32_16x16x32_bf16 v[34:37], v[172:175], v[188:191], v[34:37]
	v_mfma_f32_16x16x32_bf16 v[34:37], v[176:179], v[192:195], v[34:37]
	v_mfma_f32_16x16x32_bf16 v[22:25], v[150:153], v[196:199], v[22:25]
	v_mfma_f32_16x16x32_bf16 v[22:25], v[168:171], v[200:203], v[22:25]
	v_mfma_f32_16x16x32_bf16 v[18:21], v[172:175], v[196:199], v[18:21]
	v_mfma_f32_16x16x32_bf16 v[18:21], v[176:179], v[200:203], v[18:21]
	v_mfma_f32_16x16x32_bf16 v[6:9], v[150:153], v[204:207], v[6:9]
	v_mfma_f32_16x16x32_bf16 v[6:9], v[168:171], v[208:211], v[6:9]
	s_setprio 2
	s_barrier
	v_mfma_f32_16x16x32_bf16 v[2:5], v[172:175], v[204:207], v[2:5]
	v_mfma_f32_16x16x32_bf16 v[2:5], v[176:179], v[208:211], v[2:5]
	s_setprio 0
	s_add_i32 s74, s74, 2
	s_add_u32 s30, s30, 0x100
	s_addc_u32 s31, s31, 0
	s_add_u32 s4, s4, 0x100
	s_addc_u32 s5, s5, 0
	s_add_u32 s33, s33, 0x100
	s_addc_u32 s73, s73, 0
	s_cmp_gt_u32 s74, 29
	s_cbranch_scc0 .LBB0_654
	s_and_b64 vcc, exec, s[18:19]
	s_cbranch_vccz .LBB0_657
	s_barrier

.LBB0_1052:
	s_ashr_i32 s13, s12, 31
	s_lshl_b64 s[14:15], s[12:13], 20
	s_add_u32 s14, s28, s14
	s_addc_u32 s15, s29, s15
	s_and_b64 s[16:17], s[2:3], exec
	s_cselect_b32 s13, s15, s23
	s_cselect_b32 s67, s14, s22
	s_ashr_i32 s11, s10, 31
	s_lshl_b64 s[16:17], s[10:11], 20
	s_add_u32 s16, s30, s16
	s_addc_u32 s17, s31, s17
	s_and_b64 s[24:25], s[2:3], exec
	s_cselect_b32 s11, s17, s21
	s_cselect_b32 s73, s16, s20
	s_add_u32 s74, s20, 0x100
	s_addc_u32 s75, s21, 0
	s_add_u32 s20, s22, 0x80080
	s_addc_u32 s21, s23, 0
	s_add_u32 s76, s22, 0x100
	s_addc_u32 s77, s23, 0
	s_mov_b32 s78, -2
	s_waitcnt vmcnt(25)
	s_waitcnt vmcnt(24)
	s_waitcnt vmcnt(15)
	s_waitcnt vmcnt(14)
	s_waitcnt vmcnt(13)
	s_waitcnt vmcnt(12)
	s_waitcnt vmcnt(11)
	s_waitcnt vmcnt(10)
	s_waitcnt vmcnt(9)
	s_waitcnt vmcnt(8)
	s_waitcnt vmcnt(7)
	s_waitcnt vmcnt(6)
	s_waitcnt vmcnt(5)
	s_waitcnt vmcnt(4)
	s_waitcnt vmcnt(3)
	s_waitcnt vmcnt(2)
	s_waitcnt vmcnt(1)
	s_waitcnt vmcnt(0)
	ds_read_b128 v[130:133], v181
	ds_read_b128 v[134:137], v181 offset:1024
	ds_read_b128 v[138:141], v181 offset:2048
	ds_read_b128 v[142:145], v181 offset:3072
	ds_read_b128 v[146:149], v182
	ds_read_b128 v[150:153], v182 offset:1024
	ds_read_b128 v[154:157], v182 offset:2048
	ds_read_b128 v[158:161], v182 offset:3072
	s_cmp_eq_u32 s78, 28
	s_cselect_b32 s23, s11, s75
	s_cselect_b32 s22, s73, s74
	s_cselect_b32 s25, s13, s77
	s_cselect_b32 s24, s67, s76
	ds_read_b128 v[166:169], v183
	ds_read_b128 v[170:173], v183 offset:1024
	ds_read_b128 v[186:189], v183 offset:2048
	ds_read_b128 v[190:193], v183 offset:3072
	ds_read_b128 v[194:197], v183 offset:4096
	ds_read_b128 v[198:201], v183 offset:5120
	ds_read_b128 v[202:205], v183 offset:6144
	ds_read_b128 v[206:209], v183 offset:7168
	s_add_u32 s80, s20, 0xfff80000
	s_addc_u32 s81, s21, -1
	s_mov_b32 s79, m0
	s_mov_b32 m0, s58
	s_nop 0
	global_load_lds_dwordx4 v1, s[80:81]
	s_mov_b32 m0, s79
	s_nop 0
	s_mov_b32 s79, m0
	s_mov_b32 m0, s64
	s_nop 0
	global_load_lds_dwordx4 v177, s[80:81]
	s_mov_b32 m0, s79
	s_nop 0
	s_mov_b32 s79, m0
	s_mov_b32 m0, s59
	s_nop 0
	global_load_lds_dwordx4 v1, s[20:21]
	s_mov_b32 m0, s79
	s_nop 0
	s_mov_b32 s79, m0
	s_mov_b32 m0, s65
	s_nop 0
	global_load_lds_dwordx4 v177, s[20:21]
	s_mov_b32 m0, s79
	s_waitcnt vmcnt(8)
	s_waitcnt lgkmcnt(0)
	s_barrier
	s_setprio 1
	s_waitcnt lgkmcnt(7)
	v_mfma_f32_16x16x32_bf16 v[126:129], v[130:133], v[166:169], 0
	v_mfma_f32_16x16x32_bf16 v[126:129], v[134:137], v[170:173], v[126:129]
	s_waitcnt lgkmcnt(5)
	v_mfma_f32_16x16x32_bf16 v[122:125], v[138:141], v[166:169], 0
	v_mfma_f32_16x16x32_bf16 v[122:125], v[142:145], v[170:173], v[122:125]
	s_waitcnt lgkmcnt(3)
	v_mfma_f32_16x16x32_bf16 v[118:121], v[130:133], v[186:189], 0
	v_mfma_f32_16x16x32_bf16 v[118:121], v[134:137], v[190:193], v[118:121]
	s_waitcnt lgkmcnt(1)
	v_mfma_f32_16x16x32_bf16 v[114:117], v[138:141], v[186:189], 0
	v_mfma_f32_16x16x32_bf16 v[114:117], v[142:145], v[190:193], v[114:117]
	v_mfma_f32_16x16x32_bf16 v[94:97], v[130:133], v[194:197], 0
	v_mfma_f32_16x16x32_bf16 v[94:97], v[134:137], v[198:201], v[94:97]
	v_mfma_f32_16x16x32_bf16 v[90:93], v[138:141], v[194:197], 0
	v_mfma_f32_16x16x32_bf16 v[90:93], v[142:145], v[198:201], v[90:93]
	v_mfma_f32_16x16x32_bf16 v[86:89], v[130:133], v[202:205], 0
	v_mfma_f32_16x16x32_bf16 v[86:89], v[134:137], v[206:209], v[86:89]
	s_waitcnt lgkmcnt(0)
	v_mfma_f32_16x16x32_bf16 v[78:81], v[138:141], v[202:205], 0
	v_mfma_f32_16x16x32_bf16 v[78:81], v[142:145], v[206:209], v[78:81]
	s_setprio 0
	s_setprio 1
	v_mfma_f32_16x16x32_bf16 v[110:113], v[146:149], v[166:169], 0
	v_mfma_f32_16x16x32_bf16 v[110:113], v[150:153], v[170:173], v[110:113]
	v_mfma_f32_16x16x32_bf16 v[106:109], v[154:157], v[166:169], 0
	v_mfma_f32_16x16x32_bf16 v[106:109], v[158:161], v[170:173], v[106:109]
	v_mfma_f32_16x16x32_bf16 v[102:105], v[146:149], v[186:189], 0
	v_mfma_f32_16x16x32_bf16 v[102:105], v[150:153], v[190:193], v[102:105]
	v_mfma_f32_16x16x32_bf16 v[98:101], v[154:157], v[186:189], 0
	v_mfma_f32_16x16x32_bf16 v[98:101], v[158:161], v[190:193], v[98:101]
	v_mfma_f32_16x16x32_bf16 v[82:85], v[146:149], v[194:197], 0
	v_mfma_f32_16x16x32_bf16 v[82:85], v[150:153], v[198:201], v[82:85]
	v_mfma_f32_16x16x32_bf16 v[74:77], v[154:157], v[194:197], 0
	v_mfma_f32_16x16x32_bf16 v[74:77], v[158:161], v[198:201], v[74:77]
	v_mfma_f32_16x16x32_bf16 v[70:73], v[146:149], v[202:205], 0
	v_mfma_f32_16x16x32_bf16 v[70:73], v[150:153], v[206:209], v[70:73]
	s_setprio 2
	s_barrier
	v_mfma_f32_16x16x32_bf16 v[66:69], v[154:157], v[202:205], 0
	v_mfma_f32_16x16x32_bf16 v[66:69], v[158:161], v[206:209], v[66:69]
	s_setprio 0
	ds_read_b128 v[166:169], v183 offset:16384
	ds_read_b128 v[170:173], v183 offset:17408
	ds_read_b128 v[186:189], v183 offset:18432
	ds_read_b128 v[190:193], v183 offset:19456
	ds_read_b128 v[194:197], v183 offset:20480
	ds_read_b128 v[198:201], v183 offset:21504
	ds_read_b128 v[202:205], v183 offset:22528
	ds_read_b128 v[206:209], v183 offset:23552
	s_mov_b32 s79, m0
	s_mov_b32 m0, s35
	s_nop 0
	global_load_lds_dwordx4 v176, s[22:23]
	s_mov_b32 m0, s79
	s_add_u32 s80, s22, 0x80000
	s_mov_b32 s79, m0
	s_mov_b32 m0, s36
	s_nop 0
	global_load_lds_dwordx4 v178, s[22:23]
	s_mov_b32 m0, s79
	s_addc_u32 s81, s23, 0
	s_mov_b32 s79, m0
	s_mov_b32 m0, s37
	s_nop 0
	global_load_lds_dwordx4 v176, s[80:81]
	s_mov_b32 m0, s79
	s_nop 0
	s_mov_b32 s79, m0
	s_mov_b32 m0, s40
	s_nop 0
	global_load_lds_dwordx4 v178, s[80:81]
	s_mov_b32 m0, s79
	s_waitcnt vmcnt(4)
	s_waitcnt lgkmcnt(0)
	s_barrier
	s_setprio 1
	s_waitcnt lgkmcnt(7)
	v_mfma_f32_16x16x32_bf16 v[62:65], v[130:133], v[166:169], 0
	v_mfma_f32_16x16x32_bf16 v[62:65], v[134:137], v[170:173], v[62:65]
	s_waitcnt lgkmcnt(5)
	v_mfma_f32_16x16x32_bf16 v[58:61], v[138:141], v[166:169], 0
	v_mfma_f32_16x16x32_bf16 v[58:61], v[142:145], v[170:173], v[58:61]
	s_waitcnt lgkmcnt(3)
	v_mfma_f32_16x16x32_bf16 v[46:49], v[130:133], v[186:189], 0
	v_mfma_f32_16x16x32_bf16 v[46:49], v[134:137], v[190:193], v[46:49]
	s_waitcnt lgkmcnt(1)
	v_mfma_f32_16x16x32_bf16 v[42:45], v[138:141], v[186:189], 0
	v_mfma_f32_16x16x32_bf16 v[42:45], v[142:145], v[190:193], v[42:45]
	v_mfma_f32_16x16x32_bf16 v[30:33], v[130:133], v[194:197], 0
	v_mfma_f32_16x16x32_bf16 v[30:33], v[134:137], v[198:201], v[30:33]
	v_mfma_f32_16x16x32_bf16 v[26:29], v[138:141], v[194:197], 0
	v_mfma_f32_16x16x32_bf16 v[26:29], v[142:145], v[198:201], v[26:29]
	v_mfma_f32_16x16x32_bf16 v[14:17], v[130:133], v[202:205], 0
	v_mfma_f32_16x16x32_bf16 v[14:17], v[134:137], v[206:209], v[14:17]
	s_waitcnt lgkmcnt(0)
	v_mfma_f32_16x16x32_bf16 v[10:13], v[138:141], v[202:205], 0
	v_mfma_f32_16x16x32_bf16 v[10:13], v[142:145], v[206:209], v[10:13]
	s_setprio 0
	s_setprio 1
	v_mfma_f32_16x16x32_bf16 v[54:57], v[146:149], v[166:169], 0
	v_mfma_f32_16x16x32_bf16 v[54:57], v[150:153], v[170:173], v[54:57]
	v_mfma_f32_16x16x32_bf16 v[50:53], v[154:157], v[166:169], 0
	v_mfma_f32_16x16x32_bf16 v[50:53], v[158:161], v[170:173], v[50:53]
	v_mfma_f32_16x16x32_bf16 v[38:41], v[146:149], v[186:189], 0
	v_mfma_f32_16x16x32_bf16 v[38:41], v[150:153], v[190:193], v[38:41]
	v_mfma_f32_16x16x32_bf16 v[34:37], v[154:157], v[186:189], 0
	v_mfma_f32_16x16x32_bf16 v[34:37], v[158:161], v[190:193], v[34:37]
	v_mfma_f32_16x16x32_bf16 v[22:25], v[146:149], v[194:197], 0
	v_mfma_f32_16x16x32_bf16 v[22:25], v[150:153], v[198:201], v[22:25]
	v_mfma_f32_16x16x32_bf16 v[18:21], v[154:157], v[194:197], 0
	v_mfma_f32_16x16x32_bf16 v[18:21], v[158:161], v[198:201], v[18:21]
	v_mfma_f32_16x16x32_bf16 v[6:9], v[146:149], v[202:205], 0
	v_mfma_f32_16x16x32_bf16 v[6:9], v[150:153], v[206:209], v[6:9]
	s_setprio 2
	s_barrier
	v_mfma_f32_16x16x32_bf16 v[2:5], v[154:157], v[202:205], 0
	v_mfma_f32_16x16x32_bf16 v[2:5], v[158:161], v[206:209], v[2:5]
	s_setprio 0
	ds_read_b128 v[130:133], v184
	ds_read_b128 v[134:137], v184 offset:1024
	ds_read_b128 v[138:141], v184 offset:2048
	ds_read_b128 v[142:145], v184 offset:3072
	ds_read_b128 v[146:149], v185
	ds_read_b128 v[150:153], v185 offset:1024
	ds_read_b128 v[154:157], v185 offset:2048
	ds_read_b128 v[158:161], v185 offset:3072
	ds_read_b128 v[166:169], v183 offset:32768
	ds_read_b128 v[170:173], v183 offset:33792
	ds_read_b128 v[186:189], v183 offset:34816
	ds_read_b128 v[190:193], v183 offset:35840
	ds_read_b128 v[194:197], v183 offset:36864
	ds_read_b128 v[198:201], v183 offset:37888
	ds_read_b128 v[202:205], v183 offset:38912
	ds_read_b128 v[206:209], v183 offset:39936
	s_mov_b32 s79, m0
	s_mov_b32 m0, s34
	s_nop 0
	global_load_lds_dwordx4 v1, s[24:25]
	s_mov_b32 m0, s79
	s_nop 0
	s_mov_b32 s79, m0
	s_mov_b32 m0, s41
	s_nop 0
	global_load_lds_dwordx4 v177, s[24:25]
	s_mov_b32 m0, s79
	s_add_u32 s24, s24, 0x80000
	s_addc_u32 s25, s25, 0
	s_mov_b32 s79, m0
	s_mov_b32 m0, s42
	s_nop 0
	global_load_lds_dwordx4 v1, s[24:25]
	s_mov_b32 m0, s79
	s_nop 0
	s_mov_b32 s79, m0
	s_mov_b32 m0, s43
	s_nop 0
	global_load_lds_dwordx4 v177, s[24:25]
	s_mov_b32 m0, s79
	s_waitcnt vmcnt(8)
	s_waitcnt lgkmcnt(0)
	s_barrier
	s_setprio 1
	s_waitcnt lgkmcnt(7)
	v_mfma_f32_16x16x32_bf16 v[126:129], v[130:133], v[166:169], v[126:129]
	v_mfma_f32_16x16x32_bf16 v[126:129], v[134:137], v[170:173], v[126:129]
	s_waitcnt lgkmcnt(5)
	v_mfma_f32_16x16x32_bf16 v[122:125], v[138:141], v[166:169], v[122:125]
	v_mfma_f32_16x16x32_bf16 v[122:125], v[142:145], v[170:173], v[122:125]
	s_waitcnt lgkmcnt(3)
	v_mfma_f32_16x16x32_bf16 v[118:121], v[130:133], v[186:189], v[118:121]
	v_mfma_f32_16x16x32_bf16 v[118:121], v[134:137], v[190:193], v[118:121]
	s_waitcnt lgkmcnt(1)
	v_mfma_f32_16x16x32_bf16 v[114:117], v[138:141], v[186:189], v[114:117]
	v_mfma_f32_16x16x32_bf16 v[114:117], v[142:145], v[190:193], v[114:117]
	v_mfma_f32_16x16x32_bf16 v[94:97], v[130:133], v[194:197], v[94:97]
	v_mfma_f32_16x16x32_bf16 v[94:97], v[134:137], v[198:201], v[94:97]
	v_mfma_f32_16x16x32_bf16 v[90:93], v[138:141], v[194:197], v[90:93]
	v_mfma_f32_16x16x32_bf16 v[90:93], v[142:145], v[198:201], v[90:93]
	v_mfma_f32_16x16x32_bf16 v[86:89], v[130:133], v[202:205], v[86:89]
	v_mfma_f32_16x16x32_bf16 v[86:89], v[134:137], v[206:209], v[86:89]
	s_waitcnt lgkmcnt(0)
	v_mfma_f32_16x16x32_bf16 v[78:81], v[138:141], v[202:205], v[78:81]
	v_mfma_f32_16x16x32_bf16 v[78:81], v[142:145], v[206:209], v[78:81]
	s_setprio 0
	s_setprio 1
	v_mfma_f32_16x16x32_bf16 v[110:113], v[146:149], v[166:169], v[110:113]
	v_mfma_f32_16x16x32_bf16 v[110:113], v[150:153], v[170:173], v[110:113]
	v_mfma_f32_16x16x32_bf16 v[106:109], v[154:157], v[166:169], v[106:109]
	v_mfma_f32_16x16x32_bf16 v[106:109], v[158:161], v[170:173], v[106:109]
	v_mfma_f32_16x16x32_bf16 v[102:105], v[146:149], v[186:189], v[102:105]
	v_mfma_f32_16x16x32_bf16 v[102:105], v[150:153], v[190:193], v[102:105]
	v_mfma_f32_16x16x32_bf16 v[98:101], v[154:157], v[186:189], v[98:101]
	v_mfma_f32_16x16x32_bf16 v[98:101], v[158:161], v[190:193], v[98:101]
	v_mfma_f32_16x16x32_bf16 v[82:85], v[146:149], v[194:197], v[82:85]
	v_mfma_f32_16x16x32_bf16 v[82:85], v[150:153], v[198:201], v[82:85]
	v_mfma_f32_16x16x32_bf16 v[74:77], v[154:157], v[194:197], v[74:77]
	v_mfma_f32_16x16x32_bf16 v[74:77], v[158:161], v[198:201], v[74:77]
	v_mfma_f32_16x16x32_bf16 v[70:73], v[146:149], v[202:205], v[70:73]
	v_mfma_f32_16x16x32_bf16 v[70:73], v[150:153], v[206:209], v[70:73]
	s_setprio 2
	s_barrier
	v_mfma_f32_16x16x32_bf16 v[66:69], v[154:157], v[202:205], v[66:69]
	v_mfma_f32_16x16x32_bf16 v[66:69], v[158:161], v[206:209], v[66:69]
	s_setprio 0
	ds_read_b128 v[166:169], v183 offset:49152
	ds_read_b128 v[170:173], v183 offset:50176
	ds_read_b128 v[186:189], v183 offset:51200
	ds_read_b128 v[190:193], v183 offset:52224
	ds_read_b128 v[194:197], v183 offset:53248
	ds_read_b128 v[198:201], v183 offset:54272
	ds_read_b128 v[202:205], v183 offset:55296
	ds_read_b128 v[206:209], v183 offset:56320
	s_add_u32 s24, s22, 0x80
	s_addc_u32 s25, s23, 0
	s_mov_b32 s79, m0
	s_mov_b32 m0, s46
	s_nop 0
	global_load_lds_dwordx4 v176, s[24:25]
	s_mov_b32 m0, s79
	s_add_u32 s22, s22, 0x80080
	s_mov_b32 s79, m0
	s_mov_b32 m0, s47
	s_nop 0
	global_load_lds_dwordx4 v178, s[24:25]
	s_mov_b32 m0, s79
	s_addc_u32 s23, s23, 0
	s_mov_b32 s24, m0
	s_mov_b32 m0, s48
	s_nop 0
	global_load_lds_dwordx4 v176, s[22:23]
	s_mov_b32 m0, s24
	s_nop 0
	s_mov_b32 s24, m0
	s_mov_b32 m0, s49
	s_nop 0
	global_load_lds_dwordx4 v178, s[22:23]
	s_mov_b32 m0, s24
	s_waitcnt vmcnt(4)
	s_waitcnt lgkmcnt(0)
	s_barrier
	s_setprio 1
	s_waitcnt lgkmcnt(7)
	v_mfma_f32_16x16x32_bf16 v[62:65], v[130:133], v[166:169], v[62:65]
	v_mfma_f32_16x16x32_bf16 v[62:65], v[134:137], v[170:173], v[62:65]
	s_waitcnt lgkmcnt(5)
	v_mfma_f32_16x16x32_bf16 v[58:61], v[138:141], v[166:169], v[58:61]
	v_mfma_f32_16x16x32_bf16 v[58:61], v[142:145], v[170:173], v[58:61]
	s_waitcnt lgkmcnt(3)
	v_mfma_f32_16x16x32_bf16 v[46:49], v[130:133], v[186:189], v[46:49]
	v_mfma_f32_16x16x32_bf16 v[46:49], v[134:137], v[190:193], v[46:49]
	s_waitcnt lgkmcnt(1)
	v_mfma_f32_16x16x32_bf16 v[42:45], v[138:141], v[186:189], v[42:45]
	v_mfma_f32_16x16x32_bf16 v[42:45], v[142:145], v[190:193], v[42:45]
	v_mfma_f32_16x16x32_bf16 v[30:33], v[130:133], v[194:197], v[30:33]
	v_mfma_f32_16x16x32_bf16 v[30:33], v[134:137], v[198:201], v[30:33]
	v_mfma_f32_16x16x32_bf16 v[26:29], v[138:141], v[194:197], v[26:29]
	v_mfma_f32_16x16x32_bf16 v[26:29], v[142:145], v[198:201], v[26:29]
	v_mfma_f32_16x16x32_bf16 v[14:17], v[130:133], v[202:205], v[14:17]
	v_mfma_f32_16x16x32_bf16 v[14:17], v[134:137], v[206:209], v[14:17]
	s_waitcnt lgkmcnt(0)
	v_mfma_f32_16x16x32_bf16 v[10:13], v[138:141], v[202:205], v[10:13]
	v_mfma_f32_16x16x32_bf16 v[10:13], v[142:145], v[206:209], v[10:13]
	s_setprio 0
	s_setprio 1
	v_mfma_f32_16x16x32_bf16 v[54:57], v[146:149], v[166:169], v[54:57]
	v_mfma_f32_16x16x32_bf16 v[54:57], v[150:153], v[170:173], v[54:57]
	v_mfma_f32_16x16x32_bf16 v[50:53], v[154:157], v[166:169], v[50:53]
	v_mfma_f32_16x16x32_bf16 v[50:53], v[158:161], v[170:173], v[50:53]
	v_mfma_f32_16x16x32_bf16 v[38:41], v[146:149], v[186:189], v[38:41]
	v_mfma_f32_16x16x32_bf16 v[38:41], v[150:153], v[190:193], v[38:41]
	v_mfma_f32_16x16x32_bf16 v[34:37], v[154:157], v[186:189], v[34:37]
	v_mfma_f32_16x16x32_bf16 v[34:37], v[158:161], v[190:193], v[34:37]
	v_mfma_f32_16x16x32_bf16 v[22:25], v[146:149], v[194:197], v[22:25]
	v_mfma_f32_16x16x32_bf16 v[22:25], v[150:153], v[198:201], v[22:25]
	v_mfma_f32_16x16x32_bf16 v[18:21], v[154:157], v[194:197], v[18:21]
	v_mfma_f32_16x16x32_bf16 v[18:21], v[158:161], v[198:201], v[18:21]
	v_mfma_f32_16x16x32_bf16 v[6:9], v[146:149], v[202:205], v[6:9]
	v_mfma_f32_16x16x32_bf16 v[6:9], v[150:153], v[206:209], v[6:9]
	s_setprio 2
	s_barrier
	v_mfma_f32_16x16x32_bf16 v[2:5], v[154:157], v[202:205], v[2:5]
	v_mfma_f32_16x16x32_bf16 v[2:5], v[158:161], v[206:209], v[2:5]
	s_setprio 0
	s_add_i32 s78, s78, 2
	s_add_u32 s74, s74, 0x100
	s_addc_u32 s75, s75, 0
	s_add_u32 s20, s20, 0x100
	s_addc_u32 s21, s21, 0
	s_add_u32 s76, s76, 0x100
	s_addc_u32 s77, s77, 0
	s_cmp_gt_u32 s78, 29
	.p2align 6
.LBB0_1053:
	ds_read_b128 v[130:133], v181
	ds_read_b128 v[134:137], v181 offset:1024
	ds_read_b128 v[138:141], v181 offset:2048
	ds_read_b128 v[142:145], v181 offset:3072
	ds_read_b128 v[146:149], v182
	ds_read_b128 v[150:153], v182 offset:1024
	ds_read_b128 v[154:157], v182 offset:2048
	ds_read_b128 v[158:161], v182 offset:3072
	s_cmp_eq_u32 s78, 28
	s_cselect_b32 s23, s11, s75
	s_cselect_b32 s22, s73, s74
	s_cselect_b32 s25, s13, s77
	s_cselect_b32 s24, s67, s76
	ds_read_b128 v[166:169], v183
	ds_read_b128 v[170:173], v183 offset:1024
	ds_read_b128 v[186:189], v183 offset:2048
	ds_read_b128 v[190:193], v183 offset:3072
	ds_read_b128 v[194:197], v183 offset:4096
	ds_read_b128 v[198:201], v183 offset:5120
	ds_read_b128 v[202:205], v183 offset:6144
	ds_read_b128 v[206:209], v183 offset:7168
	s_add_u32 s80, s20, 0xfff80000
	s_addc_u32 s81, s21, -1
	s_mov_b32 s79, m0
	s_mov_b32 m0, s58
	s_nop 0
	global_load_lds_dwordx4 v1, s[80:81]
	s_mov_b32 m0, s79
	s_nop 0
	s_mov_b32 s79, m0
	s_mov_b32 m0, s64
	s_nop 0
	global_load_lds_dwordx4 v177, s[80:81]
	s_mov_b32 m0, s79
	s_nop 0
	s_mov_b32 s79, m0
	s_mov_b32 m0, s59
	s_nop 0
	global_load_lds_dwordx4 v1, s[20:21]
	s_mov_b32 m0, s79
	s_nop 0
	s_mov_b32 s79, m0
	s_mov_b32 m0, s65
	s_nop 0
	global_load_lds_dwordx4 v177, s[20:21]
	s_mov_b32 m0, s79
	s_waitcnt vmcnt(8)
	s_waitcnt lgkmcnt(0)
	s_barrier
	s_setprio 1
	s_waitcnt lgkmcnt(7)
	v_mfma_f32_16x16x32_bf16 v[126:129], v[130:133], v[166:169], v[126:129]
	v_mfma_f32_16x16x32_bf16 v[126:129], v[134:137], v[170:173], v[126:129]
	s_waitcnt lgkmcnt(5)
	v_mfma_f32_16x16x32_bf16 v[122:125], v[138:141], v[166:169], v[122:125]
	v_mfma_f32_16x16x32_bf16 v[122:125], v[142:145], v[170:173], v[122:125]
	s_waitcnt lgkmcnt(3)
	v_mfma_f32_16x16x32_bf16 v[118:121], v[130:133], v[186:189], v[118:121]
	v_mfma_f32_16x16x32_bf16 v[118:121], v[134:137], v[190:193], v[118:121]
	s_waitcnt lgkmcnt(1)
	v_mfma_f32_16x16x32_bf16 v[114:117], v[138:141], v[186:189], v[114:117]
	v_mfma_f32_16x16x32_bf16 v[114:117], v[142:145], v[190:193], v[114:117]
	v_mfma_f32_16x16x32_bf16 v[94:97], v[130:133], v[194:197], v[94:97]
	v_mfma_f32_16x16x32_bf16 v[94:97], v[134:137], v[198:201], v[94:97]
	v_mfma_f32_16x16x32_bf16 v[90:93], v[138:141], v[194:197], v[90:93]
	v_mfma_f32_16x16x32_bf16 v[90:93], v[142:145], v[198:201], v[90:93]
	v_mfma_f32_16x16x32_bf16 v[86:89], v[130:133], v[202:205], v[86:89]
	v_mfma_f32_16x16x32_bf16 v[86:89], v[134:137], v[206:209], v[86:89]
	s_waitcnt lgkmcnt(0)
	v_mfma_f32_16x16x32_bf16 v[78:81], v[138:141], v[202:205], v[78:81]
	v_mfma_f32_16x16x32_bf16 v[78:81], v[142:145], v[206:209], v[78:81]
	s_setprio 0
	s_setprio 1
	v_mfma_f32_16x16x32_bf16 v[110:113], v[146:149], v[166:169], v[110:113]
	v_mfma_f32_16x16x32_bf16 v[110:113], v[150:153], v[170:173], v[110:113]
	v_mfma_f32_16x16x32_bf16 v[106:109], v[154:157], v[166:169], v[106:109]
	v_mfma_f32_16x16x32_bf16 v[106:109], v[158:161], v[170:173], v[106:109]
	v_mfma_f32_16x16x32_bf16 v[102:105], v[146:149], v[186:189], v[102:105]
	v_mfma_f32_16x16x32_bf16 v[102:105], v[150:153], v[190:193], v[102:105]
	v_mfma_f32_16x16x32_bf16 v[98:101], v[154:157], v[186:189], v[98:101]
	v_mfma_f32_16x16x32_bf16 v[98:101], v[158:161], v[190:193], v[98:101]
	v_mfma_f32_16x16x32_bf16 v[82:85], v[146:149], v[194:197], v[82:85]
	v_mfma_f32_16x16x32_bf16 v[82:85], v[150:153], v[198:201], v[82:85]
	v_mfma_f32_16x16x32_bf16 v[74:77], v[154:157], v[194:197], v[74:77]
	v_mfma_f32_16x16x32_bf16 v[74:77], v[158:161], v[198:201], v[74:77]
	v_mfma_f32_16x16x32_bf16 v[70:73], v[146:149], v[202:205], v[70:73]
	v_mfma_f32_16x16x32_bf16 v[70:73], v[150:153], v[206:209], v[70:73]
	s_setprio 2
	s_barrier
	v_mfma_f32_16x16x32_bf16 v[66:69], v[154:157], v[202:205], v[66:69]
	v_mfma_f32_16x16x32_bf16 v[66:69], v[158:161], v[206:209], v[66:69]
	s_setprio 0
	ds_read_b128 v[166:169], v183 offset:16384
	ds_read_b128 v[170:173], v183 offset:17408
	ds_read_b128 v[186:189], v183 offset:18432
	ds_read_b128 v[190:193], v183 offset:19456
	ds_read_b128 v[194:197], v183 offset:20480
	ds_read_b128 v[198:201], v183 offset:21504
	ds_read_b128 v[202:205], v183 offset:22528
	ds_read_b128 v[206:209], v183 offset:23552
	s_mov_b32 s79, m0
	s_mov_b32 m0, s35
	s_nop 0
	global_load_lds_dwordx4 v176, s[22:23]
	s_mov_b32 m0, s79
	s_add_u32 s80, s22, 0x80000
	s_mov_b32 s79, m0
	s_mov_b32 m0, s36
	s_nop 0
	global_load_lds_dwordx4 v178, s[22:23]
	s_mov_b32 m0, s79
	s_addc_u32 s81, s23, 0
	s_mov_b32 s79, m0
	s_mov_b32 m0, s37
	s_nop 0
	global_load_lds_dwordx4 v176, s[80:81]
	s_mov_b32 m0, s79
	s_nop 0
	s_mov_b32 s79, m0
	s_mov_b32 m0, s40
	s_nop 0
	global_load_lds_dwordx4 v178, s[80:81]
	s_mov_b32 m0, s79
	s_waitcnt vmcnt(4)
	s_waitcnt lgkmcnt(0)
	s_barrier
	s_setprio 1
	s_waitcnt lgkmcnt(7)
	v_mfma_f32_16x16x32_bf16 v[62:65], v[130:133], v[166:169], v[62:65]
	v_mfma_f32_16x16x32_bf16 v[62:65], v[134:137], v[170:173], v[62:65]
	s_waitcnt lgkmcnt(5)
	v_mfma_f32_16x16x32_bf16 v[58:61], v[138:141], v[166:169], v[58:61]
	v_mfma_f32_16x16x32_bf16 v[58:61], v[142:145], v[170:173], v[58:61]
	s_waitcnt lgkmcnt(3)
	v_mfma_f32_16x16x32_bf16 v[46:49], v[130:133], v[186:189], v[46:49]
	v_mfma_f32_16x16x32_bf16 v[46:49], v[134:137], v[190:193], v[46:49]
	s_waitcnt lgkmcnt(1)
	v_mfma_f32_16x16x32_bf16 v[42:45], v[138:141], v[186:189], v[42:45]
	v_mfma_f32_16x16x32_bf16 v[42:45], v[142:145], v[190:193], v[42:45]
	v_mfma_f32_16x16x32_bf16 v[30:33], v[130:133], v[194:197], v[30:33]
	v_mfma_f32_16x16x32_bf16 v[30:33], v[134:137], v[198:201], v[30:33]
	v_mfma_f32_16x16x32_bf16 v[26:29], v[138:141], v[194:197], v[26:29]
	v_mfma_f32_16x16x32_bf16 v[26:29], v[142:145], v[198:201], v[26:29]
	v_mfma_f32_16x16x32_bf16 v[14:17], v[130:133], v[202:205], v[14:17]
	v_mfma_f32_16x16x32_bf16 v[14:17], v[134:137], v[206:209], v[14:17]
	s_waitcnt lgkmcnt(0)
	v_mfma_f32_16x16x32_bf16 v[10:13], v[138:141], v[202:205], v[10:13]
	v_mfma_f32_16x16x32_bf16 v[10:13], v[142:145], v[206:209], v[10:13]
	s_setprio 0
	s_setprio 1
	v_mfma_f32_16x16x32_bf16 v[54:57], v[146:149], v[166:169], v[54:57]
	v_mfma_f32_16x16x32_bf16 v[54:57], v[150:153], v[170:173], v[54:57]
	v_mfma_f32_16x16x32_bf16 v[50:53], v[154:157], v[166:169], v[50:53]
	v_mfma_f32_16x16x32_bf16 v[50:53], v[158:161], v[170:173], v[50:53]
	v_mfma_f32_16x16x32_bf16 v[38:41], v[146:149], v[186:189], v[38:41]
	v_mfma_f32_16x16x32_bf16 v[38:41], v[150:153], v[190:193], v[38:41]
	v_mfma_f32_16x16x32_bf16 v[34:37], v[154:157], v[186:189], v[34:37]
	v_mfma_f32_16x16x32_bf16 v[34:37], v[158:161], v[190:193], v[34:37]
	v_mfma_f32_16x16x32_bf16 v[22:25], v[146:149], v[194:197], v[22:25]
	v_mfma_f32_16x16x32_bf16 v[22:25], v[150:153], v[198:201], v[22:25]
	v_mfma_f32_16x16x32_bf16 v[18:21], v[154:157], v[194:197], v[18:21]
	v_mfma_f32_16x16x32_bf16 v[18:21], v[158:161], v[198:201], v[18:21]
	v_mfma_f32_16x16x32_bf16 v[6:9], v[146:149], v[202:205], v[6:9]
	v_mfma_f32_16x16x32_bf16 v[6:9], v[150:153], v[206:209], v[6:9]
	s_setprio 2
	s_barrier
	v_mfma_f32_16x16x32_bf16 v[2:5], v[154:157], v[202:205], v[2:5]
	v_mfma_f32_16x16x32_bf16 v[2:5], v[158:161], v[206:209], v[2:5]
	s_setprio 0
	ds_read_b128 v[130:133], v184
	ds_read_b128 v[134:137], v184 offset:1024
	ds_read_b128 v[138:141], v184 offset:2048
	ds_read_b128 v[142:145], v184 offset:3072
	ds_read_b128 v[146:149], v185
	ds_read_b128 v[150:153], v185 offset:1024
	ds_read_b128 v[154:157], v185 offset:2048
	ds_read_b128 v[158:161], v185 offset:3072
	ds_read_b128 v[166:169], v183 offset:32768
	ds_read_b128 v[170:173], v183 offset:33792
	ds_read_b128 v[186:189], v183 offset:34816
	ds_read_b128 v[190:193], v183 offset:35840
	ds_read_b128 v[194:197], v183 offset:36864
	ds_read_b128 v[198:201], v183 offset:37888
	ds_read_b128 v[202:205], v183 offset:38912
	ds_read_b128 v[206:209], v183 offset:39936
	s_mov_b32 s79, m0
	s_mov_b32 m0, s34
	s_nop 0
	global_load_lds_dwordx4 v1, s[24:25]
	s_mov_b32 m0, s79
	s_nop 0
	s_mov_b32 s79, m0
	s_mov_b32 m0, s41
	s_nop 0
	global_load_lds_dwordx4 v177, s[24:25]
	s_mov_b32 m0, s79
	s_add_u32 s24, s24, 0x80000
	s_addc_u32 s25, s25, 0
	s_mov_b32 s79, m0
	s_mov_b32 m0, s42
	s_nop 0
	global_load_lds_dwordx4 v1, s[24:25]
	s_mov_b32 m0, s79
	s_nop 0
	s_mov_b32 s79, m0
	s_mov_b32 m0, s43
	s_nop 0
	global_load_lds_dwordx4 v177, s[24:25]
	s_mov_b32 m0, s79
	s_waitcnt vmcnt(8)
	s_waitcnt lgkmcnt(0)
	s_barrier
	s_setprio 1
	s_waitcnt lgkmcnt(7)
	v_mfma_f32_16x16x32_bf16 v[126:129], v[130:133], v[166:169], v[126:129]
	v_mfma_f32_16x16x32_bf16 v[126:129], v[134:137], v[170:173], v[126:129]
	s_waitcnt lgkmcnt(5)
	v_mfma_f32_16x16x32_bf16 v[122:125], v[138:141], v[166:169], v[122:125]
	v_mfma_f32_16x16x32_bf16 v[122:125], v[142:145], v[170:173], v[122:125]
	s_waitcnt lgkmcnt(3)
	v_mfma_f32_16x16x32_bf16 v[118:121], v[130:133], v[186:189], v[118:121]
	v_mfma_f32_16x16x32_bf16 v[118:121], v[134:137], v[190:193], v[118:121]
	s_waitcnt lgkmcnt(1)
	v_mfma_f32_16x16x32_bf16 v[114:117], v[138:141], v[186:189], v[114:117]
	v_mfma_f32_16x16x32_bf16 v[114:117], v[142:145], v[190:193], v[114:117]
	v_mfma_f32_16x16x32_bf16 v[94:97], v[130:133], v[194:197], v[94:97]
	v_mfma_f32_16x16x32_bf16 v[94:97], v[134:137], v[198:201], v[94:97]
	v_mfma_f32_16x16x32_bf16 v[90:93], v[138:141], v[194:197], v[90:93]
	v_mfma_f32_16x16x32_bf16 v[90:93], v[142:145], v[198:201], v[90:93]
	v_mfma_f32_16x16x32_bf16 v[86:89], v[130:133], v[202:205], v[86:89]
	v_mfma_f32_16x16x32_bf16 v[86:89], v[134:137], v[206:209], v[86:89]
	s_waitcnt lgkmcnt(0)
	v_mfma_f32_16x16x32_bf16 v[78:81], v[138:141], v[202:205], v[78:81]
	v_mfma_f32_16x16x32_bf16 v[78:81], v[142:145], v[206:209], v[78:81]
	s_setprio 0
	s_setprio 1
	v_mfma_f32_16x16x32_bf16 v[110:113], v[146:149], v[166:169], v[110:113]
	v_mfma_f32_16x16x32_bf16 v[110:113], v[150:153], v[170:173], v[110:113]
	v_mfma_f32_16x16x32_bf16 v[106:109], v[154:157], v[166:169], v[106:109]
	v_mfma_f32_16x16x32_bf16 v[106:109], v[158:161], v[170:173], v[106:109]
	v_mfma_f32_16x16x32_bf16 v[102:105], v[146:149], v[186:189], v[102:105]
	v_mfma_f32_16x16x32_bf16 v[102:105], v[150:153], v[190:193], v[102:105]
	v_mfma_f32_16x16x32_bf16 v[98:101], v[154:157], v[186:189], v[98:101]
	v_mfma_f32_16x16x32_bf16 v[98:101], v[158:161], v[190:193], v[98:101]
	v_mfma_f32_16x16x32_bf16 v[82:85], v[146:149], v[194:197], v[82:85]
	v_mfma_f32_16x16x32_bf16 v[82:85], v[150:153], v[198:201], v[82:85]
	v_mfma_f32_16x16x32_bf16 v[74:77], v[154:157], v[194:197], v[74:77]
	v_mfma_f32_16x16x32_bf16 v[74:77], v[158:161], v[198:201], v[74:77]
	v_mfma_f32_16x16x32_bf16 v[70:73], v[146:149], v[202:205], v[70:73]
	v_mfma_f32_16x16x32_bf16 v[70:73], v[150:153], v[206:209], v[70:73]
	s_setprio 2
	s_barrier
	v_mfma_f32_16x16x32_bf16 v[66:69], v[154:157], v[202:205], v[66:69]
	v_mfma_f32_16x16x32_bf16 v[66:69], v[158:161], v[206:209], v[66:69]
	s_setprio 0
	ds_read_b128 v[166:169], v183 offset:49152
	ds_read_b128 v[170:173], v183 offset:50176
	ds_read_b128 v[186:189], v183 offset:51200
	ds_read_b128 v[190:193], v183 offset:52224
	ds_read_b128 v[194:197], v183 offset:53248
	ds_read_b128 v[198:201], v183 offset:54272
	ds_read_b128 v[202:205], v183 offset:55296
	ds_read_b128 v[206:209], v183 offset:56320
	s_add_u32 s24, s22, 0x80
	s_addc_u32 s25, s23, 0
	s_mov_b32 s79, m0
	s_mov_b32 m0, s46
	s_nop 0
	global_load_lds_dwordx4 v176, s[24:25]
	s_mov_b32 m0, s79
	s_add_u32 s22, s22, 0x80080
	s_mov_b32 s79, m0
	s_mov_b32 m0, s47
	s_nop 0
	global_load_lds_dwordx4 v178, s[24:25]
	s_mov_b32 m0, s79
	s_addc_u32 s23, s23, 0
	s_mov_b32 s24, m0
	s_mov_b32 m0, s48
	s_nop 0
	global_load_lds_dwordx4 v176, s[22:23]
	s_mov_b32 m0, s24
	s_nop 0
	s_mov_b32 s24, m0
	s_mov_b32 m0, s49
	s_nop 0
	global_load_lds_dwordx4 v178, s[22:23]
	s_mov_b32 m0, s24
	s_waitcnt vmcnt(4)
	s_waitcnt lgkmcnt(0)
	s_barrier
	s_setprio 1
	s_waitcnt lgkmcnt(7)
	v_mfma_f32_16x16x32_bf16 v[62:65], v[130:133], v[166:169], v[62:65]
	v_mfma_f32_16x16x32_bf16 v[62:65], v[134:137], v[170:173], v[62:65]
	s_waitcnt lgkmcnt(5)
	v_mfma_f32_16x16x32_bf16 v[58:61], v[138:141], v[166:169], v[58:61]
	v_mfma_f32_16x16x32_bf16 v[58:61], v[142:145], v[170:173], v[58:61]
	s_waitcnt lgkmcnt(3)
	v_mfma_f32_16x16x32_bf16 v[46:49], v[130:133], v[186:189], v[46:49]
	v_mfma_f32_16x16x32_bf16 v[46:49], v[134:137], v[190:193], v[46:49]
	s_waitcnt lgkmcnt(1)
	v_mfma_f32_16x16x32_bf16 v[42:45], v[138:141], v[186:189], v[42:45]
	v_mfma_f32_16x16x32_bf16 v[42:45], v[142:145], v[190:193], v[42:45]
	v_mfma_f32_16x16x32_bf16 v[30:33], v[130:133], v[194:197], v[30:33]
	v_mfma_f32_16x16x32_bf16 v[30:33], v[134:137], v[198:201], v[30:33]
	v_mfma_f32_16x16x32_bf16 v[26:29], v[138:141], v[194:197], v[26:29]
	v_mfma_f32_16x16x32_bf16 v[26:29], v[142:145], v[198:201], v[26:29]
	v_mfma_f32_16x16x32_bf16 v[14:17], v[130:133], v[202:205], v[14:17]
	v_mfma_f32_16x16x32_bf16 v[14:17], v[134:137], v[206:209], v[14:17]
	s_waitcnt lgkmcnt(0)
	v_mfma_f32_16x16x32_bf16 v[10:13], v[138:141], v[202:205], v[10:13]
	v_mfma_f32_16x16x32_bf16 v[10:13], v[142:145], v[206:209], v[10:13]
	s_setprio 0
	s_setprio 1
	v_mfma_f32_16x16x32_bf16 v[54:57], v[146:149], v[166:169], v[54:57]
	v_mfma_f32_16x16x32_bf16 v[54:57], v[150:153], v[170:173], v[54:57]
	v_mfma_f32_16x16x32_bf16 v[50:53], v[154:157], v[166:169], v[50:53]
	v_mfma_f32_16x16x32_bf16 v[50:53], v[158:161], v[170:173], v[50:53]
	v_mfma_f32_16x16x32_bf16 v[38:41], v[146:149], v[186:189], v[38:41]
	v_mfma_f32_16x16x32_bf16 v[38:41], v[150:153], v[190:193], v[38:41]
	v_mfma_f32_16x16x32_bf16 v[34:37], v[154:157], v[186:189], v[34:37]
	v_mfma_f32_16x16x32_bf16 v[34:37], v[158:161], v[190:193], v[34:37]
	v_mfma_f32_16x16x32_bf16 v[22:25], v[146:149], v[194:197], v[22:25]
	v_mfma_f32_16x16x32_bf16 v[22:25], v[150:153], v[198:201], v[22:25]
	v_mfma_f32_16x16x32_bf16 v[18:21], v[154:157], v[194:197], v[18:21]
	v_mfma_f32_16x16x32_bf16 v[18:21], v[158:161], v[198:201], v[18:21]
	v_mfma_f32_16x16x32_bf16 v[6:9], v[146:149], v[202:205], v[6:9]
	v_mfma_f32_16x16x32_bf16 v[6:9], v[150:153], v[206:209], v[6:9]
	s_setprio 2
	s_barrier
	v_mfma_f32_16x16x32_bf16 v[2:5], v[154:157], v[202:205], v[2:5]
	v_mfma_f32_16x16x32_bf16 v[2:5], v[158:161], v[206:209], v[2:5]
	s_setprio 0
	s_add_i32 s78, s78, 2
	s_add_u32 s74, s74, 0x100
	s_addc_u32 s75, s75, 0
	s_add_u32 s20, s20, 0x100
	s_addc_u32 s21, s21, 0
	s_add_u32 s76, s76, 0x100
	s_addc_u32 s77, s77, 0
	s_cmp_gt_u32 s78, 29
	s_cbranch_scc0 .LBB0_1053
	s_and_b64 vcc, exec, s[8:9]
	s_cbranch_vccz .LBB0_1056
	s_barrier

.LBB0_1223:
	s_ashr_i32 s11, s10, 31
	s_lshl_b64 s[12:13], s[10:11], 20
	s_add_u32 s12, s26, s12
	s_addc_u32 s13, s27, s13
	s_and_b64 s[14:15], s[2:3], exec
	s_cselect_b32 s11, s13, s21
	s_cselect_b32 s66, s12, s20
	s_ashr_i32 s9, s8, 31
	s_lshl_b64 s[14:15], s[8:9], 20
	s_add_u32 s14, s28, s14
	s_addc_u32 s15, s29, s15
	s_and_b64 s[22:23], s[2:3], exec
	s_cselect_b32 s9, s15, s19
	s_cselect_b32 s67, s14, s18
	s_add_u32 s73, s18, 0x100
	s_addc_u32 s74, s19, 0
	s_add_u32 s18, s20, 0x80080
	s_addc_u32 s19, s21, 0
	s_add_u32 s75, s20, 0x100
	s_addc_u32 s76, s21, 0
	s_mov_b32 s77, -2
	ds_read_b128 v[148:151], v143
	ds_read_b128 v[152:155], v143 offset:1024
	ds_read_b128 v[156:159], v143 offset:2048
	ds_read_b128 v[160:163], v143 offset:3072
	ds_read_b128 v[164:167], v144
	ds_read_b128 v[168:171], v144 offset:1024
	ds_read_b128 v[172:175], v144 offset:2048
	ds_read_b128 v[176:179], v144 offset:3072
	s_cmp_eq_u32 s77, 28
	s_cselect_b32 s21, s9, s74
	s_cselect_b32 s20, s67, s73
	s_cselect_b32 s23, s11, s76
	s_cselect_b32 s22, s66, s75
	ds_read_b128 v[180:183], v145
	ds_read_b128 v[184:187], v145 offset:1024
	ds_read_b128 v[188:191], v145 offset:2048
	ds_read_b128 v[192:195], v145 offset:3072
	ds_read_b128 v[196:199], v145 offset:4096
	ds_read_b128 v[200:203], v145 offset:5120
	ds_read_b128 v[204:207], v145 offset:6144
	ds_read_b128 v[208:211], v145 offset:7168
	s_add_u32 s78, s18, 0xfff80000
	s_addc_u32 s79, s19, -1
	s_mov_b32 s80, m0
	s_mov_b32 m0, s56
	s_nop 0
	global_load_lds_dwordx4 v138, s[78:79]
	s_mov_b32 m0, s80
	s_nop 0
	s_mov_b32 s80, m0
	s_mov_b32 m0, s59
	s_nop 0
	global_load_lds_dwordx4 v140, s[78:79]
	s_mov_b32 m0, s80
	s_mov_b32 s78, m0
	s_mov_b32 m0, s57
	s_nop 0
	global_load_lds_dwordx4 v138, s[18:19]
	s_mov_b32 m0, s78
	s_nop 0
	s_mov_b32 s78, m0
	s_mov_b32 m0, s64
	s_nop 0
	global_load_lds_dwordx4 v140, s[18:19]
	s_mov_b32 m0, s78
	s_waitcnt vmcnt(8)
	s_waitcnt lgkmcnt(0)
	s_barrier
	s_setprio 1
	s_waitcnt lgkmcnt(7)
	v_mfma_f32_16x16x32_bf16 v[126:129], v[148:151], v[180:183], 0
	v_mfma_f32_16x16x32_bf16 v[126:129], v[152:155], v[184:187], v[126:129]
	s_waitcnt lgkmcnt(5)
	v_mfma_f32_16x16x32_bf16 v[122:125], v[156:159], v[180:183], 0
	v_mfma_f32_16x16x32_bf16 v[122:125], v[160:163], v[184:187], v[122:125]
	s_waitcnt lgkmcnt(3)
	v_mfma_f32_16x16x32_bf16 v[110:113], v[148:151], v[188:191], 0
	v_mfma_f32_16x16x32_bf16 v[110:113], v[152:155], v[192:195], v[110:113]
	s_waitcnt lgkmcnt(1)
	v_mfma_f32_16x16x32_bf16 v[106:109], v[156:159], v[188:191], 0
	v_mfma_f32_16x16x32_bf16 v[106:109], v[160:163], v[192:195], v[106:109]
	v_mfma_f32_16x16x32_bf16 v[94:97], v[148:151], v[196:199], 0
	v_mfma_f32_16x16x32_bf16 v[94:97], v[152:155], v[200:203], v[94:97]
	v_mfma_f32_16x16x32_bf16 v[90:93], v[156:159], v[196:199], 0
	v_mfma_f32_16x16x32_bf16 v[90:93], v[160:163], v[200:203], v[90:93]
	v_mfma_f32_16x16x32_bf16 v[78:81], v[148:151], v[204:207], 0
	v_mfma_f32_16x16x32_bf16 v[78:81], v[152:155], v[208:211], v[78:81]
	s_waitcnt lgkmcnt(0)
	v_mfma_f32_16x16x32_bf16 v[74:77], v[156:159], v[204:207], 0
	v_mfma_f32_16x16x32_bf16 v[74:77], v[160:163], v[208:211], v[74:77]
	s_setprio 0
	s_setprio 1
	v_mfma_f32_16x16x32_bf16 v[118:121], v[164:167], v[180:183], 0
	v_mfma_f32_16x16x32_bf16 v[118:121], v[168:171], v[184:187], v[118:121]
	v_mfma_f32_16x16x32_bf16 v[114:117], v[172:175], v[180:183], 0
	v_mfma_f32_16x16x32_bf16 v[114:117], v[176:179], v[184:187], v[114:117]
	v_mfma_f32_16x16x32_bf16 v[102:105], v[164:167], v[188:191], 0
	v_mfma_f32_16x16x32_bf16 v[102:105], v[168:171], v[192:195], v[102:105]
	v_mfma_f32_16x16x32_bf16 v[98:101], v[172:175], v[188:191], 0
	v_mfma_f32_16x16x32_bf16 v[98:101], v[176:179], v[192:195], v[98:101]
	v_mfma_f32_16x16x32_bf16 v[86:89], v[164:167], v[196:199], 0
	v_mfma_f32_16x16x32_bf16 v[86:89], v[168:171], v[200:203], v[86:89]
	v_mfma_f32_16x16x32_bf16 v[82:85], v[172:175], v[196:199], 0
	v_mfma_f32_16x16x32_bf16 v[82:85], v[176:179], v[200:203], v[82:85]
	v_mfma_f32_16x16x32_bf16 v[70:73], v[164:167], v[204:207], 0
	v_mfma_f32_16x16x32_bf16 v[70:73], v[168:171], v[208:211], v[70:73]
	s_setprio 2
	s_barrier
	v_mfma_f32_16x16x32_bf16 v[66:69], v[172:175], v[204:207], 0
	v_mfma_f32_16x16x32_bf16 v[66:69], v[176:179], v[208:211], v[66:69]
	s_setprio 0
	ds_read_b128 v[180:183], v145 offset:16384
	ds_read_b128 v[184:187], v145 offset:17408
	ds_read_b128 v[188:191], v145 offset:18432
	ds_read_b128 v[192:195], v145 offset:19456
	ds_read_b128 v[196:199], v145 offset:20480
	ds_read_b128 v[200:203], v145 offset:21504
	ds_read_b128 v[204:207], v145 offset:22528
	ds_read_b128 v[208:211], v145 offset:23552
	s_mov_b32 s78, m0
	s_mov_b32 m0, s35
	s_nop 0
	global_load_lds_dwordx4 v139, s[20:21]
	s_mov_b32 m0, s78
	s_nop 0
	s_mov_b32 s78, m0
	s_mov_b32 m0, s36
	s_nop 0
	global_load_lds_dwordx4 v141, s[20:21]
	s_mov_b32 m0, s78
	s_add_u32 s78, s20, 0x80000
	s_addc_u32 s79, s21, 0
	s_mov_b32 s80, m0
	s_mov_b32 m0, s37
	s_nop 0
	global_load_lds_dwordx4 v139, s[78:79]
	s_mov_b32 m0, s80
	s_nop 0
	s_mov_b32 s80, m0
	s_mov_b32 m0, s40
	s_nop 0
	global_load_lds_dwordx4 v141, s[78:79]
	s_mov_b32 m0, s80
	s_waitcnt vmcnt(4)
	s_waitcnt lgkmcnt(0)
	s_barrier
	s_setprio 1
	s_waitcnt lgkmcnt(7)
	v_mfma_f32_16x16x32_bf16 v[62:65], v[148:151], v[180:183], 0
	v_mfma_f32_16x16x32_bf16 v[62:65], v[152:155], v[184:187], v[62:65]
	s_waitcnt lgkmcnt(5)
	v_mfma_f32_16x16x32_bf16 v[58:61], v[156:159], v[180:183], 0
	v_mfma_f32_16x16x32_bf16 v[58:61], v[160:163], v[184:187], v[58:61]
	s_waitcnt lgkmcnt(3)
	v_mfma_f32_16x16x32_bf16 v[46:49], v[148:151], v[188:191], 0
	v_mfma_f32_16x16x32_bf16 v[46:49], v[152:155], v[192:195], v[46:49]
	s_waitcnt lgkmcnt(1)
	v_mfma_f32_16x16x32_bf16 v[42:45], v[156:159], v[188:191], 0
	v_mfma_f32_16x16x32_bf16 v[42:45], v[160:163], v[192:195], v[42:45]
	v_mfma_f32_16x16x32_bf16 v[30:33], v[148:151], v[196:199], 0
	v_mfma_f32_16x16x32_bf16 v[30:33], v[152:155], v[200:203], v[30:33]
	v_mfma_f32_16x16x32_bf16 v[26:29], v[156:159], v[196:199], 0
	v_mfma_f32_16x16x32_bf16 v[26:29], v[160:163], v[200:203], v[26:29]
	v_mfma_f32_16x16x32_bf16 v[14:17], v[148:151], v[204:207], 0
	v_mfma_f32_16x16x32_bf16 v[14:17], v[152:155], v[208:211], v[14:17]
	s_waitcnt lgkmcnt(0)
	v_mfma_f32_16x16x32_bf16 v[10:13], v[156:159], v[204:207], 0
	v_mfma_f32_16x16x32_bf16 v[10:13], v[160:163], v[208:211], v[10:13]
	s_setprio 0
	s_setprio 1
	v_mfma_f32_16x16x32_bf16 v[54:57], v[164:167], v[180:183], 0
	v_mfma_f32_16x16x32_bf16 v[54:57], v[168:171], v[184:187], v[54:57]
	v_mfma_f32_16x16x32_bf16 v[50:53], v[172:175], v[180:183], 0
	v_mfma_f32_16x16x32_bf16 v[50:53], v[176:179], v[184:187], v[50:53]
	v_mfma_f32_16x16x32_bf16 v[38:41], v[164:167], v[188:191], 0
	v_mfma_f32_16x16x32_bf16 v[38:41], v[168:171], v[192:195], v[38:41]
	v_mfma_f32_16x16x32_bf16 v[34:37], v[172:175], v[188:191], 0
	v_mfma_f32_16x16x32_bf16 v[34:37], v[176:179], v[192:195], v[34:37]
	v_mfma_f32_16x16x32_bf16 v[22:25], v[164:167], v[196:199], 0
	v_mfma_f32_16x16x32_bf16 v[22:25], v[168:171], v[200:203], v[22:25]
	v_mfma_f32_16x16x32_bf16 v[18:21], v[172:175], v[196:199], 0
	v_mfma_f32_16x16x32_bf16 v[18:21], v[176:179], v[200:203], v[18:21]
	v_mfma_f32_16x16x32_bf16 v[6:9], v[164:167], v[204:207], 0
	v_mfma_f32_16x16x32_bf16 v[6:9], v[168:171], v[208:211], v[6:9]
	s_setprio 2
	s_barrier
	v_mfma_f32_16x16x32_bf16 v[2:5], v[172:175], v[204:207], 0
	v_mfma_f32_16x16x32_bf16 v[2:5], v[176:179], v[208:211], v[2:5]
	s_setprio 0
	ds_read_b128 v[148:151], v146
	ds_read_b128 v[152:155], v146 offset:1024
	ds_read_b128 v[156:159], v146 offset:2048
	ds_read_b128 v[160:163], v146 offset:3072
	ds_read_b128 v[164:167], v147
	ds_read_b128 v[168:171], v147 offset:1024
	ds_read_b128 v[172:175], v147 offset:2048
	ds_read_b128 v[176:179], v147 offset:3072
	ds_read_b128 v[180:183], v145 offset:32768
	ds_read_b128 v[184:187], v145 offset:33792
	ds_read_b128 v[188:191], v145 offset:34816
	ds_read_b128 v[192:195], v145 offset:35840
	ds_read_b128 v[196:199], v145 offset:36864
	ds_read_b128 v[200:203], v145 offset:37888
	ds_read_b128 v[204:207], v145 offset:38912
	ds_read_b128 v[208:211], v145 offset:39936
	s_mov_b32 s78, m0
	s_mov_b32 m0, s31
	s_nop 0
	global_load_lds_dwordx4 v138, s[22:23]
	s_mov_b32 m0, s78
	s_nop 0
	s_mov_b32 s78, m0
	s_mov_b32 m0, s41
	s_nop 0
	global_load_lds_dwordx4 v140, s[22:23]
	s_mov_b32 m0, s78
	s_add_u32 s22, s22, 0x80000
	s_addc_u32 s23, s23, 0
	s_mov_b32 s78, m0
	s_mov_b32 m0, s42
	s_nop 0
	global_load_lds_dwordx4 v138, s[22:23]
	s_mov_b32 m0, s78
	s_nop 0
	s_mov_b32 s78, m0
	s_mov_b32 m0, s43
	s_nop 0
	global_load_lds_dwordx4 v140, s[22:23]
	s_mov_b32 m0, s78
	s_waitcnt vmcnt(8)
	s_waitcnt lgkmcnt(0)
	s_barrier
	s_setprio 1
	s_waitcnt lgkmcnt(7)
	v_mfma_f32_16x16x32_bf16 v[126:129], v[148:151], v[180:183], v[126:129]
	v_mfma_f32_16x16x32_bf16 v[126:129], v[152:155], v[184:187], v[126:129]
	s_waitcnt lgkmcnt(5)
	v_mfma_f32_16x16x32_bf16 v[122:125], v[156:159], v[180:183], v[122:125]
	v_mfma_f32_16x16x32_bf16 v[122:125], v[160:163], v[184:187], v[122:125]
	s_waitcnt lgkmcnt(3)
	v_mfma_f32_16x16x32_bf16 v[110:113], v[148:151], v[188:191], v[110:113]
	v_mfma_f32_16x16x32_bf16 v[110:113], v[152:155], v[192:195], v[110:113]
	s_waitcnt lgkmcnt(1)
	v_mfma_f32_16x16x32_bf16 v[106:109], v[156:159], v[188:191], v[106:109]
	v_mfma_f32_16x16x32_bf16 v[106:109], v[160:163], v[192:195], v[106:109]
	v_mfma_f32_16x16x32_bf16 v[94:97], v[148:151], v[196:199], v[94:97]
	v_mfma_f32_16x16x32_bf16 v[94:97], v[152:155], v[200:203], v[94:97]
	v_mfma_f32_16x16x32_bf16 v[90:93], v[156:159], v[196:199], v[90:93]
	v_mfma_f32_16x16x32_bf16 v[90:93], v[160:163], v[200:203], v[90:93]
	v_mfma_f32_16x16x32_bf16 v[78:81], v[148:151], v[204:207], v[78:81]
	v_mfma_f32_16x16x32_bf16 v[78:81], v[152:155], v[208:211], v[78:81]
	s_waitcnt lgkmcnt(0)
	v_mfma_f32_16x16x32_bf16 v[74:77], v[156:159], v[204:207], v[74:77]
	v_mfma_f32_16x16x32_bf16 v[74:77], v[160:163], v[208:211], v[74:77]
	s_setprio 0
	s_setprio 1
	v_mfma_f32_16x16x32_bf16 v[118:121], v[164:167], v[180:183], v[118:121]
	v_mfma_f32_16x16x32_bf16 v[118:121], v[168:171], v[184:187], v[118:121]
	v_mfma_f32_16x16x32_bf16 v[114:117], v[172:175], v[180:183], v[114:117]
	v_mfma_f32_16x16x32_bf16 v[114:117], v[176:179], v[184:187], v[114:117]
	v_mfma_f32_16x16x32_bf16 v[102:105], v[164:167], v[188:191], v[102:105]
	v_mfma_f32_16x16x32_bf16 v[102:105], v[168:171], v[192:195], v[102:105]
	v_mfma_f32_16x16x32_bf16 v[98:101], v[172:175], v[188:191], v[98:101]
	v_mfma_f32_16x16x32_bf16 v[98:101], v[176:179], v[192:195], v[98:101]
	v_mfma_f32_16x16x32_bf16 v[86:89], v[164:167], v[196:199], v[86:89]
	v_mfma_f32_16x16x32_bf16 v[86:89], v[168:171], v[200:203], v[86:89]
	v_mfma_f32_16x16x32_bf16 v[82:85], v[172:175], v[196:199], v[82:85]
	v_mfma_f32_16x16x32_bf16 v[82:85], v[176:179], v[200:203], v[82:85]
	v_mfma_f32_16x16x32_bf16 v[70:73], v[164:167], v[204:207], v[70:73]
	v_mfma_f32_16x16x32_bf16 v[70:73], v[168:171], v[208:211], v[70:73]
	s_setprio 2
	s_barrier
	v_mfma_f32_16x16x32_bf16 v[66:69], v[172:175], v[204:207], v[66:69]
	v_mfma_f32_16x16x32_bf16 v[66:69], v[176:179], v[208:211], v[66:69]
	s_setprio 0
	ds_read_b128 v[180:183], v145 offset:49152
	ds_read_b128 v[184:187], v145 offset:50176
	ds_read_b128 v[188:191], v145 offset:51200
	ds_read_b128 v[192:195], v145 offset:52224
	ds_read_b128 v[196:199], v145 offset:53248
	ds_read_b128 v[200:203], v145 offset:54272
	ds_read_b128 v[204:207], v145 offset:55296
	ds_read_b128 v[208:211], v145 offset:56320
	s_add_u32 s22, s20, 0x80
	s_addc_u32 s23, s21, 0
	s_mov_b32 s78, m0
	s_mov_b32 m0, s46
	s_nop 0
	global_load_lds_dwordx4 v139, s[22:23]
	s_mov_b32 m0, s78
	s_add_u32 s20, s20, 0x80080
	s_mov_b32 s78, m0
	s_mov_b32 m0, s47
	s_nop 0
	global_load_lds_dwordx4 v141, s[22:23]
	s_mov_b32 m0, s78
	s_addc_u32 s21, s21, 0
	s_mov_b32 s22, m0
	s_mov_b32 m0, s48
	s_nop 0
	global_load_lds_dwordx4 v139, s[20:21]
	s_mov_b32 m0, s22
	s_nop 0
	s_mov_b32 s22, m0
	s_mov_b32 m0, s49
	s_nop 0
	global_load_lds_dwordx4 v141, s[20:21]
	s_mov_b32 m0, s22
	s_waitcnt vmcnt(4)
	s_waitcnt lgkmcnt(0)
	s_barrier
	s_setprio 1
	s_waitcnt lgkmcnt(7)
	v_mfma_f32_16x16x32_bf16 v[62:65], v[148:151], v[180:183], v[62:65]
	v_mfma_f32_16x16x32_bf16 v[62:65], v[152:155], v[184:187], v[62:65]
	s_waitcnt lgkmcnt(5)
	v_mfma_f32_16x16x32_bf16 v[58:61], v[156:159], v[180:183], v[58:61]
	v_mfma_f32_16x16x32_bf16 v[58:61], v[160:163], v[184:187], v[58:61]
	s_waitcnt lgkmcnt(3)
	v_mfma_f32_16x16x32_bf16 v[46:49], v[148:151], v[188:191], v[46:49]
	v_mfma_f32_16x16x32_bf16 v[46:49], v[152:155], v[192:195], v[46:49]
	s_waitcnt lgkmcnt(1)
	v_mfma_f32_16x16x32_bf16 v[42:45], v[156:159], v[188:191], v[42:45]
	v_mfma_f32_16x16x32_bf16 v[42:45], v[160:163], v[192:195], v[42:45]
	v_mfma_f32_16x16x32_bf16 v[30:33], v[148:151], v[196:199], v[30:33]
	v_mfma_f32_16x16x32_bf16 v[30:33], v[152:155], v[200:203], v[30:33]
	v_mfma_f32_16x16x32_bf16 v[26:29], v[156:159], v[196:199], v[26:29]
	v_mfma_f32_16x16x32_bf16 v[26:29], v[160:163], v[200:203], v[26:29]
	v_mfma_f32_16x16x32_bf16 v[14:17], v[148:151], v[204:207], v[14:17]
	v_mfma_f32_16x16x32_bf16 v[14:17], v[152:155], v[208:211], v[14:17]
	s_waitcnt lgkmcnt(0)
	v_mfma_f32_16x16x32_bf16 v[10:13], v[156:159], v[204:207], v[10:13]
	v_mfma_f32_16x16x32_bf16 v[10:13], v[160:163], v[208:211], v[10:13]
	s_setprio 0
	s_setprio 1
	v_mfma_f32_16x16x32_bf16 v[54:57], v[164:167], v[180:183], v[54:57]
	v_mfma_f32_16x16x32_bf16 v[54:57], v[168:171], v[184:187], v[54:57]
	v_mfma_f32_16x16x32_bf16 v[50:53], v[172:175], v[180:183], v[50:53]
	v_mfma_f32_16x16x32_bf16 v[50:53], v[176:179], v[184:187], v[50:53]
	v_mfma_f32_16x16x32_bf16 v[38:41], v[164:167], v[188:191], v[38:41]
	v_mfma_f32_16x16x32_bf16 v[38:41], v[168:171], v[192:195], v[38:41]
	v_mfma_f32_16x16x32_bf16 v[34:37], v[172:175], v[188:191], v[34:37]
	v_mfma_f32_16x16x32_bf16 v[34:37], v[176:179], v[192:195], v[34:37]
	v_mfma_f32_16x16x32_bf16 v[22:25], v[164:167], v[196:199], v[22:25]
	v_mfma_f32_16x16x32_bf16 v[22:25], v[168:171], v[200:203], v[22:25]
	v_mfma_f32_16x16x32_bf16 v[18:21], v[172:175], v[196:199], v[18:21]
	v_mfma_f32_16x16x32_bf16 v[18:21], v[176:179], v[200:203], v[18:21]
	v_mfma_f32_16x16x32_bf16 v[6:9], v[164:167], v[204:207], v[6:9]
	v_mfma_f32_16x16x32_bf16 v[6:9], v[168:171], v[208:211], v[6:9]
	s_setprio 2
	s_barrier
	v_mfma_f32_16x16x32_bf16 v[2:5], v[172:175], v[204:207], v[2:5]
	v_mfma_f32_16x16x32_bf16 v[2:5], v[176:179], v[208:211], v[2:5]
	s_setprio 0
	s_add_i32 s77, s77, 2
	s_add_u32 s73, s73, 0x100
	s_addc_u32 s74, s74, 0
	s_add_u32 s18, s18, 0x100
	s_addc_u32 s19, s19, 0
	s_add_u32 s75, s75, 0x100
	s_addc_u32 s76, s76, 0
	s_cmp_gt_u32 s77, 29
	.p2align 6
.LBB0_1224:
	ds_read_b128 v[148:151], v143
	ds_read_b128 v[152:155], v143 offset:1024
	ds_read_b128 v[156:159], v143 offset:2048
	ds_read_b128 v[160:163], v143 offset:3072
	ds_read_b128 v[164:167], v144
	ds_read_b128 v[168:171], v144 offset:1024
	ds_read_b128 v[172:175], v144 offset:2048
	ds_read_b128 v[176:179], v144 offset:3072
	s_cmp_eq_u32 s77, 28
	s_cselect_b32 s21, s9, s74
	s_cselect_b32 s20, s67, s73
	s_cselect_b32 s23, s11, s76
	s_cselect_b32 s22, s66, s75
	ds_read_b128 v[180:183], v145
	ds_read_b128 v[184:187], v145 offset:1024
	ds_read_b128 v[188:191], v145 offset:2048
	ds_read_b128 v[192:195], v145 offset:3072
	ds_read_b128 v[196:199], v145 offset:4096
	ds_read_b128 v[200:203], v145 offset:5120
	ds_read_b128 v[204:207], v145 offset:6144
	ds_read_b128 v[208:211], v145 offset:7168
	s_add_u32 s78, s18, 0xfff80000
	s_addc_u32 s79, s19, -1
	s_mov_b32 s80, m0
	s_mov_b32 m0, s56
	s_nop 0
	global_load_lds_dwordx4 v138, s[78:79]
	s_mov_b32 m0, s80
	s_nop 0
	s_mov_b32 s80, m0
	s_mov_b32 m0, s59
	s_nop 0
	global_load_lds_dwordx4 v140, s[78:79]
	s_mov_b32 m0, s80
	s_mov_b32 s78, m0
	s_mov_b32 m0, s57
	s_nop 0
	global_load_lds_dwordx4 v138, s[18:19]
	s_mov_b32 m0, s78
	s_nop 0
	s_mov_b32 s78, m0
	s_mov_b32 m0, s64
	s_nop 0
	global_load_lds_dwordx4 v140, s[18:19]
	s_mov_b32 m0, s78
	s_waitcnt vmcnt(8)
	s_waitcnt lgkmcnt(0)
	s_barrier
	s_setprio 1
	s_waitcnt lgkmcnt(7)
	v_mfma_f32_16x16x32_bf16 v[126:129], v[148:151], v[180:183], v[126:129]
	v_mfma_f32_16x16x32_bf16 v[126:129], v[152:155], v[184:187], v[126:129]
	s_waitcnt lgkmcnt(5)
	v_mfma_f32_16x16x32_bf16 v[122:125], v[156:159], v[180:183], v[122:125]
	v_mfma_f32_16x16x32_bf16 v[122:125], v[160:163], v[184:187], v[122:125]
	s_waitcnt lgkmcnt(3)
	v_mfma_f32_16x16x32_bf16 v[110:113], v[148:151], v[188:191], v[110:113]
	v_mfma_f32_16x16x32_bf16 v[110:113], v[152:155], v[192:195], v[110:113]
	s_waitcnt lgkmcnt(1)
	v_mfma_f32_16x16x32_bf16 v[106:109], v[156:159], v[188:191], v[106:109]
	v_mfma_f32_16x16x32_bf16 v[106:109], v[160:163], v[192:195], v[106:109]
	v_mfma_f32_16x16x32_bf16 v[94:97], v[148:151], v[196:199], v[94:97]
	v_mfma_f32_16x16x32_bf16 v[94:97], v[152:155], v[200:203], v[94:97]
	v_mfma_f32_16x16x32_bf16 v[90:93], v[156:159], v[196:199], v[90:93]
	v_mfma_f32_16x16x32_bf16 v[90:93], v[160:163], v[200:203], v[90:93]
	v_mfma_f32_16x16x32_bf16 v[78:81], v[148:151], v[204:207], v[78:81]
	v_mfma_f32_16x16x32_bf16 v[78:81], v[152:155], v[208:211], v[78:81]
	s_waitcnt lgkmcnt(0)
	v_mfma_f32_16x16x32_bf16 v[74:77], v[156:159], v[204:207], v[74:77]
	v_mfma_f32_16x16x32_bf16 v[74:77], v[160:163], v[208:211], v[74:77]
	s_setprio 0
	s_setprio 1
	v_mfma_f32_16x16x32_bf16 v[118:121], v[164:167], v[180:183], v[118:121]
	v_mfma_f32_16x16x32_bf16 v[118:121], v[168:171], v[184:187], v[118:121]
	v_mfma_f32_16x16x32_bf16 v[114:117], v[172:175], v[180:183], v[114:117]
	v_mfma_f32_16x16x32_bf16 v[114:117], v[176:179], v[184:187], v[114:117]
	v_mfma_f32_16x16x32_bf16 v[102:105], v[164:167], v[188:191], v[102:105]
	v_mfma_f32_16x16x32_bf16 v[102:105], v[168:171], v[192:195], v[102:105]
	v_mfma_f32_16x16x32_bf16 v[98:101], v[172:175], v[188:191], v[98:101]
	v_mfma_f32_16x16x32_bf16 v[98:101], v[176:179], v[192:195], v[98:101]
	v_mfma_f32_16x16x32_bf16 v[86:89], v[164:167], v[196:199], v[86:89]
	v_mfma_f32_16x16x32_bf16 v[86:89], v[168:171], v[200:203], v[86:89]
	v_mfma_f32_16x16x32_bf16 v[82:85], v[172:175], v[196:199], v[82:85]
	v_mfma_f32_16x16x32_bf16 v[82:85], v[176:179], v[200:203], v[82:85]
	v_mfma_f32_16x16x32_bf16 v[70:73], v[164:167], v[204:207], v[70:73]
	v_mfma_f32_16x16x32_bf16 v[70:73], v[168:171], v[208:211], v[70:73]
	s_setprio 2
	s_barrier
	v_mfma_f32_16x16x32_bf16 v[66:69], v[172:175], v[204:207], v[66:69]
	v_mfma_f32_16x16x32_bf16 v[66:69], v[176:179], v[208:211], v[66:69]
	s_setprio 0
	ds_read_b128 v[180:183], v145 offset:16384
	ds_read_b128 v[184:187], v145 offset:17408
	ds_read_b128 v[188:191], v145 offset:18432
	ds_read_b128 v[192:195], v145 offset:19456
	ds_read_b128 v[196:199], v145 offset:20480
	ds_read_b128 v[200:203], v145 offset:21504
	ds_read_b128 v[204:207], v145 offset:22528
	ds_read_b128 v[208:211], v145 offset:23552
	s_mov_b32 s78, m0
	s_mov_b32 m0, s35
	s_nop 0
	global_load_lds_dwordx4 v139, s[20:21]
	s_mov_b32 m0, s78
	s_nop 0
	s_mov_b32 s78, m0
	s_mov_b32 m0, s36
	s_nop 0
	global_load_lds_dwordx4 v141, s[20:21]
	s_mov_b32 m0, s78
	s_add_u32 s78, s20, 0x80000
	s_addc_u32 s79, s21, 0
	s_mov_b32 s80, m0
	s_mov_b32 m0, s37
	s_nop 0
	global_load_lds_dwordx4 v139, s[78:79]
	s_mov_b32 m0, s80
	s_nop 0
	s_mov_b32 s80, m0
	s_mov_b32 m0, s40
	s_nop 0
	global_load_lds_dwordx4 v141, s[78:79]
	s_mov_b32 m0, s80
	s_waitcnt vmcnt(4)
	s_waitcnt lgkmcnt(0)
	s_barrier
	s_setprio 1
	s_waitcnt lgkmcnt(7)
	v_mfma_f32_16x16x32_bf16 v[62:65], v[148:151], v[180:183], v[62:65]
	v_mfma_f32_16x16x32_bf16 v[62:65], v[152:155], v[184:187], v[62:65]
	s_waitcnt lgkmcnt(5)
	v_mfma_f32_16x16x32_bf16 v[58:61], v[156:159], v[180:183], v[58:61]
	v_mfma_f32_16x16x32_bf16 v[58:61], v[160:163], v[184:187], v[58:61]
	s_waitcnt lgkmcnt(3)
	v_mfma_f32_16x16x32_bf16 v[46:49], v[148:151], v[188:191], v[46:49]
	v_mfma_f32_16x16x32_bf16 v[46:49], v[152:155], v[192:195], v[46:49]
	s_waitcnt lgkmcnt(1)
	v_mfma_f32_16x16x32_bf16 v[42:45], v[156:159], v[188:191], v[42:45]
	v_mfma_f32_16x16x32_bf16 v[42:45], v[160:163], v[192:195], v[42:45]
	v_mfma_f32_16x16x32_bf16 v[30:33], v[148:151], v[196:199], v[30:33]
	v_mfma_f32_16x16x32_bf16 v[30:33], v[152:155], v[200:203], v[30:33]
	v_mfma_f32_16x16x32_bf16 v[26:29], v[156:159], v[196:199], v[26:29]
	v_mfma_f32_16x16x32_bf16 v[26:29], v[160:163], v[200:203], v[26:29]
	v_mfma_f32_16x16x32_bf16 v[14:17], v[148:151], v[204:207], v[14:17]
	v_mfma_f32_16x16x32_bf16 v[14:17], v[152:155], v[208:211], v[14:17]
	s_waitcnt lgkmcnt(0)
	v_mfma_f32_16x16x32_bf16 v[10:13], v[156:159], v[204:207], v[10:13]
	v_mfma_f32_16x16x32_bf16 v[10:13], v[160:163], v[208:211], v[10:13]
	s_setprio 0
	s_setprio 1
	v_mfma_f32_16x16x32_bf16 v[54:57], v[164:167], v[180:183], v[54:57]
	v_mfma_f32_16x16x32_bf16 v[54:57], v[168:171], v[184:187], v[54:57]
	v_mfma_f32_16x16x32_bf16 v[50:53], v[172:175], v[180:183], v[50:53]
	v_mfma_f32_16x16x32_bf16 v[50:53], v[176:179], v[184:187], v[50:53]
	v_mfma_f32_16x16x32_bf16 v[38:41], v[164:167], v[188:191], v[38:41]
	v_mfma_f32_16x16x32_bf16 v[38:41], v[168:171], v[192:195], v[38:41]
	v_mfma_f32_16x16x32_bf16 v[34:37], v[172:175], v[188:191], v[34:37]
	v_mfma_f32_16x16x32_bf16 v[34:37], v[176:179], v[192:195], v[34:37]
	v_mfma_f32_16x16x32_bf16 v[22:25], v[164:167], v[196:199], v[22:25]
	v_mfma_f32_16x16x32_bf16 v[22:25], v[168:171], v[200:203], v[22:25]
	v_mfma_f32_16x16x32_bf16 v[18:21], v[172:175], v[196:199], v[18:21]
	v_mfma_f32_16x16x32_bf16 v[18:21], v[176:179], v[200:203], v[18:21]
	v_mfma_f32_16x16x32_bf16 v[6:9], v[164:167], v[204:207], v[6:9]
	v_mfma_f32_16x16x32_bf16 v[6:9], v[168:171], v[208:211], v[6:9]
	s_setprio 2
	s_barrier
	v_mfma_f32_16x16x32_bf16 v[2:5], v[172:175], v[204:207], v[2:5]
	v_mfma_f32_16x16x32_bf16 v[2:5], v[176:179], v[208:211], v[2:5]
	s_setprio 0
	ds_read_b128 v[148:151], v146
	ds_read_b128 v[152:155], v146 offset:1024
	ds_read_b128 v[156:159], v146 offset:2048
	ds_read_b128 v[160:163], v146 offset:3072
	ds_read_b128 v[164:167], v147
	ds_read_b128 v[168:171], v147 offset:1024
	ds_read_b128 v[172:175], v147 offset:2048
	ds_read_b128 v[176:179], v147 offset:3072
	ds_read_b128 v[180:183], v145 offset:32768
	ds_read_b128 v[184:187], v145 offset:33792
	ds_read_b128 v[188:191], v145 offset:34816
	ds_read_b128 v[192:195], v145 offset:35840
	ds_read_b128 v[196:199], v145 offset:36864
	ds_read_b128 v[200:203], v145 offset:37888
	ds_read_b128 v[204:207], v145 offset:38912
	ds_read_b128 v[208:211], v145 offset:39936
	s_mov_b32 s78, m0
	s_mov_b32 m0, s31
	s_nop 0
	global_load_lds_dwordx4 v138, s[22:23]
	s_mov_b32 m0, s78
	s_nop 0
	s_mov_b32 s78, m0
	s_mov_b32 m0, s41
	s_nop 0
	global_load_lds_dwordx4 v140, s[22:23]
	s_mov_b32 m0, s78
	s_add_u32 s22, s22, 0x80000
	s_addc_u32 s23, s23, 0
	s_mov_b32 s78, m0
	s_mov_b32 m0, s42
	s_nop 0
	global_load_lds_dwordx4 v138, s[22:23]
	s_mov_b32 m0, s78
	s_nop 0
	s_mov_b32 s78, m0
	s_mov_b32 m0, s43
	s_nop 0
	global_load_lds_dwordx4 v140, s[22:23]
	s_mov_b32 m0, s78
	s_waitcnt vmcnt(8)
	s_waitcnt lgkmcnt(0)
	s_barrier
	s_setprio 1
	s_waitcnt lgkmcnt(7)
	v_mfma_f32_16x16x32_bf16 v[126:129], v[148:151], v[180:183], v[126:129]
	v_mfma_f32_16x16x32_bf16 v[126:129], v[152:155], v[184:187], v[126:129]
	s_waitcnt lgkmcnt(5)
	v_mfma_f32_16x16x32_bf16 v[122:125], v[156:159], v[180:183], v[122:125]
	v_mfma_f32_16x16x32_bf16 v[122:125], v[160:163], v[184:187], v[122:125]
	s_waitcnt lgkmcnt(3)
	v_mfma_f32_16x16x32_bf16 v[110:113], v[148:151], v[188:191], v[110:113]
	v_mfma_f32_16x16x32_bf16 v[110:113], v[152:155], v[192:195], v[110:113]
	s_waitcnt lgkmcnt(1)
	v_mfma_f32_16x16x32_bf16 v[106:109], v[156:159], v[188:191], v[106:109]
	v_mfma_f32_16x16x32_bf16 v[106:109], v[160:163], v[192:195], v[106:109]
	v_mfma_f32_16x16x32_bf16 v[94:97], v[148:151], v[196:199], v[94:97]
	v_mfma_f32_16x16x32_bf16 v[94:97], v[152:155], v[200:203], v[94:97]
	v_mfma_f32_16x16x32_bf16 v[90:93], v[156:159], v[196:199], v[90:93]
	v_mfma_f32_16x16x32_bf16 v[90:93], v[160:163], v[200:203], v[90:93]
	v_mfma_f32_16x16x32_bf16 v[78:81], v[148:151], v[204:207], v[78:81]
	v_mfma_f32_16x16x32_bf16 v[78:81], v[152:155], v[208:211], v[78:81]
	s_waitcnt lgkmcnt(0)
	v_mfma_f32_16x16x32_bf16 v[74:77], v[156:159], v[204:207], v[74:77]
	v_mfma_f32_16x16x32_bf16 v[74:77], v[160:163], v[208:211], v[74:77]
	s_setprio 0
	s_setprio 1
	v_mfma_f32_16x16x32_bf16 v[118:121], v[164:167], v[180:183], v[118:121]
	v_mfma_f32_16x16x32_bf16 v[118:121], v[168:171], v[184:187], v[118:121]
	v_mfma_f32_16x16x32_bf16 v[114:117], v[172:175], v[180:183], v[114:117]
	v_mfma_f32_16x16x32_bf16 v[114:117], v[176:179], v[184:187], v[114:117]
	v_mfma_f32_16x16x32_bf16 v[102:105], v[164:167], v[188:191], v[102:105]
	v_mfma_f32_16x16x32_bf16 v[102:105], v[168:171], v[192:195], v[102:105]
	v_mfma_f32_16x16x32_bf16 v[98:101], v[172:175], v[188:191], v[98:101]
	v_mfma_f32_16x16x32_bf16 v[98:101], v[176:179], v[192:195], v[98:101]
	v_mfma_f32_16x16x32_bf16 v[86:89], v[164:167], v[196:199], v[86:89]
	v_mfma_f32_16x16x32_bf16 v[86:89], v[168:171], v[200:203], v[86:89]
	v_mfma_f32_16x16x32_bf16 v[82:85], v[172:175], v[196:199], v[82:85]
	v_mfma_f32_16x16x32_bf16 v[82:85], v[176:179], v[200:203], v[82:85]
	v_mfma_f32_16x16x32_bf16 v[70:73], v[164:167], v[204:207], v[70:73]
	v_mfma_f32_16x16x32_bf16 v[70:73], v[168:171], v[208:211], v[70:73]
	s_setprio 2
	s_barrier
	v_mfma_f32_16x16x32_bf16 v[66:69], v[172:175], v[204:207], v[66:69]
	v_mfma_f32_16x16x32_bf16 v[66:69], v[176:179], v[208:211], v[66:69]
	s_setprio 0
	ds_read_b128 v[180:183], v145 offset:49152
	ds_read_b128 v[184:187], v145 offset:50176
	ds_read_b128 v[188:191], v145 offset:51200
	ds_read_b128 v[192:195], v145 offset:52224
	ds_read_b128 v[196:199], v145 offset:53248
	ds_read_b128 v[200:203], v145 offset:54272
	ds_read_b128 v[204:207], v145 offset:55296
	ds_read_b128 v[208:211], v145 offset:56320
	s_add_u32 s22, s20, 0x80
	s_addc_u32 s23, s21, 0
	s_mov_b32 s78, m0
	s_mov_b32 m0, s46
	s_nop 0
	global_load_lds_dwordx4 v139, s[22:23]
	s_mov_b32 m0, s78
	s_add_u32 s20, s20, 0x80080
	s_mov_b32 s78, m0
	s_mov_b32 m0, s47
	s_nop 0
	global_load_lds_dwordx4 v141, s[22:23]
	s_mov_b32 m0, s78
	s_addc_u32 s21, s21, 0
	s_mov_b32 s22, m0
	s_mov_b32 m0, s48
	s_nop 0
	global_load_lds_dwordx4 v139, s[20:21]
	s_mov_b32 m0, s22
	s_nop 0
	s_mov_b32 s22, m0
	s_mov_b32 m0, s49
	s_nop 0
	global_load_lds_dwordx4 v141, s[20:21]
	s_mov_b32 m0, s22
	s_waitcnt vmcnt(4)
	s_waitcnt lgkmcnt(0)
	s_barrier
	s_setprio 1
	s_waitcnt lgkmcnt(7)
	v_mfma_f32_16x16x32_bf16 v[62:65], v[148:151], v[180:183], v[62:65]
	v_mfma_f32_16x16x32_bf16 v[62:65], v[152:155], v[184:187], v[62:65]
	s_waitcnt lgkmcnt(5)
	v_mfma_f32_16x16x32_bf16 v[58:61], v[156:159], v[180:183], v[58:61]
	v_mfma_f32_16x16x32_bf16 v[58:61], v[160:163], v[184:187], v[58:61]
	s_waitcnt lgkmcnt(3)
	v_mfma_f32_16x16x32_bf16 v[46:49], v[148:151], v[188:191], v[46:49]
	v_mfma_f32_16x16x32_bf16 v[46:49], v[152:155], v[192:195], v[46:49]
	s_waitcnt lgkmcnt(1)
	v_mfma_f32_16x16x32_bf16 v[42:45], v[156:159], v[188:191], v[42:45]
	v_mfma_f32_16x16x32_bf16 v[42:45], v[160:163], v[192:195], v[42:45]
	v_mfma_f32_16x16x32_bf16 v[30:33], v[148:151], v[196:199], v[30:33]
	v_mfma_f32_16x16x32_bf16 v[30:33], v[152:155], v[200:203], v[30:33]
	v_mfma_f32_16x16x32_bf16 v[26:29], v[156:159], v[196:199], v[26:29]
	v_mfma_f32_16x16x32_bf16 v[26:29], v[160:163], v[200:203], v[26:29]
	v_mfma_f32_16x16x32_bf16 v[14:17], v[148:151], v[204:207], v[14:17]
	v_mfma_f32_16x16x32_bf16 v[14:17], v[152:155], v[208:211], v[14:17]
	s_waitcnt lgkmcnt(0)
	v_mfma_f32_16x16x32_bf16 v[10:13], v[156:159], v[204:207], v[10:13]
	v_mfma_f32_16x16x32_bf16 v[10:13], v[160:163], v[208:211], v[10:13]
	s_setprio 0
	s_setprio 1
	v_mfma_f32_16x16x32_bf16 v[54:57], v[164:167], v[180:183], v[54:57]
	v_mfma_f32_16x16x32_bf16 v[54:57], v[168:171], v[184:187], v[54:57]
	v_mfma_f32_16x16x32_bf16 v[50:53], v[172:175], v[180:183], v[50:53]
	v_mfma_f32_16x16x32_bf16 v[50:53], v[176:179], v[184:187], v[50:53]
	v_mfma_f32_16x16x32_bf16 v[38:41], v[164:167], v[188:191], v[38:41]
	v_mfma_f32_16x16x32_bf16 v[38:41], v[168:171], v[192:195], v[38:41]
	v_mfma_f32_16x16x32_bf16 v[34:37], v[172:175], v[188:191], v[34:37]
	v_mfma_f32_16x16x32_bf16 v[34:37], v[176:179], v[192:195], v[34:37]
	v_mfma_f32_16x16x32_bf16 v[22:25], v[164:167], v[196:199], v[22:25]
	v_mfma_f32_16x16x32_bf16 v[22:25], v[168:171], v[200:203], v[22:25]
	v_mfma_f32_16x16x32_bf16 v[18:21], v[172:175], v[196:199], v[18:21]
	v_mfma_f32_16x16x32_bf16 v[18:21], v[176:179], v[200:203], v[18:21]
	v_mfma_f32_16x16x32_bf16 v[6:9], v[164:167], v[204:207], v[6:9]
	v_mfma_f32_16x16x32_bf16 v[6:9], v[168:171], v[208:211], v[6:9]
	s_setprio 2
	s_barrier
	v_mfma_f32_16x16x32_bf16 v[2:5], v[172:175], v[204:207], v[2:5]
	v_mfma_f32_16x16x32_bf16 v[2:5], v[176:179], v[208:211], v[2:5]
	s_setprio 0
	s_add_i32 s77, s77, 2
	s_add_u32 s73, s73, 0x100
	s_addc_u32 s74, s74, 0
	s_add_u32 s18, s18, 0x100
	s_addc_u32 s19, s19, 0
	s_add_u32 s75, s75, 0x100
	s_addc_u32 s76, s76, 0
	s_cmp_gt_u32 s77, 29
	s_cbranch_scc0 .LBB0_1224
	s_and_b64 vcc, exec, s[6:7]
	s_cbranch_vccz .LBB0_1227
	s_barrier

.LBB0_1356:
	s_ashr_i32 s13, s12, 31
	s_lshl_b64 s[14:15], s[12:13], 15
	s_add_u32 s14, s28, s14
	s_addc_u32 s15, s29, s15
	s_and_b64 s[16:17], s[2:3], exec
	s_cselect_b32 s13, s15, s23
	s_cselect_b32 s67, s14, s22
	s_ashr_i32 s11, s10, 31
	s_lshl_b64 s[16:17], s[10:11], 15
	s_add_u32 s16, s30, s16
	s_addc_u32 s17, s31, s17
	s_and_b64 s[24:25], s[2:3], exec
	s_cselect_b32 s11, s17, s21
	s_cselect_b32 s73, s16, s20
	s_add_u32 s74, s20, 0x80000
	s_addc_u32 s75, s21, 0
	s_add_u32 s20, s22, 0x204000
	s_addc_u32 s21, s23, 0
	s_add_u32 s76, s22, 0x400000
	s_addc_u32 s77, s23, 0
	s_mov_b32 s78, -2
	s_waitcnt vmcnt(25)
	s_waitcnt vmcnt(24)
	s_waitcnt vmcnt(15)
	s_waitcnt vmcnt(14)
	s_waitcnt vmcnt(13)
	s_waitcnt vmcnt(12)
	s_waitcnt vmcnt(11)
	s_waitcnt vmcnt(10)
	s_waitcnt vmcnt(9)
	s_waitcnt vmcnt(8)
	s_waitcnt vmcnt(7)
	s_waitcnt vmcnt(6)
	s_waitcnt vmcnt(5)
	s_waitcnt vmcnt(4)
	s_waitcnt vmcnt(3)
	s_waitcnt vmcnt(2)
	s_waitcnt vmcnt(1)
	s_waitcnt vmcnt(0)
	ds_read_b128 v[130:133], v181
	ds_read_b128 v[134:137], v181 offset:1024
	ds_read_b128 v[138:141], v181 offset:2048
	ds_read_b128 v[142:145], v181 offset:3072
	ds_read_b128 v[150:153], v182
	ds_read_b128 v[154:157], v182 offset:1024
	ds_read_b128 v[158:161], v182 offset:2048
	ds_read_b128 v[162:165], v182 offset:3072
	s_cmpk_eq_i32 s78, 0x52
	s_cselect_b32 s23, s11, s75
	s_cselect_b32 s22, s73, s74
	s_cselect_b32 s25, s13, s77
	s_cselect_b32 s24, s67, s76
	ds_read_b128 v[166:169], v183
	ds_read_b128 v[170:173], v183 offset:1024
	ds_read_b128 v[186:189], v183 offset:2048
	ds_read_b128 v[190:193], v183 offset:3072
	ds_read_b128 v[194:197], v183 offset:4096
	ds_read_b128 v[198:201], v183 offset:5120
	ds_read_b128 v[202:205], v183 offset:6144
	ds_read_b128 v[206:209], v183 offset:7168
	s_add_u32 s80, s20, 0xffffc000
	s_addc_u32 s81, s21, -1
	s_mov_b32 s79, m0
	s_mov_b32 m0, s58
	s_nop 0
	global_load_lds_dwordx4 v1, s[80:81]
	s_mov_b32 m0, s79
	s_nop 0
	s_mov_b32 s79, m0
	s_mov_b32 m0, s64
	s_nop 0
	global_load_lds_dwordx4 v177, s[80:81]
	s_mov_b32 m0, s79
	s_nop 0
	s_mov_b32 s79, m0
	s_mov_b32 m0, s59
	s_nop 0
	global_load_lds_dwordx4 v1, s[20:21]
	s_mov_b32 m0, s79
	s_nop 0
	s_mov_b32 s79, m0
	s_mov_b32 m0, s65
	s_nop 0
	global_load_lds_dwordx4 v177, s[20:21]
	s_mov_b32 m0, s79
	s_waitcnt vmcnt(8)
	s_waitcnt lgkmcnt(0)
	s_barrier
	s_setprio 1
	s_waitcnt lgkmcnt(7)
	v_mfma_f32_16x16x32_bf16 v[126:129], v[130:133], v[166:169], 0
	v_mfma_f32_16x16x32_bf16 v[126:129], v[134:137], v[170:173], v[126:129]
	s_waitcnt lgkmcnt(5)
	v_mfma_f32_16x16x32_bf16 v[122:125], v[138:141], v[166:169], 0
	v_mfma_f32_16x16x32_bf16 v[122:125], v[142:145], v[170:173], v[122:125]
	s_waitcnt lgkmcnt(3)
	v_mfma_f32_16x16x32_bf16 v[118:121], v[130:133], v[186:189], 0
	v_mfma_f32_16x16x32_bf16 v[118:121], v[134:137], v[190:193], v[118:121]
	s_waitcnt lgkmcnt(1)
	v_mfma_f32_16x16x32_bf16 v[110:113], v[138:141], v[186:189], 0
	v_mfma_f32_16x16x32_bf16 v[110:113], v[142:145], v[190:193], v[110:113]
	v_mfma_f32_16x16x32_bf16 v[94:97], v[130:133], v[194:197], 0
	v_mfma_f32_16x16x32_bf16 v[94:97], v[134:137], v[198:201], v[94:97]
	v_mfma_f32_16x16x32_bf16 v[90:93], v[138:141], v[194:197], 0
	v_mfma_f32_16x16x32_bf16 v[90:93], v[142:145], v[198:201], v[90:93]
	v_mfma_f32_16x16x32_bf16 v[86:89], v[130:133], v[202:205], 0
	v_mfma_f32_16x16x32_bf16 v[86:89], v[134:137], v[206:209], v[86:89]
	s_waitcnt lgkmcnt(0)
	v_mfma_f32_16x16x32_bf16 v[78:81], v[138:141], v[202:205], 0
	v_mfma_f32_16x16x32_bf16 v[78:81], v[142:145], v[206:209], v[78:81]
	s_setprio 0
	s_setprio 1
	v_mfma_f32_16x16x32_bf16 v[114:117], v[150:153], v[166:169], 0
	v_mfma_f32_16x16x32_bf16 v[114:117], v[154:157], v[170:173], v[114:117]
	v_mfma_f32_16x16x32_bf16 v[106:109], v[158:161], v[166:169], 0
	v_mfma_f32_16x16x32_bf16 v[106:109], v[162:165], v[170:173], v[106:109]
	v_mfma_f32_16x16x32_bf16 v[102:105], v[150:153], v[186:189], 0
	v_mfma_f32_16x16x32_bf16 v[102:105], v[154:157], v[190:193], v[102:105]
	v_mfma_f32_16x16x32_bf16 v[98:101], v[158:161], v[186:189], 0
	v_mfma_f32_16x16x32_bf16 v[98:101], v[162:165], v[190:193], v[98:101]
	v_mfma_f32_16x16x32_bf16 v[82:85], v[150:153], v[194:197], 0
	v_mfma_f32_16x16x32_bf16 v[82:85], v[154:157], v[198:201], v[82:85]
	v_mfma_f32_16x16x32_bf16 v[74:77], v[158:161], v[194:197], 0
	v_mfma_f32_16x16x32_bf16 v[74:77], v[162:165], v[198:201], v[74:77]
	v_mfma_f32_16x16x32_bf16 v[70:73], v[150:153], v[202:205], 0
	v_mfma_f32_16x16x32_bf16 v[70:73], v[154:157], v[206:209], v[70:73]
	s_setprio 2
	s_barrier
	v_mfma_f32_16x16x32_bf16 v[66:69], v[158:161], v[202:205], 0
	v_mfma_f32_16x16x32_bf16 v[66:69], v[162:165], v[206:209], v[66:69]
	s_setprio 0
	ds_read_b128 v[166:169], v183 offset:16384
	ds_read_b128 v[170:173], v183 offset:17408
	ds_read_b128 v[186:189], v183 offset:18432
	ds_read_b128 v[190:193], v183 offset:19456
	ds_read_b128 v[194:197], v183 offset:20480
	ds_read_b128 v[198:201], v183 offset:21504
	ds_read_b128 v[202:205], v183 offset:22528
	ds_read_b128 v[206:209], v183 offset:23552
	s_mov_b32 s79, m0
	s_mov_b32 m0, s35
	s_nop 0
	global_load_lds_dwordx4 v176, s[22:23]
	s_mov_b32 m0, s79
	s_add_u32 s80, s22, 0x4000
	s_mov_b32 s79, m0
	s_mov_b32 m0, s36
	s_nop 0
	global_load_lds_dwordx4 v178, s[22:23]
	s_mov_b32 m0, s79
	s_addc_u32 s81, s23, 0
	s_mov_b32 s79, m0
	s_mov_b32 m0, s37
	s_nop 0
	global_load_lds_dwordx4 v176, s[80:81]
	s_mov_b32 m0, s79
	s_nop 0
	s_mov_b32 s79, m0
	s_mov_b32 m0, s40
	s_nop 0
	global_load_lds_dwordx4 v178, s[80:81]
	s_mov_b32 m0, s79
	s_waitcnt vmcnt(4)
	s_waitcnt lgkmcnt(0)
	s_barrier
	s_setprio 1
	s_waitcnt lgkmcnt(7)
	v_mfma_f32_16x16x32_bf16 v[62:65], v[130:133], v[166:169], 0
	v_mfma_f32_16x16x32_bf16 v[62:65], v[134:137], v[170:173], v[62:65]
	s_waitcnt lgkmcnt(5)
	v_mfma_f32_16x16x32_bf16 v[58:61], v[138:141], v[166:169], 0
	v_mfma_f32_16x16x32_bf16 v[58:61], v[142:145], v[170:173], v[58:61]
	s_waitcnt lgkmcnt(3)
	v_mfma_f32_16x16x32_bf16 v[46:49], v[130:133], v[186:189], 0
	v_mfma_f32_16x16x32_bf16 v[46:49], v[134:137], v[190:193], v[46:49]
	s_waitcnt lgkmcnt(1)
	v_mfma_f32_16x16x32_bf16 v[42:45], v[138:141], v[186:189], 0
	v_mfma_f32_16x16x32_bf16 v[42:45], v[142:145], v[190:193], v[42:45]
	v_mfma_f32_16x16x32_bf16 v[30:33], v[130:133], v[194:197], 0
	v_mfma_f32_16x16x32_bf16 v[30:33], v[134:137], v[198:201], v[30:33]
	v_mfma_f32_16x16x32_bf16 v[26:29], v[138:141], v[194:197], 0
	v_mfma_f32_16x16x32_bf16 v[26:29], v[142:145], v[198:201], v[26:29]
	v_mfma_f32_16x16x32_bf16 v[14:17], v[130:133], v[202:205], 0
	v_mfma_f32_16x16x32_bf16 v[14:17], v[134:137], v[206:209], v[14:17]
	s_waitcnt lgkmcnt(0)
	v_mfma_f32_16x16x32_bf16 v[10:13], v[138:141], v[202:205], 0
	v_mfma_f32_16x16x32_bf16 v[10:13], v[142:145], v[206:209], v[10:13]
	s_setprio 0
	s_setprio 1
	v_mfma_f32_16x16x32_bf16 v[54:57], v[150:153], v[166:169], 0
	v_mfma_f32_16x16x32_bf16 v[54:57], v[154:157], v[170:173], v[54:57]
	v_mfma_f32_16x16x32_bf16 v[50:53], v[158:161], v[166:169], 0
	v_mfma_f32_16x16x32_bf16 v[50:53], v[162:165], v[170:173], v[50:53]
	v_mfma_f32_16x16x32_bf16 v[38:41], v[150:153], v[186:189], 0
	v_mfma_f32_16x16x32_bf16 v[38:41], v[154:157], v[190:193], v[38:41]
	v_mfma_f32_16x16x32_bf16 v[34:37], v[158:161], v[186:189], 0
	v_mfma_f32_16x16x32_bf16 v[34:37], v[162:165], v[190:193], v[34:37]
	v_mfma_f32_16x16x32_bf16 v[22:25], v[150:153], v[194:197], 0
	v_mfma_f32_16x16x32_bf16 v[22:25], v[154:157], v[198:201], v[22:25]
	v_mfma_f32_16x16x32_bf16 v[18:21], v[158:161], v[194:197], 0
	v_mfma_f32_16x16x32_bf16 v[18:21], v[162:165], v[198:201], v[18:21]
	v_mfma_f32_16x16x32_bf16 v[6:9], v[150:153], v[202:205], 0
	v_mfma_f32_16x16x32_bf16 v[6:9], v[154:157], v[206:209], v[6:9]
	s_setprio 2
	s_barrier
	v_mfma_f32_16x16x32_bf16 v[2:5], v[158:161], v[202:205], 0
	v_mfma_f32_16x16x32_bf16 v[2:5], v[162:165], v[206:209], v[2:5]
	s_setprio 0
	ds_read_b128 v[130:133], v184
	ds_read_b128 v[134:137], v184 offset:1024
	ds_read_b128 v[138:141], v184 offset:2048
	ds_read_b128 v[142:145], v184 offset:3072
	ds_read_b128 v[150:153], v185
	ds_read_b128 v[154:157], v185 offset:1024
	ds_read_b128 v[158:161], v185 offset:2048
	ds_read_b128 v[162:165], v185 offset:3072
	ds_read_b128 v[166:169], v183 offset:32768
	ds_read_b128 v[170:173], v183 offset:33792
	ds_read_b128 v[186:189], v183 offset:34816
	ds_read_b128 v[190:193], v183 offset:35840
	ds_read_b128 v[194:197], v183 offset:36864
	ds_read_b128 v[198:201], v183 offset:37888
	ds_read_b128 v[202:205], v183 offset:38912
	ds_read_b128 v[206:209], v183 offset:39936
	s_mov_b32 s79, m0
	s_mov_b32 m0, s34
	s_nop 0
	global_load_lds_dwordx4 v1, s[24:25]
	s_mov_b32 m0, s79
	s_nop 0
	s_mov_b32 s79, m0
	s_mov_b32 m0, s41
	s_nop 0
	global_load_lds_dwordx4 v177, s[24:25]
	s_mov_b32 m0, s79
	s_add_u32 s24, s24, 0x4000
	s_addc_u32 s25, s25, 0
	s_mov_b32 s79, m0
	s_mov_b32 m0, s42
	s_nop 0
	global_load_lds_dwordx4 v1, s[24:25]
	s_mov_b32 m0, s79
	s_nop 0
	s_mov_b32 s79, m0
	s_mov_b32 m0, s43
	s_nop 0
	global_load_lds_dwordx4 v177, s[24:25]
	s_mov_b32 m0, s79
	s_waitcnt vmcnt(8)
	s_waitcnt lgkmcnt(0)
	s_barrier
	s_setprio 1
	s_waitcnt lgkmcnt(7)
	v_mfma_f32_16x16x32_bf16 v[126:129], v[130:133], v[166:169], v[126:129]
	v_mfma_f32_16x16x32_bf16 v[126:129], v[134:137], v[170:173], v[126:129]
	s_waitcnt lgkmcnt(5)
	v_mfma_f32_16x16x32_bf16 v[122:125], v[138:141], v[166:169], v[122:125]
	v_mfma_f32_16x16x32_bf16 v[122:125], v[142:145], v[170:173], v[122:125]
	s_waitcnt lgkmcnt(3)
	v_mfma_f32_16x16x32_bf16 v[118:121], v[130:133], v[186:189], v[118:121]
	v_mfma_f32_16x16x32_bf16 v[118:121], v[134:137], v[190:193], v[118:121]
	s_waitcnt lgkmcnt(1)
	v_mfma_f32_16x16x32_bf16 v[110:113], v[138:141], v[186:189], v[110:113]
	v_mfma_f32_16x16x32_bf16 v[110:113], v[142:145], v[190:193], v[110:113]
	v_mfma_f32_16x16x32_bf16 v[94:97], v[130:133], v[194:197], v[94:97]
	v_mfma_f32_16x16x32_bf16 v[94:97], v[134:137], v[198:201], v[94:97]
	v_mfma_f32_16x16x32_bf16 v[90:93], v[138:141], v[194:197], v[90:93]
	v_mfma_f32_16x16x32_bf16 v[90:93], v[142:145], v[198:201], v[90:93]
	v_mfma_f32_16x16x32_bf16 v[86:89], v[130:133], v[202:205], v[86:89]
	v_mfma_f32_16x16x32_bf16 v[86:89], v[134:137], v[206:209], v[86:89]
	s_waitcnt lgkmcnt(0)
	v_mfma_f32_16x16x32_bf16 v[78:81], v[138:141], v[202:205], v[78:81]
	v_mfma_f32_16x16x32_bf16 v[78:81], v[142:145], v[206:209], v[78:81]
	s_setprio 0
	s_setprio 1
	v_mfma_f32_16x16x32_bf16 v[114:117], v[150:153], v[166:169], v[114:117]
	v_mfma_f32_16x16x32_bf16 v[114:117], v[154:157], v[170:173], v[114:117]
	v_mfma_f32_16x16x32_bf16 v[106:109], v[158:161], v[166:169], v[106:109]
	v_mfma_f32_16x16x32_bf16 v[106:109], v[162:165], v[170:173], v[106:109]
	v_mfma_f32_16x16x32_bf16 v[102:105], v[150:153], v[186:189], v[102:105]
	v_mfma_f32_16x16x32_bf16 v[102:105], v[154:157], v[190:193], v[102:105]
	v_mfma_f32_16x16x32_bf16 v[98:101], v[158:161], v[186:189], v[98:101]
	v_mfma_f32_16x16x32_bf16 v[98:101], v[162:165], v[190:193], v[98:101]
	v_mfma_f32_16x16x32_bf16 v[82:85], v[150:153], v[194:197], v[82:85]
	v_mfma_f32_16x16x32_bf16 v[82:85], v[154:157], v[198:201], v[82:85]
	v_mfma_f32_16x16x32_bf16 v[74:77], v[158:161], v[194:197], v[74:77]
	v_mfma_f32_16x16x32_bf16 v[74:77], v[162:165], v[198:201], v[74:77]
	v_mfma_f32_16x16x32_bf16 v[70:73], v[150:153], v[202:205], v[70:73]
	v_mfma_f32_16x16x32_bf16 v[70:73], v[154:157], v[206:209], v[70:73]
	s_setprio 2
	s_barrier
	v_mfma_f32_16x16x32_bf16 v[66:69], v[158:161], v[202:205], v[66:69]
	v_mfma_f32_16x16x32_bf16 v[66:69], v[162:165], v[206:209], v[66:69]
	s_setprio 0
	ds_read_b128 v[166:169], v183 offset:49152
	ds_read_b128 v[170:173], v183 offset:50176
	ds_read_b128 v[186:189], v183 offset:51200
	ds_read_b128 v[190:193], v183 offset:52224
	ds_read_b128 v[194:197], v183 offset:53248
	ds_read_b128 v[198:201], v183 offset:54272
	ds_read_b128 v[202:205], v183 offset:55296
	ds_read_b128 v[206:209], v183 offset:56320
	s_add_u32 s24, s22, 0x40000
	s_addc_u32 s25, s23, 0
	s_mov_b32 s79, m0
	s_mov_b32 m0, s46
	s_nop 0
	global_load_lds_dwordx4 v176, s[24:25]
	s_mov_b32 m0, s79
	s_add_u32 s22, s22, 0x44000
	s_mov_b32 s79, m0
	s_mov_b32 m0, s47
	s_nop 0
	global_load_lds_dwordx4 v178, s[24:25]
	s_mov_b32 m0, s79
	s_addc_u32 s23, s23, 0
	s_mov_b32 s24, m0
	s_mov_b32 m0, s48
	s_nop 0
	global_load_lds_dwordx4 v176, s[22:23]
	s_mov_b32 m0, s24
	s_nop 0
	s_mov_b32 s24, m0
	s_mov_b32 m0, s49
	s_nop 0
	global_load_lds_dwordx4 v178, s[22:23]
	s_mov_b32 m0, s24
	s_waitcnt vmcnt(4)
	s_waitcnt lgkmcnt(0)
	s_barrier
	s_setprio 1
	s_waitcnt lgkmcnt(7)
	v_mfma_f32_16x16x32_bf16 v[62:65], v[130:133], v[166:169], v[62:65]
	v_mfma_f32_16x16x32_bf16 v[62:65], v[134:137], v[170:173], v[62:65]
	s_waitcnt lgkmcnt(5)
	v_mfma_f32_16x16x32_bf16 v[58:61], v[138:141], v[166:169], v[58:61]
	v_mfma_f32_16x16x32_bf16 v[58:61], v[142:145], v[170:173], v[58:61]
	s_waitcnt lgkmcnt(3)
	v_mfma_f32_16x16x32_bf16 v[46:49], v[130:133], v[186:189], v[46:49]
	v_mfma_f32_16x16x32_bf16 v[46:49], v[134:137], v[190:193], v[46:49]
	s_waitcnt lgkmcnt(1)
	v_mfma_f32_16x16x32_bf16 v[42:45], v[138:141], v[186:189], v[42:45]
	v_mfma_f32_16x16x32_bf16 v[42:45], v[142:145], v[190:193], v[42:45]
	v_mfma_f32_16x16x32_bf16 v[30:33], v[130:133], v[194:197], v[30:33]
	v_mfma_f32_16x16x32_bf16 v[30:33], v[134:137], v[198:201], v[30:33]
	v_mfma_f32_16x16x32_bf16 v[26:29], v[138:141], v[194:197], v[26:29]
	v_mfma_f32_16x16x32_bf16 v[26:29], v[142:145], v[198:201], v[26:29]
	v_mfma_f32_16x16x32_bf16 v[14:17], v[130:133], v[202:205], v[14:17]
	v_mfma_f32_16x16x32_bf16 v[14:17], v[134:137], v[206:209], v[14:17]
	s_waitcnt lgkmcnt(0)
	v_mfma_f32_16x16x32_bf16 v[10:13], v[138:141], v[202:205], v[10:13]
	v_mfma_f32_16x16x32_bf16 v[10:13], v[142:145], v[206:209], v[10:13]
	s_setprio 0
	s_setprio 1
	v_mfma_f32_16x16x32_bf16 v[54:57], v[150:153], v[166:169], v[54:57]
	v_mfma_f32_16x16x32_bf16 v[54:57], v[154:157], v[170:173], v[54:57]
	v_mfma_f32_16x16x32_bf16 v[50:53], v[158:161], v[166:169], v[50:53]
	v_mfma_f32_16x16x32_bf16 v[50:53], v[162:165], v[170:173], v[50:53]
	v_mfma_f32_16x16x32_bf16 v[38:41], v[150:153], v[186:189], v[38:41]
	v_mfma_f32_16x16x32_bf16 v[38:41], v[154:157], v[190:193], v[38:41]
	v_mfma_f32_16x16x32_bf16 v[34:37], v[158:161], v[186:189], v[34:37]
	v_mfma_f32_16x16x32_bf16 v[34:37], v[162:165], v[190:193], v[34:37]
	v_mfma_f32_16x16x32_bf16 v[22:25], v[150:153], v[194:197], v[22:25]
	v_mfma_f32_16x16x32_bf16 v[22:25], v[154:157], v[198:201], v[22:25]
	v_mfma_f32_16x16x32_bf16 v[18:21], v[158:161], v[194:197], v[18:21]
	v_mfma_f32_16x16x32_bf16 v[18:21], v[162:165], v[198:201], v[18:21]
	v_mfma_f32_16x16x32_bf16 v[6:9], v[150:153], v[202:205], v[6:9]
	v_mfma_f32_16x16x32_bf16 v[6:9], v[154:157], v[206:209], v[6:9]
	s_setprio 2
	s_barrier
	v_mfma_f32_16x16x32_bf16 v[2:5], v[158:161], v[202:205], v[2:5]
	v_mfma_f32_16x16x32_bf16 v[2:5], v[162:165], v[206:209], v[2:5]
	s_setprio 0
	s_add_i32 s78, s78, 2
	s_add_u32 s74, s74, 0x80000
	s_addc_u32 s75, s75, 0
	s_add_u32 s20, s20, 0x400000
	s_addc_u32 s21, s21, 0
	s_add_u32 s76, s76, 0x400000
	s_addc_u32 s77, s77, 0
	s_cmpk_gt_u32 s78, 0x53
	.p2align 6
.LBB0_1357:
	ds_read_b128 v[130:133], v181
	ds_read_b128 v[134:137], v181 offset:1024
	ds_read_b128 v[138:141], v181 offset:2048
	ds_read_b128 v[142:145], v181 offset:3072
	ds_read_b128 v[150:153], v182
	ds_read_b128 v[154:157], v182 offset:1024
	ds_read_b128 v[158:161], v182 offset:2048
	ds_read_b128 v[162:165], v182 offset:3072
	s_cmpk_eq_i32 s78, 0x52
	s_cselect_b32 s23, s11, s75
	s_cselect_b32 s22, s73, s74
	s_cselect_b32 s25, s13, s77
	s_cselect_b32 s24, s67, s76
	ds_read_b128 v[166:169], v183
	ds_read_b128 v[170:173], v183 offset:1024
	ds_read_b128 v[186:189], v183 offset:2048
	ds_read_b128 v[190:193], v183 offset:3072
	ds_read_b128 v[194:197], v183 offset:4096
	ds_read_b128 v[198:201], v183 offset:5120
	ds_read_b128 v[202:205], v183 offset:6144
	ds_read_b128 v[206:209], v183 offset:7168
	s_add_u32 s80, s20, 0xffffc000
	s_addc_u32 s81, s21, -1
	s_mov_b32 s79, m0
	s_mov_b32 m0, s58
	s_nop 0
	global_load_lds_dwordx4 v1, s[80:81]
	s_mov_b32 m0, s79
	s_nop 0
	s_mov_b32 s79, m0
	s_mov_b32 m0, s64
	s_nop 0
	global_load_lds_dwordx4 v177, s[80:81]
	s_mov_b32 m0, s79
	s_nop 0
	s_mov_b32 s79, m0
	s_mov_b32 m0, s59
	s_nop 0
	global_load_lds_dwordx4 v1, s[20:21]
	s_mov_b32 m0, s79
	s_nop 0
	s_mov_b32 s79, m0
	s_mov_b32 m0, s65
	s_nop 0
	global_load_lds_dwordx4 v177, s[20:21]
	s_mov_b32 m0, s79
	s_waitcnt vmcnt(8)
	s_waitcnt lgkmcnt(0)
	s_barrier
	s_setprio 1
	s_waitcnt lgkmcnt(7)
	v_mfma_f32_16x16x32_bf16 v[126:129], v[130:133], v[166:169], v[126:129]
	v_mfma_f32_16x16x32_bf16 v[126:129], v[134:137], v[170:173], v[126:129]
	s_waitcnt lgkmcnt(5)
	v_mfma_f32_16x16x32_bf16 v[122:125], v[138:141], v[166:169], v[122:125]
	v_mfma_f32_16x16x32_bf16 v[122:125], v[142:145], v[170:173], v[122:125]
	s_waitcnt lgkmcnt(3)
	v_mfma_f32_16x16x32_bf16 v[118:121], v[130:133], v[186:189], v[118:121]
	v_mfma_f32_16x16x32_bf16 v[118:121], v[134:137], v[190:193], v[118:121]
	s_waitcnt lgkmcnt(1)
	v_mfma_f32_16x16x32_bf16 v[110:113], v[138:141], v[186:189], v[110:113]
	v_mfma_f32_16x16x32_bf16 v[110:113], v[142:145], v[190:193], v[110:113]
	v_mfma_f32_16x16x32_bf16 v[94:97], v[130:133], v[194:197], v[94:97]
	v_mfma_f32_16x16x32_bf16 v[94:97], v[134:137], v[198:201], v[94:97]
	v_mfma_f32_16x16x32_bf16 v[90:93], v[138:141], v[194:197], v[90:93]
	v_mfma_f32_16x16x32_bf16 v[90:93], v[142:145], v[198:201], v[90:93]
	v_mfma_f32_16x16x32_bf16 v[86:89], v[130:133], v[202:205], v[86:89]
	v_mfma_f32_16x16x32_bf16 v[86:89], v[134:137], v[206:209], v[86:89]
	s_waitcnt lgkmcnt(0)
	v_mfma_f32_16x16x32_bf16 v[78:81], v[138:141], v[202:205], v[78:81]
	v_mfma_f32_16x16x32_bf16 v[78:81], v[142:145], v[206:209], v[78:81]
	s_setprio 0
	s_setprio 1
	v_mfma_f32_16x16x32_bf16 v[114:117], v[150:153], v[166:169], v[114:117]
	v_mfma_f32_16x16x32_bf16 v[114:117], v[154:157], v[170:173], v[114:117]
	v_mfma_f32_16x16x32_bf16 v[106:109], v[158:161], v[166:169], v[106:109]
	v_mfma_f32_16x16x32_bf16 v[106:109], v[162:165], v[170:173], v[106:109]
	v_mfma_f32_16x16x32_bf16 v[102:105], v[150:153], v[186:189], v[102:105]
	v_mfma_f32_16x16x32_bf16 v[102:105], v[154:157], v[190:193], v[102:105]
	v_mfma_f32_16x16x32_bf16 v[98:101], v[158:161], v[186:189], v[98:101]
	v_mfma_f32_16x16x32_bf16 v[98:101], v[162:165], v[190:193], v[98:101]
	v_mfma_f32_16x16x32_bf16 v[82:85], v[150:153], v[194:197], v[82:85]
	v_mfma_f32_16x16x32_bf16 v[82:85], v[154:157], v[198:201], v[82:85]
	v_mfma_f32_16x16x32_bf16 v[74:77], v[158:161], v[194:197], v[74:77]
	v_mfma_f32_16x16x32_bf16 v[74:77], v[162:165], v[198:201], v[74:77]
	v_mfma_f32_16x16x32_bf16 v[70:73], v[150:153], v[202:205], v[70:73]
	v_mfma_f32_16x16x32_bf16 v[70:73], v[154:157], v[206:209], v[70:73]
	s_setprio 2
	s_barrier
	v_mfma_f32_16x16x32_bf16 v[66:69], v[158:161], v[202:205], v[66:69]
	v_mfma_f32_16x16x32_bf16 v[66:69], v[162:165], v[206:209], v[66:69]
	s_setprio 0
	ds_read_b128 v[166:169], v183 offset:16384
	ds_read_b128 v[170:173], v183 offset:17408
	ds_read_b128 v[186:189], v183 offset:18432
	ds_read_b128 v[190:193], v183 offset:19456
	ds_read_b128 v[194:197], v183 offset:20480
	ds_read_b128 v[198:201], v183 offset:21504
	ds_read_b128 v[202:205], v183 offset:22528
	ds_read_b128 v[206:209], v183 offset:23552
	s_mov_b32 s79, m0
	s_mov_b32 m0, s35
	s_nop 0
	global_load_lds_dwordx4 v176, s[22:23]
	s_mov_b32 m0, s79
	s_add_u32 s80, s22, 0x4000
	s_mov_b32 s79, m0
	s_mov_b32 m0, s36
	s_nop 0
	global_load_lds_dwordx4 v178, s[22:23]
	s_mov_b32 m0, s79
	s_addc_u32 s81, s23, 0
	s_mov_b32 s79, m0
	s_mov_b32 m0, s37
	s_nop 0
	global_load_lds_dwordx4 v176, s[80:81]
	s_mov_b32 m0, s79
	s_nop 0
	s_mov_b32 s79, m0
	s_mov_b32 m0, s40
	s_nop 0
	global_load_lds_dwordx4 v178, s[80:81]
	s_mov_b32 m0, s79
	s_waitcnt vmcnt(4)
	s_waitcnt lgkmcnt(0)
	s_barrier
	s_setprio 1
	s_waitcnt lgkmcnt(7)
	v_mfma_f32_16x16x32_bf16 v[62:65], v[130:133], v[166:169], v[62:65]
	v_mfma_f32_16x16x32_bf16 v[62:65], v[134:137], v[170:173], v[62:65]
	s_waitcnt lgkmcnt(5)
	v_mfma_f32_16x16x32_bf16 v[58:61], v[138:141], v[166:169], v[58:61]
	v_mfma_f32_16x16x32_bf16 v[58:61], v[142:145], v[170:173], v[58:61]
	s_waitcnt lgkmcnt(3)
	v_mfma_f32_16x16x32_bf16 v[46:49], v[130:133], v[186:189], v[46:49]
	v_mfma_f32_16x16x32_bf16 v[46:49], v[134:137], v[190:193], v[46:49]
	s_waitcnt lgkmcnt(1)
	v_mfma_f32_16x16x32_bf16 v[42:45], v[138:141], v[186:189], v[42:45]
	v_mfma_f32_16x16x32_bf16 v[42:45], v[142:145], v[190:193], v[42:45]
	v_mfma_f32_16x16x32_bf16 v[30:33], v[130:133], v[194:197], v[30:33]
	v_mfma_f32_16x16x32_bf16 v[30:33], v[134:137], v[198:201], v[30:33]
	v_mfma_f32_16x16x32_bf16 v[26:29], v[138:141], v[194:197], v[26:29]
	v_mfma_f32_16x16x32_bf16 v[26:29], v[142:145], v[198:201], v[26:29]
	v_mfma_f32_16x16x32_bf16 v[14:17], v[130:133], v[202:205], v[14:17]
	v_mfma_f32_16x16x32_bf16 v[14:17], v[134:137], v[206:209], v[14:17]
	s_waitcnt lgkmcnt(0)
	v_mfma_f32_16x16x32_bf16 v[10:13], v[138:141], v[202:205], v[10:13]
	v_mfma_f32_16x16x32_bf16 v[10:13], v[142:145], v[206:209], v[10:13]
	s_setprio 0
	s_setprio 1
	v_mfma_f32_16x16x32_bf16 v[54:57], v[150:153], v[166:169], v[54:57]
	v_mfma_f32_16x16x32_bf16 v[54:57], v[154:157], v[170:173], v[54:57]
	v_mfma_f32_16x16x32_bf16 v[50:53], v[158:161], v[166:169], v[50:53]
	v_mfma_f32_16x16x32_bf16 v[50:53], v[162:165], v[170:173], v[50:53]
	v_mfma_f32_16x16x32_bf16 v[38:41], v[150:153], v[186:189], v[38:41]
	v_mfma_f32_16x16x32_bf16 v[38:41], v[154:157], v[190:193], v[38:41]
	v_mfma_f32_16x16x32_bf16 v[34:37], v[158:161], v[186:189], v[34:37]
	v_mfma_f32_16x16x32_bf16 v[34:37], v[162:165], v[190:193], v[34:37]
	v_mfma_f32_16x16x32_bf16 v[22:25], v[150:153], v[194:197], v[22:25]
	v_mfma_f32_16x16x32_bf16 v[22:25], v[154:157], v[198:201], v[22:25]
	v_mfma_f32_16x16x32_bf16 v[18:21], v[158:161], v[194:197], v[18:21]
	v_mfma_f32_16x16x32_bf16 v[18:21], v[162:165], v[198:201], v[18:21]
	v_mfma_f32_16x16x32_bf16 v[6:9], v[150:153], v[202:205], v[6:9]
	v_mfma_f32_16x16x32_bf16 v[6:9], v[154:157], v[206:209], v[6:9]
	s_setprio 2
	s_barrier
	v_mfma_f32_16x16x32_bf16 v[2:5], v[158:161], v[202:205], v[2:5]
	v_mfma_f32_16x16x32_bf16 v[2:5], v[162:165], v[206:209], v[2:5]
	s_setprio 0
	ds_read_b128 v[130:133], v184
	ds_read_b128 v[134:137], v184 offset:1024
	ds_read_b128 v[138:141], v184 offset:2048
	ds_read_b128 v[142:145], v184 offset:3072
	ds_read_b128 v[150:153], v185
	ds_read_b128 v[154:157], v185 offset:1024
	ds_read_b128 v[158:161], v185 offset:2048
	ds_read_b128 v[162:165], v185 offset:3072
	ds_read_b128 v[166:169], v183 offset:32768
	ds_read_b128 v[170:173], v183 offset:33792
	ds_read_b128 v[186:189], v183 offset:34816
	ds_read_b128 v[190:193], v183 offset:35840
	ds_read_b128 v[194:197], v183 offset:36864
	ds_read_b128 v[198:201], v183 offset:37888
	ds_read_b128 v[202:205], v183 offset:38912
	ds_read_b128 v[206:209], v183 offset:39936
	s_mov_b32 s79, m0
	s_mov_b32 m0, s34
	s_nop 0
	global_load_lds_dwordx4 v1, s[24:25]
	s_mov_b32 m0, s79
	s_nop 0
	s_mov_b32 s79, m0
	s_mov_b32 m0, s41
	s_nop 0
	global_load_lds_dwordx4 v177, s[24:25]
	s_mov_b32 m0, s79
	s_add_u32 s24, s24, 0x4000
	s_addc_u32 s25, s25, 0
	s_mov_b32 s79, m0
	s_mov_b32 m0, s42
	s_nop 0
	global_load_lds_dwordx4 v1, s[24:25]
	s_mov_b32 m0, s79
	s_nop 0
	s_mov_b32 s79, m0
	s_mov_b32 m0, s43
	s_nop 0
	global_load_lds_dwordx4 v177, s[24:25]
	s_mov_b32 m0, s79
	s_waitcnt vmcnt(8)
	s_waitcnt lgkmcnt(0)
	s_barrier
	s_setprio 1
	s_waitcnt lgkmcnt(7)
	v_mfma_f32_16x16x32_bf16 v[126:129], v[130:133], v[166:169], v[126:129]
	v_mfma_f32_16x16x32_bf16 v[126:129], v[134:137], v[170:173], v[126:129]
	s_waitcnt lgkmcnt(5)
	v_mfma_f32_16x16x32_bf16 v[122:125], v[138:141], v[166:169], v[122:125]
	v_mfma_f32_16x16x32_bf16 v[122:125], v[142:145], v[170:173], v[122:125]
	s_waitcnt lgkmcnt(3)
	v_mfma_f32_16x16x32_bf16 v[118:121], v[130:133], v[186:189], v[118:121]
	v_mfma_f32_16x16x32_bf16 v[118:121], v[134:137], v[190:193], v[118:121]
	s_waitcnt lgkmcnt(1)
	v_mfma_f32_16x16x32_bf16 v[110:113], v[138:141], v[186:189], v[110:113]
	v_mfma_f32_16x16x32_bf16 v[110:113], v[142:145], v[190:193], v[110:113]
	v_mfma_f32_16x16x32_bf16 v[94:97], v[130:133], v[194:197], v[94:97]
	v_mfma_f32_16x16x32_bf16 v[94:97], v[134:137], v[198:201], v[94:97]
	v_mfma_f32_16x16x32_bf16 v[90:93], v[138:141], v[194:197], v[90:93]
	v_mfma_f32_16x16x32_bf16 v[90:93], v[142:145], v[198:201], v[90:93]
	v_mfma_f32_16x16x32_bf16 v[86:89], v[130:133], v[202:205], v[86:89]
	v_mfma_f32_16x16x32_bf16 v[86:89], v[134:137], v[206:209], v[86:89]
	s_waitcnt lgkmcnt(0)
	v_mfma_f32_16x16x32_bf16 v[78:81], v[138:141], v[202:205], v[78:81]
	v_mfma_f32_16x16x32_bf16 v[78:81], v[142:145], v[206:209], v[78:81]
	s_setprio 0
	s_setprio 1
	v_mfma_f32_16x16x32_bf16 v[114:117], v[150:153], v[166:169], v[114:117]
	v_mfma_f32_16x16x32_bf16 v[114:117], v[154:157], v[170:173], v[114:117]
	v_mfma_f32_16x16x32_bf16 v[106:109], v[158:161], v[166:169], v[106:109]
	v_mfma_f32_16x16x32_bf16 v[106:109], v[162:165], v[170:173], v[106:109]
	v_mfma_f32_16x16x32_bf16 v[102:105], v[150:153], v[186:189], v[102:105]
	v_mfma_f32_16x16x32_bf16 v[102:105], v[154:157], v[190:193], v[102:105]
	v_mfma_f32_16x16x32_bf16 v[98:101], v[158:161], v[186:189], v[98:101]
	v_mfma_f32_16x16x32_bf16 v[98:101], v[162:165], v[190:193], v[98:101]
	v_mfma_f32_16x16x32_bf16 v[82:85], v[150:153], v[194:197], v[82:85]
	v_mfma_f32_16x16x32_bf16 v[82:85], v[154:157], v[198:201], v[82:85]
	v_mfma_f32_16x16x32_bf16 v[74:77], v[158:161], v[194:197], v[74:77]
	v_mfma_f32_16x16x32_bf16 v[74:77], v[162:165], v[198:201], v[74:77]
	v_mfma_f32_16x16x32_bf16 v[70:73], v[150:153], v[202:205], v[70:73]
	v_mfma_f32_16x16x32_bf16 v[70:73], v[154:157], v[206:209], v[70:73]
	s_setprio 2
	s_barrier
	v_mfma_f32_16x16x32_bf16 v[66:69], v[158:161], v[202:205], v[66:69]
	v_mfma_f32_16x16x32_bf16 v[66:69], v[162:165], v[206:209], v[66:69]
	s_setprio 0
	ds_read_b128 v[166:169], v183 offset:49152
	ds_read_b128 v[170:173], v183 offset:50176
	ds_read_b128 v[186:189], v183 offset:51200
	ds_read_b128 v[190:193], v183 offset:52224
	ds_read_b128 v[194:197], v183 offset:53248
	ds_read_b128 v[198:201], v183 offset:54272
	ds_read_b128 v[202:205], v183 offset:55296
	ds_read_b128 v[206:209], v183 offset:56320
	s_add_u32 s24, s22, 0x40000
	s_addc_u32 s25, s23, 0
	s_mov_b32 s79, m0
	s_mov_b32 m0, s46
	s_nop 0
	global_load_lds_dwordx4 v176, s[24:25]
	s_mov_b32 m0, s79
	s_add_u32 s22, s22, 0x44000
	s_mov_b32 s79, m0
	s_mov_b32 m0, s47
	s_nop 0
	global_load_lds_dwordx4 v178, s[24:25]
	s_mov_b32 m0, s79
	s_addc_u32 s23, s23, 0
	s_mov_b32 s24, m0
	s_mov_b32 m0, s48
	s_nop 0
	global_load_lds_dwordx4 v176, s[22:23]
	s_mov_b32 m0, s24
	s_nop 0
	s_mov_b32 s24, m0
	s_mov_b32 m0, s49
	s_nop 0
	global_load_lds_dwordx4 v178, s[22:23]
	s_mov_b32 m0, s24
	s_waitcnt vmcnt(4)
	s_waitcnt lgkmcnt(0)
	s_barrier
	s_setprio 1
	s_waitcnt lgkmcnt(7)
	v_mfma_f32_16x16x32_bf16 v[62:65], v[130:133], v[166:169], v[62:65]
	v_mfma_f32_16x16x32_bf16 v[62:65], v[134:137], v[170:173], v[62:65]
	s_waitcnt lgkmcnt(5)
	v_mfma_f32_16x16x32_bf16 v[58:61], v[138:141], v[166:169], v[58:61]
	v_mfma_f32_16x16x32_bf16 v[58:61], v[142:145], v[170:173], v[58:61]
	s_waitcnt lgkmcnt(3)
	v_mfma_f32_16x16x32_bf16 v[46:49], v[130:133], v[186:189], v[46:49]
	v_mfma_f32_16x16x32_bf16 v[46:49], v[134:137], v[190:193], v[46:49]
	s_waitcnt lgkmcnt(1)
	v_mfma_f32_16x16x32_bf16 v[42:45], v[138:141], v[186:189], v[42:45]
	v_mfma_f32_16x16x32_bf16 v[42:45], v[142:145], v[190:193], v[42:45]
	v_mfma_f32_16x16x32_bf16 v[30:33], v[130:133], v[194:197], v[30:33]
	v_mfma_f32_16x16x32_bf16 v[30:33], v[134:137], v[198:201], v[30:33]
	v_mfma_f32_16x16x32_bf16 v[26:29], v[138:141], v[194:197], v[26:29]
	v_mfma_f32_16x16x32_bf16 v[26:29], v[142:145], v[198:201], v[26:29]
	v_mfma_f32_16x16x32_bf16 v[14:17], v[130:133], v[202:205], v[14:17]
	v_mfma_f32_16x16x32_bf16 v[14:17], v[134:137], v[206:209], v[14:17]
	s_waitcnt lgkmcnt(0)
	v_mfma_f32_16x16x32_bf16 v[10:13], v[138:141], v[202:205], v[10:13]
	v_mfma_f32_16x16x32_bf16 v[10:13], v[142:145], v[206:209], v[10:13]
	s_setprio 0
	s_setprio 1
	v_mfma_f32_16x16x32_bf16 v[54:57], v[150:153], v[166:169], v[54:57]
	v_mfma_f32_16x16x32_bf16 v[54:57], v[154:157], v[170:173], v[54:57]
	v_mfma_f32_16x16x32_bf16 v[50:53], v[158:161], v[166:169], v[50:53]
	v_mfma_f32_16x16x32_bf16 v[50:53], v[162:165], v[170:173], v[50:53]
	v_mfma_f32_16x16x32_bf16 v[38:41], v[150:153], v[186:189], v[38:41]
	v_mfma_f32_16x16x32_bf16 v[38:41], v[154:157], v[190:193], v[38:41]
	v_mfma_f32_16x16x32_bf16 v[34:37], v[158:161], v[186:189], v[34:37]
	v_mfma_f32_16x16x32_bf16 v[34:37], v[162:165], v[190:193], v[34:37]
	v_mfma_f32_16x16x32_bf16 v[22:25], v[150:153], v[194:197], v[22:25]
	v_mfma_f32_16x16x32_bf16 v[22:25], v[154:157], v[198:201], v[22:25]
	v_mfma_f32_16x16x32_bf16 v[18:21], v[158:161], v[194:197], v[18:21]
	v_mfma_f32_16x16x32_bf16 v[18:21], v[162:165], v[198:201], v[18:21]
	v_mfma_f32_16x16x32_bf16 v[6:9], v[150:153], v[202:205], v[6:9]
	v_mfma_f32_16x16x32_bf16 v[6:9], v[154:157], v[206:209], v[6:9]
	s_setprio 2
	s_barrier
	v_mfma_f32_16x16x32_bf16 v[2:5], v[158:161], v[202:205], v[2:5]
	v_mfma_f32_16x16x32_bf16 v[2:5], v[162:165], v[206:209], v[2:5]
	s_setprio 0
	s_add_i32 s78, s78, 2
	s_add_u32 s74, s74, 0x80000
	s_addc_u32 s75, s75, 0
	s_add_u32 s20, s20, 0x400000
	s_addc_u32 s21, s21, 0
	s_add_u32 s76, s76, 0x400000
	s_addc_u32 s77, s77, 0
	s_cmpk_gt_u32 s78, 0x53
	s_cbranch_scc0 .LBB0_1357
	s_and_b64 vcc, exec, s[8:9]
	s_cbranch_vccz .LBB0_1360
	s_barrier

.LBB0_1784:
	s_ashr_i32 s11, s10, 31
	s_lshl_b64 s[12:13], s[10:11], 20
	s_add_u32 s12, s26, s12
	s_addc_u32 s13, s27, s13
	s_and_b64 s[14:15], s[2:3], exec
	s_cselect_b32 s11, s13, s21
	s_cselect_b32 s64, s12, s20
	s_ashr_i32 s9, s8, 31
	s_lshl_b64 s[14:15], s[8:9], 20
	s_add_u32 s14, s28, s14
	s_addc_u32 s15, s29, s15
	s_and_b64 s[22:23], s[2:3], exec
	s_cselect_b32 s9, s15, s19
	s_cselect_b32 s65, s14, s18
	s_add_u32 s66, s18, 0x100
	s_addc_u32 s67, s19, 0
	s_add_u32 s18, s20, 0x80080
	s_addc_u32 s19, s21, 0
	s_add_u32 s70, s20, 0x100
	s_addc_u32 s71, s21, 0
	s_mov_b32 s73, -2
	ds_read_b128 v[148:151], v143
	ds_read_b128 v[152:155], v143 offset:1024
	ds_read_b128 v[156:159], v143 offset:2048
	ds_read_b128 v[160:163], v143 offset:3072
	ds_read_b128 v[164:167], v144
	ds_read_b128 v[168:171], v144 offset:1024
	ds_read_b128 v[172:175], v144 offset:2048
	ds_read_b128 v[176:179], v144 offset:3072
	s_cmp_eq_u32 s73, 28
	s_cselect_b32 s21, s9, s67
	s_cselect_b32 s20, s65, s66
	s_cselect_b32 s23, s11, s71
	s_cselect_b32 s22, s64, s70
	ds_read_b128 v[180:183], v145
	ds_read_b128 v[184:187], v145 offset:1024
	ds_read_b128 v[188:191], v145 offset:2048
	ds_read_b128 v[192:195], v145 offset:3072
	ds_read_b128 v[196:199], v145 offset:4096
	ds_read_b128 v[200:203], v145 offset:5120
	ds_read_b128 v[204:207], v145 offset:6144
	ds_read_b128 v[208:211], v145 offset:7168
	s_add_u32 s74, s18, 0xfff80000
	s_addc_u32 s75, s19, -1
	s_mov_b32 s76, m0
	s_mov_b32 m0, s56
	s_nop 0
	global_load_lds_dwordx4 v138, s[74:75]
	s_mov_b32 m0, s76
	s_nop 0
	s_mov_b32 s76, m0
	s_mov_b32 m0, s59
	s_nop 0
	global_load_lds_dwordx4 v140, s[74:75]
	s_mov_b32 m0, s76
	s_mov_b32 s74, m0
	s_mov_b32 m0, s57
	s_nop 0
	global_load_lds_dwordx4 v138, s[18:19]
	s_mov_b32 m0, s74
	s_nop 0
	s_mov_b32 s74, m0
	s_mov_b32 m0, s62
	s_nop 0
	global_load_lds_dwordx4 v140, s[18:19]
	s_mov_b32 m0, s74
	s_waitcnt vmcnt(8)
	s_waitcnt lgkmcnt(0)
	s_barrier
	s_setprio 1
	s_waitcnt lgkmcnt(7)
	v_mfma_f32_16x16x32_bf16 v[126:129], v[148:151], v[180:183], 0
	v_mfma_f32_16x16x32_bf16 v[126:129], v[152:155], v[184:187], v[126:129]
	s_waitcnt lgkmcnt(5)
	v_mfma_f32_16x16x32_bf16 v[122:125], v[156:159], v[180:183], 0
	v_mfma_f32_16x16x32_bf16 v[122:125], v[160:163], v[184:187], v[122:125]
	s_waitcnt lgkmcnt(3)
	v_mfma_f32_16x16x32_bf16 v[110:113], v[148:151], v[188:191], 0
	v_mfma_f32_16x16x32_bf16 v[110:113], v[152:155], v[192:195], v[110:113]
	s_waitcnt lgkmcnt(1)
	v_mfma_f32_16x16x32_bf16 v[106:109], v[156:159], v[188:191], 0
	v_mfma_f32_16x16x32_bf16 v[106:109], v[160:163], v[192:195], v[106:109]
	v_mfma_f32_16x16x32_bf16 v[94:97], v[148:151], v[196:199], 0
	v_mfma_f32_16x16x32_bf16 v[94:97], v[152:155], v[200:203], v[94:97]
	v_mfma_f32_16x16x32_bf16 v[90:93], v[156:159], v[196:199], 0
	v_mfma_f32_16x16x32_bf16 v[90:93], v[160:163], v[200:203], v[90:93]
	v_mfma_f32_16x16x32_bf16 v[78:81], v[148:151], v[204:207], 0
	v_mfma_f32_16x16x32_bf16 v[78:81], v[152:155], v[208:211], v[78:81]
	s_waitcnt lgkmcnt(0)
	v_mfma_f32_16x16x32_bf16 v[74:77], v[156:159], v[204:207], 0
	v_mfma_f32_16x16x32_bf16 v[74:77], v[160:163], v[208:211], v[74:77]
	s_setprio 0
	s_setprio 1
	v_mfma_f32_16x16x32_bf16 v[118:121], v[164:167], v[180:183], 0
	v_mfma_f32_16x16x32_bf16 v[118:121], v[168:171], v[184:187], v[118:121]
	v_mfma_f32_16x16x32_bf16 v[114:117], v[172:175], v[180:183], 0
	v_mfma_f32_16x16x32_bf16 v[114:117], v[176:179], v[184:187], v[114:117]
	v_mfma_f32_16x16x32_bf16 v[102:105], v[164:167], v[188:191], 0
	v_mfma_f32_16x16x32_bf16 v[102:105], v[168:171], v[192:195], v[102:105]
	v_mfma_f32_16x16x32_bf16 v[98:101], v[172:175], v[188:191], 0
	v_mfma_f32_16x16x32_bf16 v[98:101], v[176:179], v[192:195], v[98:101]
	v_mfma_f32_16x16x32_bf16 v[86:89], v[164:167], v[196:199], 0
	v_mfma_f32_16x16x32_bf16 v[86:89], v[168:171], v[200:203], v[86:89]
	v_mfma_f32_16x16x32_bf16 v[82:85], v[172:175], v[196:199], 0
	v_mfma_f32_16x16x32_bf16 v[82:85], v[176:179], v[200:203], v[82:85]
	v_mfma_f32_16x16x32_bf16 v[70:73], v[164:167], v[204:207], 0
	v_mfma_f32_16x16x32_bf16 v[70:73], v[168:171], v[208:211], v[70:73]
	s_setprio 2
	s_barrier
	v_mfma_f32_16x16x32_bf16 v[66:69], v[172:175], v[204:207], 0
	v_mfma_f32_16x16x32_bf16 v[66:69], v[176:179], v[208:211], v[66:69]
	s_setprio 0
	ds_read_b128 v[180:183], v145 offset:16384
	ds_read_b128 v[184:187], v145 offset:17408
	ds_read_b128 v[188:191], v145 offset:18432
	ds_read_b128 v[192:195], v145 offset:19456
	ds_read_b128 v[196:199], v145 offset:20480
	ds_read_b128 v[200:203], v145 offset:21504
	ds_read_b128 v[204:207], v145 offset:22528
	ds_read_b128 v[208:211], v145 offset:23552
	s_mov_b32 s74, m0
	s_mov_b32 m0, s35
	s_nop 0
	global_load_lds_dwordx4 v139, s[20:21]
	s_mov_b32 m0, s74
	s_nop 0
	s_mov_b32 s74, m0
	s_mov_b32 m0, s36
	s_nop 0
	global_load_lds_dwordx4 v141, s[20:21]
	s_mov_b32 m0, s74
	s_add_u32 s74, s20, 0x80000
	s_addc_u32 s75, s21, 0
	s_mov_b32 s76, m0
	s_mov_b32 m0, s37
	s_nop 0
	global_load_lds_dwordx4 v139, s[74:75]
	s_mov_b32 m0, s76
	s_nop 0
	s_mov_b32 s76, m0
	s_mov_b32 m0, s40
	s_nop 0
	global_load_lds_dwordx4 v141, s[74:75]
	s_mov_b32 m0, s76
	s_waitcnt vmcnt(4)
	s_waitcnt lgkmcnt(0)
	s_barrier
	s_setprio 1
	s_waitcnt lgkmcnt(7)
	v_mfma_f32_16x16x32_bf16 v[62:65], v[148:151], v[180:183], 0
	v_mfma_f32_16x16x32_bf16 v[62:65], v[152:155], v[184:187], v[62:65]
	s_waitcnt lgkmcnt(5)
	v_mfma_f32_16x16x32_bf16 v[58:61], v[156:159], v[180:183], 0
	v_mfma_f32_16x16x32_bf16 v[58:61], v[160:163], v[184:187], v[58:61]
	s_waitcnt lgkmcnt(3)
	v_mfma_f32_16x16x32_bf16 v[46:49], v[148:151], v[188:191], 0
	v_mfma_f32_16x16x32_bf16 v[46:49], v[152:155], v[192:195], v[46:49]
	s_waitcnt lgkmcnt(1)
	v_mfma_f32_16x16x32_bf16 v[42:45], v[156:159], v[188:191], 0
	v_mfma_f32_16x16x32_bf16 v[42:45], v[160:163], v[192:195], v[42:45]
	v_mfma_f32_16x16x32_bf16 v[30:33], v[148:151], v[196:199], 0
	v_mfma_f32_16x16x32_bf16 v[30:33], v[152:155], v[200:203], v[30:33]
	v_mfma_f32_16x16x32_bf16 v[26:29], v[156:159], v[196:199], 0
	v_mfma_f32_16x16x32_bf16 v[26:29], v[160:163], v[200:203], v[26:29]
	v_mfma_f32_16x16x32_bf16 v[14:17], v[148:151], v[204:207], 0
	v_mfma_f32_16x16x32_bf16 v[14:17], v[152:155], v[208:211], v[14:17]
	s_waitcnt lgkmcnt(0)
	v_mfma_f32_16x16x32_bf16 v[10:13], v[156:159], v[204:207], 0
	v_mfma_f32_16x16x32_bf16 v[10:13], v[160:163], v[208:211], v[10:13]
	s_setprio 0
	s_setprio 1
	v_mfma_f32_16x16x32_bf16 v[54:57], v[164:167], v[180:183], 0
	v_mfma_f32_16x16x32_bf16 v[54:57], v[168:171], v[184:187], v[54:57]
	v_mfma_f32_16x16x32_bf16 v[50:53], v[172:175], v[180:183], 0
	v_mfma_f32_16x16x32_bf16 v[50:53], v[176:179], v[184:187], v[50:53]
	v_mfma_f32_16x16x32_bf16 v[38:41], v[164:167], v[188:191], 0
	v_mfma_f32_16x16x32_bf16 v[38:41], v[168:171], v[192:195], v[38:41]
	v_mfma_f32_16x16x32_bf16 v[34:37], v[172:175], v[188:191], 0
	v_mfma_f32_16x16x32_bf16 v[34:37], v[176:179], v[192:195], v[34:37]
	v_mfma_f32_16x16x32_bf16 v[22:25], v[164:167], v[196:199], 0
	v_mfma_f32_16x16x32_bf16 v[22:25], v[168:171], v[200:203], v[22:25]
	v_mfma_f32_16x16x32_bf16 v[18:21], v[172:175], v[196:199], 0
	v_mfma_f32_16x16x32_bf16 v[18:21], v[176:179], v[200:203], v[18:21]
	v_mfma_f32_16x16x32_bf16 v[6:9], v[164:167], v[204:207], 0
	v_mfma_f32_16x16x32_bf16 v[6:9], v[168:171], v[208:211], v[6:9]
	s_setprio 2
	s_barrier
	v_mfma_f32_16x16x32_bf16 v[2:5], v[172:175], v[204:207], 0
	v_mfma_f32_16x16x32_bf16 v[2:5], v[176:179], v[208:211], v[2:5]
	s_setprio 0
	ds_read_b128 v[148:151], v146
	ds_read_b128 v[152:155], v146 offset:1024
	ds_read_b128 v[156:159], v146 offset:2048
	ds_read_b128 v[160:163], v146 offset:3072
	ds_read_b128 v[164:167], v147
	ds_read_b128 v[168:171], v147 offset:1024
	ds_read_b128 v[172:175], v147 offset:2048
	ds_read_b128 v[176:179], v147 offset:3072
	ds_read_b128 v[180:183], v145 offset:32768
	ds_read_b128 v[184:187], v145 offset:33792
	ds_read_b128 v[188:191], v145 offset:34816
	ds_read_b128 v[192:195], v145 offset:35840
	ds_read_b128 v[196:199], v145 offset:36864
	ds_read_b128 v[200:203], v145 offset:37888
	ds_read_b128 v[204:207], v145 offset:38912
	ds_read_b128 v[208:211], v145 offset:39936
	s_mov_b32 s74, m0
	s_mov_b32 m0, s31
	s_nop 0
	global_load_lds_dwordx4 v138, s[22:23]
	s_mov_b32 m0, s74
	s_nop 0
	s_mov_b32 s74, m0
	s_mov_b32 m0, s41
	s_nop 0
	global_load_lds_dwordx4 v140, s[22:23]
	s_mov_b32 m0, s74
	s_add_u32 s22, s22, 0x80000
	s_addc_u32 s23, s23, 0
	s_mov_b32 s74, m0
	s_mov_b32 m0, s42
	s_nop 0
	global_load_lds_dwordx4 v138, s[22:23]
	s_mov_b32 m0, s74
	s_nop 0
	s_mov_b32 s74, m0
	s_mov_b32 m0, s43
	s_nop 0
	global_load_lds_dwordx4 v140, s[22:23]
	s_mov_b32 m0, s74
	s_waitcnt vmcnt(8)
	s_waitcnt lgkmcnt(0)
	s_barrier
	s_setprio 1
	s_waitcnt lgkmcnt(7)
	v_mfma_f32_16x16x32_bf16 v[126:129], v[148:151], v[180:183], v[126:129]
	v_mfma_f32_16x16x32_bf16 v[126:129], v[152:155], v[184:187], v[126:129]
	s_waitcnt lgkmcnt(5)
	v_mfma_f32_16x16x32_bf16 v[122:125], v[156:159], v[180:183], v[122:125]
	v_mfma_f32_16x16x32_bf16 v[122:125], v[160:163], v[184:187], v[122:125]
	s_waitcnt lgkmcnt(3)
	v_mfma_f32_16x16x32_bf16 v[110:113], v[148:151], v[188:191], v[110:113]
	v_mfma_f32_16x16x32_bf16 v[110:113], v[152:155], v[192:195], v[110:113]
	s_waitcnt lgkmcnt(1)
	v_mfma_f32_16x16x32_bf16 v[106:109], v[156:159], v[188:191], v[106:109]
	v_mfma_f32_16x16x32_bf16 v[106:109], v[160:163], v[192:195], v[106:109]
	v_mfma_f32_16x16x32_bf16 v[94:97], v[148:151], v[196:199], v[94:97]
	v_mfma_f32_16x16x32_bf16 v[94:97], v[152:155], v[200:203], v[94:97]
	v_mfma_f32_16x16x32_bf16 v[90:93], v[156:159], v[196:199], v[90:93]
	v_mfma_f32_16x16x32_bf16 v[90:93], v[160:163], v[200:203], v[90:93]
	v_mfma_f32_16x16x32_bf16 v[78:81], v[148:151], v[204:207], v[78:81]
	v_mfma_f32_16x16x32_bf16 v[78:81], v[152:155], v[208:211], v[78:81]
	s_waitcnt lgkmcnt(0)
	v_mfma_f32_16x16x32_bf16 v[74:77], v[156:159], v[204:207], v[74:77]
	v_mfma_f32_16x16x32_bf16 v[74:77], v[160:163], v[208:211], v[74:77]
	s_setprio 0
	s_setprio 1
	v_mfma_f32_16x16x32_bf16 v[118:121], v[164:167], v[180:183], v[118:121]
	v_mfma_f32_16x16x32_bf16 v[118:121], v[168:171], v[184:187], v[118:121]
	v_mfma_f32_16x16x32_bf16 v[114:117], v[172:175], v[180:183], v[114:117]
	v_mfma_f32_16x16x32_bf16 v[114:117], v[176:179], v[184:187], v[114:117]
	v_mfma_f32_16x16x32_bf16 v[102:105], v[164:167], v[188:191], v[102:105]
	v_mfma_f32_16x16x32_bf16 v[102:105], v[168:171], v[192:195], v[102:105]
	v_mfma_f32_16x16x32_bf16 v[98:101], v[172:175], v[188:191], v[98:101]
	v_mfma_f32_16x16x32_bf16 v[98:101], v[176:179], v[192:195], v[98:101]
	v_mfma_f32_16x16x32_bf16 v[86:89], v[164:167], v[196:199], v[86:89]
	v_mfma_f32_16x16x32_bf16 v[86:89], v[168:171], v[200:203], v[86:89]
	v_mfma_f32_16x16x32_bf16 v[82:85], v[172:175], v[196:199], v[82:85]
	v_mfma_f32_16x16x32_bf16 v[82:85], v[176:179], v[200:203], v[82:85]
	v_mfma_f32_16x16x32_bf16 v[70:73], v[164:167], v[204:207], v[70:73]
	v_mfma_f32_16x16x32_bf16 v[70:73], v[168:171], v[208:211], v[70:73]
	s_setprio 2
	s_barrier
	v_mfma_f32_16x16x32_bf16 v[66:69], v[172:175], v[204:207], v[66:69]
	v_mfma_f32_16x16x32_bf16 v[66:69], v[176:179], v[208:211], v[66:69]
	s_setprio 0
	ds_read_b128 v[180:183], v145 offset:49152
	ds_read_b128 v[184:187], v145 offset:50176
	ds_read_b128 v[188:191], v145 offset:51200
	ds_read_b128 v[192:195], v145 offset:52224
	ds_read_b128 v[196:199], v145 offset:53248
	ds_read_b128 v[200:203], v145 offset:54272
	ds_read_b128 v[204:207], v145 offset:55296
	ds_read_b128 v[208:211], v145 offset:56320
	s_add_u32 s22, s20, 0x80
	s_addc_u32 s23, s21, 0
	s_mov_b32 s74, m0
	s_mov_b32 m0, s46
	s_nop 0
	global_load_lds_dwordx4 v139, s[22:23]
	s_mov_b32 m0, s74
	s_add_u32 s20, s20, 0x80080
	s_mov_b32 s74, m0
	s_mov_b32 m0, s47
	s_nop 0
	global_load_lds_dwordx4 v141, s[22:23]
	s_mov_b32 m0, s74
	s_addc_u32 s21, s21, 0
	s_mov_b32 s22, m0
	s_mov_b32 m0, s48
	s_nop 0
	global_load_lds_dwordx4 v139, s[20:21]
	s_mov_b32 m0, s22
	s_nop 0
	s_mov_b32 s22, m0
	s_mov_b32 m0, s49
	s_nop 0
	global_load_lds_dwordx4 v141, s[20:21]
	s_mov_b32 m0, s22
	s_waitcnt vmcnt(4)
	s_waitcnt lgkmcnt(0)
	s_barrier
	s_setprio 1
	s_waitcnt lgkmcnt(7)
	v_mfma_f32_16x16x32_bf16 v[62:65], v[148:151], v[180:183], v[62:65]
	v_mfma_f32_16x16x32_bf16 v[62:65], v[152:155], v[184:187], v[62:65]
	s_waitcnt lgkmcnt(5)
	v_mfma_f32_16x16x32_bf16 v[58:61], v[156:159], v[180:183], v[58:61]
	v_mfma_f32_16x16x32_bf16 v[58:61], v[160:163], v[184:187], v[58:61]
	s_waitcnt lgkmcnt(3)
	v_mfma_f32_16x16x32_bf16 v[46:49], v[148:151], v[188:191], v[46:49]
	v_mfma_f32_16x16x32_bf16 v[46:49], v[152:155], v[192:195], v[46:49]
	s_waitcnt lgkmcnt(1)
	v_mfma_f32_16x16x32_bf16 v[42:45], v[156:159], v[188:191], v[42:45]
	v_mfma_f32_16x16x32_bf16 v[42:45], v[160:163], v[192:195], v[42:45]
	v_mfma_f32_16x16x32_bf16 v[30:33], v[148:151], v[196:199], v[30:33]
	v_mfma_f32_16x16x32_bf16 v[30:33], v[152:155], v[200:203], v[30:33]
	v_mfma_f32_16x16x32_bf16 v[26:29], v[156:159], v[196:199], v[26:29]
	v_mfma_f32_16x16x32_bf16 v[26:29], v[160:163], v[200:203], v[26:29]
	v_mfma_f32_16x16x32_bf16 v[14:17], v[148:151], v[204:207], v[14:17]
	v_mfma_f32_16x16x32_bf16 v[14:17], v[152:155], v[208:211], v[14:17]
	s_waitcnt lgkmcnt(0)
	v_mfma_f32_16x16x32_bf16 v[10:13], v[156:159], v[204:207], v[10:13]
	v_mfma_f32_16x16x32_bf16 v[10:13], v[160:163], v[208:211], v[10:13]
	s_setprio 0
	s_setprio 1
	v_mfma_f32_16x16x32_bf16 v[54:57], v[164:167], v[180:183], v[54:57]
	v_mfma_f32_16x16x32_bf16 v[54:57], v[168:171], v[184:187], v[54:57]
	v_mfma_f32_16x16x32_bf16 v[50:53], v[172:175], v[180:183], v[50:53]
	v_mfma_f32_16x16x32_bf16 v[50:53], v[176:179], v[184:187], v[50:53]
	v_mfma_f32_16x16x32_bf16 v[38:41], v[164:167], v[188:191], v[38:41]
	v_mfma_f32_16x16x32_bf16 v[38:41], v[168:171], v[192:195], v[38:41]
	v_mfma_f32_16x16x32_bf16 v[34:37], v[172:175], v[188:191], v[34:37]
	v_mfma_f32_16x16x32_bf16 v[34:37], v[176:179], v[192:195], v[34:37]
	v_mfma_f32_16x16x32_bf16 v[22:25], v[164:167], v[196:199], v[22:25]
	v_mfma_f32_16x16x32_bf16 v[22:25], v[168:171], v[200:203], v[22:25]
	v_mfma_f32_16x16x32_bf16 v[18:21], v[172:175], v[196:199], v[18:21]
	v_mfma_f32_16x16x32_bf16 v[18:21], v[176:179], v[200:203], v[18:21]
	v_mfma_f32_16x16x32_bf16 v[6:9], v[164:167], v[204:207], v[6:9]
	v_mfma_f32_16x16x32_bf16 v[6:9], v[168:171], v[208:211], v[6:9]
	s_setprio 2
	s_barrier
	v_mfma_f32_16x16x32_bf16 v[2:5], v[172:175], v[204:207], v[2:5]
	v_mfma_f32_16x16x32_bf16 v[2:5], v[176:179], v[208:211], v[2:5]
	s_setprio 0
	s_add_i32 s73, s73, 2
	s_add_u32 s66, s66, 0x100
	s_addc_u32 s67, s67, 0
	s_add_u32 s18, s18, 0x100
	s_addc_u32 s19, s19, 0
	s_add_u32 s70, s70, 0x100
	s_addc_u32 s71, s71, 0
	s_cmp_gt_u32 s73, 29
	.p2align 6
.LBB0_1785:
	ds_read_b128 v[148:151], v143
	ds_read_b128 v[152:155], v143 offset:1024
	ds_read_b128 v[156:159], v143 offset:2048
	ds_read_b128 v[160:163], v143 offset:3072
	ds_read_b128 v[164:167], v144
	ds_read_b128 v[168:171], v144 offset:1024
	ds_read_b128 v[172:175], v144 offset:2048
	ds_read_b128 v[176:179], v144 offset:3072
	s_cmp_eq_u32 s73, 28
	s_cselect_b32 s21, s9, s67
	s_cselect_b32 s20, s65, s66
	s_cselect_b32 s23, s11, s71
	s_cselect_b32 s22, s64, s70
	ds_read_b128 v[180:183], v145
	ds_read_b128 v[184:187], v145 offset:1024
	ds_read_b128 v[188:191], v145 offset:2048
	ds_read_b128 v[192:195], v145 offset:3072
	ds_read_b128 v[196:199], v145 offset:4096
	ds_read_b128 v[200:203], v145 offset:5120
	ds_read_b128 v[204:207], v145 offset:6144
	ds_read_b128 v[208:211], v145 offset:7168
	s_add_u32 s74, s18, 0xfff80000
	s_addc_u32 s75, s19, -1
	s_mov_b32 s76, m0
	s_mov_b32 m0, s56
	s_nop 0
	global_load_lds_dwordx4 v138, s[74:75]
	s_mov_b32 m0, s76
	s_nop 0
	s_mov_b32 s76, m0
	s_mov_b32 m0, s59
	s_nop 0
	global_load_lds_dwordx4 v140, s[74:75]
	s_mov_b32 m0, s76
	s_mov_b32 s74, m0
	s_mov_b32 m0, s57
	s_nop 0
	global_load_lds_dwordx4 v138, s[18:19]
	s_mov_b32 m0, s74
	s_nop 0
	s_mov_b32 s74, m0
	s_mov_b32 m0, s62
	s_nop 0
	global_load_lds_dwordx4 v140, s[18:19]
	s_mov_b32 m0, s74
	s_waitcnt vmcnt(8)
	s_waitcnt lgkmcnt(0)
	s_barrier
	s_setprio 1
	s_waitcnt lgkmcnt(7)
	v_mfma_f32_16x16x32_bf16 v[126:129], v[148:151], v[180:183], v[126:129]
	v_mfma_f32_16x16x32_bf16 v[126:129], v[152:155], v[184:187], v[126:129]
	s_waitcnt lgkmcnt(5)
	v_mfma_f32_16x16x32_bf16 v[122:125], v[156:159], v[180:183], v[122:125]
	v_mfma_f32_16x16x32_bf16 v[122:125], v[160:163], v[184:187], v[122:125]
	s_waitcnt lgkmcnt(3)
	v_mfma_f32_16x16x32_bf16 v[110:113], v[148:151], v[188:191], v[110:113]
	v_mfma_f32_16x16x32_bf16 v[110:113], v[152:155], v[192:195], v[110:113]
	s_waitcnt lgkmcnt(1)
	v_mfma_f32_16x16x32_bf16 v[106:109], v[156:159], v[188:191], v[106:109]
	v_mfma_f32_16x16x32_bf16 v[106:109], v[160:163], v[192:195], v[106:109]
	v_mfma_f32_16x16x32_bf16 v[94:97], v[148:151], v[196:199], v[94:97]
	v_mfma_f32_16x16x32_bf16 v[94:97], v[152:155], v[200:203], v[94:97]
	v_mfma_f32_16x16x32_bf16 v[90:93], v[156:159], v[196:199], v[90:93]
	v_mfma_f32_16x16x32_bf16 v[90:93], v[160:163], v[200:203], v[90:93]
	v_mfma_f32_16x16x32_bf16 v[78:81], v[148:151], v[204:207], v[78:81]
	v_mfma_f32_16x16x32_bf16 v[78:81], v[152:155], v[208:211], v[78:81]
	s_waitcnt lgkmcnt(0)
	v_mfma_f32_16x16x32_bf16 v[74:77], v[156:159], v[204:207], v[74:77]
	v_mfma_f32_16x16x32_bf16 v[74:77], v[160:163], v[208:211], v[74:77]
	s_setprio 0
	s_setprio 1
	v_mfma_f32_16x16x32_bf16 v[118:121], v[164:167], v[180:183], v[118:121]
	v_mfma_f32_16x16x32_bf16 v[118:121], v[168:171], v[184:187], v[118:121]
	v_mfma_f32_16x16x32_bf16 v[114:117], v[172:175], v[180:183], v[114:117]
	v_mfma_f32_16x16x32_bf16 v[114:117], v[176:179], v[184:187], v[114:117]
	v_mfma_f32_16x16x32_bf16 v[102:105], v[164:167], v[188:191], v[102:105]
	v_mfma_f32_16x16x32_bf16 v[102:105], v[168:171], v[192:195], v[102:105]
	v_mfma_f32_16x16x32_bf16 v[98:101], v[172:175], v[188:191], v[98:101]
	v_mfma_f32_16x16x32_bf16 v[98:101], v[176:179], v[192:195], v[98:101]
	v_mfma_f32_16x16x32_bf16 v[86:89], v[164:167], v[196:199], v[86:89]
	v_mfma_f32_16x16x32_bf16 v[86:89], v[168:171], v[200:203], v[86:89]
	v_mfma_f32_16x16x32_bf16 v[82:85], v[172:175], v[196:199], v[82:85]
	v_mfma_f32_16x16x32_bf16 v[82:85], v[176:179], v[200:203], v[82:85]
	v_mfma_f32_16x16x32_bf16 v[70:73], v[164:167], v[204:207], v[70:73]
	v_mfma_f32_16x16x32_bf16 v[70:73], v[168:171], v[208:211], v[70:73]
	s_setprio 2
	s_barrier
	v_mfma_f32_16x16x32_bf16 v[66:69], v[172:175], v[204:207], v[66:69]
	v_mfma_f32_16x16x32_bf16 v[66:69], v[176:179], v[208:211], v[66:69]
	s_setprio 0
	ds_read_b128 v[180:183], v145 offset:16384
	ds_read_b128 v[184:187], v145 offset:17408
	ds_read_b128 v[188:191], v145 offset:18432
	ds_read_b128 v[192:195], v145 offset:19456
	ds_read_b128 v[196:199], v145 offset:20480
	ds_read_b128 v[200:203], v145 offset:21504
	ds_read_b128 v[204:207], v145 offset:22528
	ds_read_b128 v[208:211], v145 offset:23552
	s_mov_b32 s74, m0
	s_mov_b32 m0, s35
	s_nop 0
	global_load_lds_dwordx4 v139, s[20:21]
	s_mov_b32 m0, s74
	s_nop 0
	s_mov_b32 s74, m0
	s_mov_b32 m0, s36
	s_nop 0
	global_load_lds_dwordx4 v141, s[20:21]
	s_mov_b32 m0, s74
	s_add_u32 s74, s20, 0x80000
	s_addc_u32 s75, s21, 0
	s_mov_b32 s76, m0
	s_mov_b32 m0, s37
	s_nop 0
	global_load_lds_dwordx4 v139, s[74:75]
	s_mov_b32 m0, s76
	s_nop 0
	s_mov_b32 s76, m0
	s_mov_b32 m0, s40
	s_nop 0
	global_load_lds_dwordx4 v141, s[74:75]
	s_mov_b32 m0, s76
	s_waitcnt vmcnt(4)
	s_waitcnt lgkmcnt(0)
	s_barrier
	s_setprio 1
	s_waitcnt lgkmcnt(7)
	v_mfma_f32_16x16x32_bf16 v[62:65], v[148:151], v[180:183], v[62:65]
	v_mfma_f32_16x16x32_bf16 v[62:65], v[152:155], v[184:187], v[62:65]
	s_waitcnt lgkmcnt(5)
	v_mfma_f32_16x16x32_bf16 v[58:61], v[156:159], v[180:183], v[58:61]
	v_mfma_f32_16x16x32_bf16 v[58:61], v[160:163], v[184:187], v[58:61]
	s_waitcnt lgkmcnt(3)
	v_mfma_f32_16x16x32_bf16 v[46:49], v[148:151], v[188:191], v[46:49]
	v_mfma_f32_16x16x32_bf16 v[46:49], v[152:155], v[192:195], v[46:49]
	s_waitcnt lgkmcnt(1)
	v_mfma_f32_16x16x32_bf16 v[42:45], v[156:159], v[188:191], v[42:45]
	v_mfma_f32_16x16x32_bf16 v[42:45], v[160:163], v[192:195], v[42:45]
	v_mfma_f32_16x16x32_bf16 v[30:33], v[148:151], v[196:199], v[30:33]
	v_mfma_f32_16x16x32_bf16 v[30:33], v[152:155], v[200:203], v[30:33]
	v_mfma_f32_16x16x32_bf16 v[26:29], v[156:159], v[196:199], v[26:29]
	v_mfma_f32_16x16x32_bf16 v[26:29], v[160:163], v[200:203], v[26:29]
	v_mfma_f32_16x16x32_bf16 v[14:17], v[148:151], v[204:207], v[14:17]
	v_mfma_f32_16x16x32_bf16 v[14:17], v[152:155], v[208:211], v[14:17]
	s_waitcnt lgkmcnt(0)
	v_mfma_f32_16x16x32_bf16 v[10:13], v[156:159], v[204:207], v[10:13]
	v_mfma_f32_16x16x32_bf16 v[10:13], v[160:163], v[208:211], v[10:13]
	s_setprio 0
	s_setprio 1
	v_mfma_f32_16x16x32_bf16 v[54:57], v[164:167], v[180:183], v[54:57]
	v_mfma_f32_16x16x32_bf16 v[54:57], v[168:171], v[184:187], v[54:57]
	v_mfma_f32_16x16x32_bf16 v[50:53], v[172:175], v[180:183], v[50:53]
	v_mfma_f32_16x16x32_bf16 v[50:53], v[176:179], v[184:187], v[50:53]
	v_mfma_f32_16x16x32_bf16 v[38:41], v[164:167], v[188:191], v[38:41]
	v_mfma_f32_16x16x32_bf16 v[38:41], v[168:171], v[192:195], v[38:41]
	v_mfma_f32_16x16x32_bf16 v[34:37], v[172:175], v[188:191], v[34:37]
	v_mfma_f32_16x16x32_bf16 v[34:37], v[176:179], v[192:195], v[34:37]
	v_mfma_f32_16x16x32_bf16 v[22:25], v[164:167], v[196:199], v[22:25]
	v_mfma_f32_16x16x32_bf16 v[22:25], v[168:171], v[200:203], v[22:25]
	v_mfma_f32_16x16x32_bf16 v[18:21], v[172:175], v[196:199], v[18:21]
	v_mfma_f32_16x16x32_bf16 v[18:21], v[176:179], v[200:203], v[18:21]
	v_mfma_f32_16x16x32_bf16 v[6:9], v[164:167], v[204:207], v[6:9]
	v_mfma_f32_16x16x32_bf16 v[6:9], v[168:171], v[208:211], v[6:9]
	s_setprio 2
	s_barrier
	v_mfma_f32_16x16x32_bf16 v[2:5], v[172:175], v[204:207], v[2:5]
	v_mfma_f32_16x16x32_bf16 v[2:5], v[176:179], v[208:211], v[2:5]
	s_setprio 0
	ds_read_b128 v[148:151], v146
	ds_read_b128 v[152:155], v146 offset:1024
	ds_read_b128 v[156:159], v146 offset:2048
	ds_read_b128 v[160:163], v146 offset:3072
	ds_read_b128 v[164:167], v147
	ds_read_b128 v[168:171], v147 offset:1024
	ds_read_b128 v[172:175], v147 offset:2048
	ds_read_b128 v[176:179], v147 offset:3072
	ds_read_b128 v[180:183], v145 offset:32768
	ds_read_b128 v[184:187], v145 offset:33792
	ds_read_b128 v[188:191], v145 offset:34816
	ds_read_b128 v[192:195], v145 offset:35840
	ds_read_b128 v[196:199], v145 offset:36864
	ds_read_b128 v[200:203], v145 offset:37888
	ds_read_b128 v[204:207], v145 offset:38912
	ds_read_b128 v[208:211], v145 offset:39936
	s_mov_b32 s74, m0
	s_mov_b32 m0, s31
	s_nop 0
	global_load_lds_dwordx4 v138, s[22:23]
	s_mov_b32 m0, s74
	s_nop 0
	s_mov_b32 s74, m0
	s_mov_b32 m0, s41
	s_nop 0
	global_load_lds_dwordx4 v140, s[22:23]
	s_mov_b32 m0, s74
	s_add_u32 s22, s22, 0x80000
	s_addc_u32 s23, s23, 0
	s_mov_b32 s74, m0
	s_mov_b32 m0, s42
	s_nop 0
	global_load_lds_dwordx4 v138, s[22:23]
	s_mov_b32 m0, s74
	s_nop 0
	s_mov_b32 s74, m0
	s_mov_b32 m0, s43
	s_nop 0
	global_load_lds_dwordx4 v140, s[22:23]
	s_mov_b32 m0, s74
	s_waitcnt vmcnt(8)
	s_waitcnt lgkmcnt(0)
	s_barrier
	s_setprio 1
	s_waitcnt lgkmcnt(7)
	v_mfma_f32_16x16x32_bf16 v[126:129], v[148:151], v[180:183], v[126:129]
	v_mfma_f32_16x16x32_bf16 v[126:129], v[152:155], v[184:187], v[126:129]
	s_waitcnt lgkmcnt(5)
	v_mfma_f32_16x16x32_bf16 v[122:125], v[156:159], v[180:183], v[122:125]
	v_mfma_f32_16x16x32_bf16 v[122:125], v[160:163], v[184:187], v[122:125]
	s_waitcnt lgkmcnt(3)
	v_mfma_f32_16x16x32_bf16 v[110:113], v[148:151], v[188:191], v[110:113]
	v_mfma_f32_16x16x32_bf16 v[110:113], v[152:155], v[192:195], v[110:113]
	s_waitcnt lgkmcnt(1)
	v_mfma_f32_16x16x32_bf16 v[106:109], v[156:159], v[188:191], v[106:109]
	v_mfma_f32_16x16x32_bf16 v[106:109], v[160:163], v[192:195], v[106:109]
	v_mfma_f32_16x16x32_bf16 v[94:97], v[148:151], v[196:199], v[94:97]
	v_mfma_f32_16x16x32_bf16 v[94:97], v[152:155], v[200:203], v[94:97]
	v_mfma_f32_16x16x32_bf16 v[90:93], v[156:159], v[196:199], v[90:93]
	v_mfma_f32_16x16x32_bf16 v[90:93], v[160:163], v[200:203], v[90:93]
	v_mfma_f32_16x16x32_bf16 v[78:81], v[148:151], v[204:207], v[78:81]
	v_mfma_f32_16x16x32_bf16 v[78:81], v[152:155], v[208:211], v[78:81]
	s_waitcnt lgkmcnt(0)
	v_mfma_f32_16x16x32_bf16 v[74:77], v[156:159], v[204:207], v[74:77]
	v_mfma_f32_16x16x32_bf16 v[74:77], v[160:163], v[208:211], v[74:77]
	s_setprio 0
	s_setprio 1
	v_mfma_f32_16x16x32_bf16 v[118:121], v[164:167], v[180:183], v[118:121]
	v_mfma_f32_16x16x32_bf16 v[118:121], v[168:171], v[184:187], v[118:121]
	v_mfma_f32_16x16x32_bf16 v[114:117], v[172:175], v[180:183], v[114:117]
	v_mfma_f32_16x16x32_bf16 v[114:117], v[176:179], v[184:187], v[114:117]
	v_mfma_f32_16x16x32_bf16 v[102:105], v[164:167], v[188:191], v[102:105]
	v_mfma_f32_16x16x32_bf16 v[102:105], v[168:171], v[192:195], v[102:105]
	v_mfma_f32_16x16x32_bf16 v[98:101], v[172:175], v[188:191], v[98:101]
	v_mfma_f32_16x16x32_bf16 v[98:101], v[176:179], v[192:195], v[98:101]
	v_mfma_f32_16x16x32_bf16 v[86:89], v[164:167], v[196:199], v[86:89]
	v_mfma_f32_16x16x32_bf16 v[86:89], v[168:171], v[200:203], v[86:89]
	v_mfma_f32_16x16x32_bf16 v[82:85], v[172:175], v[196:199], v[82:85]
	v_mfma_f32_16x16x32_bf16 v[82:85], v[176:179], v[200:203], v[82:85]
	v_mfma_f32_16x16x32_bf16 v[70:73], v[164:167], v[204:207], v[70:73]
	v_mfma_f32_16x16x32_bf16 v[70:73], v[168:171], v[208:211], v[70:73]
	s_setprio 2
	s_barrier
	v_mfma_f32_16x16x32_bf16 v[66:69], v[172:175], v[204:207], v[66:69]
	v_mfma_f32_16x16x32_bf16 v[66:69], v[176:179], v[208:211], v[66:69]
	s_setprio 0
	ds_read_b128 v[180:183], v145 offset:49152
	ds_read_b128 v[184:187], v145 offset:50176
	ds_read_b128 v[188:191], v145 offset:51200
	ds_read_b128 v[192:195], v145 offset:52224
	ds_read_b128 v[196:199], v145 offset:53248
	ds_read_b128 v[200:203], v145 offset:54272
	ds_read_b128 v[204:207], v145 offset:55296
	ds_read_b128 v[208:211], v145 offset:56320
	s_add_u32 s22, s20, 0x80
	s_addc_u32 s23, s21, 0
	s_mov_b32 s74, m0
	s_mov_b32 m0, s46
	s_nop 0
	global_load_lds_dwordx4 v139, s[22:23]
	s_mov_b32 m0, s74
	s_add_u32 s20, s20, 0x80080
	s_mov_b32 s74, m0
	s_mov_b32 m0, s47
	s_nop 0
	global_load_lds_dwordx4 v141, s[22:23]
	s_mov_b32 m0, s74
	s_addc_u32 s21, s21, 0
	s_mov_b32 s22, m0
	s_mov_b32 m0, s48
	s_nop 0
	global_load_lds_dwordx4 v139, s[20:21]
	s_mov_b32 m0, s22
	s_nop 0
	s_mov_b32 s22, m0
	s_mov_b32 m0, s49
	s_nop 0
	global_load_lds_dwordx4 v141, s[20:21]
	s_mov_b32 m0, s22
	s_waitcnt vmcnt(4)
	s_waitcnt lgkmcnt(0)
	s_barrier
	s_setprio 1
	s_waitcnt lgkmcnt(7)
	v_mfma_f32_16x16x32_bf16 v[62:65], v[148:151], v[180:183], v[62:65]
	v_mfma_f32_16x16x32_bf16 v[62:65], v[152:155], v[184:187], v[62:65]
	s_waitcnt lgkmcnt(5)
	v_mfma_f32_16x16x32_bf16 v[58:61], v[156:159], v[180:183], v[58:61]
	v_mfma_f32_16x16x32_bf16 v[58:61], v[160:163], v[184:187], v[58:61]
	s_waitcnt lgkmcnt(3)
	v_mfma_f32_16x16x32_bf16 v[46:49], v[148:151], v[188:191], v[46:49]
	v_mfma_f32_16x16x32_bf16 v[46:49], v[152:155], v[192:195], v[46:49]
	s_waitcnt lgkmcnt(1)
	v_mfma_f32_16x16x32_bf16 v[42:45], v[156:159], v[188:191], v[42:45]
	v_mfma_f32_16x16x32_bf16 v[42:45], v[160:163], v[192:195], v[42:45]
	v_mfma_f32_16x16x32_bf16 v[30:33], v[148:151], v[196:199], v[30:33]
	v_mfma_f32_16x16x32_bf16 v[30:33], v[152:155], v[200:203], v[30:33]
	v_mfma_f32_16x16x32_bf16 v[26:29], v[156:159], v[196:199], v[26:29]
	v_mfma_f32_16x16x32_bf16 v[26:29], v[160:163], v[200:203], v[26:29]
	v_mfma_f32_16x16x32_bf16 v[14:17], v[148:151], v[204:207], v[14:17]
	v_mfma_f32_16x16x32_bf16 v[14:17], v[152:155], v[208:211], v[14:17]
	s_waitcnt lgkmcnt(0)
	v_mfma_f32_16x16x32_bf16 v[10:13], v[156:159], v[204:207], v[10:13]
	v_mfma_f32_16x16x32_bf16 v[10:13], v[160:163], v[208:211], v[10:13]
	s_setprio 0
	s_setprio 1
	v_mfma_f32_16x16x32_bf16 v[54:57], v[164:167], v[180:183], v[54:57]
	v_mfma_f32_16x16x32_bf16 v[54:57], v[168:171], v[184:187], v[54:57]
	v_mfma_f32_16x16x32_bf16 v[50:53], v[172:175], v[180:183], v[50:53]
	v_mfma_f32_16x16x32_bf16 v[50:53], v[176:179], v[184:187], v[50:53]
	v_mfma_f32_16x16x32_bf16 v[38:41], v[164:167], v[188:191], v[38:41]
	v_mfma_f32_16x16x32_bf16 v[38:41], v[168:171], v[192:195], v[38:41]
	v_mfma_f32_16x16x32_bf16 v[34:37], v[172:175], v[188:191], v[34:37]
	v_mfma_f32_16x16x32_bf16 v[34:37], v[176:179], v[192:195], v[34:37]
	v_mfma_f32_16x16x32_bf16 v[22:25], v[164:167], v[196:199], v[22:25]
	v_mfma_f32_16x16x32_bf16 v[22:25], v[168:171], v[200:203], v[22:25]
	v_mfma_f32_16x16x32_bf16 v[18:21], v[172:175], v[196:199], v[18:21]
	v_mfma_f32_16x16x32_bf16 v[18:21], v[176:179], v[200:203], v[18:21]
	v_mfma_f32_16x16x32_bf16 v[6:9], v[164:167], v[204:207], v[6:9]
	v_mfma_f32_16x16x32_bf16 v[6:9], v[168:171], v[208:211], v[6:9]
	s_setprio 2
	s_barrier
	v_mfma_f32_16x16x32_bf16 v[2:5], v[172:175], v[204:207], v[2:5]
	v_mfma_f32_16x16x32_bf16 v[2:5], v[176:179], v[208:211], v[2:5]
	s_setprio 0
	s_add_i32 s73, s73, 2
	s_add_u32 s66, s66, 0x100
	s_addc_u32 s67, s67, 0
	s_add_u32 s18, s18, 0x100
	s_addc_u32 s19, s19, 0
	s_add_u32 s70, s70, 0x100
	s_addc_u32 s71, s71, 0
	s_cmp_gt_u32 s73, 29
	s_cbranch_scc0 .LBB0_1785
	s_and_b64 vcc, exec, s[6:7]
	s_cbranch_vccz .LBB0_1788
	s_barrier

.LBB0_1951:
	s_ashr_i32 s13, s12, 31
	s_lshl_b64 s[14:15], s[12:13], 15
	s_add_u32 s14, s28, s14
	s_addc_u32 s15, s29, s15
	s_and_b64 s[16:17], s[2:3], exec
	s_cselect_b32 s13, s15, s23
	s_cselect_b32 s65, s14, s22
	s_ashr_i32 s11, s10, 31
	s_lshl_b64 s[16:17], s[10:11], 15
	s_add_u32 s16, s30, s16
	s_addc_u32 s17, s31, s17
	s_and_b64 s[24:25], s[2:3], exec
	s_cselect_b32 s11, s17, s21
	s_cselect_b32 s66, s16, s20
	s_add_u32 s67, s20, 0x80000
	s_addc_u32 s70, s21, 0
	s_add_u32 s20, s22, 0x204000
	s_addc_u32 s21, s23, 0
	s_add_u32 s71, s22, 0x400000
	s_addc_u32 s73, s23, 0
	s_mov_b32 s74, -2
	s_waitcnt vmcnt(25)
	s_waitcnt vmcnt(24)
	s_waitcnt vmcnt(4)
	s_waitcnt vmcnt(2)
	s_waitcnt vmcnt(1)
	s_waitcnt vmcnt(0)
	ds_read_b128 v[130:133], v181
	ds_read_b128 v[134:137], v181 offset:1024
	ds_read_b128 v[138:141], v181 offset:2048
	ds_read_b128 v[142:145], v181 offset:3072
	ds_read_b128 v[150:153], v182
	ds_read_b128 v[154:157], v182 offset:1024
	ds_read_b128 v[158:161], v182 offset:2048
	ds_read_b128 v[162:165], v182 offset:3072
	s_cmpk_eq_i32 s74, 0x52
	s_cselect_b32 s23, s11, s70
	s_cselect_b32 s22, s66, s67
	s_cselect_b32 s25, s13, s73
	s_cselect_b32 s24, s65, s71
	ds_read_b128 v[166:169], v183
	ds_read_b128 v[170:173], v183 offset:1024
	ds_read_b128 v[186:189], v183 offset:2048
	ds_read_b128 v[190:193], v183 offset:3072
	ds_read_b128 v[194:197], v183 offset:4096
	ds_read_b128 v[198:201], v183 offset:5120
	ds_read_b128 v[202:205], v183 offset:6144
	ds_read_b128 v[206:209], v183 offset:7168
	s_add_u32 s76, s20, 0xffffc000
	s_addc_u32 s77, s21, -1
	s_mov_b32 s75, m0
	s_mov_b32 m0, s58
	s_nop 0
	global_load_lds_dwordx4 v1, s[76:77]
	s_mov_b32 m0, s75
	s_nop 0
	s_mov_b32 s75, m0
	s_mov_b32 m0, s62
	s_nop 0
	global_load_lds_dwordx4 v177, s[76:77]
	s_mov_b32 m0, s75
	s_nop 0
	s_mov_b32 s75, m0
	s_mov_b32 m0, s59
	s_nop 0
	global_load_lds_dwordx4 v1, s[20:21]
	s_mov_b32 m0, s75
	s_nop 0
	s_mov_b32 s75, m0
	s_mov_b32 m0, s63
	s_nop 0
	global_load_lds_dwordx4 v177, s[20:21]
	s_mov_b32 m0, s75
	s_waitcnt vmcnt(8)
	s_waitcnt lgkmcnt(0)
	s_barrier
	s_setprio 1
	s_waitcnt lgkmcnt(7)
	v_mfma_f32_16x16x32_bf16 v[126:129], v[130:133], v[166:169], 0
	v_mfma_f32_16x16x32_bf16 v[126:129], v[134:137], v[170:173], v[126:129]
	s_waitcnt lgkmcnt(5)
	v_mfma_f32_16x16x32_bf16 v[122:125], v[138:141], v[166:169], 0
	v_mfma_f32_16x16x32_bf16 v[122:125], v[142:145], v[170:173], v[122:125]
	s_waitcnt lgkmcnt(3)
	v_mfma_f32_16x16x32_bf16 v[118:121], v[130:133], v[186:189], 0
	v_mfma_f32_16x16x32_bf16 v[118:121], v[134:137], v[190:193], v[118:121]
	s_waitcnt lgkmcnt(1)
	v_mfma_f32_16x16x32_bf16 v[110:113], v[138:141], v[186:189], 0
	v_mfma_f32_16x16x32_bf16 v[110:113], v[142:145], v[190:193], v[110:113]
	v_mfma_f32_16x16x32_bf16 v[94:97], v[130:133], v[194:197], 0
	v_mfma_f32_16x16x32_bf16 v[94:97], v[134:137], v[198:201], v[94:97]
	v_mfma_f32_16x16x32_bf16 v[90:93], v[138:141], v[194:197], 0
	v_mfma_f32_16x16x32_bf16 v[90:93], v[142:145], v[198:201], v[90:93]
	v_mfma_f32_16x16x32_bf16 v[86:89], v[130:133], v[202:205], 0
	v_mfma_f32_16x16x32_bf16 v[86:89], v[134:137], v[206:209], v[86:89]
	s_waitcnt lgkmcnt(0)
	v_mfma_f32_16x16x32_bf16 v[78:81], v[138:141], v[202:205], 0
	v_mfma_f32_16x16x32_bf16 v[78:81], v[142:145], v[206:209], v[78:81]
	s_setprio 0
	s_setprio 1
	v_mfma_f32_16x16x32_bf16 v[114:117], v[150:153], v[166:169], 0
	v_mfma_f32_16x16x32_bf16 v[114:117], v[154:157], v[170:173], v[114:117]
	v_mfma_f32_16x16x32_bf16 v[106:109], v[158:161], v[166:169], 0
	v_mfma_f32_16x16x32_bf16 v[106:109], v[162:165], v[170:173], v[106:109]
	v_mfma_f32_16x16x32_bf16 v[102:105], v[150:153], v[186:189], 0
	v_mfma_f32_16x16x32_bf16 v[102:105], v[154:157], v[190:193], v[102:105]
	v_mfma_f32_16x16x32_bf16 v[98:101], v[158:161], v[186:189], 0
	v_mfma_f32_16x16x32_bf16 v[98:101], v[162:165], v[190:193], v[98:101]
	v_mfma_f32_16x16x32_bf16 v[82:85], v[150:153], v[194:197], 0
	v_mfma_f32_16x16x32_bf16 v[82:85], v[154:157], v[198:201], v[82:85]
	v_mfma_f32_16x16x32_bf16 v[74:77], v[158:161], v[194:197], 0
	v_mfma_f32_16x16x32_bf16 v[74:77], v[162:165], v[198:201], v[74:77]
	v_mfma_f32_16x16x32_bf16 v[70:73], v[150:153], v[202:205], 0
	v_mfma_f32_16x16x32_bf16 v[70:73], v[154:157], v[206:209], v[70:73]
	s_setprio 2
	s_barrier
	v_mfma_f32_16x16x32_bf16 v[66:69], v[158:161], v[202:205], 0
	v_mfma_f32_16x16x32_bf16 v[66:69], v[162:165], v[206:209], v[66:69]
	s_setprio 0
	ds_read_b128 v[166:169], v183 offset:16384
	ds_read_b128 v[170:173], v183 offset:17408
	ds_read_b128 v[186:189], v183 offset:18432
	ds_read_b128 v[190:193], v183 offset:19456
	ds_read_b128 v[194:197], v183 offset:20480
	ds_read_b128 v[198:201], v183 offset:21504
	ds_read_b128 v[202:205], v183 offset:22528
	ds_read_b128 v[206:209], v183 offset:23552
	s_mov_b32 s75, m0
	s_mov_b32 m0, s35
	s_nop 0
	global_load_lds_dwordx4 v176, s[22:23]
	s_mov_b32 m0, s75
	s_add_u32 s76, s22, 0x4000
	s_mov_b32 s75, m0
	s_mov_b32 m0, s36
	s_nop 0
	global_load_lds_dwordx4 v178, s[22:23]
	s_mov_b32 m0, s75
	s_addc_u32 s77, s23, 0
	s_mov_b32 s75, m0
	s_mov_b32 m0, s37
	s_nop 0
	global_load_lds_dwordx4 v176, s[76:77]
	s_mov_b32 m0, s75
	s_nop 0
	s_mov_b32 s75, m0
	s_mov_b32 m0, s40
	s_nop 0
	global_load_lds_dwordx4 v178, s[76:77]
	s_mov_b32 m0, s75
	s_waitcnt vmcnt(4)
	s_waitcnt lgkmcnt(0)
	s_barrier
	s_setprio 1
	s_waitcnt lgkmcnt(7)
	v_mfma_f32_16x16x32_bf16 v[62:65], v[130:133], v[166:169], 0
	v_mfma_f32_16x16x32_bf16 v[62:65], v[134:137], v[170:173], v[62:65]
	s_waitcnt lgkmcnt(5)
	v_mfma_f32_16x16x32_bf16 v[58:61], v[138:141], v[166:169], 0
	v_mfma_f32_16x16x32_bf16 v[58:61], v[142:145], v[170:173], v[58:61]
	s_waitcnt lgkmcnt(3)
	v_mfma_f32_16x16x32_bf16 v[46:49], v[130:133], v[186:189], 0
	v_mfma_f32_16x16x32_bf16 v[46:49], v[134:137], v[190:193], v[46:49]
	s_waitcnt lgkmcnt(1)
	v_mfma_f32_16x16x32_bf16 v[42:45], v[138:141], v[186:189], 0
	v_mfma_f32_16x16x32_bf16 v[42:45], v[142:145], v[190:193], v[42:45]
	v_mfma_f32_16x16x32_bf16 v[30:33], v[130:133], v[194:197], 0
	v_mfma_f32_16x16x32_bf16 v[30:33], v[134:137], v[198:201], v[30:33]
	v_mfma_f32_16x16x32_bf16 v[26:29], v[138:141], v[194:197], 0
	v_mfma_f32_16x16x32_bf16 v[26:29], v[142:145], v[198:201], v[26:29]
	v_mfma_f32_16x16x32_bf16 v[14:17], v[130:133], v[202:205], 0
	v_mfma_f32_16x16x32_bf16 v[14:17], v[134:137], v[206:209], v[14:17]
	s_waitcnt lgkmcnt(0)
	v_mfma_f32_16x16x32_bf16 v[10:13], v[138:141], v[202:205], 0
	v_mfma_f32_16x16x32_bf16 v[10:13], v[142:145], v[206:209], v[10:13]
	s_setprio 0
	s_setprio 1
	v_mfma_f32_16x16x32_bf16 v[54:57], v[150:153], v[166:169], 0
	v_mfma_f32_16x16x32_bf16 v[54:57], v[154:157], v[170:173], v[54:57]
	v_mfma_f32_16x16x32_bf16 v[50:53], v[158:161], v[166:169], 0
	v_mfma_f32_16x16x32_bf16 v[50:53], v[162:165], v[170:173], v[50:53]
	v_mfma_f32_16x16x32_bf16 v[38:41], v[150:153], v[186:189], 0
	v_mfma_f32_16x16x32_bf16 v[38:41], v[154:157], v[190:193], v[38:41]
	v_mfma_f32_16x16x32_bf16 v[34:37], v[158:161], v[186:189], 0
	v_mfma_f32_16x16x32_bf16 v[34:37], v[162:165], v[190:193], v[34:37]
	v_mfma_f32_16x16x32_bf16 v[22:25], v[150:153], v[194:197], 0
	v_mfma_f32_16x16x32_bf16 v[22:25], v[154:157], v[198:201], v[22:25]
	v_mfma_f32_16x16x32_bf16 v[18:21], v[158:161], v[194:197], 0
	v_mfma_f32_16x16x32_bf16 v[18:21], v[162:165], v[198:201], v[18:21]
	v_mfma_f32_16x16x32_bf16 v[6:9], v[150:153], v[202:205], 0
	v_mfma_f32_16x16x32_bf16 v[6:9], v[154:157], v[206:209], v[6:9]
	s_setprio 2
	s_barrier
	v_mfma_f32_16x16x32_bf16 v[2:5], v[158:161], v[202:205], 0
	v_mfma_f32_16x16x32_bf16 v[2:5], v[162:165], v[206:209], v[2:5]
	s_setprio 0
	ds_read_b128 v[130:133], v184
	ds_read_b128 v[134:137], v184 offset:1024
	ds_read_b128 v[138:141], v184 offset:2048
	ds_read_b128 v[142:145], v184 offset:3072
	ds_read_b128 v[150:153], v185
	ds_read_b128 v[154:157], v185 offset:1024
	ds_read_b128 v[158:161], v185 offset:2048
	ds_read_b128 v[162:165], v185 offset:3072
	ds_read_b128 v[166:169], v183 offset:32768
	ds_read_b128 v[170:173], v183 offset:33792
	ds_read_b128 v[186:189], v183 offset:34816
	ds_read_b128 v[190:193], v183 offset:35840
	ds_read_b128 v[194:197], v183 offset:36864
	ds_read_b128 v[198:201], v183 offset:37888
	ds_read_b128 v[202:205], v183 offset:38912
	ds_read_b128 v[206:209], v183 offset:39936
	s_mov_b32 s75, m0
	s_mov_b32 m0, s34
	s_nop 0
	global_load_lds_dwordx4 v1, s[24:25]
	s_mov_b32 m0, s75
	s_nop 0
	s_mov_b32 s75, m0
	s_mov_b32 m0, s41
	s_nop 0
	global_load_lds_dwordx4 v177, s[24:25]
	s_mov_b32 m0, s75
	s_add_u32 s24, s24, 0x4000
	s_addc_u32 s25, s25, 0
	s_mov_b32 s75, m0
	s_mov_b32 m0, s42
	s_nop 0
	global_load_lds_dwordx4 v1, s[24:25]
	s_mov_b32 m0, s75
	s_nop 0
	s_mov_b32 s75, m0
	s_mov_b32 m0, s43
	s_nop 0
	global_load_lds_dwordx4 v177, s[24:25]
	s_mov_b32 m0, s75
	s_waitcnt vmcnt(8)
	s_waitcnt lgkmcnt(0)
	s_barrier
	s_setprio 1
	s_waitcnt lgkmcnt(7)
	v_mfma_f32_16x16x32_bf16 v[126:129], v[130:133], v[166:169], v[126:129]
	v_mfma_f32_16x16x32_bf16 v[126:129], v[134:137], v[170:173], v[126:129]
	s_waitcnt lgkmcnt(5)
	v_mfma_f32_16x16x32_bf16 v[122:125], v[138:141], v[166:169], v[122:125]
	v_mfma_f32_16x16x32_bf16 v[122:125], v[142:145], v[170:173], v[122:125]
	s_waitcnt lgkmcnt(3)
	v_mfma_f32_16x16x32_bf16 v[118:121], v[130:133], v[186:189], v[118:121]
	v_mfma_f32_16x16x32_bf16 v[118:121], v[134:137], v[190:193], v[118:121]
	s_waitcnt lgkmcnt(1)
	v_mfma_f32_16x16x32_bf16 v[110:113], v[138:141], v[186:189], v[110:113]
	v_mfma_f32_16x16x32_bf16 v[110:113], v[142:145], v[190:193], v[110:113]
	v_mfma_f32_16x16x32_bf16 v[94:97], v[130:133], v[194:197], v[94:97]
	v_mfma_f32_16x16x32_bf16 v[94:97], v[134:137], v[198:201], v[94:97]
	v_mfma_f32_16x16x32_bf16 v[90:93], v[138:141], v[194:197], v[90:93]
	v_mfma_f32_16x16x32_bf16 v[90:93], v[142:145], v[198:201], v[90:93]
	v_mfma_f32_16x16x32_bf16 v[86:89], v[130:133], v[202:205], v[86:89]
	v_mfma_f32_16x16x32_bf16 v[86:89], v[134:137], v[206:209], v[86:89]
	s_waitcnt lgkmcnt(0)
	v_mfma_f32_16x16x32_bf16 v[78:81], v[138:141], v[202:205], v[78:81]
	v_mfma_f32_16x16x32_bf16 v[78:81], v[142:145], v[206:209], v[78:81]
	s_setprio 0
	s_setprio 1
	v_mfma_f32_16x16x32_bf16 v[114:117], v[150:153], v[166:169], v[114:117]
	v_mfma_f32_16x16x32_bf16 v[114:117], v[154:157], v[170:173], v[114:117]
	v_mfma_f32_16x16x32_bf16 v[106:109], v[158:161], v[166:169], v[106:109]
	v_mfma_f32_16x16x32_bf16 v[106:109], v[162:165], v[170:173], v[106:109]
	v_mfma_f32_16x16x32_bf16 v[102:105], v[150:153], v[186:189], v[102:105]
	v_mfma_f32_16x16x32_bf16 v[102:105], v[154:157], v[190:193], v[102:105]
	v_mfma_f32_16x16x32_bf16 v[98:101], v[158:161], v[186:189], v[98:101]
	v_mfma_f32_16x16x32_bf16 v[98:101], v[162:165], v[190:193], v[98:101]
	v_mfma_f32_16x16x32_bf16 v[82:85], v[150:153], v[194:197], v[82:85]
	v_mfma_f32_16x16x32_bf16 v[82:85], v[154:157], v[198:201], v[82:85]
	v_mfma_f32_16x16x32_bf16 v[74:77], v[158:161], v[194:197], v[74:77]
	v_mfma_f32_16x16x32_bf16 v[74:77], v[162:165], v[198:201], v[74:77]
	v_mfma_f32_16x16x32_bf16 v[70:73], v[150:153], v[202:205], v[70:73]
	v_mfma_f32_16x16x32_bf16 v[70:73], v[154:157], v[206:209], v[70:73]
	s_setprio 2
	s_barrier
	v_mfma_f32_16x16x32_bf16 v[66:69], v[158:161], v[202:205], v[66:69]
	v_mfma_f32_16x16x32_bf16 v[66:69], v[162:165], v[206:209], v[66:69]
	s_setprio 0
	ds_read_b128 v[166:169], v183 offset:49152
	ds_read_b128 v[170:173], v183 offset:50176
	ds_read_b128 v[186:189], v183 offset:51200
	ds_read_b128 v[190:193], v183 offset:52224
	ds_read_b128 v[194:197], v183 offset:53248
	ds_read_b128 v[198:201], v183 offset:54272
	ds_read_b128 v[202:205], v183 offset:55296
	ds_read_b128 v[206:209], v183 offset:56320
	s_add_u32 s24, s22, 0x40000
	s_addc_u32 s25, s23, 0
	s_mov_b32 s75, m0
	s_mov_b32 m0, s46
	s_nop 0
	global_load_lds_dwordx4 v176, s[24:25]
	s_mov_b32 m0, s75
	s_add_u32 s22, s22, 0x44000
	s_mov_b32 s75, m0
	s_mov_b32 m0, s47
	s_nop 0
	global_load_lds_dwordx4 v178, s[24:25]
	s_mov_b32 m0, s75
	s_addc_u32 s23, s23, 0
	s_mov_b32 s24, m0
	s_mov_b32 m0, s48
	s_nop 0
	global_load_lds_dwordx4 v176, s[22:23]
	s_mov_b32 m0, s24
	s_nop 0
	s_mov_b32 s24, m0
	s_mov_b32 m0, s49
	s_nop 0
	global_load_lds_dwordx4 v178, s[22:23]
	s_mov_b32 m0, s24
	s_waitcnt vmcnt(4)
	s_waitcnt lgkmcnt(0)
	s_barrier
	s_setprio 1
	s_waitcnt lgkmcnt(7)
	v_mfma_f32_16x16x32_bf16 v[62:65], v[130:133], v[166:169], v[62:65]
	v_mfma_f32_16x16x32_bf16 v[62:65], v[134:137], v[170:173], v[62:65]
	s_waitcnt lgkmcnt(5)
	v_mfma_f32_16x16x32_bf16 v[58:61], v[138:141], v[166:169], v[58:61]
	v_mfma_f32_16x16x32_bf16 v[58:61], v[142:145], v[170:173], v[58:61]
	s_waitcnt lgkmcnt(3)
	v_mfma_f32_16x16x32_bf16 v[46:49], v[130:133], v[186:189], v[46:49]
	v_mfma_f32_16x16x32_bf16 v[46:49], v[134:137], v[190:193], v[46:49]
	s_waitcnt lgkmcnt(1)
	v_mfma_f32_16x16x32_bf16 v[42:45], v[138:141], v[186:189], v[42:45]
	v_mfma_f32_16x16x32_bf16 v[42:45], v[142:145], v[190:193], v[42:45]
	v_mfma_f32_16x16x32_bf16 v[30:33], v[130:133], v[194:197], v[30:33]
	v_mfma_f32_16x16x32_bf16 v[30:33], v[134:137], v[198:201], v[30:33]
	v_mfma_f32_16x16x32_bf16 v[26:29], v[138:141], v[194:197], v[26:29]
	v_mfma_f32_16x16x32_bf16 v[26:29], v[142:145], v[198:201], v[26:29]
	v_mfma_f32_16x16x32_bf16 v[14:17], v[130:133], v[202:205], v[14:17]
	v_mfma_f32_16x16x32_bf16 v[14:17], v[134:137], v[206:209], v[14:17]
	s_waitcnt lgkmcnt(0)
	v_mfma_f32_16x16x32_bf16 v[10:13], v[138:141], v[202:205], v[10:13]
	v_mfma_f32_16x16x32_bf16 v[10:13], v[142:145], v[206:209], v[10:13]
	s_setprio 0
	s_setprio 1
	v_mfma_f32_16x16x32_bf16 v[54:57], v[150:153], v[166:169], v[54:57]
	v_mfma_f32_16x16x32_bf16 v[54:57], v[154:157], v[170:173], v[54:57]
	v_mfma_f32_16x16x32_bf16 v[50:53], v[158:161], v[166:169], v[50:53]
	v_mfma_f32_16x16x32_bf16 v[50:53], v[162:165], v[170:173], v[50:53]
	v_mfma_f32_16x16x32_bf16 v[38:41], v[150:153], v[186:189], v[38:41]
	v_mfma_f32_16x16x32_bf16 v[38:41], v[154:157], v[190:193], v[38:41]
	v_mfma_f32_16x16x32_bf16 v[34:37], v[158:161], v[186:189], v[34:37]
	v_mfma_f32_16x16x32_bf16 v[34:37], v[162:165], v[190:193], v[34:37]
	v_mfma_f32_16x16x32_bf16 v[22:25], v[150:153], v[194:197], v[22:25]
	v_mfma_f32_16x16x32_bf16 v[22:25], v[154:157], v[198:201], v[22:25]
	v_mfma_f32_16x16x32_bf16 v[18:21], v[158:161], v[194:197], v[18:21]
	v_mfma_f32_16x16x32_bf16 v[18:21], v[162:165], v[198:201], v[18:21]
	v_mfma_f32_16x16x32_bf16 v[6:9], v[150:153], v[202:205], v[6:9]
	v_mfma_f32_16x16x32_bf16 v[6:9], v[154:157], v[206:209], v[6:9]
	s_setprio 2
	s_barrier
	v_mfma_f32_16x16x32_bf16 v[2:5], v[158:161], v[202:205], v[2:5]
	v_mfma_f32_16x16x32_bf16 v[2:5], v[162:165], v[206:209], v[2:5]
	s_setprio 0
	s_add_i32 s74, s74, 2
	s_add_u32 s67, s67, 0x80000
	s_addc_u32 s70, s70, 0
	s_add_u32 s20, s20, 0x400000
	s_addc_u32 s21, s21, 0
	s_add_u32 s71, s71, 0x400000
	s_addc_u32 s73, s73, 0
	s_cmpk_gt_u32 s74, 0x53
	.p2align 6
.LBB0_1952:
	ds_read_b128 v[130:133], v181
	ds_read_b128 v[134:137], v181 offset:1024
	ds_read_b128 v[138:141], v181 offset:2048
	ds_read_b128 v[142:145], v181 offset:3072
	ds_read_b128 v[150:153], v182
	ds_read_b128 v[154:157], v182 offset:1024
	ds_read_b128 v[158:161], v182 offset:2048
	ds_read_b128 v[162:165], v182 offset:3072
	s_cmpk_eq_i32 s74, 0x52
	s_cselect_b32 s23, s11, s70
	s_cselect_b32 s22, s66, s67
	s_cselect_b32 s25, s13, s73
	s_cselect_b32 s24, s65, s71
	ds_read_b128 v[166:169], v183
	ds_read_b128 v[170:173], v183 offset:1024
	ds_read_b128 v[186:189], v183 offset:2048
	ds_read_b128 v[190:193], v183 offset:3072
	ds_read_b128 v[194:197], v183 offset:4096
	ds_read_b128 v[198:201], v183 offset:5120
	ds_read_b128 v[202:205], v183 offset:6144
	ds_read_b128 v[206:209], v183 offset:7168
	s_add_u32 s76, s20, 0xffffc000
	s_addc_u32 s77, s21, -1
	s_mov_b32 s75, m0
	s_mov_b32 m0, s58
	s_nop 0
	global_load_lds_dwordx4 v1, s[76:77]
	s_mov_b32 m0, s75
	s_nop 0
	s_mov_b32 s75, m0
	s_mov_b32 m0, s62
	s_nop 0
	global_load_lds_dwordx4 v177, s[76:77]
	s_mov_b32 m0, s75
	s_nop 0
	s_mov_b32 s75, m0
	s_mov_b32 m0, s59
	s_nop 0
	global_load_lds_dwordx4 v1, s[20:21]
	s_mov_b32 m0, s75
	s_nop 0
	s_mov_b32 s75, m0
	s_mov_b32 m0, s63
	s_nop 0
	global_load_lds_dwordx4 v177, s[20:21]
	s_mov_b32 m0, s75
	s_waitcnt vmcnt(8)
	s_waitcnt lgkmcnt(0)
	s_barrier
	s_setprio 1
	s_waitcnt lgkmcnt(7)
	v_mfma_f32_16x16x32_bf16 v[126:129], v[130:133], v[166:169], v[126:129]
	v_mfma_f32_16x16x32_bf16 v[126:129], v[134:137], v[170:173], v[126:129]
	s_waitcnt lgkmcnt(5)
	v_mfma_f32_16x16x32_bf16 v[122:125], v[138:141], v[166:169], v[122:125]
	v_mfma_f32_16x16x32_bf16 v[122:125], v[142:145], v[170:173], v[122:125]
	s_waitcnt lgkmcnt(3)
	v_mfma_f32_16x16x32_bf16 v[118:121], v[130:133], v[186:189], v[118:121]
	v_mfma_f32_16x16x32_bf16 v[118:121], v[134:137], v[190:193], v[118:121]
	s_waitcnt lgkmcnt(1)
	v_mfma_f32_16x16x32_bf16 v[110:113], v[138:141], v[186:189], v[110:113]
	v_mfma_f32_16x16x32_bf16 v[110:113], v[142:145], v[190:193], v[110:113]
	v_mfma_f32_16x16x32_bf16 v[94:97], v[130:133], v[194:197], v[94:97]
	v_mfma_f32_16x16x32_bf16 v[94:97], v[134:137], v[198:201], v[94:97]
	v_mfma_f32_16x16x32_bf16 v[90:93], v[138:141], v[194:197], v[90:93]
	v_mfma_f32_16x16x32_bf16 v[90:93], v[142:145], v[198:201], v[90:93]
	v_mfma_f32_16x16x32_bf16 v[86:89], v[130:133], v[202:205], v[86:89]
	v_mfma_f32_16x16x32_bf16 v[86:89], v[134:137], v[206:209], v[86:89]
	s_waitcnt lgkmcnt(0)
	v_mfma_f32_16x16x32_bf16 v[78:81], v[138:141], v[202:205], v[78:81]
	v_mfma_f32_16x16x32_bf16 v[78:81], v[142:145], v[206:209], v[78:81]
	s_setprio 0
	s_setprio 1
	v_mfma_f32_16x16x32_bf16 v[114:117], v[150:153], v[166:169], v[114:117]
	v_mfma_f32_16x16x32_bf16 v[114:117], v[154:157], v[170:173], v[114:117]
	v_mfma_f32_16x16x32_bf16 v[106:109], v[158:161], v[166:169], v[106:109]
	v_mfma_f32_16x16x32_bf16 v[106:109], v[162:165], v[170:173], v[106:109]
	v_mfma_f32_16x16x32_bf16 v[102:105], v[150:153], v[186:189], v[102:105]
	v_mfma_f32_16x16x32_bf16 v[102:105], v[154:157], v[190:193], v[102:105]
	v_mfma_f32_16x16x32_bf16 v[98:101], v[158:161], v[186:189], v[98:101]
	v_mfma_f32_16x16x32_bf16 v[98:101], v[162:165], v[190:193], v[98:101]
	v_mfma_f32_16x16x32_bf16 v[82:85], v[150:153], v[194:197], v[82:85]
	v_mfma_f32_16x16x32_bf16 v[82:85], v[154:157], v[198:201], v[82:85]
	v_mfma_f32_16x16x32_bf16 v[74:77], v[158:161], v[194:197], v[74:77]
	v_mfma_f32_16x16x32_bf16 v[74:77], v[162:165], v[198:201], v[74:77]
	v_mfma_f32_16x16x32_bf16 v[70:73], v[150:153], v[202:205], v[70:73]
	v_mfma_f32_16x16x32_bf16 v[70:73], v[154:157], v[206:209], v[70:73]
	s_setprio 2
	s_barrier
	v_mfma_f32_16x16x32_bf16 v[66:69], v[158:161], v[202:205], v[66:69]
	v_mfma_f32_16x16x32_bf16 v[66:69], v[162:165], v[206:209], v[66:69]
	s_setprio 0
	ds_read_b128 v[166:169], v183 offset:16384
	ds_read_b128 v[170:173], v183 offset:17408
	ds_read_b128 v[186:189], v183 offset:18432
	ds_read_b128 v[190:193], v183 offset:19456
	ds_read_b128 v[194:197], v183 offset:20480
	ds_read_b128 v[198:201], v183 offset:21504
	ds_read_b128 v[202:205], v183 offset:22528
	ds_read_b128 v[206:209], v183 offset:23552
	s_mov_b32 s75, m0
	s_mov_b32 m0, s35
	s_nop 0
	global_load_lds_dwordx4 v176, s[22:23]
	s_mov_b32 m0, s75
	s_add_u32 s76, s22, 0x4000
	s_mov_b32 s75, m0
	s_mov_b32 m0, s36
	s_nop 0
	global_load_lds_dwordx4 v178, s[22:23]
	s_mov_b32 m0, s75
	s_addc_u32 s77, s23, 0
	s_mov_b32 s75, m0
	s_mov_b32 m0, s37
	s_nop 0
	global_load_lds_dwordx4 v176, s[76:77]
	s_mov_b32 m0, s75
	s_nop 0
	s_mov_b32 s75, m0
	s_mov_b32 m0, s40
	s_nop 0
	global_load_lds_dwordx4 v178, s[76:77]
	s_mov_b32 m0, s75
	s_waitcnt vmcnt(4)
	s_waitcnt lgkmcnt(0)
	s_barrier
	s_setprio 1
	s_waitcnt lgkmcnt(7)
	v_mfma_f32_16x16x32_bf16 v[62:65], v[130:133], v[166:169], v[62:65]
	v_mfma_f32_16x16x32_bf16 v[62:65], v[134:137], v[170:173], v[62:65]
	s_waitcnt lgkmcnt(5)
	v_mfma_f32_16x16x32_bf16 v[58:61], v[138:141], v[166:169], v[58:61]
	v_mfma_f32_16x16x32_bf16 v[58:61], v[142:145], v[170:173], v[58:61]
	s_waitcnt lgkmcnt(3)
	v_mfma_f32_16x16x32_bf16 v[46:49], v[130:133], v[186:189], v[46:49]
	v_mfma_f32_16x16x32_bf16 v[46:49], v[134:137], v[190:193], v[46:49]
	s_waitcnt lgkmcnt(1)
	v_mfma_f32_16x16x32_bf16 v[42:45], v[138:141], v[186:189], v[42:45]
	v_mfma_f32_16x16x32_bf16 v[42:45], v[142:145], v[190:193], v[42:45]
	v_mfma_f32_16x16x32_bf16 v[30:33], v[130:133], v[194:197], v[30:33]
	v_mfma_f32_16x16x32_bf16 v[30:33], v[134:137], v[198:201], v[30:33]
	v_mfma_f32_16x16x32_bf16 v[26:29], v[138:141], v[194:197], v[26:29]
	v_mfma_f32_16x16x32_bf16 v[26:29], v[142:145], v[198:201], v[26:29]
	v_mfma_f32_16x16x32_bf16 v[14:17], v[130:133], v[202:205], v[14:17]
	v_mfma_f32_16x16x32_bf16 v[14:17], v[134:137], v[206:209], v[14:17]
	s_waitcnt lgkmcnt(0)
	v_mfma_f32_16x16x32_bf16 v[10:13], v[138:141], v[202:205], v[10:13]
	v_mfma_f32_16x16x32_bf16 v[10:13], v[142:145], v[206:209], v[10:13]
	s_setprio 0
	s_setprio 1
	v_mfma_f32_16x16x32_bf16 v[54:57], v[150:153], v[166:169], v[54:57]
	v_mfma_f32_16x16x32_bf16 v[54:57], v[154:157], v[170:173], v[54:57]
	v_mfma_f32_16x16x32_bf16 v[50:53], v[158:161], v[166:169], v[50:53]
	v_mfma_f32_16x16x32_bf16 v[50:53], v[162:165], v[170:173], v[50:53]
	v_mfma_f32_16x16x32_bf16 v[38:41], v[150:153], v[186:189], v[38:41]
	v_mfma_f32_16x16x32_bf16 v[38:41], v[154:157], v[190:193], v[38:41]
	v_mfma_f32_16x16x32_bf16 v[34:37], v[158:161], v[186:189], v[34:37]
	v_mfma_f32_16x16x32_bf16 v[34:37], v[162:165], v[190:193], v[34:37]
	v_mfma_f32_16x16x32_bf16 v[22:25], v[150:153], v[194:197], v[22:25]
	v_mfma_f32_16x16x32_bf16 v[22:25], v[154:157], v[198:201], v[22:25]
	v_mfma_f32_16x16x32_bf16 v[18:21], v[158:161], v[194:197], v[18:21]
	v_mfma_f32_16x16x32_bf16 v[18:21], v[162:165], v[198:201], v[18:21]
	v_mfma_f32_16x16x32_bf16 v[6:9], v[150:153], v[202:205], v[6:9]
	v_mfma_f32_16x16x32_bf16 v[6:9], v[154:157], v[206:209], v[6:9]
	s_setprio 2
	s_barrier
	v_mfma_f32_16x16x32_bf16 v[2:5], v[158:161], v[202:205], v[2:5]
	v_mfma_f32_16x16x32_bf16 v[2:5], v[162:165], v[206:209], v[2:5]
	s_setprio 0
	ds_read_b128 v[130:133], v184
	ds_read_b128 v[134:137], v184 offset:1024
	ds_read_b128 v[138:141], v184 offset:2048
	ds_read_b128 v[142:145], v184 offset:3072
	ds_read_b128 v[150:153], v185
	ds_read_b128 v[154:157], v185 offset:1024
	ds_read_b128 v[158:161], v185 offset:2048
	ds_read_b128 v[162:165], v185 offset:3072
	ds_read_b128 v[166:169], v183 offset:32768
	ds_read_b128 v[170:173], v183 offset:33792
	ds_read_b128 v[186:189], v183 offset:34816
	ds_read_b128 v[190:193], v183 offset:35840
	ds_read_b128 v[194:197], v183 offset:36864
	ds_read_b128 v[198:201], v183 offset:37888
	ds_read_b128 v[202:205], v183 offset:38912
	ds_read_b128 v[206:209], v183 offset:39936
	s_mov_b32 s75, m0
	s_mov_b32 m0, s34
	s_nop 0
	global_load_lds_dwordx4 v1, s[24:25]
	s_mov_b32 m0, s75
	s_nop 0
	s_mov_b32 s75, m0
	s_mov_b32 m0, s41
	s_nop 0
	global_load_lds_dwordx4 v177, s[24:25]
	s_mov_b32 m0, s75
	s_add_u32 s24, s24, 0x4000
	s_addc_u32 s25, s25, 0
	s_mov_b32 s75, m0
	s_mov_b32 m0, s42
	s_nop 0
	global_load_lds_dwordx4 v1, s[24:25]
	s_mov_b32 m0, s75
	s_nop 0
	s_mov_b32 s75, m0
	s_mov_b32 m0, s43
	s_nop 0
	global_load_lds_dwordx4 v177, s[24:25]
	s_mov_b32 m0, s75
	s_waitcnt vmcnt(8)
	s_waitcnt lgkmcnt(0)
	s_barrier
	s_setprio 1
	s_waitcnt lgkmcnt(7)
	v_mfma_f32_16x16x32_bf16 v[126:129], v[130:133], v[166:169], v[126:129]
	v_mfma_f32_16x16x32_bf16 v[126:129], v[134:137], v[170:173], v[126:129]
	s_waitcnt lgkmcnt(5)
	v_mfma_f32_16x16x32_bf16 v[122:125], v[138:141], v[166:169], v[122:125]
	v_mfma_f32_16x16x32_bf16 v[122:125], v[142:145], v[170:173], v[122:125]
	s_waitcnt lgkmcnt(3)
	v_mfma_f32_16x16x32_bf16 v[118:121], v[130:133], v[186:189], v[118:121]
	v_mfma_f32_16x16x32_bf16 v[118:121], v[134:137], v[190:193], v[118:121]
	s_waitcnt lgkmcnt(1)
	v_mfma_f32_16x16x32_bf16 v[110:113], v[138:141], v[186:189], v[110:113]
	v_mfma_f32_16x16x32_bf16 v[110:113], v[142:145], v[190:193], v[110:113]
	v_mfma_f32_16x16x32_bf16 v[94:97], v[130:133], v[194:197], v[94:97]
	v_mfma_f32_16x16x32_bf16 v[94:97], v[134:137], v[198:201], v[94:97]
	v_mfma_f32_16x16x32_bf16 v[90:93], v[138:141], v[194:197], v[90:93]
	v_mfma_f32_16x16x32_bf16 v[90:93], v[142:145], v[198:201], v[90:93]
	v_mfma_f32_16x16x32_bf16 v[86:89], v[130:133], v[202:205], v[86:89]
	v_mfma_f32_16x16x32_bf16 v[86:89], v[134:137], v[206:209], v[86:89]
	s_waitcnt lgkmcnt(0)
	v_mfma_f32_16x16x32_bf16 v[78:81], v[138:141], v[202:205], v[78:81]
	v_mfma_f32_16x16x32_bf16 v[78:81], v[142:145], v[206:209], v[78:81]
	s_setprio 0
	s_setprio 1
	v_mfma_f32_16x16x32_bf16 v[114:117], v[150:153], v[166:169], v[114:117]
	v_mfma_f32_16x16x32_bf16 v[114:117], v[154:157], v[170:173], v[114:117]
	v_mfma_f32_16x16x32_bf16 v[106:109], v[158:161], v[166:169], v[106:109]
	v_mfma_f32_16x16x32_bf16 v[106:109], v[162:165], v[170:173], v[106:109]
	v_mfma_f32_16x16x32_bf16 v[102:105], v[150:153], v[186:189], v[102:105]
	v_mfma_f32_16x16x32_bf16 v[102:105], v[154:157], v[190:193], v[102:105]
	v_mfma_f32_16x16x32_bf16 v[98:101], v[158:161], v[186:189], v[98:101]
	v_mfma_f32_16x16x32_bf16 v[98:101], v[162:165], v[190:193], v[98:101]
	v_mfma_f32_16x16x32_bf16 v[82:85], v[150:153], v[194:197], v[82:85]
	v_mfma_f32_16x16x32_bf16 v[82:85], v[154:157], v[198:201], v[82:85]
	v_mfma_f32_16x16x32_bf16 v[74:77], v[158:161], v[194:197], v[74:77]
	v_mfma_f32_16x16x32_bf16 v[74:77], v[162:165], v[198:201], v[74:77]
	v_mfma_f32_16x16x32_bf16 v[70:73], v[150:153], v[202:205], v[70:73]
	v_mfma_f32_16x16x32_bf16 v[70:73], v[154:157], v[206:209], v[70:73]
	s_setprio 2
	s_barrier
	v_mfma_f32_16x16x32_bf16 v[66:69], v[158:161], v[202:205], v[66:69]
	v_mfma_f32_16x16x32_bf16 v[66:69], v[162:165], v[206:209], v[66:69]
	s_setprio 0
	ds_read_b128 v[166:169], v183 offset:49152
	ds_read_b128 v[170:173], v183 offset:50176
	ds_read_b128 v[186:189], v183 offset:51200
	ds_read_b128 v[190:193], v183 offset:52224
	ds_read_b128 v[194:197], v183 offset:53248
	ds_read_b128 v[198:201], v183 offset:54272
	ds_read_b128 v[202:205], v183 offset:55296
	ds_read_b128 v[206:209], v183 offset:56320
	s_add_u32 s24, s22, 0x40000
	s_addc_u32 s25, s23, 0
	s_mov_b32 s75, m0
	s_mov_b32 m0, s46
	s_nop 0
	global_load_lds_dwordx4 v176, s[24:25]
	s_mov_b32 m0, s75
	s_add_u32 s22, s22, 0x44000
	s_mov_b32 s75, m0
	s_mov_b32 m0, s47
	s_nop 0
	global_load_lds_dwordx4 v178, s[24:25]
	s_mov_b32 m0, s75
	s_addc_u32 s23, s23, 0
	s_mov_b32 s24, m0
	s_mov_b32 m0, s48
	s_nop 0
	global_load_lds_dwordx4 v176, s[22:23]
	s_mov_b32 m0, s24
	s_nop 0
	s_mov_b32 s24, m0
	s_mov_b32 m0, s49
	s_nop 0
	global_load_lds_dwordx4 v178, s[22:23]
	s_mov_b32 m0, s24
	s_waitcnt vmcnt(4)
	s_waitcnt lgkmcnt(0)
	s_barrier
	s_setprio 1
	s_waitcnt lgkmcnt(7)
	v_mfma_f32_16x16x32_bf16 v[62:65], v[130:133], v[166:169], v[62:65]
	v_mfma_f32_16x16x32_bf16 v[62:65], v[134:137], v[170:173], v[62:65]
	s_waitcnt lgkmcnt(5)
	v_mfma_f32_16x16x32_bf16 v[58:61], v[138:141], v[166:169], v[58:61]
	v_mfma_f32_16x16x32_bf16 v[58:61], v[142:145], v[170:173], v[58:61]
	s_waitcnt lgkmcnt(3)
	v_mfma_f32_16x16x32_bf16 v[46:49], v[130:133], v[186:189], v[46:49]
	v_mfma_f32_16x16x32_bf16 v[46:49], v[134:137], v[190:193], v[46:49]
	s_waitcnt lgkmcnt(1)
	v_mfma_f32_16x16x32_bf16 v[42:45], v[138:141], v[186:189], v[42:45]
	v_mfma_f32_16x16x32_bf16 v[42:45], v[142:145], v[190:193], v[42:45]
	v_mfma_f32_16x16x32_bf16 v[30:33], v[130:133], v[194:197], v[30:33]
	v_mfma_f32_16x16x32_bf16 v[30:33], v[134:137], v[198:201], v[30:33]
	v_mfma_f32_16x16x32_bf16 v[26:29], v[138:141], v[194:197], v[26:29]
	v_mfma_f32_16x16x32_bf16 v[26:29], v[142:145], v[198:201], v[26:29]
	v_mfma_f32_16x16x32_bf16 v[14:17], v[130:133], v[202:205], v[14:17]
	v_mfma_f32_16x16x32_bf16 v[14:17], v[134:137], v[206:209], v[14:17]
	s_waitcnt lgkmcnt(0)
	v_mfma_f32_16x16x32_bf16 v[10:13], v[138:141], v[202:205], v[10:13]
	v_mfma_f32_16x16x32_bf16 v[10:13], v[142:145], v[206:209], v[10:13]
	s_setprio 0
	s_setprio 1
	v_mfma_f32_16x16x32_bf16 v[54:57], v[150:153], v[166:169], v[54:57]
	v_mfma_f32_16x16x32_bf16 v[54:57], v[154:157], v[170:173], v[54:57]
	v_mfma_f32_16x16x32_bf16 v[50:53], v[158:161], v[166:169], v[50:53]
	v_mfma_f32_16x16x32_bf16 v[50:53], v[162:165], v[170:173], v[50:53]
	v_mfma_f32_16x16x32_bf16 v[38:41], v[150:153], v[186:189], v[38:41]
	v_mfma_f32_16x16x32_bf16 v[38:41], v[154:157], v[190:193], v[38:41]
	v_mfma_f32_16x16x32_bf16 v[34:37], v[158:161], v[186:189], v[34:37]
	v_mfma_f32_16x16x32_bf16 v[34:37], v[162:165], v[190:193], v[34:37]
	v_mfma_f32_16x16x32_bf16 v[22:25], v[150:153], v[194:197], v[22:25]
	v_mfma_f32_16x16x32_bf16 v[22:25], v[154:157], v[198:201], v[22:25]
	v_mfma_f32_16x16x32_bf16 v[18:21], v[158:161], v[194:197], v[18:21]
	v_mfma_f32_16x16x32_bf16 v[18:21], v[162:165], v[198:201], v[18:21]
	v_mfma_f32_16x16x32_bf16 v[6:9], v[150:153], v[202:205], v[6:9]
	v_mfma_f32_16x16x32_bf16 v[6:9], v[154:157], v[206:209], v[6:9]
	s_setprio 2
	s_barrier
	v_mfma_f32_16x16x32_bf16 v[2:5], v[158:161], v[202:205], v[2:5]
	v_mfma_f32_16x16x32_bf16 v[2:5], v[162:165], v[206:209], v[2:5]
	s_setprio 0
	s_add_i32 s74, s74, 2
	s_add_u32 s67, s67, 0x80000
	s_addc_u32 s70, s70, 0
	s_add_u32 s20, s20, 0x400000
	s_addc_u32 s21, s21, 0
	s_add_u32 s71, s71, 0x400000
	s_addc_u32 s73, s73, 0
	s_cmpk_gt_u32 s74, 0x53
	s_cbranch_scc0 .LBB0_1952
	s_and_b64 vcc, exec, s[8:9]
	s_cbranch_vccz .LBB0_1955
	s_barrier

.LBB0_2409:
	s_ashr_i32 s17, s16, 31
	s_lshl_b64 s[18:19], s[16:17], 20
	s_add_u32 s18, s33, s18
	s_addc_u32 s19, s34, s19
	s_and_b64 s[20:21], s[2:3], exec
	s_cselect_b32 s17, s19, s27
	s_cselect_b32 s71, s18, s26
	s_ashr_i32 s15, s14, 31
	s_lshl_b64 s[20:21], s[14:15], 20
	s_add_u32 s20, s35, s20
	s_addc_u32 s21, s36, s21
	s_and_b64 s[28:29], s[2:3], exec
	s_cselect_b32 s15, s21, s25
	s_cselect_b32 s73, s20, s24
	s_add_u32 s74, s24, 0x100
	s_addc_u32 s75, s25, 0
	s_add_u32 s24, s26, 0x80080
	s_addc_u32 s25, s27, 0
	s_add_u32 s76, s26, 0x100
	s_addc_u32 s77, s27, 0
	s_mov_b32 s78, -2
	s_waitcnt vmcnt(25)
	s_waitcnt vmcnt(24)
	s_waitcnt vmcnt(4)
	s_waitcnt vmcnt(2)
	s_waitcnt vmcnt(1)
	s_waitcnt vmcnt(0)
	ds_read_b128 v[130:133], v181
	ds_read_b128 v[134:137], v181 offset:1024
	ds_read_b128 v[138:141], v181 offset:2048
	ds_read_b128 v[142:145], v181 offset:3072
	ds_read_b128 v[146:149], v182
	ds_read_b128 v[150:153], v182 offset:1024
	ds_read_b128 v[154:157], v182 offset:2048
	ds_read_b128 v[158:161], v182 offset:3072
	s_cmp_eq_u32 s78, 28
	s_cselect_b32 s27, s15, s75
	s_cselect_b32 s26, s73, s74
	s_cselect_b32 s29, s17, s77
	s_cselect_b32 s28, s71, s76
	ds_read_b128 v[166:169], v183
	ds_read_b128 v[170:173], v183 offset:1024
	ds_read_b128 v[186:189], v183 offset:2048
	ds_read_b128 v[190:193], v183 offset:3072
	ds_read_b128 v[194:197], v183 offset:4096
	ds_read_b128 v[198:201], v183 offset:5120
	ds_read_b128 v[202:205], v183 offset:6144
	ds_read_b128 v[206:209], v183 offset:7168
	s_add_u32 s80, s24, 0xfff80000
	s_addc_u32 s81, s25, -1
	s_mov_b32 s79, m0
	s_mov_b32 m0, s64
	s_nop 0
	global_load_lds_dwordx4 v1, s[80:81]
	s_mov_b32 m0, s79
	s_nop 0
	s_mov_b32 s79, m0
	s_mov_b32 m0, s66
	s_nop 0
	global_load_lds_dwordx4 v177, s[80:81]
	s_mov_b32 m0, s79
	s_nop 0
	s_mov_b32 s79, m0
	s_mov_b32 m0, s65
	s_nop 0
	global_load_lds_dwordx4 v1, s[24:25]
	s_mov_b32 m0, s79
	s_nop 0
	s_mov_b32 s79, m0
	s_mov_b32 m0, s67
	s_nop 0
	global_load_lds_dwordx4 v177, s[24:25]
	s_mov_b32 m0, s79
	s_waitcnt vmcnt(8)
	s_waitcnt lgkmcnt(0)
	s_barrier
	s_setprio 1
	s_waitcnt lgkmcnt(7)
	v_mfma_f32_16x16x32_bf16 v[126:129], v[130:133], v[166:169], 0
	v_mfma_f32_16x16x32_bf16 v[126:129], v[134:137], v[170:173], v[126:129]
	s_waitcnt lgkmcnt(5)
	v_mfma_f32_16x16x32_bf16 v[122:125], v[138:141], v[166:169], 0
	v_mfma_f32_16x16x32_bf16 v[122:125], v[142:145], v[170:173], v[122:125]
	s_waitcnt lgkmcnt(3)
	v_mfma_f32_16x16x32_bf16 v[118:121], v[130:133], v[186:189], 0
	v_mfma_f32_16x16x32_bf16 v[118:121], v[134:137], v[190:193], v[118:121]
	s_waitcnt lgkmcnt(1)
	v_mfma_f32_16x16x32_bf16 v[114:117], v[138:141], v[186:189], 0
	v_mfma_f32_16x16x32_bf16 v[114:117], v[142:145], v[190:193], v[114:117]
	v_mfma_f32_16x16x32_bf16 v[94:97], v[130:133], v[194:197], 0
	v_mfma_f32_16x16x32_bf16 v[94:97], v[134:137], v[198:201], v[94:97]
	v_mfma_f32_16x16x32_bf16 v[90:93], v[138:141], v[194:197], 0
	v_mfma_f32_16x16x32_bf16 v[90:93], v[142:145], v[198:201], v[90:93]
	v_mfma_f32_16x16x32_bf16 v[86:89], v[130:133], v[202:205], 0
	v_mfma_f32_16x16x32_bf16 v[86:89], v[134:137], v[206:209], v[86:89]
	s_waitcnt lgkmcnt(0)
	v_mfma_f32_16x16x32_bf16 v[78:81], v[138:141], v[202:205], 0
	v_mfma_f32_16x16x32_bf16 v[78:81], v[142:145], v[206:209], v[78:81]
	s_setprio 0
	s_setprio 1
	v_mfma_f32_16x16x32_bf16 v[110:113], v[146:149], v[166:169], 0
	v_mfma_f32_16x16x32_bf16 v[110:113], v[150:153], v[170:173], v[110:113]
	v_mfma_f32_16x16x32_bf16 v[106:109], v[154:157], v[166:169], 0
	v_mfma_f32_16x16x32_bf16 v[106:109], v[158:161], v[170:173], v[106:109]
	v_mfma_f32_16x16x32_bf16 v[102:105], v[146:149], v[186:189], 0
	v_mfma_f32_16x16x32_bf16 v[102:105], v[150:153], v[190:193], v[102:105]
	v_mfma_f32_16x16x32_bf16 v[98:101], v[154:157], v[186:189], 0
	v_mfma_f32_16x16x32_bf16 v[98:101], v[158:161], v[190:193], v[98:101]
	v_mfma_f32_16x16x32_bf16 v[82:85], v[146:149], v[194:197], 0
	v_mfma_f32_16x16x32_bf16 v[82:85], v[150:153], v[198:201], v[82:85]
	v_mfma_f32_16x16x32_bf16 v[74:77], v[154:157], v[194:197], 0
	v_mfma_f32_16x16x32_bf16 v[74:77], v[158:161], v[198:201], v[74:77]
	v_mfma_f32_16x16x32_bf16 v[70:73], v[146:149], v[202:205], 0
	v_mfma_f32_16x16x32_bf16 v[70:73], v[150:153], v[206:209], v[70:73]
	s_setprio 2
	s_barrier
	v_mfma_f32_16x16x32_bf16 v[66:69], v[154:157], v[202:205], 0
	v_mfma_f32_16x16x32_bf16 v[66:69], v[158:161], v[206:209], v[66:69]
	s_setprio 0
	ds_read_b128 v[166:169], v183 offset:16384
	ds_read_b128 v[170:173], v183 offset:17408
	ds_read_b128 v[186:189], v183 offset:18432
	ds_read_b128 v[190:193], v183 offset:19456
	ds_read_b128 v[194:197], v183 offset:20480
	ds_read_b128 v[198:201], v183 offset:21504
	ds_read_b128 v[202:205], v183 offset:22528
	ds_read_b128 v[206:209], v183 offset:23552
	s_mov_b32 s79, m0
	s_mov_b32 m0, s41
	s_nop 0
	global_load_lds_dwordx4 v176, s[26:27]
	s_mov_b32 m0, s79
	s_add_u32 s80, s26, 0x80000
	s_mov_b32 s79, m0
	s_mov_b32 m0, s42
	s_nop 0
	global_load_lds_dwordx4 v178, s[26:27]
	s_mov_b32 m0, s79
	s_addc_u32 s81, s27, 0
	s_mov_b32 s79, m0
	s_mov_b32 m0, s43
	s_nop 0
	global_load_lds_dwordx4 v176, s[80:81]
	s_mov_b32 m0, s79
	s_nop 0
	s_mov_b32 s79, m0
	s_mov_b32 m0, s46
	s_nop 0
	global_load_lds_dwordx4 v178, s[80:81]
	s_mov_b32 m0, s79
	s_waitcnt vmcnt(4)
	s_waitcnt lgkmcnt(0)
	s_barrier
	s_setprio 1
	s_waitcnt lgkmcnt(7)
	v_mfma_f32_16x16x32_bf16 v[62:65], v[130:133], v[166:169], 0
	v_mfma_f32_16x16x32_bf16 v[62:65], v[134:137], v[170:173], v[62:65]
	s_waitcnt lgkmcnt(5)
	v_mfma_f32_16x16x32_bf16 v[58:61], v[138:141], v[166:169], 0
	v_mfma_f32_16x16x32_bf16 v[58:61], v[142:145], v[170:173], v[58:61]
	s_waitcnt lgkmcnt(3)
	v_mfma_f32_16x16x32_bf16 v[46:49], v[130:133], v[186:189], 0
	v_mfma_f32_16x16x32_bf16 v[46:49], v[134:137], v[190:193], v[46:49]
	s_waitcnt lgkmcnt(1)
	v_mfma_f32_16x16x32_bf16 v[42:45], v[138:141], v[186:189], 0
	v_mfma_f32_16x16x32_bf16 v[42:45], v[142:145], v[190:193], v[42:45]
	v_mfma_f32_16x16x32_bf16 v[30:33], v[130:133], v[194:197], 0
	v_mfma_f32_16x16x32_bf16 v[30:33], v[134:137], v[198:201], v[30:33]
	v_mfma_f32_16x16x32_bf16 v[26:29], v[138:141], v[194:197], 0
	v_mfma_f32_16x16x32_bf16 v[26:29], v[142:145], v[198:201], v[26:29]
	v_mfma_f32_16x16x32_bf16 v[14:17], v[130:133], v[202:205], 0
	v_mfma_f32_16x16x32_bf16 v[14:17], v[134:137], v[206:209], v[14:17]
	s_waitcnt lgkmcnt(0)
	v_mfma_f32_16x16x32_bf16 v[10:13], v[138:141], v[202:205], 0
	v_mfma_f32_16x16x32_bf16 v[10:13], v[142:145], v[206:209], v[10:13]
	s_setprio 0
	s_setprio 1
	v_mfma_f32_16x16x32_bf16 v[54:57], v[146:149], v[166:169], 0
	v_mfma_f32_16x16x32_bf16 v[54:57], v[150:153], v[170:173], v[54:57]
	v_mfma_f32_16x16x32_bf16 v[50:53], v[154:157], v[166:169], 0
	v_mfma_f32_16x16x32_bf16 v[50:53], v[158:161], v[170:173], v[50:53]
	v_mfma_f32_16x16x32_bf16 v[38:41], v[146:149], v[186:189], 0
	v_mfma_f32_16x16x32_bf16 v[38:41], v[150:153], v[190:193], v[38:41]
	v_mfma_f32_16x16x32_bf16 v[34:37], v[154:157], v[186:189], 0
	v_mfma_f32_16x16x32_bf16 v[34:37], v[158:161], v[190:193], v[34:37]
	v_mfma_f32_16x16x32_bf16 v[22:25], v[146:149], v[194:197], 0
	v_mfma_f32_16x16x32_bf16 v[22:25], v[150:153], v[198:201], v[22:25]
	v_mfma_f32_16x16x32_bf16 v[18:21], v[154:157], v[194:197], 0
	v_mfma_f32_16x16x32_bf16 v[18:21], v[158:161], v[198:201], v[18:21]
	v_mfma_f32_16x16x32_bf16 v[6:9], v[146:149], v[202:205], 0
	v_mfma_f32_16x16x32_bf16 v[6:9], v[150:153], v[206:209], v[6:9]
	s_setprio 2
	s_barrier
	v_mfma_f32_16x16x32_bf16 v[2:5], v[154:157], v[202:205], 0
	v_mfma_f32_16x16x32_bf16 v[2:5], v[158:161], v[206:209], v[2:5]
	s_setprio 0
	ds_read_b128 v[130:133], v184
	ds_read_b128 v[134:137], v184 offset:1024
	ds_read_b128 v[138:141], v184 offset:2048
	ds_read_b128 v[142:145], v184 offset:3072
	ds_read_b128 v[146:149], v185
	ds_read_b128 v[150:153], v185 offset:1024
	ds_read_b128 v[154:157], v185 offset:2048
	ds_read_b128 v[158:161], v185 offset:3072
	ds_read_b128 v[166:169], v183 offset:32768
	ds_read_b128 v[170:173], v183 offset:33792
	ds_read_b128 v[186:189], v183 offset:34816
	ds_read_b128 v[190:193], v183 offset:35840
	ds_read_b128 v[194:197], v183 offset:36864
	ds_read_b128 v[198:201], v183 offset:37888
	ds_read_b128 v[202:205], v183 offset:38912
	ds_read_b128 v[206:209], v183 offset:39936
	s_mov_b32 s79, m0
	s_mov_b32 m0, s40
	s_nop 0
	global_load_lds_dwordx4 v1, s[28:29]
	s_mov_b32 m0, s79
	s_nop 0
	s_mov_b32 s79, m0
	s_mov_b32 m0, s47
	s_nop 0
	global_load_lds_dwordx4 v177, s[28:29]
	s_mov_b32 m0, s79
	s_add_u32 s28, s28, 0x80000
	s_addc_u32 s29, s29, 0
	s_mov_b32 s79, m0
	s_mov_b32 m0, s48
	s_nop 0
	global_load_lds_dwordx4 v1, s[28:29]
	s_mov_b32 m0, s79
	s_nop 0
	s_mov_b32 s79, m0
	s_mov_b32 m0, s49
	s_nop 0
	global_load_lds_dwordx4 v177, s[28:29]
	s_mov_b32 m0, s79
	s_waitcnt vmcnt(8)
	s_waitcnt lgkmcnt(0)
	s_barrier
	s_setprio 1
	s_waitcnt lgkmcnt(7)
	v_mfma_f32_16x16x32_bf16 v[126:129], v[130:133], v[166:169], v[126:129]
	v_mfma_f32_16x16x32_bf16 v[126:129], v[134:137], v[170:173], v[126:129]
	s_waitcnt lgkmcnt(5)
	v_mfma_f32_16x16x32_bf16 v[122:125], v[138:141], v[166:169], v[122:125]
	v_mfma_f32_16x16x32_bf16 v[122:125], v[142:145], v[170:173], v[122:125]
	s_waitcnt lgkmcnt(3)
	v_mfma_f32_16x16x32_bf16 v[118:121], v[130:133], v[186:189], v[118:121]
	v_mfma_f32_16x16x32_bf16 v[118:121], v[134:137], v[190:193], v[118:121]
	s_waitcnt lgkmcnt(1)
	v_mfma_f32_16x16x32_bf16 v[114:117], v[138:141], v[186:189], v[114:117]
	v_mfma_f32_16x16x32_bf16 v[114:117], v[142:145], v[190:193], v[114:117]
	v_mfma_f32_16x16x32_bf16 v[94:97], v[130:133], v[194:197], v[94:97]
	v_mfma_f32_16x16x32_bf16 v[94:97], v[134:137], v[198:201], v[94:97]
	v_mfma_f32_16x16x32_bf16 v[90:93], v[138:141], v[194:197], v[90:93]
	v_mfma_f32_16x16x32_bf16 v[90:93], v[142:145], v[198:201], v[90:93]
	v_mfma_f32_16x16x32_bf16 v[86:89], v[130:133], v[202:205], v[86:89]
	v_mfma_f32_16x16x32_bf16 v[86:89], v[134:137], v[206:209], v[86:89]
	s_waitcnt lgkmcnt(0)
	v_mfma_f32_16x16x32_bf16 v[78:81], v[138:141], v[202:205], v[78:81]
	v_mfma_f32_16x16x32_bf16 v[78:81], v[142:145], v[206:209], v[78:81]
	s_setprio 0
	s_setprio 1
	v_mfma_f32_16x16x32_bf16 v[110:113], v[146:149], v[166:169], v[110:113]
	v_mfma_f32_16x16x32_bf16 v[110:113], v[150:153], v[170:173], v[110:113]
	v_mfma_f32_16x16x32_bf16 v[106:109], v[154:157], v[166:169], v[106:109]
	v_mfma_f32_16x16x32_bf16 v[106:109], v[158:161], v[170:173], v[106:109]
	v_mfma_f32_16x16x32_bf16 v[102:105], v[146:149], v[186:189], v[102:105]
	v_mfma_f32_16x16x32_bf16 v[102:105], v[150:153], v[190:193], v[102:105]
	v_mfma_f32_16x16x32_bf16 v[98:101], v[154:157], v[186:189], v[98:101]
	v_mfma_f32_16x16x32_bf16 v[98:101], v[158:161], v[190:193], v[98:101]
	v_mfma_f32_16x16x32_bf16 v[82:85], v[146:149], v[194:197], v[82:85]
	v_mfma_f32_16x16x32_bf16 v[82:85], v[150:153], v[198:201], v[82:85]
	v_mfma_f32_16x16x32_bf16 v[74:77], v[154:157], v[194:197], v[74:77]
	v_mfma_f32_16x16x32_bf16 v[74:77], v[158:161], v[198:201], v[74:77]
	v_mfma_f32_16x16x32_bf16 v[70:73], v[146:149], v[202:205], v[70:73]
	v_mfma_f32_16x16x32_bf16 v[70:73], v[150:153], v[206:209], v[70:73]
	s_setprio 2
	s_barrier
	v_mfma_f32_16x16x32_bf16 v[66:69], v[154:157], v[202:205], v[66:69]
	v_mfma_f32_16x16x32_bf16 v[66:69], v[158:161], v[206:209], v[66:69]
	s_setprio 0
	ds_read_b128 v[166:169], v183 offset:49152
	ds_read_b128 v[170:173], v183 offset:50176
	ds_read_b128 v[186:189], v183 offset:51200
	ds_read_b128 v[190:193], v183 offset:52224
	ds_read_b128 v[194:197], v183 offset:53248
	ds_read_b128 v[198:201], v183 offset:54272
	ds_read_b128 v[202:205], v183 offset:55296
	ds_read_b128 v[206:209], v183 offset:56320
	s_add_u32 s28, s26, 0x80
	s_addc_u32 s29, s27, 0
	s_mov_b32 s79, m0
	s_mov_b32 m0, s56
	s_nop 0
	global_load_lds_dwordx4 v176, s[28:29]
	s_mov_b32 m0, s79
	s_add_u32 s26, s26, 0x80080
	s_mov_b32 s79, m0
	s_mov_b32 m0, s57
	s_nop 0
	global_load_lds_dwordx4 v178, s[28:29]
	s_mov_b32 m0, s79
	s_addc_u32 s27, s27, 0
	s_mov_b32 s28, m0
	s_mov_b32 m0, s58
	s_nop 0
	global_load_lds_dwordx4 v176, s[26:27]
	s_mov_b32 m0, s28
	s_nop 0
	s_mov_b32 s28, m0
	s_mov_b32 m0, s59
	s_nop 0
	global_load_lds_dwordx4 v178, s[26:27]
	s_mov_b32 m0, s28
	s_waitcnt vmcnt(4)
	s_waitcnt lgkmcnt(0)
	s_barrier
	s_setprio 1
	s_waitcnt lgkmcnt(7)
	v_mfma_f32_16x16x32_bf16 v[62:65], v[130:133], v[166:169], v[62:65]
	v_mfma_f32_16x16x32_bf16 v[62:65], v[134:137], v[170:173], v[62:65]
	s_waitcnt lgkmcnt(5)
	v_mfma_f32_16x16x32_bf16 v[58:61], v[138:141], v[166:169], v[58:61]
	v_mfma_f32_16x16x32_bf16 v[58:61], v[142:145], v[170:173], v[58:61]
	s_waitcnt lgkmcnt(3)
	v_mfma_f32_16x16x32_bf16 v[46:49], v[130:133], v[186:189], v[46:49]
	v_mfma_f32_16x16x32_bf16 v[46:49], v[134:137], v[190:193], v[46:49]
	s_waitcnt lgkmcnt(1)
	v_mfma_f32_16x16x32_bf16 v[42:45], v[138:141], v[186:189], v[42:45]
	v_mfma_f32_16x16x32_bf16 v[42:45], v[142:145], v[190:193], v[42:45]
	v_mfma_f32_16x16x32_bf16 v[30:33], v[130:133], v[194:197], v[30:33]
	v_mfma_f32_16x16x32_bf16 v[30:33], v[134:137], v[198:201], v[30:33]
	v_mfma_f32_16x16x32_bf16 v[26:29], v[138:141], v[194:197], v[26:29]
	v_mfma_f32_16x16x32_bf16 v[26:29], v[142:145], v[198:201], v[26:29]
	v_mfma_f32_16x16x32_bf16 v[14:17], v[130:133], v[202:205], v[14:17]
	v_mfma_f32_16x16x32_bf16 v[14:17], v[134:137], v[206:209], v[14:17]
	s_waitcnt lgkmcnt(0)
	v_mfma_f32_16x16x32_bf16 v[10:13], v[138:141], v[202:205], v[10:13]
	v_mfma_f32_16x16x32_bf16 v[10:13], v[142:145], v[206:209], v[10:13]
	s_setprio 0
	s_setprio 1
	v_mfma_f32_16x16x32_bf16 v[54:57], v[146:149], v[166:169], v[54:57]
	v_mfma_f32_16x16x32_bf16 v[54:57], v[150:153], v[170:173], v[54:57]
	v_mfma_f32_16x16x32_bf16 v[50:53], v[154:157], v[166:169], v[50:53]
	v_mfma_f32_16x16x32_bf16 v[50:53], v[158:161], v[170:173], v[50:53]
	v_mfma_f32_16x16x32_bf16 v[38:41], v[146:149], v[186:189], v[38:41]
	v_mfma_f32_16x16x32_bf16 v[38:41], v[150:153], v[190:193], v[38:41]
	v_mfma_f32_16x16x32_bf16 v[34:37], v[154:157], v[186:189], v[34:37]
	v_mfma_f32_16x16x32_bf16 v[34:37], v[158:161], v[190:193], v[34:37]
	v_mfma_f32_16x16x32_bf16 v[22:25], v[146:149], v[194:197], v[22:25]
	v_mfma_f32_16x16x32_bf16 v[22:25], v[150:153], v[198:201], v[22:25]
	v_mfma_f32_16x16x32_bf16 v[18:21], v[154:157], v[194:197], v[18:21]
	v_mfma_f32_16x16x32_bf16 v[18:21], v[158:161], v[198:201], v[18:21]
	v_mfma_f32_16x16x32_bf16 v[6:9], v[146:149], v[202:205], v[6:9]
	v_mfma_f32_16x16x32_bf16 v[6:9], v[150:153], v[206:209], v[6:9]
	s_setprio 2
	s_barrier
	v_mfma_f32_16x16x32_bf16 v[2:5], v[154:157], v[202:205], v[2:5]
	v_mfma_f32_16x16x32_bf16 v[2:5], v[158:161], v[206:209], v[2:5]
	s_setprio 0
	s_add_i32 s78, s78, 2
	s_add_u32 s74, s74, 0x100
	s_addc_u32 s75, s75, 0
	s_add_u32 s24, s24, 0x100
	s_addc_u32 s25, s25, 0
	s_add_u32 s76, s76, 0x100
	s_addc_u32 s77, s77, 0
	s_cmp_gt_u32 s78, 29
	.p2align 6
.LBB0_2410:
	ds_read_b128 v[130:133], v181
	ds_read_b128 v[134:137], v181 offset:1024
	ds_read_b128 v[138:141], v181 offset:2048
	ds_read_b128 v[142:145], v181 offset:3072
	ds_read_b128 v[146:149], v182
	ds_read_b128 v[150:153], v182 offset:1024
	ds_read_b128 v[154:157], v182 offset:2048
	ds_read_b128 v[158:161], v182 offset:3072
	s_cmp_eq_u32 s78, 28
	s_cselect_b32 s27, s15, s75
	s_cselect_b32 s26, s73, s74
	s_cselect_b32 s29, s17, s77
	s_cselect_b32 s28, s71, s76
	ds_read_b128 v[166:169], v183
	ds_read_b128 v[170:173], v183 offset:1024
	ds_read_b128 v[186:189], v183 offset:2048
	ds_read_b128 v[190:193], v183 offset:3072
	ds_read_b128 v[194:197], v183 offset:4096
	ds_read_b128 v[198:201], v183 offset:5120
	ds_read_b128 v[202:205], v183 offset:6144
	ds_read_b128 v[206:209], v183 offset:7168
	s_add_u32 s80, s24, 0xfff80000
	s_addc_u32 s81, s25, -1
	s_mov_b32 s79, m0
	s_mov_b32 m0, s64
	s_nop 0
	global_load_lds_dwordx4 v1, s[80:81]
	s_mov_b32 m0, s79
	s_nop 0
	s_mov_b32 s79, m0
	s_mov_b32 m0, s66
	s_nop 0
	global_load_lds_dwordx4 v177, s[80:81]
	s_mov_b32 m0, s79
	s_nop 0
	s_mov_b32 s79, m0
	s_mov_b32 m0, s65
	s_nop 0
	global_load_lds_dwordx4 v1, s[24:25]
	s_mov_b32 m0, s79
	s_nop 0
	s_mov_b32 s79, m0
	s_mov_b32 m0, s67
	s_nop 0
	global_load_lds_dwordx4 v177, s[24:25]
	s_mov_b32 m0, s79
	s_waitcnt vmcnt(8)
	s_waitcnt lgkmcnt(0)
	s_barrier
	s_setprio 1
	s_waitcnt lgkmcnt(7)
	v_mfma_f32_16x16x32_bf16 v[126:129], v[130:133], v[166:169], v[126:129]
	v_mfma_f32_16x16x32_bf16 v[126:129], v[134:137], v[170:173], v[126:129]
	s_waitcnt lgkmcnt(5)
	v_mfma_f32_16x16x32_bf16 v[122:125], v[138:141], v[166:169], v[122:125]
	v_mfma_f32_16x16x32_bf16 v[122:125], v[142:145], v[170:173], v[122:125]
	s_waitcnt lgkmcnt(3)
	v_mfma_f32_16x16x32_bf16 v[118:121], v[130:133], v[186:189], v[118:121]
	v_mfma_f32_16x16x32_bf16 v[118:121], v[134:137], v[190:193], v[118:121]
	s_waitcnt lgkmcnt(1)
	v_mfma_f32_16x16x32_bf16 v[114:117], v[138:141], v[186:189], v[114:117]
	v_mfma_f32_16x16x32_bf16 v[114:117], v[142:145], v[190:193], v[114:117]
	v_mfma_f32_16x16x32_bf16 v[94:97], v[130:133], v[194:197], v[94:97]
	v_mfma_f32_16x16x32_bf16 v[94:97], v[134:137], v[198:201], v[94:97]
	v_mfma_f32_16x16x32_bf16 v[90:93], v[138:141], v[194:197], v[90:93]
	v_mfma_f32_16x16x32_bf16 v[90:93], v[142:145], v[198:201], v[90:93]
	v_mfma_f32_16x16x32_bf16 v[86:89], v[130:133], v[202:205], v[86:89]
	v_mfma_f32_16x16x32_bf16 v[86:89], v[134:137], v[206:209], v[86:89]
	s_waitcnt lgkmcnt(0)
	v_mfma_f32_16x16x32_bf16 v[78:81], v[138:141], v[202:205], v[78:81]
	v_mfma_f32_16x16x32_bf16 v[78:81], v[142:145], v[206:209], v[78:81]
	s_setprio 0
	s_setprio 1
	v_mfma_f32_16x16x32_bf16 v[110:113], v[146:149], v[166:169], v[110:113]
	v_mfma_f32_16x16x32_bf16 v[110:113], v[150:153], v[170:173], v[110:113]
	v_mfma_f32_16x16x32_bf16 v[106:109], v[154:157], v[166:169], v[106:109]
	v_mfma_f32_16x16x32_bf16 v[106:109], v[158:161], v[170:173], v[106:109]
	v_mfma_f32_16x16x32_bf16 v[102:105], v[146:149], v[186:189], v[102:105]
	v_mfma_f32_16x16x32_bf16 v[102:105], v[150:153], v[190:193], v[102:105]
	v_mfma_f32_16x16x32_bf16 v[98:101], v[154:157], v[186:189], v[98:101]
	v_mfma_f32_16x16x32_bf16 v[98:101], v[158:161], v[190:193], v[98:101]
	v_mfma_f32_16x16x32_bf16 v[82:85], v[146:149], v[194:197], v[82:85]
	v_mfma_f32_16x16x32_bf16 v[82:85], v[150:153], v[198:201], v[82:85]
	v_mfma_f32_16x16x32_bf16 v[74:77], v[154:157], v[194:197], v[74:77]
	v_mfma_f32_16x16x32_bf16 v[74:77], v[158:161], v[198:201], v[74:77]
	v_mfma_f32_16x16x32_bf16 v[70:73], v[146:149], v[202:205], v[70:73]
	v_mfma_f32_16x16x32_bf16 v[70:73], v[150:153], v[206:209], v[70:73]
	s_setprio 2
	s_barrier
	v_mfma_f32_16x16x32_bf16 v[66:69], v[154:157], v[202:205], v[66:69]
	v_mfma_f32_16x16x32_bf16 v[66:69], v[158:161], v[206:209], v[66:69]
	s_setprio 0
	ds_read_b128 v[166:169], v183 offset:16384
	ds_read_b128 v[170:173], v183 offset:17408
	ds_read_b128 v[186:189], v183 offset:18432
	ds_read_b128 v[190:193], v183 offset:19456
	ds_read_b128 v[194:197], v183 offset:20480
	ds_read_b128 v[198:201], v183 offset:21504
	ds_read_b128 v[202:205], v183 offset:22528
	ds_read_b128 v[206:209], v183 offset:23552
	s_mov_b32 s79, m0
	s_mov_b32 m0, s41
	s_nop 0
	global_load_lds_dwordx4 v176, s[26:27]
	s_mov_b32 m0, s79
	s_add_u32 s80, s26, 0x80000
	s_mov_b32 s79, m0
	s_mov_b32 m0, s42
	s_nop 0
	global_load_lds_dwordx4 v178, s[26:27]
	s_mov_b32 m0, s79
	s_addc_u32 s81, s27, 0
	s_mov_b32 s79, m0
	s_mov_b32 m0, s43
	s_nop 0
	global_load_lds_dwordx4 v176, s[80:81]
	s_mov_b32 m0, s79
	s_nop 0
	s_mov_b32 s79, m0
	s_mov_b32 m0, s46
	s_nop 0
	global_load_lds_dwordx4 v178, s[80:81]
	s_mov_b32 m0, s79
	s_waitcnt vmcnt(4)
	s_waitcnt lgkmcnt(0)
	s_barrier
	s_setprio 1
	s_waitcnt lgkmcnt(7)
	v_mfma_f32_16x16x32_bf16 v[62:65], v[130:133], v[166:169], v[62:65]
	v_mfma_f32_16x16x32_bf16 v[62:65], v[134:137], v[170:173], v[62:65]
	s_waitcnt lgkmcnt(5)
	v_mfma_f32_16x16x32_bf16 v[58:61], v[138:141], v[166:169], v[58:61]
	v_mfma_f32_16x16x32_bf16 v[58:61], v[142:145], v[170:173], v[58:61]
	s_waitcnt lgkmcnt(3)
	v_mfma_f32_16x16x32_bf16 v[46:49], v[130:133], v[186:189], v[46:49]
	v_mfma_f32_16x16x32_bf16 v[46:49], v[134:137], v[190:193], v[46:49]
	s_waitcnt lgkmcnt(1)
	v_mfma_f32_16x16x32_bf16 v[42:45], v[138:141], v[186:189], v[42:45]
	v_mfma_f32_16x16x32_bf16 v[42:45], v[142:145], v[190:193], v[42:45]
	v_mfma_f32_16x16x32_bf16 v[30:33], v[130:133], v[194:197], v[30:33]
	v_mfma_f32_16x16x32_bf16 v[30:33], v[134:137], v[198:201], v[30:33]
	v_mfma_f32_16x16x32_bf16 v[26:29], v[138:141], v[194:197], v[26:29]
	v_mfma_f32_16x16x32_bf16 v[26:29], v[142:145], v[198:201], v[26:29]
	v_mfma_f32_16x16x32_bf16 v[14:17], v[130:133], v[202:205], v[14:17]
	v_mfma_f32_16x16x32_bf16 v[14:17], v[134:137], v[206:209], v[14:17]
	s_waitcnt lgkmcnt(0)
	v_mfma_f32_16x16x32_bf16 v[10:13], v[138:141], v[202:205], v[10:13]
	v_mfma_f32_16x16x32_bf16 v[10:13], v[142:145], v[206:209], v[10:13]
	s_setprio 0
	s_setprio 1
	v_mfma_f32_16x16x32_bf16 v[54:57], v[146:149], v[166:169], v[54:57]
	v_mfma_f32_16x16x32_bf16 v[54:57], v[150:153], v[170:173], v[54:57]
	v_mfma_f32_16x16x32_bf16 v[50:53], v[154:157], v[166:169], v[50:53]
	v_mfma_f32_16x16x32_bf16 v[50:53], v[158:161], v[170:173], v[50:53]
	v_mfma_f32_16x16x32_bf16 v[38:41], v[146:149], v[186:189], v[38:41]
	v_mfma_f32_16x16x32_bf16 v[38:41], v[150:153], v[190:193], v[38:41]
	v_mfma_f32_16x16x32_bf16 v[34:37], v[154:157], v[186:189], v[34:37]
	v_mfma_f32_16x16x32_bf16 v[34:37], v[158:161], v[190:193], v[34:37]
	v_mfma_f32_16x16x32_bf16 v[22:25], v[146:149], v[194:197], v[22:25]
	v_mfma_f32_16x16x32_bf16 v[22:25], v[150:153], v[198:201], v[22:25]
	v_mfma_f32_16x16x32_bf16 v[18:21], v[154:157], v[194:197], v[18:21]
	v_mfma_f32_16x16x32_bf16 v[18:21], v[158:161], v[198:201], v[18:21]
	v_mfma_f32_16x16x32_bf16 v[6:9], v[146:149], v[202:205], v[6:9]
	v_mfma_f32_16x16x32_bf16 v[6:9], v[150:153], v[206:209], v[6:9]
	s_setprio 2
	s_barrier
	v_mfma_f32_16x16x32_bf16 v[2:5], v[154:157], v[202:205], v[2:5]
	v_mfma_f32_16x16x32_bf16 v[2:5], v[158:161], v[206:209], v[2:5]
	s_setprio 0
	ds_read_b128 v[130:133], v184
	ds_read_b128 v[134:137], v184 offset:1024
	ds_read_b128 v[138:141], v184 offset:2048
	ds_read_b128 v[142:145], v184 offset:3072
	ds_read_b128 v[146:149], v185
	ds_read_b128 v[150:153], v185 offset:1024
	ds_read_b128 v[154:157], v185 offset:2048
	ds_read_b128 v[158:161], v185 offset:3072
	ds_read_b128 v[166:169], v183 offset:32768
	ds_read_b128 v[170:173], v183 offset:33792
	ds_read_b128 v[186:189], v183 offset:34816
	ds_read_b128 v[190:193], v183 offset:35840
	ds_read_b128 v[194:197], v183 offset:36864
	ds_read_b128 v[198:201], v183 offset:37888
	ds_read_b128 v[202:205], v183 offset:38912
	ds_read_b128 v[206:209], v183 offset:39936
	s_mov_b32 s79, m0
	s_mov_b32 m0, s40
	s_nop 0
	global_load_lds_dwordx4 v1, s[28:29]
	s_mov_b32 m0, s79
	s_nop 0
	s_mov_b32 s79, m0
	s_mov_b32 m0, s47
	s_nop 0
	global_load_lds_dwordx4 v177, s[28:29]
	s_mov_b32 m0, s79
	s_add_u32 s28, s28, 0x80000
	s_addc_u32 s29, s29, 0
	s_mov_b32 s79, m0
	s_mov_b32 m0, s48
	s_nop 0
	global_load_lds_dwordx4 v1, s[28:29]
	s_mov_b32 m0, s79
	s_nop 0
	s_mov_b32 s79, m0
	s_mov_b32 m0, s49
	s_nop 0
	global_load_lds_dwordx4 v177, s[28:29]
	s_mov_b32 m0, s79
	s_waitcnt vmcnt(8)
	s_waitcnt lgkmcnt(0)
	s_barrier
	s_setprio 1
	s_waitcnt lgkmcnt(7)
	v_mfma_f32_16x16x32_bf16 v[126:129], v[130:133], v[166:169], v[126:129]
	v_mfma_f32_16x16x32_bf16 v[126:129], v[134:137], v[170:173], v[126:129]
	s_waitcnt lgkmcnt(5)
	v_mfma_f32_16x16x32_bf16 v[122:125], v[138:141], v[166:169], v[122:125]
	v_mfma_f32_16x16x32_bf16 v[122:125], v[142:145], v[170:173], v[122:125]
	s_waitcnt lgkmcnt(3)
	v_mfma_f32_16x16x32_bf16 v[118:121], v[130:133], v[186:189], v[118:121]
	v_mfma_f32_16x16x32_bf16 v[118:121], v[134:137], v[190:193], v[118:121]
	s_waitcnt lgkmcnt(1)
	v_mfma_f32_16x16x32_bf16 v[114:117], v[138:141], v[186:189], v[114:117]
	v_mfma_f32_16x16x32_bf16 v[114:117], v[142:145], v[190:193], v[114:117]
	v_mfma_f32_16x16x32_bf16 v[94:97], v[130:133], v[194:197], v[94:97]
	v_mfma_f32_16x16x32_bf16 v[94:97], v[134:137], v[198:201], v[94:97]
	v_mfma_f32_16x16x32_bf16 v[90:93], v[138:141], v[194:197], v[90:93]
	v_mfma_f32_16x16x32_bf16 v[90:93], v[142:145], v[198:201], v[90:93]
	v_mfma_f32_16x16x32_bf16 v[86:89], v[130:133], v[202:205], v[86:89]
	v_mfma_f32_16x16x32_bf16 v[86:89], v[134:137], v[206:209], v[86:89]
	s_waitcnt lgkmcnt(0)
	v_mfma_f32_16x16x32_bf16 v[78:81], v[138:141], v[202:205], v[78:81]
	v_mfma_f32_16x16x32_bf16 v[78:81], v[142:145], v[206:209], v[78:81]
	s_setprio 0
	s_setprio 1
	v_mfma_f32_16x16x32_bf16 v[110:113], v[146:149], v[166:169], v[110:113]
	v_mfma_f32_16x16x32_bf16 v[110:113], v[150:153], v[170:173], v[110:113]
	v_mfma_f32_16x16x32_bf16 v[106:109], v[154:157], v[166:169], v[106:109]
	v_mfma_f32_16x16x32_bf16 v[106:109], v[158:161], v[170:173], v[106:109]
	v_mfma_f32_16x16x32_bf16 v[102:105], v[146:149], v[186:189], v[102:105]
	v_mfma_f32_16x16x32_bf16 v[102:105], v[150:153], v[190:193], v[102:105]
	v_mfma_f32_16x16x32_bf16 v[98:101], v[154:157], v[186:189], v[98:101]
	v_mfma_f32_16x16x32_bf16 v[98:101], v[158:161], v[190:193], v[98:101]
	v_mfma_f32_16x16x32_bf16 v[82:85], v[146:149], v[194:197], v[82:85]
	v_mfma_f32_16x16x32_bf16 v[82:85], v[150:153], v[198:201], v[82:85]
	v_mfma_f32_16x16x32_bf16 v[74:77], v[154:157], v[194:197], v[74:77]
	v_mfma_f32_16x16x32_bf16 v[74:77], v[158:161], v[198:201], v[74:77]
	v_mfma_f32_16x16x32_bf16 v[70:73], v[146:149], v[202:205], v[70:73]
	v_mfma_f32_16x16x32_bf16 v[70:73], v[150:153], v[206:209], v[70:73]
	s_setprio 2
	s_barrier
	v_mfma_f32_16x16x32_bf16 v[66:69], v[154:157], v[202:205], v[66:69]
	v_mfma_f32_16x16x32_bf16 v[66:69], v[158:161], v[206:209], v[66:69]
	s_setprio 0
	ds_read_b128 v[166:169], v183 offset:49152
	ds_read_b128 v[170:173], v183 offset:50176
	ds_read_b128 v[186:189], v183 offset:51200
	ds_read_b128 v[190:193], v183 offset:52224
	ds_read_b128 v[194:197], v183 offset:53248
	ds_read_b128 v[198:201], v183 offset:54272
	ds_read_b128 v[202:205], v183 offset:55296
	ds_read_b128 v[206:209], v183 offset:56320
	s_add_u32 s28, s26, 0x80
	s_addc_u32 s29, s27, 0
	s_mov_b32 s79, m0
	s_mov_b32 m0, s56
	s_nop 0
	global_load_lds_dwordx4 v176, s[28:29]
	s_mov_b32 m0, s79
	s_add_u32 s26, s26, 0x80080
	s_mov_b32 s79, m0
	s_mov_b32 m0, s57
	s_nop 0
	global_load_lds_dwordx4 v178, s[28:29]
	s_mov_b32 m0, s79
	s_addc_u32 s27, s27, 0
	s_mov_b32 s28, m0
	s_mov_b32 m0, s58
	s_nop 0
	global_load_lds_dwordx4 v176, s[26:27]
	s_mov_b32 m0, s28
	s_nop 0
	s_mov_b32 s28, m0
	s_mov_b32 m0, s59
	s_nop 0
	global_load_lds_dwordx4 v178, s[26:27]
	s_mov_b32 m0, s28
	s_waitcnt vmcnt(4)
	s_waitcnt lgkmcnt(0)
	s_barrier
	s_setprio 1
	s_waitcnt lgkmcnt(7)
	v_mfma_f32_16x16x32_bf16 v[62:65], v[130:133], v[166:169], v[62:65]
	v_mfma_f32_16x16x32_bf16 v[62:65], v[134:137], v[170:173], v[62:65]
	s_waitcnt lgkmcnt(5)
	v_mfma_f32_16x16x32_bf16 v[58:61], v[138:141], v[166:169], v[58:61]
	v_mfma_f32_16x16x32_bf16 v[58:61], v[142:145], v[170:173], v[58:61]
	s_waitcnt lgkmcnt(3)
	v_mfma_f32_16x16x32_bf16 v[46:49], v[130:133], v[186:189], v[46:49]
	v_mfma_f32_16x16x32_bf16 v[46:49], v[134:137], v[190:193], v[46:49]
	s_waitcnt lgkmcnt(1)
	v_mfma_f32_16x16x32_bf16 v[42:45], v[138:141], v[186:189], v[42:45]
	v_mfma_f32_16x16x32_bf16 v[42:45], v[142:145], v[190:193], v[42:45]
	v_mfma_f32_16x16x32_bf16 v[30:33], v[130:133], v[194:197], v[30:33]
	v_mfma_f32_16x16x32_bf16 v[30:33], v[134:137], v[198:201], v[30:33]
	v_mfma_f32_16x16x32_bf16 v[26:29], v[138:141], v[194:197], v[26:29]
	v_mfma_f32_16x16x32_bf16 v[26:29], v[142:145], v[198:201], v[26:29]
	v_mfma_f32_16x16x32_bf16 v[14:17], v[130:133], v[202:205], v[14:17]
	v_mfma_f32_16x16x32_bf16 v[14:17], v[134:137], v[206:209], v[14:17]
	s_waitcnt lgkmcnt(0)
	v_mfma_f32_16x16x32_bf16 v[10:13], v[138:141], v[202:205], v[10:13]
	v_mfma_f32_16x16x32_bf16 v[10:13], v[142:145], v[206:209], v[10:13]
	s_setprio 0
	s_setprio 1
	v_mfma_f32_16x16x32_bf16 v[54:57], v[146:149], v[166:169], v[54:57]
	v_mfma_f32_16x16x32_bf16 v[54:57], v[150:153], v[170:173], v[54:57]
	v_mfma_f32_16x16x32_bf16 v[50:53], v[154:157], v[166:169], v[50:53]
	v_mfma_f32_16x16x32_bf16 v[50:53], v[158:161], v[170:173], v[50:53]
	v_mfma_f32_16x16x32_bf16 v[38:41], v[146:149], v[186:189], v[38:41]
	v_mfma_f32_16x16x32_bf16 v[38:41], v[150:153], v[190:193], v[38:41]
	v_mfma_f32_16x16x32_bf16 v[34:37], v[154:157], v[186:189], v[34:37]
	v_mfma_f32_16x16x32_bf16 v[34:37], v[158:161], v[190:193], v[34:37]
	v_mfma_f32_16x16x32_bf16 v[22:25], v[146:149], v[194:197], v[22:25]
	v_mfma_f32_16x16x32_bf16 v[22:25], v[150:153], v[198:201], v[22:25]
	v_mfma_f32_16x16x32_bf16 v[18:21], v[154:157], v[194:197], v[18:21]
	v_mfma_f32_16x16x32_bf16 v[18:21], v[158:161], v[198:201], v[18:21]
	v_mfma_f32_16x16x32_bf16 v[6:9], v[146:149], v[202:205], v[6:9]
	v_mfma_f32_16x16x32_bf16 v[6:9], v[150:153], v[206:209], v[6:9]
	s_setprio 2
	s_barrier
	v_mfma_f32_16x16x32_bf16 v[2:5], v[154:157], v[202:205], v[2:5]
	v_mfma_f32_16x16x32_bf16 v[2:5], v[158:161], v[206:209], v[2:5]
	s_setprio 0
	s_add_i32 s78, s78, 2
	s_add_u32 s74, s74, 0x100
	s_addc_u32 s75, s75, 0
	s_add_u32 s24, s24, 0x100
	s_addc_u32 s25, s25, 0
	s_add_u32 s76, s76, 0x100
	s_addc_u32 s77, s77, 0
	s_cmp_gt_u32 s78, 29
	s_cbranch_scc0 .LBB0_2410
	s_and_b64 vcc, exec, s[8:9]
	s_cbranch_vccz .LBB0_2413
	s_barrier

.LBB0_2593:
	s_ashr_i32 s11, s10, 31
	s_lshl_b64 s[12:13], s[10:11], 20
	s_add_u32 s12, s26, s12
	s_addc_u32 s13, s27, s13
	s_and_b64 s[14:15], s[2:3], exec
	s_cselect_b32 s11, s13, s21
	s_cselect_b32 s62, s12, s20
	s_ashr_i32 s9, s8, 31
	s_lshl_b64 s[14:15], s[8:9], 20
	s_add_u32 s14, s28, s14
	s_addc_u32 s15, s29, s15
	s_and_b64 s[22:23], s[2:3], exec
	s_cselect_b32 s9, s15, s19
	s_cselect_b32 s63, s14, s18
	s_add_u32 s64, s18, 0x100
	s_addc_u32 s65, s19, 0
	s_add_u32 s18, s20, 0x80080
	s_addc_u32 s19, s21, 0
	s_add_u32 s66, s20, 0x100
	s_addc_u32 s67, s21, 0
	s_mov_b32 s70, -2
	ds_read_b128 v[148:151], v143
	ds_read_b128 v[152:155], v143 offset:1024
	ds_read_b128 v[156:159], v143 offset:2048
	ds_read_b128 v[160:163], v143 offset:3072
	ds_read_b128 v[164:167], v144
	ds_read_b128 v[168:171], v144 offset:1024
	ds_read_b128 v[172:175], v144 offset:2048
	ds_read_b128 v[176:179], v144 offset:3072
	s_cmp_eq_u32 s70, 28
	s_cselect_b32 s21, s9, s65
	s_cselect_b32 s20, s63, s64
	s_cselect_b32 s23, s11, s67
	s_cselect_b32 s22, s62, s66
	ds_read_b128 v[180:183], v145
	ds_read_b128 v[184:187], v145 offset:1024
	ds_read_b128 v[188:191], v145 offset:2048
	ds_read_b128 v[192:195], v145 offset:3072
	ds_read_b128 v[196:199], v145 offset:4096
	ds_read_b128 v[200:203], v145 offset:5120
	ds_read_b128 v[204:207], v145 offset:6144
	ds_read_b128 v[208:211], v145 offset:7168
	s_add_u32 s74, s18, 0xfff80000
	s_addc_u32 s75, s19, -1
	s_mov_b32 s71, m0
	s_mov_b32 m0, s48
	s_nop 0
	global_load_lds_dwordx4 v138, s[74:75]
	s_mov_b32 m0, s71
	s_nop 0
	s_mov_b32 s71, m0
	s_mov_b32 m0, s57
	s_nop 0
	global_load_lds_dwordx4 v140, s[74:75]
	s_mov_b32 m0, s71
	s_nop 0
	s_mov_b32 s71, m0
	s_mov_b32 m0, s49
	s_nop 0
	global_load_lds_dwordx4 v138, s[18:19]
	s_mov_b32 m0, s71
	s_nop 0
	s_mov_b32 s71, m0
	s_mov_b32 m0, s58
	s_nop 0
	global_load_lds_dwordx4 v140, s[18:19]
	s_mov_b32 m0, s71
	s_waitcnt vmcnt(8)
	s_waitcnt lgkmcnt(0)
	s_barrier
	s_setprio 1
	s_waitcnt lgkmcnt(7)
	v_mfma_f32_16x16x32_bf16 v[126:129], v[148:151], v[180:183], 0
	v_mfma_f32_16x16x32_bf16 v[126:129], v[152:155], v[184:187], v[126:129]
	s_waitcnt lgkmcnt(5)
	v_mfma_f32_16x16x32_bf16 v[122:125], v[156:159], v[180:183], 0
	v_mfma_f32_16x16x32_bf16 v[122:125], v[160:163], v[184:187], v[122:125]
	s_waitcnt lgkmcnt(3)
	v_mfma_f32_16x16x32_bf16 v[110:113], v[148:151], v[188:191], 0
	v_mfma_f32_16x16x32_bf16 v[110:113], v[152:155], v[192:195], v[110:113]
	s_waitcnt lgkmcnt(1)
	v_mfma_f32_16x16x32_bf16 v[106:109], v[156:159], v[188:191], 0
	v_mfma_f32_16x16x32_bf16 v[106:109], v[160:163], v[192:195], v[106:109]
	v_mfma_f32_16x16x32_bf16 v[94:97], v[148:151], v[196:199], 0
	v_mfma_f32_16x16x32_bf16 v[94:97], v[152:155], v[200:203], v[94:97]
	v_mfma_f32_16x16x32_bf16 v[90:93], v[156:159], v[196:199], 0
	v_mfma_f32_16x16x32_bf16 v[90:93], v[160:163], v[200:203], v[90:93]
	v_mfma_f32_16x16x32_bf16 v[78:81], v[148:151], v[204:207], 0
	v_mfma_f32_16x16x32_bf16 v[78:81], v[152:155], v[208:211], v[78:81]
	s_waitcnt lgkmcnt(0)
	v_mfma_f32_16x16x32_bf16 v[74:77], v[156:159], v[204:207], 0
	v_mfma_f32_16x16x32_bf16 v[74:77], v[160:163], v[208:211], v[74:77]
	s_setprio 0
	s_setprio 1
	v_mfma_f32_16x16x32_bf16 v[118:121], v[164:167], v[180:183], 0
	v_mfma_f32_16x16x32_bf16 v[118:121], v[168:171], v[184:187], v[118:121]
	v_mfma_f32_16x16x32_bf16 v[114:117], v[172:175], v[180:183], 0
	v_mfma_f32_16x16x32_bf16 v[114:117], v[176:179], v[184:187], v[114:117]
	v_mfma_f32_16x16x32_bf16 v[102:105], v[164:167], v[188:191], 0
	v_mfma_f32_16x16x32_bf16 v[102:105], v[168:171], v[192:195], v[102:105]
	v_mfma_f32_16x16x32_bf16 v[98:101], v[172:175], v[188:191], 0
	v_mfma_f32_16x16x32_bf16 v[98:101], v[176:179], v[192:195], v[98:101]
	v_mfma_f32_16x16x32_bf16 v[86:89], v[164:167], v[196:199], 0
	v_mfma_f32_16x16x32_bf16 v[86:89], v[168:171], v[200:203], v[86:89]
	v_mfma_f32_16x16x32_bf16 v[82:85], v[172:175], v[196:199], 0
	v_mfma_f32_16x16x32_bf16 v[82:85], v[176:179], v[200:203], v[82:85]
	v_mfma_f32_16x16x32_bf16 v[70:73], v[164:167], v[204:207], 0
	v_mfma_f32_16x16x32_bf16 v[70:73], v[168:171], v[208:211], v[70:73]
	s_setprio 2
	s_barrier
	v_mfma_f32_16x16x32_bf16 v[66:69], v[172:175], v[204:207], 0
	v_mfma_f32_16x16x32_bf16 v[66:69], v[176:179], v[208:211], v[66:69]
	s_setprio 0
	ds_read_b128 v[180:183], v145 offset:16384
	ds_read_b128 v[184:187], v145 offset:17408
	ds_read_b128 v[188:191], v145 offset:18432
	ds_read_b128 v[192:195], v145 offset:19456
	ds_read_b128 v[196:199], v145 offset:20480
	ds_read_b128 v[200:203], v145 offset:21504
	ds_read_b128 v[204:207], v145 offset:22528
	ds_read_b128 v[208:211], v145 offset:23552
	s_mov_b32 s71, m0
	s_mov_b32 m0, s35
	s_nop 0
	global_load_lds_dwordx4 v139, s[20:21]
	s_mov_b32 m0, s71
	s_add_u32 s74, s20, 0x80000
	s_mov_b32 s71, m0
	s_mov_b32 m0, s36
	s_nop 0
	global_load_lds_dwordx4 v141, s[20:21]
	s_mov_b32 m0, s71
	s_addc_u32 s75, s21, 0
	s_mov_b32 s71, m0
	s_mov_b32 m0, s37
	s_nop 0
	global_load_lds_dwordx4 v139, s[74:75]
	s_mov_b32 m0, s71
	s_nop 0
	s_mov_b32 s71, m0
	s_mov_b32 m0, s40
	s_nop 0
	global_load_lds_dwordx4 v141, s[74:75]
	s_mov_b32 m0, s71
	s_waitcnt vmcnt(4)
	s_waitcnt lgkmcnt(0)
	s_barrier
	s_setprio 1
	s_waitcnt lgkmcnt(7)
	v_mfma_f32_16x16x32_bf16 v[62:65], v[148:151], v[180:183], 0
	v_mfma_f32_16x16x32_bf16 v[62:65], v[152:155], v[184:187], v[62:65]
	s_waitcnt lgkmcnt(5)
	v_mfma_f32_16x16x32_bf16 v[58:61], v[156:159], v[180:183], 0
	v_mfma_f32_16x16x32_bf16 v[58:61], v[160:163], v[184:187], v[58:61]
	s_waitcnt lgkmcnt(3)
	v_mfma_f32_16x16x32_bf16 v[46:49], v[148:151], v[188:191], 0
	v_mfma_f32_16x16x32_bf16 v[46:49], v[152:155], v[192:195], v[46:49]
	s_waitcnt lgkmcnt(1)
	v_mfma_f32_16x16x32_bf16 v[42:45], v[156:159], v[188:191], 0
	v_mfma_f32_16x16x32_bf16 v[42:45], v[160:163], v[192:195], v[42:45]
	v_mfma_f32_16x16x32_bf16 v[30:33], v[148:151], v[196:199], 0
	v_mfma_f32_16x16x32_bf16 v[30:33], v[152:155], v[200:203], v[30:33]
	v_mfma_f32_16x16x32_bf16 v[26:29], v[156:159], v[196:199], 0
	v_mfma_f32_16x16x32_bf16 v[26:29], v[160:163], v[200:203], v[26:29]
	v_mfma_f32_16x16x32_bf16 v[14:17], v[148:151], v[204:207], 0
	v_mfma_f32_16x16x32_bf16 v[14:17], v[152:155], v[208:211], v[14:17]
	s_waitcnt lgkmcnt(0)
	v_mfma_f32_16x16x32_bf16 v[10:13], v[156:159], v[204:207], 0
	v_mfma_f32_16x16x32_bf16 v[10:13], v[160:163], v[208:211], v[10:13]
	s_setprio 0
	s_setprio 1
	v_mfma_f32_16x16x32_bf16 v[54:57], v[164:167], v[180:183], 0
	v_mfma_f32_16x16x32_bf16 v[54:57], v[168:171], v[184:187], v[54:57]
	v_mfma_f32_16x16x32_bf16 v[50:53], v[172:175], v[180:183], 0
	v_mfma_f32_16x16x32_bf16 v[50:53], v[176:179], v[184:187], v[50:53]
	v_mfma_f32_16x16x32_bf16 v[38:41], v[164:167], v[188:191], 0
	v_mfma_f32_16x16x32_bf16 v[38:41], v[168:171], v[192:195], v[38:41]
	v_mfma_f32_16x16x32_bf16 v[34:37], v[172:175], v[188:191], 0
	v_mfma_f32_16x16x32_bf16 v[34:37], v[176:179], v[192:195], v[34:37]
	v_mfma_f32_16x16x32_bf16 v[22:25], v[164:167], v[196:199], 0
	v_mfma_f32_16x16x32_bf16 v[22:25], v[168:171], v[200:203], v[22:25]
	v_mfma_f32_16x16x32_bf16 v[18:21], v[172:175], v[196:199], 0
	v_mfma_f32_16x16x32_bf16 v[18:21], v[176:179], v[200:203], v[18:21]
	v_mfma_f32_16x16x32_bf16 v[6:9], v[164:167], v[204:207], 0
	v_mfma_f32_16x16x32_bf16 v[6:9], v[168:171], v[208:211], v[6:9]
	s_setprio 2
	s_barrier
	v_mfma_f32_16x16x32_bf16 v[2:5], v[172:175], v[204:207], 0
	v_mfma_f32_16x16x32_bf16 v[2:5], v[176:179], v[208:211], v[2:5]
	s_setprio 0
	ds_read_b128 v[148:151], v146
	ds_read_b128 v[152:155], v146 offset:1024
	ds_read_b128 v[156:159], v146 offset:2048
	ds_read_b128 v[160:163], v146 offset:3072
	ds_read_b128 v[164:167], v147
	ds_read_b128 v[168:171], v147 offset:1024
	ds_read_b128 v[172:175], v147 offset:2048
	ds_read_b128 v[176:179], v147 offset:3072
	ds_read_b128 v[180:183], v145 offset:32768
	ds_read_b128 v[184:187], v145 offset:33792
	ds_read_b128 v[188:191], v145 offset:34816
	ds_read_b128 v[192:195], v145 offset:35840
	ds_read_b128 v[196:199], v145 offset:36864
	ds_read_b128 v[200:203], v145 offset:37888
	ds_read_b128 v[204:207], v145 offset:38912
	ds_read_b128 v[208:211], v145 offset:39936
	s_mov_b32 s71, m0
	s_mov_b32 m0, s31
	s_nop 0
	global_load_lds_dwordx4 v138, s[22:23]
	s_mov_b32 m0, s71
	s_nop 0
	s_mov_b32 s71, m0
	s_mov_b32 m0, s41
	s_nop 0
	global_load_lds_dwordx4 v140, s[22:23]
	s_mov_b32 m0, s71
	s_add_u32 s22, s22, 0x80000
	s_addc_u32 s23, s23, 0
	s_mov_b32 s71, m0
	s_mov_b32 m0, s42
	s_nop 0
	global_load_lds_dwordx4 v138, s[22:23]
	s_mov_b32 m0, s71
	s_nop 0
	s_mov_b32 s71, m0
	s_mov_b32 m0, s43
	s_nop 0
	global_load_lds_dwordx4 v140, s[22:23]
	s_mov_b32 m0, s71
	s_waitcnt vmcnt(8)
	s_waitcnt lgkmcnt(0)
	s_barrier
	s_setprio 1
	s_waitcnt lgkmcnt(7)
	v_mfma_f32_16x16x32_bf16 v[126:129], v[148:151], v[180:183], v[126:129]
	v_mfma_f32_16x16x32_bf16 v[126:129], v[152:155], v[184:187], v[126:129]
	s_waitcnt lgkmcnt(5)
	v_mfma_f32_16x16x32_bf16 v[122:125], v[156:159], v[180:183], v[122:125]
	v_mfma_f32_16x16x32_bf16 v[122:125], v[160:163], v[184:187], v[122:125]
	s_waitcnt lgkmcnt(3)
	v_mfma_f32_16x16x32_bf16 v[110:113], v[148:151], v[188:191], v[110:113]
	v_mfma_f32_16x16x32_bf16 v[110:113], v[152:155], v[192:195], v[110:113]
	s_waitcnt lgkmcnt(1)
	v_mfma_f32_16x16x32_bf16 v[106:109], v[156:159], v[188:191], v[106:109]
	v_mfma_f32_16x16x32_bf16 v[106:109], v[160:163], v[192:195], v[106:109]
	v_mfma_f32_16x16x32_bf16 v[94:97], v[148:151], v[196:199], v[94:97]
	v_mfma_f32_16x16x32_bf16 v[94:97], v[152:155], v[200:203], v[94:97]
	v_mfma_f32_16x16x32_bf16 v[90:93], v[156:159], v[196:199], v[90:93]
	v_mfma_f32_16x16x32_bf16 v[90:93], v[160:163], v[200:203], v[90:93]
	v_mfma_f32_16x16x32_bf16 v[78:81], v[148:151], v[204:207], v[78:81]
	v_mfma_f32_16x16x32_bf16 v[78:81], v[152:155], v[208:211], v[78:81]
	s_waitcnt lgkmcnt(0)
	v_mfma_f32_16x16x32_bf16 v[74:77], v[156:159], v[204:207], v[74:77]
	v_mfma_f32_16x16x32_bf16 v[74:77], v[160:163], v[208:211], v[74:77]
	s_setprio 0
	s_setprio 1
	v_mfma_f32_16x16x32_bf16 v[118:121], v[164:167], v[180:183], v[118:121]
	v_mfma_f32_16x16x32_bf16 v[118:121], v[168:171], v[184:187], v[118:121]
	v_mfma_f32_16x16x32_bf16 v[114:117], v[172:175], v[180:183], v[114:117]
	v_mfma_f32_16x16x32_bf16 v[114:117], v[176:179], v[184:187], v[114:117]
	v_mfma_f32_16x16x32_bf16 v[102:105], v[164:167], v[188:191], v[102:105]
	v_mfma_f32_16x16x32_bf16 v[102:105], v[168:171], v[192:195], v[102:105]
	v_mfma_f32_16x16x32_bf16 v[98:101], v[172:175], v[188:191], v[98:101]
	v_mfma_f32_16x16x32_bf16 v[98:101], v[176:179], v[192:195], v[98:101]
	v_mfma_f32_16x16x32_bf16 v[86:89], v[164:167], v[196:199], v[86:89]
	v_mfma_f32_16x16x32_bf16 v[86:89], v[168:171], v[200:203], v[86:89]
	v_mfma_f32_16x16x32_bf16 v[82:85], v[172:175], v[196:199], v[82:85]
	v_mfma_f32_16x16x32_bf16 v[82:85], v[176:179], v[200:203], v[82:85]
	v_mfma_f32_16x16x32_bf16 v[70:73], v[164:167], v[204:207], v[70:73]
	v_mfma_f32_16x16x32_bf16 v[70:73], v[168:171], v[208:211], v[70:73]
	s_setprio 2
	s_barrier
	v_mfma_f32_16x16x32_bf16 v[66:69], v[172:175], v[204:207], v[66:69]
	v_mfma_f32_16x16x32_bf16 v[66:69], v[176:179], v[208:211], v[66:69]
	s_setprio 0
	ds_read_b128 v[180:183], v145 offset:49152
	ds_read_b128 v[184:187], v145 offset:50176
	ds_read_b128 v[188:191], v145 offset:51200
	ds_read_b128 v[192:195], v145 offset:52224
	ds_read_b128 v[196:199], v145 offset:53248
	ds_read_b128 v[200:203], v145 offset:54272
	ds_read_b128 v[204:207], v145 offset:55296
	ds_read_b128 v[208:211], v145 offset:56320
	s_add_u32 s22, s20, 0x80
	s_addc_u32 s23, s21, 0
	s_mov_b32 s71, m0
	s_mov_b32 m0, s44
	s_nop 0
	global_load_lds_dwordx4 v139, s[22:23]
	s_mov_b32 m0, s71
	s_add_u32 s20, s20, 0x80080
	s_mov_b32 s71, m0
	s_mov_b32 m0, s45
	s_nop 0
	global_load_lds_dwordx4 v141, s[22:23]
	s_mov_b32 m0, s71
	s_addc_u32 s21, s21, 0
	s_mov_b32 s22, m0
	s_mov_b32 m0, s46
	s_nop 0
	global_load_lds_dwordx4 v139, s[20:21]
	s_mov_b32 m0, s22
	s_nop 0
	s_mov_b32 s22, m0
	s_mov_b32 m0, s47
	s_nop 0
	global_load_lds_dwordx4 v141, s[20:21]
	s_mov_b32 m0, s22
	s_waitcnt vmcnt(4)
	s_waitcnt lgkmcnt(0)
	s_barrier
	s_setprio 1
	s_waitcnt lgkmcnt(7)
	v_mfma_f32_16x16x32_bf16 v[62:65], v[148:151], v[180:183], v[62:65]
	v_mfma_f32_16x16x32_bf16 v[62:65], v[152:155], v[184:187], v[62:65]
	s_waitcnt lgkmcnt(5)
	v_mfma_f32_16x16x32_bf16 v[58:61], v[156:159], v[180:183], v[58:61]
	v_mfma_f32_16x16x32_bf16 v[58:61], v[160:163], v[184:187], v[58:61]
	s_waitcnt lgkmcnt(3)
	v_mfma_f32_16x16x32_bf16 v[46:49], v[148:151], v[188:191], v[46:49]
	v_mfma_f32_16x16x32_bf16 v[46:49], v[152:155], v[192:195], v[46:49]
	s_waitcnt lgkmcnt(1)
	v_mfma_f32_16x16x32_bf16 v[42:45], v[156:159], v[188:191], v[42:45]
	v_mfma_f32_16x16x32_bf16 v[42:45], v[160:163], v[192:195], v[42:45]
	v_mfma_f32_16x16x32_bf16 v[30:33], v[148:151], v[196:199], v[30:33]
	v_mfma_f32_16x16x32_bf16 v[30:33], v[152:155], v[200:203], v[30:33]
	v_mfma_f32_16x16x32_bf16 v[26:29], v[156:159], v[196:199], v[26:29]
	v_mfma_f32_16x16x32_bf16 v[26:29], v[160:163], v[200:203], v[26:29]
	v_mfma_f32_16x16x32_bf16 v[14:17], v[148:151], v[204:207], v[14:17]
	v_mfma_f32_16x16x32_bf16 v[14:17], v[152:155], v[208:211], v[14:17]
	s_waitcnt lgkmcnt(0)
	v_mfma_f32_16x16x32_bf16 v[10:13], v[156:159], v[204:207], v[10:13]
	v_mfma_f32_16x16x32_bf16 v[10:13], v[160:163], v[208:211], v[10:13]
	s_setprio 0
	s_setprio 1
	v_mfma_f32_16x16x32_bf16 v[54:57], v[164:167], v[180:183], v[54:57]
	v_mfma_f32_16x16x32_bf16 v[54:57], v[168:171], v[184:187], v[54:57]
	v_mfma_f32_16x16x32_bf16 v[50:53], v[172:175], v[180:183], v[50:53]
	v_mfma_f32_16x16x32_bf16 v[50:53], v[176:179], v[184:187], v[50:53]
	v_mfma_f32_16x16x32_bf16 v[38:41], v[164:167], v[188:191], v[38:41]
	v_mfma_f32_16x16x32_bf16 v[38:41], v[168:171], v[192:195], v[38:41]
	v_mfma_f32_16x16x32_bf16 v[34:37], v[172:175], v[188:191], v[34:37]
	v_mfma_f32_16x16x32_bf16 v[34:37], v[176:179], v[192:195], v[34:37]
	v_mfma_f32_16x16x32_bf16 v[22:25], v[164:167], v[196:199], v[22:25]
	v_mfma_f32_16x16x32_bf16 v[22:25], v[168:171], v[200:203], v[22:25]
	v_mfma_f32_16x16x32_bf16 v[18:21], v[172:175], v[196:199], v[18:21]
	v_mfma_f32_16x16x32_bf16 v[18:21], v[176:179], v[200:203], v[18:21]
	v_mfma_f32_16x16x32_bf16 v[6:9], v[164:167], v[204:207], v[6:9]
	v_mfma_f32_16x16x32_bf16 v[6:9], v[168:171], v[208:211], v[6:9]
	s_setprio 2
	s_barrier
	v_mfma_f32_16x16x32_bf16 v[2:5], v[172:175], v[204:207], v[2:5]
	v_mfma_f32_16x16x32_bf16 v[2:5], v[176:179], v[208:211], v[2:5]
	s_setprio 0
	s_add_i32 s70, s70, 2
	s_add_u32 s64, s64, 0x100
	s_addc_u32 s65, s65, 0
	s_add_u32 s18, s18, 0x100
	s_addc_u32 s19, s19, 0
	s_add_u32 s66, s66, 0x100
	s_addc_u32 s67, s67, 0
	s_cmp_gt_u32 s70, 29
	.p2align 6
.LBB0_2594:
	ds_read_b128 v[148:151], v143
	ds_read_b128 v[152:155], v143 offset:1024
	ds_read_b128 v[156:159], v143 offset:2048
	ds_read_b128 v[160:163], v143 offset:3072
	ds_read_b128 v[164:167], v144
	ds_read_b128 v[168:171], v144 offset:1024
	ds_read_b128 v[172:175], v144 offset:2048
	ds_read_b128 v[176:179], v144 offset:3072
	s_cmp_eq_u32 s70, 28
	s_cselect_b32 s21, s9, s65
	s_cselect_b32 s20, s63, s64
	s_cselect_b32 s23, s11, s67
	s_cselect_b32 s22, s62, s66
	ds_read_b128 v[180:183], v145
	ds_read_b128 v[184:187], v145 offset:1024
	ds_read_b128 v[188:191], v145 offset:2048
	ds_read_b128 v[192:195], v145 offset:3072
	ds_read_b128 v[196:199], v145 offset:4096
	ds_read_b128 v[200:203], v145 offset:5120
	ds_read_b128 v[204:207], v145 offset:6144
	ds_read_b128 v[208:211], v145 offset:7168
	s_add_u32 s74, s18, 0xfff80000
	s_addc_u32 s75, s19, -1
	s_mov_b32 s71, m0
	s_mov_b32 m0, s48
	s_nop 0
	global_load_lds_dwordx4 v138, s[74:75]
	s_mov_b32 m0, s71
	s_nop 0
	s_mov_b32 s71, m0
	s_mov_b32 m0, s57
	s_nop 0
	global_load_lds_dwordx4 v140, s[74:75]
	s_mov_b32 m0, s71
	s_nop 0
	s_mov_b32 s71, m0
	s_mov_b32 m0, s49
	s_nop 0
	global_load_lds_dwordx4 v138, s[18:19]
	s_mov_b32 m0, s71
	s_nop 0
	s_mov_b32 s71, m0
	s_mov_b32 m0, s58
	s_nop 0
	global_load_lds_dwordx4 v140, s[18:19]
	s_mov_b32 m0, s71
	s_waitcnt vmcnt(8)
	s_waitcnt lgkmcnt(0)
	s_barrier
	s_setprio 1
	s_waitcnt lgkmcnt(7)
	v_mfma_f32_16x16x32_bf16 v[126:129], v[148:151], v[180:183], v[126:129]
	v_mfma_f32_16x16x32_bf16 v[126:129], v[152:155], v[184:187], v[126:129]
	s_waitcnt lgkmcnt(5)
	v_mfma_f32_16x16x32_bf16 v[122:125], v[156:159], v[180:183], v[122:125]
	v_mfma_f32_16x16x32_bf16 v[122:125], v[160:163], v[184:187], v[122:125]
	s_waitcnt lgkmcnt(3)
	v_mfma_f32_16x16x32_bf16 v[110:113], v[148:151], v[188:191], v[110:113]
	v_mfma_f32_16x16x32_bf16 v[110:113], v[152:155], v[192:195], v[110:113]
	s_waitcnt lgkmcnt(1)
	v_mfma_f32_16x16x32_bf16 v[106:109], v[156:159], v[188:191], v[106:109]
	v_mfma_f32_16x16x32_bf16 v[106:109], v[160:163], v[192:195], v[106:109]
	v_mfma_f32_16x16x32_bf16 v[94:97], v[148:151], v[196:199], v[94:97]
	v_mfma_f32_16x16x32_bf16 v[94:97], v[152:155], v[200:203], v[94:97]
	v_mfma_f32_16x16x32_bf16 v[90:93], v[156:159], v[196:199], v[90:93]
	v_mfma_f32_16x16x32_bf16 v[90:93], v[160:163], v[200:203], v[90:93]
	v_mfma_f32_16x16x32_bf16 v[78:81], v[148:151], v[204:207], v[78:81]
	v_mfma_f32_16x16x32_bf16 v[78:81], v[152:155], v[208:211], v[78:81]
	s_waitcnt lgkmcnt(0)
	v_mfma_f32_16x16x32_bf16 v[74:77], v[156:159], v[204:207], v[74:77]
	v_mfma_f32_16x16x32_bf16 v[74:77], v[160:163], v[208:211], v[74:77]
	s_setprio 0
	s_setprio 1
	v_mfma_f32_16x16x32_bf16 v[118:121], v[164:167], v[180:183], v[118:121]
	v_mfma_f32_16x16x32_bf16 v[118:121], v[168:171], v[184:187], v[118:121]
	v_mfma_f32_16x16x32_bf16 v[114:117], v[172:175], v[180:183], v[114:117]
	v_mfma_f32_16x16x32_bf16 v[114:117], v[176:179], v[184:187], v[114:117]
	v_mfma_f32_16x16x32_bf16 v[102:105], v[164:167], v[188:191], v[102:105]
	v_mfma_f32_16x16x32_bf16 v[102:105], v[168:171], v[192:195], v[102:105]
	v_mfma_f32_16x16x32_bf16 v[98:101], v[172:175], v[188:191], v[98:101]
	v_mfma_f32_16x16x32_bf16 v[98:101], v[176:179], v[192:195], v[98:101]
	v_mfma_f32_16x16x32_bf16 v[86:89], v[164:167], v[196:199], v[86:89]
	v_mfma_f32_16x16x32_bf16 v[86:89], v[168:171], v[200:203], v[86:89]
	v_mfma_f32_16x16x32_bf16 v[82:85], v[172:175], v[196:199], v[82:85]
	v_mfma_f32_16x16x32_bf16 v[82:85], v[176:179], v[200:203], v[82:85]
	v_mfma_f32_16x16x32_bf16 v[70:73], v[164:167], v[204:207], v[70:73]
	v_mfma_f32_16x16x32_bf16 v[70:73], v[168:171], v[208:211], v[70:73]
	s_setprio 2
	s_barrier
	v_mfma_f32_16x16x32_bf16 v[66:69], v[172:175], v[204:207], v[66:69]
	v_mfma_f32_16x16x32_bf16 v[66:69], v[176:179], v[208:211], v[66:69]
	s_setprio 0
	ds_read_b128 v[180:183], v145 offset:16384
	ds_read_b128 v[184:187], v145 offset:17408
	ds_read_b128 v[188:191], v145 offset:18432
	ds_read_b128 v[192:195], v145 offset:19456
	ds_read_b128 v[196:199], v145 offset:20480
	ds_read_b128 v[200:203], v145 offset:21504
	ds_read_b128 v[204:207], v145 offset:22528
	ds_read_b128 v[208:211], v145 offset:23552
	s_mov_b32 s71, m0
	s_mov_b32 m0, s35
	s_nop 0
	global_load_lds_dwordx4 v139, s[20:21]
	s_mov_b32 m0, s71
	s_add_u32 s74, s20, 0x80000
	s_mov_b32 s71, m0
	s_mov_b32 m0, s36
	s_nop 0
	global_load_lds_dwordx4 v141, s[20:21]
	s_mov_b32 m0, s71
	s_addc_u32 s75, s21, 0
	s_mov_b32 s71, m0
	s_mov_b32 m0, s37
	s_nop 0
	global_load_lds_dwordx4 v139, s[74:75]
	s_mov_b32 m0, s71
	s_nop 0
	s_mov_b32 s71, m0
	s_mov_b32 m0, s40
	s_nop 0
	global_load_lds_dwordx4 v141, s[74:75]
	s_mov_b32 m0, s71
	s_waitcnt vmcnt(4)
	s_waitcnt lgkmcnt(0)
	s_barrier
	s_setprio 1
	s_waitcnt lgkmcnt(7)
	v_mfma_f32_16x16x32_bf16 v[62:65], v[148:151], v[180:183], v[62:65]
	v_mfma_f32_16x16x32_bf16 v[62:65], v[152:155], v[184:187], v[62:65]
	s_waitcnt lgkmcnt(5)
	v_mfma_f32_16x16x32_bf16 v[58:61], v[156:159], v[180:183], v[58:61]
	v_mfma_f32_16x16x32_bf16 v[58:61], v[160:163], v[184:187], v[58:61]
	s_waitcnt lgkmcnt(3)
	v_mfma_f32_16x16x32_bf16 v[46:49], v[148:151], v[188:191], v[46:49]
	v_mfma_f32_16x16x32_bf16 v[46:49], v[152:155], v[192:195], v[46:49]
	s_waitcnt lgkmcnt(1)
	v_mfma_f32_16x16x32_bf16 v[42:45], v[156:159], v[188:191], v[42:45]
	v_mfma_f32_16x16x32_bf16 v[42:45], v[160:163], v[192:195], v[42:45]
	v_mfma_f32_16x16x32_bf16 v[30:33], v[148:151], v[196:199], v[30:33]
	v_mfma_f32_16x16x32_bf16 v[30:33], v[152:155], v[200:203], v[30:33]
	v_mfma_f32_16x16x32_bf16 v[26:29], v[156:159], v[196:199], v[26:29]
	v_mfma_f32_16x16x32_bf16 v[26:29], v[160:163], v[200:203], v[26:29]
	v_mfma_f32_16x16x32_bf16 v[14:17], v[148:151], v[204:207], v[14:17]
	v_mfma_f32_16x16x32_bf16 v[14:17], v[152:155], v[208:211], v[14:17]
	s_waitcnt lgkmcnt(0)
	v_mfma_f32_16x16x32_bf16 v[10:13], v[156:159], v[204:207], v[10:13]
	v_mfma_f32_16x16x32_bf16 v[10:13], v[160:163], v[208:211], v[10:13]
	s_setprio 0
	s_setprio 1
	v_mfma_f32_16x16x32_bf16 v[54:57], v[164:167], v[180:183], v[54:57]
	v_mfma_f32_16x16x32_bf16 v[54:57], v[168:171], v[184:187], v[54:57]
	v_mfma_f32_16x16x32_bf16 v[50:53], v[172:175], v[180:183], v[50:53]
	v_mfma_f32_16x16x32_bf16 v[50:53], v[176:179], v[184:187], v[50:53]
	v_mfma_f32_16x16x32_bf16 v[38:41], v[164:167], v[188:191], v[38:41]
	v_mfma_f32_16x16x32_bf16 v[38:41], v[168:171], v[192:195], v[38:41]
	v_mfma_f32_16x16x32_bf16 v[34:37], v[172:175], v[188:191], v[34:37]
	v_mfma_f32_16x16x32_bf16 v[34:37], v[176:179], v[192:195], v[34:37]
	v_mfma_f32_16x16x32_bf16 v[22:25], v[164:167], v[196:199], v[22:25]
	v_mfma_f32_16x16x32_bf16 v[22:25], v[168:171], v[200:203], v[22:25]
	v_mfma_f32_16x16x32_bf16 v[18:21], v[172:175], v[196:199], v[18:21]
	v_mfma_f32_16x16x32_bf16 v[18:21], v[176:179], v[200:203], v[18:21]
	v_mfma_f32_16x16x32_bf16 v[6:9], v[164:167], v[204:207], v[6:9]
	v_mfma_f32_16x16x32_bf16 v[6:9], v[168:171], v[208:211], v[6:9]
	s_setprio 2
	s_barrier
	v_mfma_f32_16x16x32_bf16 v[2:5], v[172:175], v[204:207], v[2:5]
	v_mfma_f32_16x16x32_bf16 v[2:5], v[176:179], v[208:211], v[2:5]
	s_setprio 0
	ds_read_b128 v[148:151], v146
	ds_read_b128 v[152:155], v146 offset:1024
	ds_read_b128 v[156:159], v146 offset:2048
	ds_read_b128 v[160:163], v146 offset:3072
	ds_read_b128 v[164:167], v147
	ds_read_b128 v[168:171], v147 offset:1024
	ds_read_b128 v[172:175], v147 offset:2048
	ds_read_b128 v[176:179], v147 offset:3072
	ds_read_b128 v[180:183], v145 offset:32768
	ds_read_b128 v[184:187], v145 offset:33792
	ds_read_b128 v[188:191], v145 offset:34816
	ds_read_b128 v[192:195], v145 offset:35840
	ds_read_b128 v[196:199], v145 offset:36864
	ds_read_b128 v[200:203], v145 offset:37888
	ds_read_b128 v[204:207], v145 offset:38912
	ds_read_b128 v[208:211], v145 offset:39936
	s_mov_b32 s71, m0
	s_mov_b32 m0, s31
	s_nop 0
	global_load_lds_dwordx4 v138, s[22:23]
	s_mov_b32 m0, s71
	s_nop 0
	s_mov_b32 s71, m0
	s_mov_b32 m0, s41
	s_nop 0
	global_load_lds_dwordx4 v140, s[22:23]
	s_mov_b32 m0, s71
	s_add_u32 s22, s22, 0x80000
	s_addc_u32 s23, s23, 0
	s_mov_b32 s71, m0
	s_mov_b32 m0, s42
	s_nop 0
	global_load_lds_dwordx4 v138, s[22:23]
	s_mov_b32 m0, s71
	s_nop 0
	s_mov_b32 s71, m0
	s_mov_b32 m0, s43
	s_nop 0
	global_load_lds_dwordx4 v140, s[22:23]
	s_mov_b32 m0, s71
	s_waitcnt vmcnt(8)
	s_waitcnt lgkmcnt(0)
	s_barrier
	s_setprio 1
	s_waitcnt lgkmcnt(7)
	v_mfma_f32_16x16x32_bf16 v[126:129], v[148:151], v[180:183], v[126:129]
	v_mfma_f32_16x16x32_bf16 v[126:129], v[152:155], v[184:187], v[126:129]
	s_waitcnt lgkmcnt(5)
	v_mfma_f32_16x16x32_bf16 v[122:125], v[156:159], v[180:183], v[122:125]
	v_mfma_f32_16x16x32_bf16 v[122:125], v[160:163], v[184:187], v[122:125]
	s_waitcnt lgkmcnt(3)
	v_mfma_f32_16x16x32_bf16 v[110:113], v[148:151], v[188:191], v[110:113]
	v_mfma_f32_16x16x32_bf16 v[110:113], v[152:155], v[192:195], v[110:113]
	s_waitcnt lgkmcnt(1)
	v_mfma_f32_16x16x32_bf16 v[106:109], v[156:159], v[188:191], v[106:109]
	v_mfma_f32_16x16x32_bf16 v[106:109], v[160:163], v[192:195], v[106:109]
	v_mfma_f32_16x16x32_bf16 v[94:97], v[148:151], v[196:199], v[94:97]
	v_mfma_f32_16x16x32_bf16 v[94:97], v[152:155], v[200:203], v[94:97]
	v_mfma_f32_16x16x32_bf16 v[90:93], v[156:159], v[196:199], v[90:93]
	v_mfma_f32_16x16x32_bf16 v[90:93], v[160:163], v[200:203], v[90:93]
	v_mfma_f32_16x16x32_bf16 v[78:81], v[148:151], v[204:207], v[78:81]
	v_mfma_f32_16x16x32_bf16 v[78:81], v[152:155], v[208:211], v[78:81]
	s_waitcnt lgkmcnt(0)
	v_mfma_f32_16x16x32_bf16 v[74:77], v[156:159], v[204:207], v[74:77]
	v_mfma_f32_16x16x32_bf16 v[74:77], v[160:163], v[208:211], v[74:77]
	s_setprio 0
	s_setprio 1
	v_mfma_f32_16x16x32_bf16 v[118:121], v[164:167], v[180:183], v[118:121]
	v_mfma_f32_16x16x32_bf16 v[118:121], v[168:171], v[184:187], v[118:121]
	v_mfma_f32_16x16x32_bf16 v[114:117], v[172:175], v[180:183], v[114:117]
	v_mfma_f32_16x16x32_bf16 v[114:117], v[176:179], v[184:187], v[114:117]
	v_mfma_f32_16x16x32_bf16 v[102:105], v[164:167], v[188:191], v[102:105]
	v_mfma_f32_16x16x32_bf16 v[102:105], v[168:171], v[192:195], v[102:105]
	v_mfma_f32_16x16x32_bf16 v[98:101], v[172:175], v[188:191], v[98:101]
	v_mfma_f32_16x16x32_bf16 v[98:101], v[176:179], v[192:195], v[98:101]
	v_mfma_f32_16x16x32_bf16 v[86:89], v[164:167], v[196:199], v[86:89]
	v_mfma_f32_16x16x32_bf16 v[86:89], v[168:171], v[200:203], v[86:89]
	v_mfma_f32_16x16x32_bf16 v[82:85], v[172:175], v[196:199], v[82:85]
	v_mfma_f32_16x16x32_bf16 v[82:85], v[176:179], v[200:203], v[82:85]
	v_mfma_f32_16x16x32_bf16 v[70:73], v[164:167], v[204:207], v[70:73]
	v_mfma_f32_16x16x32_bf16 v[70:73], v[168:171], v[208:211], v[70:73]
	s_setprio 2
	s_barrier
	v_mfma_f32_16x16x32_bf16 v[66:69], v[172:175], v[204:207], v[66:69]
	v_mfma_f32_16x16x32_bf16 v[66:69], v[176:179], v[208:211], v[66:69]
	s_setprio 0
	ds_read_b128 v[180:183], v145 offset:49152
	ds_read_b128 v[184:187], v145 offset:50176
	ds_read_b128 v[188:191], v145 offset:51200
	ds_read_b128 v[192:195], v145 offset:52224
	ds_read_b128 v[196:199], v145 offset:53248
	ds_read_b128 v[200:203], v145 offset:54272
	ds_read_b128 v[204:207], v145 offset:55296
	ds_read_b128 v[208:211], v145 offset:56320
	s_add_u32 s22, s20, 0x80
	s_addc_u32 s23, s21, 0
	s_mov_b32 s71, m0
	s_mov_b32 m0, s44
	s_nop 0
	global_load_lds_dwordx4 v139, s[22:23]
	s_mov_b32 m0, s71
	s_add_u32 s20, s20, 0x80080
	s_mov_b32 s71, m0
	s_mov_b32 m0, s45
	s_nop 0
	global_load_lds_dwordx4 v141, s[22:23]
	s_mov_b32 m0, s71
	s_addc_u32 s21, s21, 0
	s_mov_b32 s22, m0
	s_mov_b32 m0, s46
	s_nop 0
	global_load_lds_dwordx4 v139, s[20:21]
	s_mov_b32 m0, s22
	s_nop 0
	s_mov_b32 s22, m0
	s_mov_b32 m0, s47
	s_nop 0
	global_load_lds_dwordx4 v141, s[20:21]
	s_mov_b32 m0, s22
	s_waitcnt vmcnt(4)
	s_waitcnt lgkmcnt(0)
	s_barrier
	s_setprio 1
	s_waitcnt lgkmcnt(7)
	v_mfma_f32_16x16x32_bf16 v[62:65], v[148:151], v[180:183], v[62:65]
	v_mfma_f32_16x16x32_bf16 v[62:65], v[152:155], v[184:187], v[62:65]
	s_waitcnt lgkmcnt(5)
	v_mfma_f32_16x16x32_bf16 v[58:61], v[156:159], v[180:183], v[58:61]
	v_mfma_f32_16x16x32_bf16 v[58:61], v[160:163], v[184:187], v[58:61]
	s_waitcnt lgkmcnt(3)
	v_mfma_f32_16x16x32_bf16 v[46:49], v[148:151], v[188:191], v[46:49]
	v_mfma_f32_16x16x32_bf16 v[46:49], v[152:155], v[192:195], v[46:49]
	s_waitcnt lgkmcnt(1)
	v_mfma_f32_16x16x32_bf16 v[42:45], v[156:159], v[188:191], v[42:45]
	v_mfma_f32_16x16x32_bf16 v[42:45], v[160:163], v[192:195], v[42:45]
	v_mfma_f32_16x16x32_bf16 v[30:33], v[148:151], v[196:199], v[30:33]
	v_mfma_f32_16x16x32_bf16 v[30:33], v[152:155], v[200:203], v[30:33]
	v_mfma_f32_16x16x32_bf16 v[26:29], v[156:159], v[196:199], v[26:29]
	v_mfma_f32_16x16x32_bf16 v[26:29], v[160:163], v[200:203], v[26:29]
	v_mfma_f32_16x16x32_bf16 v[14:17], v[148:151], v[204:207], v[14:17]
	v_mfma_f32_16x16x32_bf16 v[14:17], v[152:155], v[208:211], v[14:17]
	s_waitcnt lgkmcnt(0)
	v_mfma_f32_16x16x32_bf16 v[10:13], v[156:159], v[204:207], v[10:13]
	v_mfma_f32_16x16x32_bf16 v[10:13], v[160:163], v[208:211], v[10:13]
	s_setprio 0
	s_setprio 1
	v_mfma_f32_16x16x32_bf16 v[54:57], v[164:167], v[180:183], v[54:57]
	v_mfma_f32_16x16x32_bf16 v[54:57], v[168:171], v[184:187], v[54:57]
	v_mfma_f32_16x16x32_bf16 v[50:53], v[172:175], v[180:183], v[50:53]
	v_mfma_f32_16x16x32_bf16 v[50:53], v[176:179], v[184:187], v[50:53]
	v_mfma_f32_16x16x32_bf16 v[38:41], v[164:167], v[188:191], v[38:41]
	v_mfma_f32_16x16x32_bf16 v[38:41], v[168:171], v[192:195], v[38:41]
	v_mfma_f32_16x16x32_bf16 v[34:37], v[172:175], v[188:191], v[34:37]
	v_mfma_f32_16x16x32_bf16 v[34:37], v[176:179], v[192:195], v[34:37]
	v_mfma_f32_16x16x32_bf16 v[22:25], v[164:167], v[196:199], v[22:25]
	v_mfma_f32_16x16x32_bf16 v[22:25], v[168:171], v[200:203], v[22:25]
	v_mfma_f32_16x16x32_bf16 v[18:21], v[172:175], v[196:199], v[18:21]
	v_mfma_f32_16x16x32_bf16 v[18:21], v[176:179], v[200:203], v[18:21]
	v_mfma_f32_16x16x32_bf16 v[6:9], v[164:167], v[204:207], v[6:9]
	v_mfma_f32_16x16x32_bf16 v[6:9], v[168:171], v[208:211], v[6:9]
	s_setprio 2
	s_barrier
	v_mfma_f32_16x16x32_bf16 v[2:5], v[172:175], v[204:207], v[2:5]
	v_mfma_f32_16x16x32_bf16 v[2:5], v[176:179], v[208:211], v[2:5]
	s_setprio 0
	s_add_i32 s70, s70, 2
	s_add_u32 s64, s64, 0x100
	s_addc_u32 s65, s65, 0
	s_add_u32 s18, s18, 0x100
	s_addc_u32 s19, s19, 0
	s_add_u32 s66, s66, 0x100
	s_addc_u32 s67, s67, 0
	s_cmp_gt_u32 s70, 29
	s_cbranch_scc0 .LBB0_2594
	s_and_b64 vcc, exec, s[6:7]
	s_cbranch_vccz .LBB0_2597
	s_barrier

.LBB0_2791:
	s_ashr_i32 s21, s20, 31
	s_lshl_b64 s[22:23], s[20:21], 15
	s_add_u32 s22, s37, s22
	s_addc_u32 s23, s40, s23
	s_and_b64 s[24:25], s[2:3], exec
	s_cselect_b32 s21, s23, s31
	s_cselect_b32 s63, s22, s30
	s_ashr_i32 s19, s18, 31
	s_lshl_b64 s[24:25], s[18:19], 15
	s_add_u32 s24, s41, s24
	s_addc_u32 s25, s42, s25
	s_and_b64 s[34:35], s[2:3], exec
	s_cselect_b32 s19, s25, s29
	s_cselect_b32 s64, s24, s28
	s_add_u32 s65, s28, 0x80000
	s_addc_u32 s66, s29, 0
	s_add_u32 s28, s30, 0x204000
	s_addc_u32 s29, s31, 0
	s_add_u32 s67, s30, 0x400000
	s_addc_u32 s68, s31, 0
	s_mov_b32 s69, -2
	s_waitcnt vmcnt(25)
	s_waitcnt vmcnt(24)
	s_waitcnt vmcnt(4)
	s_waitcnt vmcnt(2)
	s_waitcnt vmcnt(1)
	s_waitcnt vmcnt(0)
	ds_read_b128 v[130:133], v181
	ds_read_b128 v[134:137], v181 offset:1024
	ds_read_b128 v[138:141], v181 offset:2048
	ds_read_b128 v[142:145], v181 offset:3072
	ds_read_b128 v[150:153], v182
	ds_read_b128 v[154:157], v182 offset:1024
	ds_read_b128 v[158:161], v182 offset:2048
	ds_read_b128 v[162:165], v182 offset:3072
	s_cmpk_eq_i32 s69, 0x52
	s_cselect_b32 s31, s19, s66
	s_cselect_b32 s30, s64, s65
	s_cselect_b32 s35, s21, s68
	s_cselect_b32 s34, s63, s67
	ds_read_b128 v[166:169], v183
	ds_read_b128 v[170:173], v183 offset:1024
	ds_read_b128 v[186:189], v183 offset:2048
	ds_read_b128 v[190:193], v183 offset:3072
	ds_read_b128 v[194:197], v183 offset:4096
	ds_read_b128 v[198:201], v183 offset:5120
	ds_read_b128 v[202:205], v183 offset:6144
	ds_read_b128 v[206:209], v183 offset:7168
	s_add_u32 s70, s28, 0xffffc000
	s_addc_u32 s71, s29, -1
	s_mov_b32 s73, m0
	s_mov_b32 m0, s57
	s_nop 0
	global_load_lds_dwordx4 v1, s[70:71]
	s_mov_b32 m0, s73
	s_nop 0
	s_mov_b32 s73, m0
	s_mov_b32 m0, s59
	s_nop 0
	global_load_lds_dwordx4 v177, s[70:71]
	s_mov_b32 m0, s73
	s_mov_b32 s70, m0
	s_mov_b32 m0, s58
	s_nop 0
	global_load_lds_dwordx4 v1, s[28:29]
	s_mov_b32 m0, s70
	s_nop 0
	s_mov_b32 s70, m0
	s_mov_b32 m0, s60
	s_nop 0
	global_load_lds_dwordx4 v177, s[28:29]
	s_mov_b32 m0, s70
	s_waitcnt vmcnt(8)
	s_waitcnt lgkmcnt(0)
	s_barrier
	s_setprio 1
	s_waitcnt lgkmcnt(7)
	v_mfma_f32_16x16x32_bf16 v[126:129], v[130:133], v[166:169], 0
	v_mfma_f32_16x16x32_bf16 v[126:129], v[134:137], v[170:173], v[126:129]
	s_waitcnt lgkmcnt(5)
	v_mfma_f32_16x16x32_bf16 v[122:125], v[138:141], v[166:169], 0
	v_mfma_f32_16x16x32_bf16 v[122:125], v[142:145], v[170:173], v[122:125]
	s_waitcnt lgkmcnt(3)
	v_mfma_f32_16x16x32_bf16 v[118:121], v[130:133], v[186:189], 0
	v_mfma_f32_16x16x32_bf16 v[118:121], v[134:137], v[190:193], v[118:121]
	s_waitcnt lgkmcnt(1)
	v_mfma_f32_16x16x32_bf16 v[110:113], v[138:141], v[186:189], 0
	v_mfma_f32_16x16x32_bf16 v[110:113], v[142:145], v[190:193], v[110:113]
	v_mfma_f32_16x16x32_bf16 v[94:97], v[130:133], v[194:197], 0
	v_mfma_f32_16x16x32_bf16 v[94:97], v[134:137], v[198:201], v[94:97]
	v_mfma_f32_16x16x32_bf16 v[90:93], v[138:141], v[194:197], 0
	v_mfma_f32_16x16x32_bf16 v[90:93], v[142:145], v[198:201], v[90:93]
	v_mfma_f32_16x16x32_bf16 v[86:89], v[130:133], v[202:205], 0
	v_mfma_f32_16x16x32_bf16 v[86:89], v[134:137], v[206:209], v[86:89]
	s_waitcnt lgkmcnt(0)
	v_mfma_f32_16x16x32_bf16 v[78:81], v[138:141], v[202:205], 0
	v_mfma_f32_16x16x32_bf16 v[78:81], v[142:145], v[206:209], v[78:81]
	s_setprio 0
	s_setprio 1
	v_mfma_f32_16x16x32_bf16 v[114:117], v[150:153], v[166:169], 0
	v_mfma_f32_16x16x32_bf16 v[114:117], v[154:157], v[170:173], v[114:117]
	v_mfma_f32_16x16x32_bf16 v[106:109], v[158:161], v[166:169], 0
	v_mfma_f32_16x16x32_bf16 v[106:109], v[162:165], v[170:173], v[106:109]
	v_mfma_f32_16x16x32_bf16 v[102:105], v[150:153], v[186:189], 0
	v_mfma_f32_16x16x32_bf16 v[102:105], v[154:157], v[190:193], v[102:105]
	v_mfma_f32_16x16x32_bf16 v[98:101], v[158:161], v[186:189], 0
	v_mfma_f32_16x16x32_bf16 v[98:101], v[162:165], v[190:193], v[98:101]
	v_mfma_f32_16x16x32_bf16 v[82:85], v[150:153], v[194:197], 0
	v_mfma_f32_16x16x32_bf16 v[82:85], v[154:157], v[198:201], v[82:85]
	v_mfma_f32_16x16x32_bf16 v[74:77], v[158:161], v[194:197], 0
	v_mfma_f32_16x16x32_bf16 v[74:77], v[162:165], v[198:201], v[74:77]
	v_mfma_f32_16x16x32_bf16 v[70:73], v[150:153], v[202:205], 0
	v_mfma_f32_16x16x32_bf16 v[70:73], v[154:157], v[206:209], v[70:73]
	s_setprio 2
	s_barrier
	v_mfma_f32_16x16x32_bf16 v[66:69], v[158:161], v[202:205], 0
	v_mfma_f32_16x16x32_bf16 v[66:69], v[162:165], v[206:209], v[66:69]
	s_setprio 0
	ds_read_b128 v[166:169], v183 offset:16384
	ds_read_b128 v[170:173], v183 offset:17408
	ds_read_b128 v[186:189], v183 offset:18432
	ds_read_b128 v[190:193], v183 offset:19456
	ds_read_b128 v[194:197], v183 offset:20480
	ds_read_b128 v[198:201], v183 offset:21504
	ds_read_b128 v[202:205], v183 offset:22528
	ds_read_b128 v[206:209], v183 offset:23552
	s_mov_b32 s70, m0
	s_mov_b32 m0, s27
	s_nop 0
	global_load_lds_dwordx4 v176, s[30:31]
	s_mov_b32 m0, s70
	s_nop 0
	s_mov_b32 s70, m0
	s_mov_b32 m0, s45
	s_nop 0
	global_load_lds_dwordx4 v178, s[30:31]
	s_mov_b32 m0, s70
	s_add_u32 s70, s30, 0x4000
	s_addc_u32 s71, s31, 0
	s_mov_b32 s73, m0
	s_mov_b32 m0, s46
	s_nop 0
	global_load_lds_dwordx4 v176, s[70:71]
	s_mov_b32 m0, s73
	s_nop 0
	s_mov_b32 s73, m0
	s_mov_b32 m0, s47
	s_nop 0
	global_load_lds_dwordx4 v178, s[70:71]
	s_mov_b32 m0, s73
	s_waitcnt vmcnt(4)
	s_waitcnt lgkmcnt(0)
	s_barrier
	s_setprio 1
	s_waitcnt lgkmcnt(7)
	v_mfma_f32_16x16x32_bf16 v[62:65], v[130:133], v[166:169], 0
	v_mfma_f32_16x16x32_bf16 v[62:65], v[134:137], v[170:173], v[62:65]
	s_waitcnt lgkmcnt(5)
	v_mfma_f32_16x16x32_bf16 v[58:61], v[138:141], v[166:169], 0
	v_mfma_f32_16x16x32_bf16 v[58:61], v[142:145], v[170:173], v[58:61]
	s_waitcnt lgkmcnt(3)
	v_mfma_f32_16x16x32_bf16 v[46:49], v[130:133], v[186:189], 0
	v_mfma_f32_16x16x32_bf16 v[46:49], v[134:137], v[190:193], v[46:49]
	s_waitcnt lgkmcnt(1)
	v_mfma_f32_16x16x32_bf16 v[42:45], v[138:141], v[186:189], 0
	v_mfma_f32_16x16x32_bf16 v[42:45], v[142:145], v[190:193], v[42:45]
	v_mfma_f32_16x16x32_bf16 v[30:33], v[130:133], v[194:197], 0
	v_mfma_f32_16x16x32_bf16 v[30:33], v[134:137], v[198:201], v[30:33]
	v_mfma_f32_16x16x32_bf16 v[26:29], v[138:141], v[194:197], 0
	v_mfma_f32_16x16x32_bf16 v[26:29], v[142:145], v[198:201], v[26:29]
	v_mfma_f32_16x16x32_bf16 v[14:17], v[130:133], v[202:205], 0
	v_mfma_f32_16x16x32_bf16 v[14:17], v[134:137], v[206:209], v[14:17]
	s_waitcnt lgkmcnt(0)
	v_mfma_f32_16x16x32_bf16 v[10:13], v[138:141], v[202:205], 0
	v_mfma_f32_16x16x32_bf16 v[10:13], v[142:145], v[206:209], v[10:13]
	s_setprio 0
	s_setprio 1
	v_mfma_f32_16x16x32_bf16 v[54:57], v[150:153], v[166:169], 0
	v_mfma_f32_16x16x32_bf16 v[54:57], v[154:157], v[170:173], v[54:57]
	v_mfma_f32_16x16x32_bf16 v[50:53], v[158:161], v[166:169], 0
	v_mfma_f32_16x16x32_bf16 v[50:53], v[162:165], v[170:173], v[50:53]
	v_mfma_f32_16x16x32_bf16 v[38:41], v[150:153], v[186:189], 0
	v_mfma_f32_16x16x32_bf16 v[38:41], v[154:157], v[190:193], v[38:41]
	v_mfma_f32_16x16x32_bf16 v[34:37], v[158:161], v[186:189], 0
	v_mfma_f32_16x16x32_bf16 v[34:37], v[162:165], v[190:193], v[34:37]
	v_mfma_f32_16x16x32_bf16 v[22:25], v[150:153], v[194:197], 0
	v_mfma_f32_16x16x32_bf16 v[22:25], v[154:157], v[198:201], v[22:25]
	v_mfma_f32_16x16x32_bf16 v[18:21], v[158:161], v[194:197], 0
	v_mfma_f32_16x16x32_bf16 v[18:21], v[162:165], v[198:201], v[18:21]
	v_mfma_f32_16x16x32_bf16 v[6:9], v[150:153], v[202:205], 0
	v_mfma_f32_16x16x32_bf16 v[6:9], v[154:157], v[206:209], v[6:9]
	s_setprio 2
	s_barrier
	v_mfma_f32_16x16x32_bf16 v[2:5], v[158:161], v[202:205], 0
	v_mfma_f32_16x16x32_bf16 v[2:5], v[162:165], v[206:209], v[2:5]
	s_setprio 0
	ds_read_b128 v[130:133], v184
	ds_read_b128 v[134:137], v184 offset:1024
	ds_read_b128 v[138:141], v184 offset:2048
	ds_read_b128 v[142:145], v184 offset:3072
	ds_read_b128 v[150:153], v185
	ds_read_b128 v[154:157], v185 offset:1024
	ds_read_b128 v[158:161], v185 offset:2048
	ds_read_b128 v[162:165], v185 offset:3072
	ds_read_b128 v[166:169], v183 offset:32768
	ds_read_b128 v[170:173], v183 offset:33792
	ds_read_b128 v[186:189], v183 offset:34816
	ds_read_b128 v[190:193], v183 offset:35840
	ds_read_b128 v[194:197], v183 offset:36864
	ds_read_b128 v[198:201], v183 offset:37888
	ds_read_b128 v[202:205], v183 offset:38912
	ds_read_b128 v[206:209], v183 offset:39936
	s_mov_b32 s70, m0
	s_mov_b32 m0, s44
	s_nop 0
	global_load_lds_dwordx4 v1, s[34:35]
	s_mov_b32 m0, s70
	s_nop 0
	s_mov_b32 s70, m0
	s_mov_b32 m0, s48
	s_nop 0
	global_load_lds_dwordx4 v177, s[34:35]
	s_mov_b32 m0, s70
	s_add_u32 s34, s34, 0x4000
	s_addc_u32 s35, s35, 0
	s_mov_b32 s70, m0
	s_mov_b32 m0, s49
	s_nop 0
	global_load_lds_dwordx4 v1, s[34:35]
	s_mov_b32 m0, s70
	s_nop 0
	s_mov_b32 s70, m0
	s_mov_b32 m0, s50
	s_nop 0
	global_load_lds_dwordx4 v177, s[34:35]
	s_mov_b32 m0, s70
	s_waitcnt vmcnt(8)
	s_waitcnt lgkmcnt(0)
	s_barrier
	s_setprio 1
	s_waitcnt lgkmcnt(7)
	v_mfma_f32_16x16x32_bf16 v[126:129], v[130:133], v[166:169], v[126:129]
	v_mfma_f32_16x16x32_bf16 v[126:129], v[134:137], v[170:173], v[126:129]
	s_waitcnt lgkmcnt(5)
	v_mfma_f32_16x16x32_bf16 v[122:125], v[138:141], v[166:169], v[122:125]
	v_mfma_f32_16x16x32_bf16 v[122:125], v[142:145], v[170:173], v[122:125]
	s_waitcnt lgkmcnt(3)
	v_mfma_f32_16x16x32_bf16 v[118:121], v[130:133], v[186:189], v[118:121]
	v_mfma_f32_16x16x32_bf16 v[118:121], v[134:137], v[190:193], v[118:121]
	s_waitcnt lgkmcnt(1)
	v_mfma_f32_16x16x32_bf16 v[110:113], v[138:141], v[186:189], v[110:113]
	v_mfma_f32_16x16x32_bf16 v[110:113], v[142:145], v[190:193], v[110:113]
	v_mfma_f32_16x16x32_bf16 v[94:97], v[130:133], v[194:197], v[94:97]
	v_mfma_f32_16x16x32_bf16 v[94:97], v[134:137], v[198:201], v[94:97]
	v_mfma_f32_16x16x32_bf16 v[90:93], v[138:141], v[194:197], v[90:93]
	v_mfma_f32_16x16x32_bf16 v[90:93], v[142:145], v[198:201], v[90:93]
	v_mfma_f32_16x16x32_bf16 v[86:89], v[130:133], v[202:205], v[86:89]
	v_mfma_f32_16x16x32_bf16 v[86:89], v[134:137], v[206:209], v[86:89]
	s_waitcnt lgkmcnt(0)
	v_mfma_f32_16x16x32_bf16 v[78:81], v[138:141], v[202:205], v[78:81]
	v_mfma_f32_16x16x32_bf16 v[78:81], v[142:145], v[206:209], v[78:81]
	s_setprio 0
	s_setprio 1
	v_mfma_f32_16x16x32_bf16 v[114:117], v[150:153], v[166:169], v[114:117]
	v_mfma_f32_16x16x32_bf16 v[114:117], v[154:157], v[170:173], v[114:117]
	v_mfma_f32_16x16x32_bf16 v[106:109], v[158:161], v[166:169], v[106:109]
	v_mfma_f32_16x16x32_bf16 v[106:109], v[162:165], v[170:173], v[106:109]
	v_mfma_f32_16x16x32_bf16 v[102:105], v[150:153], v[186:189], v[102:105]
	v_mfma_f32_16x16x32_bf16 v[102:105], v[154:157], v[190:193], v[102:105]
	v_mfma_f32_16x16x32_bf16 v[98:101], v[158:161], v[186:189], v[98:101]
	v_mfma_f32_16x16x32_bf16 v[98:101], v[162:165], v[190:193], v[98:101]
	v_mfma_f32_16x16x32_bf16 v[82:85], v[150:153], v[194:197], v[82:85]
	v_mfma_f32_16x16x32_bf16 v[82:85], v[154:157], v[198:201], v[82:85]
	v_mfma_f32_16x16x32_bf16 v[74:77], v[158:161], v[194:197], v[74:77]
	v_mfma_f32_16x16x32_bf16 v[74:77], v[162:165], v[198:201], v[74:77]
	v_mfma_f32_16x16x32_bf16 v[70:73], v[150:153], v[202:205], v[70:73]
	v_mfma_f32_16x16x32_bf16 v[70:73], v[154:157], v[206:209], v[70:73]
	s_setprio 2
	s_barrier
	v_mfma_f32_16x16x32_bf16 v[66:69], v[158:161], v[202:205], v[66:69]
	v_mfma_f32_16x16x32_bf16 v[66:69], v[162:165], v[206:209], v[66:69]
	s_setprio 0
	ds_read_b128 v[166:169], v183 offset:49152
	ds_read_b128 v[170:173], v183 offset:50176
	ds_read_b128 v[186:189], v183 offset:51200
	ds_read_b128 v[190:193], v183 offset:52224
	ds_read_b128 v[194:197], v183 offset:53248
	ds_read_b128 v[198:201], v183 offset:54272
	ds_read_b128 v[202:205], v183 offset:55296
	ds_read_b128 v[206:209], v183 offset:56320
	s_add_u32 s34, s30, 0x40000
	s_addc_u32 s35, s31, 0
	s_mov_b32 s70, m0
	s_mov_b32 m0, s51
	s_nop 0
	global_load_lds_dwordx4 v176, s[34:35]
	s_mov_b32 m0, s70
	s_add_u32 s30, s30, 0x44000
	s_mov_b32 s70, m0
	s_mov_b32 m0, s52
	s_nop 0
	global_load_lds_dwordx4 v178, s[34:35]
	s_mov_b32 m0, s70
	s_addc_u32 s31, s31, 0
	s_mov_b32 s34, m0
	s_mov_b32 m0, s53
	s_nop 0
	global_load_lds_dwordx4 v176, s[30:31]
	s_mov_b32 m0, s34
	s_nop 0
	s_mov_b32 s34, m0
	s_mov_b32 m0, s54
	s_nop 0
	global_load_lds_dwordx4 v178, s[30:31]
	s_mov_b32 m0, s34
	s_waitcnt vmcnt(4)
	s_waitcnt lgkmcnt(0)
	s_barrier
	s_setprio 1
	s_waitcnt lgkmcnt(7)
	v_mfma_f32_16x16x32_bf16 v[62:65], v[130:133], v[166:169], v[62:65]
	v_mfma_f32_16x16x32_bf16 v[62:65], v[134:137], v[170:173], v[62:65]
	s_waitcnt lgkmcnt(5)
	v_mfma_f32_16x16x32_bf16 v[58:61], v[138:141], v[166:169], v[58:61]
	v_mfma_f32_16x16x32_bf16 v[58:61], v[142:145], v[170:173], v[58:61]
	s_waitcnt lgkmcnt(3)
	v_mfma_f32_16x16x32_bf16 v[46:49], v[130:133], v[186:189], v[46:49]
	v_mfma_f32_16x16x32_bf16 v[46:49], v[134:137], v[190:193], v[46:49]
	s_waitcnt lgkmcnt(1)
	v_mfma_f32_16x16x32_bf16 v[42:45], v[138:141], v[186:189], v[42:45]
	v_mfma_f32_16x16x32_bf16 v[42:45], v[142:145], v[190:193], v[42:45]
	v_mfma_f32_16x16x32_bf16 v[30:33], v[130:133], v[194:197], v[30:33]
	v_mfma_f32_16x16x32_bf16 v[30:33], v[134:137], v[198:201], v[30:33]
	v_mfma_f32_16x16x32_bf16 v[26:29], v[138:141], v[194:197], v[26:29]
	v_mfma_f32_16x16x32_bf16 v[26:29], v[142:145], v[198:201], v[26:29]
	v_mfma_f32_16x16x32_bf16 v[14:17], v[130:133], v[202:205], v[14:17]
	v_mfma_f32_16x16x32_bf16 v[14:17], v[134:137], v[206:209], v[14:17]
	s_waitcnt lgkmcnt(0)
	v_mfma_f32_16x16x32_bf16 v[10:13], v[138:141], v[202:205], v[10:13]
	v_mfma_f32_16x16x32_bf16 v[10:13], v[142:145], v[206:209], v[10:13]
	s_setprio 0
	s_setprio 1
	v_mfma_f32_16x16x32_bf16 v[54:57], v[150:153], v[166:169], v[54:57]
	v_mfma_f32_16x16x32_bf16 v[54:57], v[154:157], v[170:173], v[54:57]
	v_mfma_f32_16x16x32_bf16 v[50:53], v[158:161], v[166:169], v[50:53]
	v_mfma_f32_16x16x32_bf16 v[50:53], v[162:165], v[170:173], v[50:53]
	v_mfma_f32_16x16x32_bf16 v[38:41], v[150:153], v[186:189], v[38:41]
	v_mfma_f32_16x16x32_bf16 v[38:41], v[154:157], v[190:193], v[38:41]
	v_mfma_f32_16x16x32_bf16 v[34:37], v[158:161], v[186:189], v[34:37]
	v_mfma_f32_16x16x32_bf16 v[34:37], v[162:165], v[190:193], v[34:37]
	v_mfma_f32_16x16x32_bf16 v[22:25], v[150:153], v[194:197], v[22:25]
	v_mfma_f32_16x16x32_bf16 v[22:25], v[154:157], v[198:201], v[22:25]
	v_mfma_f32_16x16x32_bf16 v[18:21], v[158:161], v[194:197], v[18:21]
	v_mfma_f32_16x16x32_bf16 v[18:21], v[162:165], v[198:201], v[18:21]
	v_mfma_f32_16x16x32_bf16 v[6:9], v[150:153], v[202:205], v[6:9]
	v_mfma_f32_16x16x32_bf16 v[6:9], v[154:157], v[206:209], v[6:9]
	s_setprio 2
	s_barrier
	v_mfma_f32_16x16x32_bf16 v[2:5], v[158:161], v[202:205], v[2:5]
	v_mfma_f32_16x16x32_bf16 v[2:5], v[162:165], v[206:209], v[2:5]
	s_setprio 0
	s_add_i32 s69, s69, 2
	s_add_u32 s65, s65, 0x80000
	s_addc_u32 s66, s66, 0
	s_add_u32 s28, s28, 0x400000
	s_addc_u32 s29, s29, 0
	s_add_u32 s67, s67, 0x400000
	s_addc_u32 s68, s68, 0
	s_cmpk_gt_u32 s69, 0x53
	.p2align 6
.LBB0_2792:
	ds_read_b128 v[130:133], v181
	ds_read_b128 v[134:137], v181 offset:1024
	ds_read_b128 v[138:141], v181 offset:2048
	ds_read_b128 v[142:145], v181 offset:3072
	ds_read_b128 v[150:153], v182
	ds_read_b128 v[154:157], v182 offset:1024
	ds_read_b128 v[158:161], v182 offset:2048
	ds_read_b128 v[162:165], v182 offset:3072
	s_cmpk_eq_i32 s69, 0x52
	s_cselect_b32 s31, s19, s66
	s_cselect_b32 s30, s64, s65
	s_cselect_b32 s35, s21, s68
	s_cselect_b32 s34, s63, s67
	ds_read_b128 v[166:169], v183
	ds_read_b128 v[170:173], v183 offset:1024
	ds_read_b128 v[186:189], v183 offset:2048
	ds_read_b128 v[190:193], v183 offset:3072
	ds_read_b128 v[194:197], v183 offset:4096
	ds_read_b128 v[198:201], v183 offset:5120
	ds_read_b128 v[202:205], v183 offset:6144
	ds_read_b128 v[206:209], v183 offset:7168
	s_add_u32 s70, s28, 0xffffc000
	s_addc_u32 s71, s29, -1
	s_mov_b32 s73, m0
	s_mov_b32 m0, s57
	s_nop 0
	global_load_lds_dwordx4 v1, s[70:71]
	s_mov_b32 m0, s73
	s_nop 0
	s_mov_b32 s73, m0
	s_mov_b32 m0, s59
	s_nop 0
	global_load_lds_dwordx4 v177, s[70:71]
	s_mov_b32 m0, s73
	s_mov_b32 s70, m0
	s_mov_b32 m0, s58
	s_nop 0
	global_load_lds_dwordx4 v1, s[28:29]
	s_mov_b32 m0, s70
	s_nop 0
	s_mov_b32 s70, m0
	s_mov_b32 m0, s60
	s_nop 0
	global_load_lds_dwordx4 v177, s[28:29]
	s_mov_b32 m0, s70
	s_waitcnt vmcnt(8)
	s_waitcnt lgkmcnt(0)
	s_barrier
	s_setprio 1
	s_waitcnt lgkmcnt(7)
	v_mfma_f32_16x16x32_bf16 v[126:129], v[130:133], v[166:169], v[126:129]
	v_mfma_f32_16x16x32_bf16 v[126:129], v[134:137], v[170:173], v[126:129]
	s_waitcnt lgkmcnt(5)
	v_mfma_f32_16x16x32_bf16 v[122:125], v[138:141], v[166:169], v[122:125]
	v_mfma_f32_16x16x32_bf16 v[122:125], v[142:145], v[170:173], v[122:125]
	s_waitcnt lgkmcnt(3)
	v_mfma_f32_16x16x32_bf16 v[118:121], v[130:133], v[186:189], v[118:121]
	v_mfma_f32_16x16x32_bf16 v[118:121], v[134:137], v[190:193], v[118:121]
	s_waitcnt lgkmcnt(1)
	v_mfma_f32_16x16x32_bf16 v[110:113], v[138:141], v[186:189], v[110:113]
	v_mfma_f32_16x16x32_bf16 v[110:113], v[142:145], v[190:193], v[110:113]
	v_mfma_f32_16x16x32_bf16 v[94:97], v[130:133], v[194:197], v[94:97]
	v_mfma_f32_16x16x32_bf16 v[94:97], v[134:137], v[198:201], v[94:97]
	v_mfma_f32_16x16x32_bf16 v[90:93], v[138:141], v[194:197], v[90:93]
	v_mfma_f32_16x16x32_bf16 v[90:93], v[142:145], v[198:201], v[90:93]
	v_mfma_f32_16x16x32_bf16 v[86:89], v[130:133], v[202:205], v[86:89]
	v_mfma_f32_16x16x32_bf16 v[86:89], v[134:137], v[206:209], v[86:89]
	s_waitcnt lgkmcnt(0)
	v_mfma_f32_16x16x32_bf16 v[78:81], v[138:141], v[202:205], v[78:81]
	v_mfma_f32_16x16x32_bf16 v[78:81], v[142:145], v[206:209], v[78:81]
	s_setprio 0
	s_setprio 1
	v_mfma_f32_16x16x32_bf16 v[114:117], v[150:153], v[166:169], v[114:117]
	v_mfma_f32_16x16x32_bf16 v[114:117], v[154:157], v[170:173], v[114:117]
	v_mfma_f32_16x16x32_bf16 v[106:109], v[158:161], v[166:169], v[106:109]
	v_mfma_f32_16x16x32_bf16 v[106:109], v[162:165], v[170:173], v[106:109]
	v_mfma_f32_16x16x32_bf16 v[102:105], v[150:153], v[186:189], v[102:105]
	v_mfma_f32_16x16x32_bf16 v[102:105], v[154:157], v[190:193], v[102:105]
	v_mfma_f32_16x16x32_bf16 v[98:101], v[158:161], v[186:189], v[98:101]
	v_mfma_f32_16x16x32_bf16 v[98:101], v[162:165], v[190:193], v[98:101]
	v_mfma_f32_16x16x32_bf16 v[82:85], v[150:153], v[194:197], v[82:85]
	v_mfma_f32_16x16x32_bf16 v[82:85], v[154:157], v[198:201], v[82:85]
	v_mfma_f32_16x16x32_bf16 v[74:77], v[158:161], v[194:197], v[74:77]
	v_mfma_f32_16x16x32_bf16 v[74:77], v[162:165], v[198:201], v[74:77]
	v_mfma_f32_16x16x32_bf16 v[70:73], v[150:153], v[202:205], v[70:73]
	v_mfma_f32_16x16x32_bf16 v[70:73], v[154:157], v[206:209], v[70:73]
	s_setprio 2
	s_barrier
	v_mfma_f32_16x16x32_bf16 v[66:69], v[158:161], v[202:205], v[66:69]
	v_mfma_f32_16x16x32_bf16 v[66:69], v[162:165], v[206:209], v[66:69]
	s_setprio 0
	ds_read_b128 v[166:169], v183 offset:16384
	ds_read_b128 v[170:173], v183 offset:17408
	ds_read_b128 v[186:189], v183 offset:18432
	ds_read_b128 v[190:193], v183 offset:19456
	ds_read_b128 v[194:197], v183 offset:20480
	ds_read_b128 v[198:201], v183 offset:21504
	ds_read_b128 v[202:205], v183 offset:22528
	ds_read_b128 v[206:209], v183 offset:23552
	s_mov_b32 s70, m0
	s_mov_b32 m0, s27
	s_nop 0
	global_load_lds_dwordx4 v176, s[30:31]
	s_mov_b32 m0, s70
	s_nop 0
	s_mov_b32 s70, m0
	s_mov_b32 m0, s45
	s_nop 0
	global_load_lds_dwordx4 v178, s[30:31]
	s_mov_b32 m0, s70
	s_add_u32 s70, s30, 0x4000
	s_addc_u32 s71, s31, 0
	s_mov_b32 s73, m0
	s_mov_b32 m0, s46
	s_nop 0
	global_load_lds_dwordx4 v176, s[70:71]
	s_mov_b32 m0, s73
	s_nop 0
	s_mov_b32 s73, m0
	s_mov_b32 m0, s47
	s_nop 0
	global_load_lds_dwordx4 v178, s[70:71]
	s_mov_b32 m0, s73
	s_waitcnt vmcnt(4)
	s_waitcnt lgkmcnt(0)
	s_barrier
	s_setprio 1
	s_waitcnt lgkmcnt(7)
	v_mfma_f32_16x16x32_bf16 v[62:65], v[130:133], v[166:169], v[62:65]
	v_mfma_f32_16x16x32_bf16 v[62:65], v[134:137], v[170:173], v[62:65]
	s_waitcnt lgkmcnt(5)
	v_mfma_f32_16x16x32_bf16 v[58:61], v[138:141], v[166:169], v[58:61]
	v_mfma_f32_16x16x32_bf16 v[58:61], v[142:145], v[170:173], v[58:61]
	s_waitcnt lgkmcnt(3)
	v_mfma_f32_16x16x32_bf16 v[46:49], v[130:133], v[186:189], v[46:49]
	v_mfma_f32_16x16x32_bf16 v[46:49], v[134:137], v[190:193], v[46:49]
	s_waitcnt lgkmcnt(1)
	v_mfma_f32_16x16x32_bf16 v[42:45], v[138:141], v[186:189], v[42:45]
	v_mfma_f32_16x16x32_bf16 v[42:45], v[142:145], v[190:193], v[42:45]
	v_mfma_f32_16x16x32_bf16 v[30:33], v[130:133], v[194:197], v[30:33]
	v_mfma_f32_16x16x32_bf16 v[30:33], v[134:137], v[198:201], v[30:33]
	v_mfma_f32_16x16x32_bf16 v[26:29], v[138:141], v[194:197], v[26:29]
	v_mfma_f32_16x16x32_bf16 v[26:29], v[142:145], v[198:201], v[26:29]
	v_mfma_f32_16x16x32_bf16 v[14:17], v[130:133], v[202:205], v[14:17]
	v_mfma_f32_16x16x32_bf16 v[14:17], v[134:137], v[206:209], v[14:17]
	s_waitcnt lgkmcnt(0)
	v_mfma_f32_16x16x32_bf16 v[10:13], v[138:141], v[202:205], v[10:13]
	v_mfma_f32_16x16x32_bf16 v[10:13], v[142:145], v[206:209], v[10:13]
	s_setprio 0
	s_setprio 1
	v_mfma_f32_16x16x32_bf16 v[54:57], v[150:153], v[166:169], v[54:57]
	v_mfma_f32_16x16x32_bf16 v[54:57], v[154:157], v[170:173], v[54:57]
	v_mfma_f32_16x16x32_bf16 v[50:53], v[158:161], v[166:169], v[50:53]
	v_mfma_f32_16x16x32_bf16 v[50:53], v[162:165], v[170:173], v[50:53]
	v_mfma_f32_16x16x32_bf16 v[38:41], v[150:153], v[186:189], v[38:41]
	v_mfma_f32_16x16x32_bf16 v[38:41], v[154:157], v[190:193], v[38:41]
	v_mfma_f32_16x16x32_bf16 v[34:37], v[158:161], v[186:189], v[34:37]
	v_mfma_f32_16x16x32_bf16 v[34:37], v[162:165], v[190:193], v[34:37]
	v_mfma_f32_16x16x32_bf16 v[22:25], v[150:153], v[194:197], v[22:25]
	v_mfma_f32_16x16x32_bf16 v[22:25], v[154:157], v[198:201], v[22:25]
	v_mfma_f32_16x16x32_bf16 v[18:21], v[158:161], v[194:197], v[18:21]
	v_mfma_f32_16x16x32_bf16 v[18:21], v[162:165], v[198:201], v[18:21]
	v_mfma_f32_16x16x32_bf16 v[6:9], v[150:153], v[202:205], v[6:9]
	v_mfma_f32_16x16x32_bf16 v[6:9], v[154:157], v[206:209], v[6:9]
	s_setprio 2
	s_barrier
	v_mfma_f32_16x16x32_bf16 v[2:5], v[158:161], v[202:205], v[2:5]
	v_mfma_f32_16x16x32_bf16 v[2:5], v[162:165], v[206:209], v[2:5]
	s_setprio 0
	ds_read_b128 v[130:133], v184
	ds_read_b128 v[134:137], v184 offset:1024
	ds_read_b128 v[138:141], v184 offset:2048
	ds_read_b128 v[142:145], v184 offset:3072
	ds_read_b128 v[150:153], v185
	ds_read_b128 v[154:157], v185 offset:1024
	ds_read_b128 v[158:161], v185 offset:2048
	ds_read_b128 v[162:165], v185 offset:3072
	ds_read_b128 v[166:169], v183 offset:32768
	ds_read_b128 v[170:173], v183 offset:33792
	ds_read_b128 v[186:189], v183 offset:34816
	ds_read_b128 v[190:193], v183 offset:35840
	ds_read_b128 v[194:197], v183 offset:36864
	ds_read_b128 v[198:201], v183 offset:37888
	ds_read_b128 v[202:205], v183 offset:38912
	ds_read_b128 v[206:209], v183 offset:39936
	s_mov_b32 s70, m0
	s_mov_b32 m0, s44
	s_nop 0
	global_load_lds_dwordx4 v1, s[34:35]
	s_mov_b32 m0, s70
	s_nop 0
	s_mov_b32 s70, m0
	s_mov_b32 m0, s48
	s_nop 0
	global_load_lds_dwordx4 v177, s[34:35]
	s_mov_b32 m0, s70
	s_add_u32 s34, s34, 0x4000
	s_addc_u32 s35, s35, 0
	s_mov_b32 s70, m0
	s_mov_b32 m0, s49
	s_nop 0
	global_load_lds_dwordx4 v1, s[34:35]
	s_mov_b32 m0, s70
	s_nop 0
	s_mov_b32 s70, m0
	s_mov_b32 m0, s50
	s_nop 0
	global_load_lds_dwordx4 v177, s[34:35]
	s_mov_b32 m0, s70
	s_waitcnt vmcnt(8)
	s_waitcnt lgkmcnt(0)
	s_barrier
	s_setprio 1
	s_waitcnt lgkmcnt(7)
	v_mfma_f32_16x16x32_bf16 v[126:129], v[130:133], v[166:169], v[126:129]
	v_mfma_f32_16x16x32_bf16 v[126:129], v[134:137], v[170:173], v[126:129]
	s_waitcnt lgkmcnt(5)
	v_mfma_f32_16x16x32_bf16 v[122:125], v[138:141], v[166:169], v[122:125]
	v_mfma_f32_16x16x32_bf16 v[122:125], v[142:145], v[170:173], v[122:125]
	s_waitcnt lgkmcnt(3)
	v_mfma_f32_16x16x32_bf16 v[118:121], v[130:133], v[186:189], v[118:121]
	v_mfma_f32_16x16x32_bf16 v[118:121], v[134:137], v[190:193], v[118:121]
	s_waitcnt lgkmcnt(1)
	v_mfma_f32_16x16x32_bf16 v[110:113], v[138:141], v[186:189], v[110:113]
	v_mfma_f32_16x16x32_bf16 v[110:113], v[142:145], v[190:193], v[110:113]
	v_mfma_f32_16x16x32_bf16 v[94:97], v[130:133], v[194:197], v[94:97]
	v_mfma_f32_16x16x32_bf16 v[94:97], v[134:137], v[198:201], v[94:97]
	v_mfma_f32_16x16x32_bf16 v[90:93], v[138:141], v[194:197], v[90:93]
	v_mfma_f32_16x16x32_bf16 v[90:93], v[142:145], v[198:201], v[90:93]
	v_mfma_f32_16x16x32_bf16 v[86:89], v[130:133], v[202:205], v[86:89]
	v_mfma_f32_16x16x32_bf16 v[86:89], v[134:137], v[206:209], v[86:89]
	s_waitcnt lgkmcnt(0)
	v_mfma_f32_16x16x32_bf16 v[78:81], v[138:141], v[202:205], v[78:81]
	v_mfma_f32_16x16x32_bf16 v[78:81], v[142:145], v[206:209], v[78:81]
	s_setprio 0
	s_setprio 1
	v_mfma_f32_16x16x32_bf16 v[114:117], v[150:153], v[166:169], v[114:117]
	v_mfma_f32_16x16x32_bf16 v[114:117], v[154:157], v[170:173], v[114:117]
	v_mfma_f32_16x16x32_bf16 v[106:109], v[158:161], v[166:169], v[106:109]
	v_mfma_f32_16x16x32_bf16 v[106:109], v[162:165], v[170:173], v[106:109]
	v_mfma_f32_16x16x32_bf16 v[102:105], v[150:153], v[186:189], v[102:105]
	v_mfma_f32_16x16x32_bf16 v[102:105], v[154:157], v[190:193], v[102:105]
	v_mfma_f32_16x16x32_bf16 v[98:101], v[158:161], v[186:189], v[98:101]
	v_mfma_f32_16x16x32_bf16 v[98:101], v[162:165], v[190:193], v[98:101]
	v_mfma_f32_16x16x32_bf16 v[82:85], v[150:153], v[194:197], v[82:85]
	v_mfma_f32_16x16x32_bf16 v[82:85], v[154:157], v[198:201], v[82:85]
	v_mfma_f32_16x16x32_bf16 v[74:77], v[158:161], v[194:197], v[74:77]
	v_mfma_f32_16x16x32_bf16 v[74:77], v[162:165], v[198:201], v[74:77]
	v_mfma_f32_16x16x32_bf16 v[70:73], v[150:153], v[202:205], v[70:73]
	v_mfma_f32_16x16x32_bf16 v[70:73], v[154:157], v[206:209], v[70:73]
	s_setprio 2
	s_barrier
	v_mfma_f32_16x16x32_bf16 v[66:69], v[158:161], v[202:205], v[66:69]
	v_mfma_f32_16x16x32_bf16 v[66:69], v[162:165], v[206:209], v[66:69]
	s_setprio 0
	ds_read_b128 v[166:169], v183 offset:49152
	ds_read_b128 v[170:173], v183 offset:50176
	ds_read_b128 v[186:189], v183 offset:51200
	ds_read_b128 v[190:193], v183 offset:52224
	ds_read_b128 v[194:197], v183 offset:53248
	ds_read_b128 v[198:201], v183 offset:54272
	ds_read_b128 v[202:205], v183 offset:55296
	ds_read_b128 v[206:209], v183 offset:56320
	s_add_u32 s34, s30, 0x40000
	s_addc_u32 s35, s31, 0
	s_mov_b32 s70, m0
	s_mov_b32 m0, s51
	s_nop 0
	global_load_lds_dwordx4 v176, s[34:35]
	s_mov_b32 m0, s70
	s_add_u32 s30, s30, 0x44000
	s_mov_b32 s70, m0
	s_mov_b32 m0, s52
	s_nop 0
	global_load_lds_dwordx4 v178, s[34:35]
	s_mov_b32 m0, s70
	s_addc_u32 s31, s31, 0
	s_mov_b32 s34, m0
	s_mov_b32 m0, s53
	s_nop 0
	global_load_lds_dwordx4 v176, s[30:31]
	s_mov_b32 m0, s34
	s_nop 0
	s_mov_b32 s34, m0
	s_mov_b32 m0, s54
	s_nop 0
	global_load_lds_dwordx4 v178, s[30:31]
	s_mov_b32 m0, s34
	s_waitcnt vmcnt(4)
	s_waitcnt lgkmcnt(0)
	s_barrier
	s_setprio 1
	s_waitcnt lgkmcnt(7)
	v_mfma_f32_16x16x32_bf16 v[62:65], v[130:133], v[166:169], v[62:65]
	v_mfma_f32_16x16x32_bf16 v[62:65], v[134:137], v[170:173], v[62:65]
	s_waitcnt lgkmcnt(5)
	v_mfma_f32_16x16x32_bf16 v[58:61], v[138:141], v[166:169], v[58:61]
	v_mfma_f32_16x16x32_bf16 v[58:61], v[142:145], v[170:173], v[58:61]
	s_waitcnt lgkmcnt(3)
	v_mfma_f32_16x16x32_bf16 v[46:49], v[130:133], v[186:189], v[46:49]
	v_mfma_f32_16x16x32_bf16 v[46:49], v[134:137], v[190:193], v[46:49]
	s_waitcnt lgkmcnt(1)
	v_mfma_f32_16x16x32_bf16 v[42:45], v[138:141], v[186:189], v[42:45]
	v_mfma_f32_16x16x32_bf16 v[42:45], v[142:145], v[190:193], v[42:45]
	v_mfma_f32_16x16x32_bf16 v[30:33], v[130:133], v[194:197], v[30:33]
	v_mfma_f32_16x16x32_bf16 v[30:33], v[134:137], v[198:201], v[30:33]
	v_mfma_f32_16x16x32_bf16 v[26:29], v[138:141], v[194:197], v[26:29]
	v_mfma_f32_16x16x32_bf16 v[26:29], v[142:145], v[198:201], v[26:29]
	v_mfma_f32_16x16x32_bf16 v[14:17], v[130:133], v[202:205], v[14:17]
	v_mfma_f32_16x16x32_bf16 v[14:17], v[134:137], v[206:209], v[14:17]
	s_waitcnt lgkmcnt(0)
	v_mfma_f32_16x16x32_bf16 v[10:13], v[138:141], v[202:205], v[10:13]
	v_mfma_f32_16x16x32_bf16 v[10:13], v[142:145], v[206:209], v[10:13]
	s_setprio 0
	s_setprio 1
	v_mfma_f32_16x16x32_bf16 v[54:57], v[150:153], v[166:169], v[54:57]
	v_mfma_f32_16x16x32_bf16 v[54:57], v[154:157], v[170:173], v[54:57]
	v_mfma_f32_16x16x32_bf16 v[50:53], v[158:161], v[166:169], v[50:53]
	v_mfma_f32_16x16x32_bf16 v[50:53], v[162:165], v[170:173], v[50:53]
	v_mfma_f32_16x16x32_bf16 v[38:41], v[150:153], v[186:189], v[38:41]
	v_mfma_f32_16x16x32_bf16 v[38:41], v[154:157], v[190:193], v[38:41]
	v_mfma_f32_16x16x32_bf16 v[34:37], v[158:161], v[186:189], v[34:37]
	v_mfma_f32_16x16x32_bf16 v[34:37], v[162:165], v[190:193], v[34:37]
	v_mfma_f32_16x16x32_bf16 v[22:25], v[150:153], v[194:197], v[22:25]
	v_mfma_f32_16x16x32_bf16 v[22:25], v[154:157], v[198:201], v[22:25]
	v_mfma_f32_16x16x32_bf16 v[18:21], v[158:161], v[194:197], v[18:21]
	v_mfma_f32_16x16x32_bf16 v[18:21], v[162:165], v[198:201], v[18:21]
	v_mfma_f32_16x16x32_bf16 v[6:9], v[150:153], v[202:205], v[6:9]
	v_mfma_f32_16x16x32_bf16 v[6:9], v[154:157], v[206:209], v[6:9]
	s_setprio 2
	s_barrier
	v_mfma_f32_16x16x32_bf16 v[2:5], v[158:161], v[202:205], v[2:5]
	v_mfma_f32_16x16x32_bf16 v[2:5], v[162:165], v[206:209], v[2:5]
	s_setprio 0
	s_add_i32 s69, s69, 2
	s_add_u32 s65, s65, 0x80000
	s_addc_u32 s66, s66, 0
	s_add_u32 s28, s28, 0x400000
	s_addc_u32 s29, s29, 0
	s_add_u32 s67, s67, 0x400000
	s_addc_u32 s68, s68, 0
	s_cmpk_gt_u32 s69, 0x53
	s_cbranch_scc0 .LBB0_2792
	s_and_b64 vcc, exec, s[8:9]
	s_cbranch_vccz .LBB0_2795
	s_barrier
